# v60 + post-MMA s_barrier issued before s_setprio 0 (arrive one issue slot earlier)
# baseline (speedup 1.0000x reference)
.LBB0_297:
	s_add_u32 s47, s38, s46
	s_addc_u32 s66, s39, 0
	s_add_u32 s64, s47, 0x100
	s_addc_u32 s65, s66, 0
	s_and_b64 s[48:49], s[44:45], exec
	s_cselect_b32 s49, s70, s65
	s_cselect_b32 s48, s71, s64
	s_add_u32 s46, s36, s46
	s_addc_u32 s64, s37, 0
	s_add_u32 s46, s46, 0x100
	s_addc_u32 s64, s64, 0
	s_and_b64 s[44:45], s[44:45], exec
	s_cselect_b32 s65, s72, s64
	s_cselect_b32 s64, s73, s46
	s_add_u32 s68, s47, 0x10080
	ds_read_b128 v[150:153], v146
	ds_read_b128 v[154:157], v146 offset:1024
	ds_read_b128 v[158:161], v146 offset:2048
	ds_read_b128 v[162:165], v146 offset:3072
	ds_read_b128 v[166:169], v147
	ds_read_b128 v[170:173], v147 offset:1024
	ds_read_b128 v[174:177], v147 offset:2048
	ds_read_b128 v[178:181], v147 offset:3072
	s_addc_u32 s69, s66, 0
	s_add_i32 s83, s30, s2
	s_add_i32 m0, s16, 0xc000
	s_add_i32 s84, s16, 0xe000
	s_add_i32 s80, s83, 0x2000
	s_add_u32 s66, s64, 0x40000
	s_addc_u32 s67, s65, 0
	s_add_i32 s82, s31, s2
	s_add_i32 s81, s82, 0x2000
	s_add_i32 s79, 0, 0x18000
	s_add_i32 s78, 0, 0x1c000
	s_add_u32 s46, s48, 0x10000
	s_addc_u32 s47, s49, 0
	s_add_i32 s77, s79, s2
	s_add_i32 s75, s77, 0x2000
	s_add_u32 s44, s64, 0x40080
	s_addc_u32 s45, s65, 0
	s_add_i32 s76, s78, s2
	s_add_i32 s74, s76, 0x2000
	v_lshl_add_u64 v[202:203], s[68:69], 0, v[130:131]
	ds_read_b128 v[182:185], v148
	ds_read_b128 v[186:189], v148 offset:1024
	ds_read_b128 v[190:193], v148 offset:2048
	ds_read_b128 v[194:197], v148 offset:3072
	ds_read_b128 v[198:201], v148 offset:4096
	ds_read_b128 v[206:209], v148 offset:5120
	ds_read_b128 v[210:213], v148 offset:6144
	ds_read_b128 v[214:217], v148 offset:7168
	global_load_lds_dwordx4 v[202:203], off
	v_lshl_add_u64 v[202:203], s[68:69], 0, v[132:133]
	s_mov_b32 m0, s84
	s_nop 0
	global_load_lds_dwordx4 v[202:203], off
	s_waitcnt vmcnt(8)
	s_waitcnt lgkmcnt(0)
	s_setprio 1
	s_barrier
	v_mfma_f32_16x16x32_bf16 v[126:129], v[150:153], v[182:185], v[126:129]
	v_mfma_f32_16x16x32_bf16 v[122:125], v[158:161], v[182:185], v[122:125]
	v_mfma_f32_16x16x32_bf16 v[118:121], v[150:153], v[190:193], v[118:121]
	v_mfma_f32_16x16x32_bf16 v[114:117], v[158:161], v[190:193], v[114:117]
	v_mfma_f32_16x16x32_bf16 v[102:105], v[150:153], v[198:201], v[102:105]
	v_mfma_f32_16x16x32_bf16 v[98:101], v[158:161], v[198:201], v[98:101]
	v_mfma_f32_16x16x32_bf16 v[86:89], v[150:153], v[210:213], v[86:89]
	v_mfma_f32_16x16x32_bf16 v[82:85], v[158:161], v[210:213], v[82:85]
	v_mfma_f32_16x16x32_bf16 v[126:129], v[154:157], v[186:189], v[126:129]
	v_mfma_f32_16x16x32_bf16 v[122:125], v[162:165], v[186:189], v[122:125]
	v_mfma_f32_16x16x32_bf16 v[118:121], v[154:157], v[194:197], v[118:121]
	v_mfma_f32_16x16x32_bf16 v[114:117], v[162:165], v[194:197], v[114:117]
	v_mfma_f32_16x16x32_bf16 v[102:105], v[154:157], v[206:209], v[102:105]
	v_mfma_f32_16x16x32_bf16 v[98:101], v[162:165], v[206:209], v[98:101]
	v_mfma_f32_16x16x32_bf16 v[86:89], v[154:157], v[214:217], v[86:89]
	v_mfma_f32_16x16x32_bf16 v[82:85], v[162:165], v[214:217], v[82:85]
	v_mfma_f32_16x16x32_bf16 v[110:113], v[166:169], v[182:185], v[110:113]
	v_mfma_f32_16x16x32_bf16 v[106:109], v[174:177], v[182:185], v[106:109]
	v_mfma_f32_16x16x32_bf16 v[94:97], v[166:169], v[190:193], v[94:97]
	v_mfma_f32_16x16x32_bf16 v[90:93], v[174:177], v[190:193], v[90:93]
	v_mfma_f32_16x16x32_bf16 v[78:81], v[166:169], v[198:201], v[78:81]
	v_mfma_f32_16x16x32_bf16 v[74:77], v[174:177], v[198:201], v[74:77]
	v_mfma_f32_16x16x32_bf16 v[70:73], v[166:169], v[210:213], v[70:73]
	v_mfma_f32_16x16x32_bf16 v[66:69], v[174:177], v[210:213], v[66:69]
	v_mfma_f32_16x16x32_bf16 v[110:113], v[170:173], v[186:189], v[110:113]
	v_mfma_f32_16x16x32_bf16 v[106:109], v[178:181], v[186:189], v[106:109]
	v_mfma_f32_16x16x32_bf16 v[94:97], v[170:173], v[194:197], v[94:97]
	v_mfma_f32_16x16x32_bf16 v[90:93], v[178:181], v[194:197], v[90:93]
	v_mfma_f32_16x16x32_bf16 v[78:81], v[170:173], v[206:209], v[78:81]
	v_mfma_f32_16x16x32_bf16 v[74:77], v[178:181], v[206:209], v[74:77]
	v_mfma_f32_16x16x32_bf16 v[70:73], v[170:173], v[214:217], v[70:73]
	v_mfma_f32_16x16x32_bf16 v[66:69], v[178:181], v[214:217], v[66:69]
	s_barrier
	s_setprio 0
	s_mov_b32 m0, s83
	v_lshl_add_u64 v[202:203], s[64:65], 0, v[136:137]
	ds_read_b128 v[182:185], v148 offset:16384
	ds_read_b128 v[186:189], v148 offset:17408
	ds_read_b128 v[190:193], v148 offset:18432
	ds_read_b128 v[194:197], v148 offset:19456
	ds_read_b128 v[198:201], v148 offset:20480
	ds_read_b128 v[206:209], v148 offset:21504
	ds_read_b128 v[210:213], v148 offset:22528
	ds_read_b128 v[214:217], v148 offset:23552
	global_load_lds_dwordx4 v[202:203], off
	v_lshl_add_u64 v[218:219], s[64:65], 0, v[134:135]
	s_mov_b32 m0, s80
	v_lshl_add_u64 v[220:221], s[66:67], 0, v[136:137]
	global_load_lds_dwordx4 v[218:219], off
	s_mov_b32 m0, s82
	v_lshl_add_u64 v[222:223], s[48:49], 0, v[132:133]
	global_load_lds_dwordx4 v[220:221], off
	v_lshl_add_u64 v[220:221], s[66:67], 0, v[134:135]
	s_mov_b32 m0, s81
	s_nop 0
	global_load_lds_dwordx4 v[220:221], off
	v_lshl_add_u64 v[220:221], s[48:49], 0, v[130:131]
	s_mov_b32 m0, s16
	s_nop 0
	global_load_lds_dwordx4 v[220:221], off
	s_mov_b32 m0, s17
	s_nop 0
	global_load_lds_dwordx4 v[222:223], off
	s_waitcnt vmcnt(8)
	s_waitcnt lgkmcnt(0)
	s_setprio 1
	s_barrier
	v_mfma_f32_16x16x32_bf16 v[62:65], v[150:153], v[182:185], v[62:65]
	v_mfma_f32_16x16x32_bf16 v[58:61], v[158:161], v[182:185], v[58:61]
	v_mfma_f32_16x16x32_bf16 v[54:57], v[150:153], v[190:193], v[54:57]
	v_mfma_f32_16x16x32_bf16 v[50:53], v[158:161], v[190:193], v[50:53]
	v_mfma_f32_16x16x32_bf16 v[38:41], v[150:153], v[198:201], v[38:41]
	v_mfma_f32_16x16x32_bf16 v[34:37], v[158:161], v[198:201], v[34:37]
	v_mfma_f32_16x16x32_bf16 v[22:25], v[150:153], v[210:213], v[22:25]
	v_mfma_f32_16x16x32_bf16 v[18:21], v[158:161], v[210:213], v[18:21]
	v_mfma_f32_16x16x32_bf16 v[62:65], v[154:157], v[186:189], v[62:65]
	v_mfma_f32_16x16x32_bf16 v[58:61], v[162:165], v[186:189], v[58:61]
	v_mfma_f32_16x16x32_bf16 v[54:57], v[154:157], v[194:197], v[54:57]
	v_mfma_f32_16x16x32_bf16 v[50:53], v[162:165], v[194:197], v[50:53]
	v_mfma_f32_16x16x32_bf16 v[38:41], v[154:157], v[206:209], v[38:41]
	v_mfma_f32_16x16x32_bf16 v[34:37], v[162:165], v[206:209], v[34:37]
	v_mfma_f32_16x16x32_bf16 v[22:25], v[154:157], v[214:217], v[22:25]
	v_mfma_f32_16x16x32_bf16 v[18:21], v[162:165], v[214:217], v[18:21]
	v_mfma_f32_16x16x32_bf16 v[46:49], v[166:169], v[182:185], v[46:49]
	v_mfma_f32_16x16x32_bf16 v[42:45], v[174:177], v[182:185], v[42:45]
	v_mfma_f32_16x16x32_bf16 v[30:33], v[166:169], v[190:193], v[30:33]
	v_mfma_f32_16x16x32_bf16 v[26:29], v[174:177], v[190:193], v[26:29]
	v_mfma_f32_16x16x32_bf16 v[14:17], v[166:169], v[198:201], v[14:17]
	v_mfma_f32_16x16x32_bf16 v[10:13], v[174:177], v[198:201], v[10:13]
	v_mfma_f32_16x16x32_bf16 v[6:9], v[166:169], v[210:213], v[6:9]
	v_mfma_f32_16x16x32_bf16 v[2:5], v[174:177], v[210:213], v[2:5]
	v_mfma_f32_16x16x32_bf16 v[46:49], v[170:173], v[186:189], v[46:49]
	v_mfma_f32_16x16x32_bf16 v[42:45], v[178:181], v[186:189], v[42:45]
	v_mfma_f32_16x16x32_bf16 v[30:33], v[170:173], v[194:197], v[30:33]
	v_mfma_f32_16x16x32_bf16 v[26:29], v[178:181], v[194:197], v[26:29]
	v_mfma_f32_16x16x32_bf16 v[14:17], v[170:173], v[206:209], v[14:17]
	v_mfma_f32_16x16x32_bf16 v[10:13], v[178:181], v[206:209], v[10:13]
	v_mfma_f32_16x16x32_bf16 v[6:9], v[170:173], v[214:217], v[6:9]
	v_mfma_f32_16x16x32_bf16 v[2:5], v[178:181], v[214:217], v[2:5]
	s_barrier
	s_setprio 0
	v_add_u32_e32 v149, s79, v145
	ds_read_b128 v[150:153], v149
	ds_read_b128 v[154:157], v149 offset:1024
	ds_read_b128 v[158:161], v149 offset:2048
	ds_read_b128 v[162:165], v149 offset:3072
	v_add_u32_e32 v149, s78, v145
	ds_read_b128 v[166:169], v149
	ds_read_b128 v[170:173], v149 offset:1024
	ds_read_b128 v[174:177], v149 offset:2048
	ds_read_b128 v[178:181], v149 offset:3072
	s_mov_b32 m0, s18
	v_lshl_add_u64 v[224:225], s[46:47], 0, v[130:131]
	ds_read_b128 v[182:185], v148 offset:32768
	ds_read_b128 v[186:189], v148 offset:33792
	ds_read_b128 v[190:193], v148 offset:34816
	ds_read_b128 v[194:197], v148 offset:35840
	ds_read_b128 v[198:201], v148 offset:36864
	ds_read_b128 v[206:209], v148 offset:37888
	ds_read_b128 v[210:213], v148 offset:38912
	ds_read_b128 v[214:217], v148 offset:39936
	global_load_lds_dwordx4 v[224:225], off
	v_lshl_add_u64 v[224:225], s[46:47], 0, v[132:133]
	s_mov_b32 m0, s19
	s_nop 0
	global_load_lds_dwordx4 v[224:225], off
	s_waitcnt vmcnt(8)
	s_waitcnt lgkmcnt(0)
	s_setprio 1
	s_barrier
	v_mfma_f32_16x16x32_bf16 v[126:129], v[150:153], v[182:185], v[126:129]
	v_mfma_f32_16x16x32_bf16 v[122:125], v[158:161], v[182:185], v[122:125]
	v_mfma_f32_16x16x32_bf16 v[118:121], v[150:153], v[190:193], v[118:121]
	v_mfma_f32_16x16x32_bf16 v[114:117], v[158:161], v[190:193], v[114:117]
	v_mfma_f32_16x16x32_bf16 v[102:105], v[150:153], v[198:201], v[102:105]
	v_mfma_f32_16x16x32_bf16 v[98:101], v[158:161], v[198:201], v[98:101]
	v_mfma_f32_16x16x32_bf16 v[86:89], v[150:153], v[210:213], v[86:89]
	v_mfma_f32_16x16x32_bf16 v[82:85], v[158:161], v[210:213], v[82:85]
	v_mfma_f32_16x16x32_bf16 v[126:129], v[154:157], v[186:189], v[126:129]
	v_mfma_f32_16x16x32_bf16 v[122:125], v[162:165], v[186:189], v[122:125]
	v_mfma_f32_16x16x32_bf16 v[118:121], v[154:157], v[194:197], v[118:121]
	v_mfma_f32_16x16x32_bf16 v[114:117], v[162:165], v[194:197], v[114:117]
	v_mfma_f32_16x16x32_bf16 v[102:105], v[154:157], v[206:209], v[102:105]
	v_mfma_f32_16x16x32_bf16 v[98:101], v[162:165], v[206:209], v[98:101]
	v_mfma_f32_16x16x32_bf16 v[86:89], v[154:157], v[214:217], v[86:89]
	v_mfma_f32_16x16x32_bf16 v[82:85], v[162:165], v[214:217], v[82:85]
	v_mfma_f32_16x16x32_bf16 v[110:113], v[166:169], v[182:185], v[110:113]
	v_mfma_f32_16x16x32_bf16 v[106:109], v[174:177], v[182:185], v[106:109]
	v_mfma_f32_16x16x32_bf16 v[94:97], v[166:169], v[190:193], v[94:97]
	v_mfma_f32_16x16x32_bf16 v[90:93], v[174:177], v[190:193], v[90:93]
	v_mfma_f32_16x16x32_bf16 v[78:81], v[166:169], v[198:201], v[78:81]
	v_mfma_f32_16x16x32_bf16 v[74:77], v[174:177], v[198:201], v[74:77]
	v_mfma_f32_16x16x32_bf16 v[70:73], v[166:169], v[210:213], v[70:73]
	v_mfma_f32_16x16x32_bf16 v[66:69], v[174:177], v[210:213], v[66:69]
	v_mfma_f32_16x16x32_bf16 v[110:113], v[170:173], v[186:189], v[110:113]
	v_mfma_f32_16x16x32_bf16 v[106:109], v[178:181], v[186:189], v[106:109]
	v_mfma_f32_16x16x32_bf16 v[94:97], v[170:173], v[194:197], v[94:97]
	v_mfma_f32_16x16x32_bf16 v[90:93], v[178:181], v[194:197], v[90:93]
	v_mfma_f32_16x16x32_bf16 v[78:81], v[170:173], v[206:209], v[78:81]
	v_mfma_f32_16x16x32_bf16 v[74:77], v[178:181], v[206:209], v[74:77]
	v_mfma_f32_16x16x32_bf16 v[70:73], v[170:173], v[214:217], v[70:73]
	v_mfma_f32_16x16x32_bf16 v[66:69], v[178:181], v[214:217], v[66:69]
	s_barrier
	s_setprio 0
	s_mov_b32 m0, s77
	v_lshl_add_u64 v[202:203], v[202:203], 0, s[8:9]
	ds_read_b128 v[182:185], v148 offset:49152
	ds_read_b128 v[186:189], v148 offset:50176
	ds_read_b128 v[190:193], v148 offset:51200
	ds_read_b128 v[194:197], v148 offset:52224
	ds_read_b128 v[198:201], v148 offset:53248
	ds_read_b128 v[206:209], v148 offset:54272
	ds_read_b128 v[210:213], v148 offset:55296
	ds_read_b128 v[214:217], v148 offset:56320
	global_load_lds_dwordx4 v[202:203], off
	v_lshl_add_u64 v[202:203], v[218:219], 0, s[8:9]
	s_mov_b32 m0, s75
	s_nop 0
	global_load_lds_dwordx4 v[202:203], off
	v_lshl_add_u64 v[202:203], s[44:45], 0, v[136:137]
	s_mov_b32 m0, s76
	s_nop 0
	global_load_lds_dwordx4 v[202:203], off
	v_lshl_add_u64 v[202:203], s[44:45], 0, v[134:135]
	s_mov_b32 m0, s74
	s_nop 0
	global_load_lds_dwordx4 v[202:203], off
	v_lshl_add_u64 v[202:203], v[220:221], 0, s[8:9]
	s_mov_b32 m0, s28
	s_nop 0
	global_load_lds_dwordx4 v[202:203], off
	v_lshl_add_u64 v[202:203], v[222:223], 0, s[8:9]
	s_mov_b32 m0, s29
	s_nop 0
	global_load_lds_dwordx4 v[202:203], off
	s_waitcnt vmcnt(8)
	s_waitcnt lgkmcnt(0)
	s_setprio 1
	s_barrier
	v_mfma_f32_16x16x32_bf16 v[62:65], v[150:153], v[182:185], v[62:65]
	v_mfma_f32_16x16x32_bf16 v[58:61], v[158:161], v[182:185], v[58:61]
	v_mfma_f32_16x16x32_bf16 v[54:57], v[150:153], v[190:193], v[54:57]
	v_mfma_f32_16x16x32_bf16 v[50:53], v[158:161], v[190:193], v[50:53]
	v_mfma_f32_16x16x32_bf16 v[38:41], v[150:153], v[198:201], v[38:41]
	v_mfma_f32_16x16x32_bf16 v[34:37], v[158:161], v[198:201], v[34:37]
	v_mfma_f32_16x16x32_bf16 v[22:25], v[150:153], v[210:213], v[22:25]
	v_mfma_f32_16x16x32_bf16 v[18:21], v[158:161], v[210:213], v[18:21]
	v_mfma_f32_16x16x32_bf16 v[62:65], v[154:157], v[186:189], v[62:65]
	v_mfma_f32_16x16x32_bf16 v[58:61], v[162:165], v[186:189], v[58:61]
	v_mfma_f32_16x16x32_bf16 v[54:57], v[154:157], v[194:197], v[54:57]
	v_mfma_f32_16x16x32_bf16 v[50:53], v[162:165], v[194:197], v[50:53]
	v_mfma_f32_16x16x32_bf16 v[38:41], v[154:157], v[206:209], v[38:41]
	v_mfma_f32_16x16x32_bf16 v[34:37], v[162:165], v[206:209], v[34:37]
	v_mfma_f32_16x16x32_bf16 v[22:25], v[154:157], v[214:217], v[22:25]
	v_mfma_f32_16x16x32_bf16 v[18:21], v[162:165], v[214:217], v[18:21]
	v_mfma_f32_16x16x32_bf16 v[46:49], v[166:169], v[182:185], v[46:49]
	v_mfma_f32_16x16x32_bf16 v[42:45], v[174:177], v[182:185], v[42:45]
	v_mfma_f32_16x16x32_bf16 v[30:33], v[166:169], v[190:193], v[30:33]
	v_mfma_f32_16x16x32_bf16 v[26:29], v[174:177], v[190:193], v[26:29]
	v_mfma_f32_16x16x32_bf16 v[14:17], v[166:169], v[198:201], v[14:17]
	v_mfma_f32_16x16x32_bf16 v[10:13], v[174:177], v[198:201], v[10:13]
	v_mfma_f32_16x16x32_bf16 v[6:9], v[166:169], v[210:213], v[6:9]
	v_mfma_f32_16x16x32_bf16 v[2:5], v[174:177], v[210:213], v[2:5]
	v_mfma_f32_16x16x32_bf16 v[46:49], v[170:173], v[186:189], v[46:49]
	v_mfma_f32_16x16x32_bf16 v[42:45], v[178:181], v[186:189], v[42:45]
	v_mfma_f32_16x16x32_bf16 v[30:33], v[170:173], v[194:197], v[30:33]
	v_mfma_f32_16x16x32_bf16 v[26:29], v[178:181], v[194:197], v[26:29]
	v_mfma_f32_16x16x32_bf16 v[14:17], v[170:173], v[206:209], v[14:17]
	v_mfma_f32_16x16x32_bf16 v[10:13], v[178:181], v[206:209], v[10:13]
	v_mfma_f32_16x16x32_bf16 v[6:9], v[170:173], v[214:217], v[6:9]
	v_mfma_f32_16x16x32_bf16 v[2:5], v[178:181], v[214:217], v[2:5]
	s_barrier
	s_setprio 0
	s_movk_i32 s46, 0x100
	s_andn2_b64 vcc, exec, s[42:43]
	s_mov_b64 s[44:45], -1
	s_mov_b64 s[42:43], 0
	s_cbranch_vccz .LBB0_297
	s_and_b64 vcc, exec, s[10:11]
	s_cbranch_vccz .LBB0_300
	s_barrier

.LBB0_313:
	s_add_u32 s49, s38, s48
	s_addc_u32 s68, s39, 0
	s_add_u32 s66, s49, 0x100
	s_addc_u32 s67, s68, 0
	s_and_b64 s[64:65], s[46:47], exec
	s_cselect_b32 s65, s43, s67
	s_cselect_b32 s64, s75, s66
	s_add_u32 s48, s36, s48
	s_addc_u32 s66, s37, 0
	s_add_u32 s48, s48, 0x100
	s_addc_u32 s66, s66, 0
	s_and_b64 s[46:47], s[46:47], exec
	s_cselect_b32 s67, s76, s66
	s_cselect_b32 s66, s77, s48
	s_add_u32 s70, s49, 0x10080
	ds_read_b128 v[144:147], v140
	ds_read_b128 v[148:151], v140 offset:1024
	ds_read_b128 v[152:155], v140 offset:2048
	ds_read_b128 v[156:159], v140 offset:3072
	ds_read_b128 v[160:163], v141
	ds_read_b128 v[164:167], v141 offset:1024
	ds_read_b128 v[168:171], v141 offset:2048
	ds_read_b128 v[172:175], v141 offset:3072
	s_addc_u32 s71, s68, 0
	s_add_i32 s87, s33, s2
	s_add_i32 m0, s16, 0xc000
	s_add_i32 s88, s16, 0xe000
	s_add_i32 s84, s87, 0x2000
	s_add_u32 s68, s66, 0x1000
	s_addc_u32 s69, s67, 0
	s_add_i32 s86, s34, s2
	s_add_i32 s85, s86, 0x2000
	s_add_i32 s83, 0, 0x18000
	s_add_i32 s82, 0, 0x1c000
	s_add_u32 s48, s64, 0x10000
	s_addc_u32 s49, s65, 0
	s_add_i32 s81, s83, s2
	s_add_i32 s79, s81, 0x2000
	s_add_u32 s46, s66, 0x1080
	s_addc_u32 s47, s67, 0
	s_add_i32 s80, s82, s2
	s_add_i32 s78, s80, 0x2000
	v_lshl_add_u64 v[210:211], s[70:71], 0, v[130:131]
	ds_read_b128 v[176:179], v142
	ds_read_b128 v[180:183], v142 offset:1024
	ds_read_b128 v[184:187], v142 offset:2048
	ds_read_b128 v[188:191], v142 offset:3072
	ds_read_b128 v[192:195], v142 offset:4096
	ds_read_b128 v[196:199], v142 offset:5120
	ds_read_b128 v[200:203], v142 offset:6144
	ds_read_b128 v[206:209], v142 offset:7168
	global_load_lds_dwordx4 v[210:211], off
	v_lshl_add_u64 v[210:211], s[70:71], 0, v[132:133]
	s_mov_b32 m0, s88
	s_nop 0
	global_load_lds_dwordx4 v[210:211], off
	s_waitcnt vmcnt(8)
	s_waitcnt lgkmcnt(0)
	s_setprio 1
	s_barrier
	v_mfma_f32_16x16x32_bf16 v[126:129], v[144:147], v[176:179], v[126:129]
	v_mfma_f32_16x16x32_bf16 v[122:125], v[152:155], v[176:179], v[122:125]
	v_mfma_f32_16x16x32_bf16 v[118:121], v[144:147], v[184:187], v[118:121]
	v_mfma_f32_16x16x32_bf16 v[114:117], v[152:155], v[184:187], v[114:117]
	v_mfma_f32_16x16x32_bf16 v[102:105], v[144:147], v[192:195], v[102:105]
	v_mfma_f32_16x16x32_bf16 v[98:101], v[152:155], v[192:195], v[98:101]
	v_mfma_f32_16x16x32_bf16 v[86:89], v[144:147], v[200:203], v[86:89]
	v_mfma_f32_16x16x32_bf16 v[82:85], v[152:155], v[200:203], v[82:85]
	v_mfma_f32_16x16x32_bf16 v[126:129], v[148:151], v[180:183], v[126:129]
	v_mfma_f32_16x16x32_bf16 v[122:125], v[156:159], v[180:183], v[122:125]
	v_mfma_f32_16x16x32_bf16 v[118:121], v[148:151], v[188:191], v[118:121]
	v_mfma_f32_16x16x32_bf16 v[114:117], v[156:159], v[188:191], v[114:117]
	v_mfma_f32_16x16x32_bf16 v[102:105], v[148:151], v[196:199], v[102:105]
	v_mfma_f32_16x16x32_bf16 v[98:101], v[156:159], v[196:199], v[98:101]
	v_mfma_f32_16x16x32_bf16 v[86:89], v[148:151], v[206:209], v[86:89]
	v_mfma_f32_16x16x32_bf16 v[82:85], v[156:159], v[206:209], v[82:85]
	v_mfma_f32_16x16x32_bf16 v[110:113], v[160:163], v[176:179], v[110:113]
	v_mfma_f32_16x16x32_bf16 v[106:109], v[168:171], v[176:179], v[106:109]
	v_mfma_f32_16x16x32_bf16 v[94:97], v[160:163], v[184:187], v[94:97]
	v_mfma_f32_16x16x32_bf16 v[90:93], v[168:171], v[184:187], v[90:93]
	v_mfma_f32_16x16x32_bf16 v[78:81], v[160:163], v[192:195], v[78:81]
	v_mfma_f32_16x16x32_bf16 v[74:77], v[168:171], v[192:195], v[74:77]
	v_mfma_f32_16x16x32_bf16 v[70:73], v[160:163], v[200:203], v[70:73]
	v_mfma_f32_16x16x32_bf16 v[66:69], v[168:171], v[200:203], v[66:69]
	v_mfma_f32_16x16x32_bf16 v[110:113], v[164:167], v[180:183], v[110:113]
	v_mfma_f32_16x16x32_bf16 v[106:109], v[172:175], v[180:183], v[106:109]
	v_mfma_f32_16x16x32_bf16 v[94:97], v[164:167], v[188:191], v[94:97]
	v_mfma_f32_16x16x32_bf16 v[90:93], v[172:175], v[188:191], v[90:93]
	v_mfma_f32_16x16x32_bf16 v[78:81], v[164:167], v[196:199], v[78:81]
	v_mfma_f32_16x16x32_bf16 v[74:77], v[172:175], v[196:199], v[74:77]
	v_mfma_f32_16x16x32_bf16 v[70:73], v[164:167], v[206:209], v[70:73]
	v_mfma_f32_16x16x32_bf16 v[66:69], v[172:175], v[206:209], v[66:69]
	s_barrier
	s_setprio 0
	s_mov_b32 m0, s87
	v_lshl_add_u64 v[210:211], s[66:67], 0, v[136:137]
	ds_read_b128 v[176:179], v142 offset:16384
	ds_read_b128 v[180:183], v142 offset:17408
	ds_read_b128 v[184:187], v142 offset:18432
	ds_read_b128 v[188:191], v142 offset:19456
	ds_read_b128 v[192:195], v142 offset:20480
	ds_read_b128 v[196:199], v142 offset:21504
	ds_read_b128 v[200:203], v142 offset:22528
	ds_read_b128 v[206:209], v142 offset:23552
	global_load_lds_dwordx4 v[210:211], off
	v_lshl_add_u64 v[212:213], s[66:67], 0, v[134:135]
	s_mov_b32 m0, s84
	v_lshl_add_u64 v[214:215], s[68:69], 0, v[136:137]
	global_load_lds_dwordx4 v[212:213], off
	s_mov_b32 m0, s86
	v_lshl_add_u64 v[216:217], s[64:65], 0, v[132:133]
	global_load_lds_dwordx4 v[214:215], off
	v_lshl_add_u64 v[214:215], s[68:69], 0, v[134:135]
	s_mov_b32 m0, s85
	s_nop 0
	global_load_lds_dwordx4 v[214:215], off
	v_lshl_add_u64 v[214:215], s[64:65], 0, v[130:131]
	s_mov_b32 m0, s16
	s_nop 0
	global_load_lds_dwordx4 v[214:215], off
	s_mov_b32 m0, s17
	s_nop 0
	global_load_lds_dwordx4 v[216:217], off
	s_waitcnt vmcnt(8)
	s_waitcnt lgkmcnt(0)
	s_setprio 1
	s_barrier
	v_mfma_f32_16x16x32_bf16 v[62:65], v[144:147], v[176:179], v[62:65]
	v_mfma_f32_16x16x32_bf16 v[58:61], v[152:155], v[176:179], v[58:61]
	v_mfma_f32_16x16x32_bf16 v[54:57], v[144:147], v[184:187], v[54:57]
	v_mfma_f32_16x16x32_bf16 v[50:53], v[152:155], v[184:187], v[50:53]
	v_mfma_f32_16x16x32_bf16 v[38:41], v[144:147], v[192:195], v[38:41]
	v_mfma_f32_16x16x32_bf16 v[34:37], v[152:155], v[192:195], v[34:37]
	v_mfma_f32_16x16x32_bf16 v[22:25], v[144:147], v[200:203], v[22:25]
	v_mfma_f32_16x16x32_bf16 v[18:21], v[152:155], v[200:203], v[18:21]
	v_mfma_f32_16x16x32_bf16 v[62:65], v[148:151], v[180:183], v[62:65]
	v_mfma_f32_16x16x32_bf16 v[58:61], v[156:159], v[180:183], v[58:61]
	v_mfma_f32_16x16x32_bf16 v[54:57], v[148:151], v[188:191], v[54:57]
	v_mfma_f32_16x16x32_bf16 v[50:53], v[156:159], v[188:191], v[50:53]
	v_mfma_f32_16x16x32_bf16 v[38:41], v[148:151], v[196:199], v[38:41]
	v_mfma_f32_16x16x32_bf16 v[34:37], v[156:159], v[196:199], v[34:37]
	v_mfma_f32_16x16x32_bf16 v[22:25], v[148:151], v[206:209], v[22:25]
	v_mfma_f32_16x16x32_bf16 v[18:21], v[156:159], v[206:209], v[18:21]
	v_mfma_f32_16x16x32_bf16 v[46:49], v[160:163], v[176:179], v[46:49]
	v_mfma_f32_16x16x32_bf16 v[42:45], v[168:171], v[176:179], v[42:45]
	v_mfma_f32_16x16x32_bf16 v[30:33], v[160:163], v[184:187], v[30:33]
	v_mfma_f32_16x16x32_bf16 v[26:29], v[168:171], v[184:187], v[26:29]
	v_mfma_f32_16x16x32_bf16 v[14:17], v[160:163], v[192:195], v[14:17]
	v_mfma_f32_16x16x32_bf16 v[10:13], v[168:171], v[192:195], v[10:13]
	v_mfma_f32_16x16x32_bf16 v[6:9], v[160:163], v[200:203], v[6:9]
	v_mfma_f32_16x16x32_bf16 v[2:5], v[168:171], v[200:203], v[2:5]
	v_mfma_f32_16x16x32_bf16 v[46:49], v[164:167], v[180:183], v[46:49]
	v_mfma_f32_16x16x32_bf16 v[42:45], v[172:175], v[180:183], v[42:45]
	v_mfma_f32_16x16x32_bf16 v[30:33], v[164:167], v[188:191], v[30:33]
	v_mfma_f32_16x16x32_bf16 v[26:29], v[172:175], v[188:191], v[26:29]
	v_mfma_f32_16x16x32_bf16 v[14:17], v[164:167], v[196:199], v[14:17]
	v_mfma_f32_16x16x32_bf16 v[10:13], v[172:175], v[196:199], v[10:13]
	v_mfma_f32_16x16x32_bf16 v[6:9], v[164:167], v[206:209], v[6:9]
	v_mfma_f32_16x16x32_bf16 v[2:5], v[172:175], v[206:209], v[2:5]
	s_barrier
	s_setprio 0
	v_add_u32_e32 v143, s83, v139
	ds_read_b128 v[144:147], v143
	ds_read_b128 v[148:151], v143 offset:1024
	ds_read_b128 v[152:155], v143 offset:2048
	ds_read_b128 v[156:159], v143 offset:3072
	v_add_u32_e32 v143, s82, v139
	ds_read_b128 v[160:163], v143
	ds_read_b128 v[164:167], v143 offset:1024
	ds_read_b128 v[168:171], v143 offset:2048
	ds_read_b128 v[172:175], v143 offset:3072
	s_mov_b32 m0, s18
	v_lshl_add_u64 v[218:219], s[48:49], 0, v[130:131]
	ds_read_b128 v[176:179], v142 offset:32768
	ds_read_b128 v[180:183], v142 offset:33792
	ds_read_b128 v[184:187], v142 offset:34816
	ds_read_b128 v[188:191], v142 offset:35840
	ds_read_b128 v[192:195], v142 offset:36864
	ds_read_b128 v[196:199], v142 offset:37888
	ds_read_b128 v[200:203], v142 offset:38912
	ds_read_b128 v[206:209], v142 offset:39936
	global_load_lds_dwordx4 v[218:219], off
	v_lshl_add_u64 v[218:219], s[48:49], 0, v[132:133]
	s_mov_b32 m0, s19
	s_nop 0
	global_load_lds_dwordx4 v[218:219], off
	s_waitcnt vmcnt(8)
	s_waitcnt lgkmcnt(0)
	s_setprio 1
	s_barrier
	v_mfma_f32_16x16x32_bf16 v[126:129], v[144:147], v[176:179], v[126:129]
	v_mfma_f32_16x16x32_bf16 v[122:125], v[152:155], v[176:179], v[122:125]
	v_mfma_f32_16x16x32_bf16 v[118:121], v[144:147], v[184:187], v[118:121]
	v_mfma_f32_16x16x32_bf16 v[114:117], v[152:155], v[184:187], v[114:117]
	v_mfma_f32_16x16x32_bf16 v[102:105], v[144:147], v[192:195], v[102:105]
	v_mfma_f32_16x16x32_bf16 v[98:101], v[152:155], v[192:195], v[98:101]
	v_mfma_f32_16x16x32_bf16 v[86:89], v[144:147], v[200:203], v[86:89]
	v_mfma_f32_16x16x32_bf16 v[82:85], v[152:155], v[200:203], v[82:85]
	v_mfma_f32_16x16x32_bf16 v[126:129], v[148:151], v[180:183], v[126:129]
	v_mfma_f32_16x16x32_bf16 v[122:125], v[156:159], v[180:183], v[122:125]
	v_mfma_f32_16x16x32_bf16 v[118:121], v[148:151], v[188:191], v[118:121]
	v_mfma_f32_16x16x32_bf16 v[114:117], v[156:159], v[188:191], v[114:117]
	v_mfma_f32_16x16x32_bf16 v[102:105], v[148:151], v[196:199], v[102:105]
	v_mfma_f32_16x16x32_bf16 v[98:101], v[156:159], v[196:199], v[98:101]
	v_mfma_f32_16x16x32_bf16 v[86:89], v[148:151], v[206:209], v[86:89]
	v_mfma_f32_16x16x32_bf16 v[82:85], v[156:159], v[206:209], v[82:85]
	v_mfma_f32_16x16x32_bf16 v[110:113], v[160:163], v[176:179], v[110:113]
	v_mfma_f32_16x16x32_bf16 v[106:109], v[168:171], v[176:179], v[106:109]
	v_mfma_f32_16x16x32_bf16 v[94:97], v[160:163], v[184:187], v[94:97]
	v_mfma_f32_16x16x32_bf16 v[90:93], v[168:171], v[184:187], v[90:93]
	v_mfma_f32_16x16x32_bf16 v[78:81], v[160:163], v[192:195], v[78:81]
	v_mfma_f32_16x16x32_bf16 v[74:77], v[168:171], v[192:195], v[74:77]
	v_mfma_f32_16x16x32_bf16 v[70:73], v[160:163], v[200:203], v[70:73]
	v_mfma_f32_16x16x32_bf16 v[66:69], v[168:171], v[200:203], v[66:69]
	v_mfma_f32_16x16x32_bf16 v[110:113], v[164:167], v[180:183], v[110:113]
	v_mfma_f32_16x16x32_bf16 v[106:109], v[172:175], v[180:183], v[106:109]
	v_mfma_f32_16x16x32_bf16 v[94:97], v[164:167], v[188:191], v[94:97]
	v_mfma_f32_16x16x32_bf16 v[90:93], v[172:175], v[188:191], v[90:93]
	v_mfma_f32_16x16x32_bf16 v[78:81], v[164:167], v[196:199], v[78:81]
	v_mfma_f32_16x16x32_bf16 v[74:77], v[172:175], v[196:199], v[74:77]
	v_mfma_f32_16x16x32_bf16 v[70:73], v[164:167], v[206:209], v[70:73]
	v_mfma_f32_16x16x32_bf16 v[66:69], v[172:175], v[206:209], v[66:69]
	s_barrier
	s_setprio 0
	s_mov_b32 m0, s81
	v_lshl_add_u64 v[210:211], v[210:211], 0, s[8:9]
	ds_read_b128 v[176:179], v142 offset:49152
	ds_read_b128 v[180:183], v142 offset:50176
	ds_read_b128 v[184:187], v142 offset:51200
	ds_read_b128 v[188:191], v142 offset:52224
	ds_read_b128 v[192:195], v142 offset:53248
	ds_read_b128 v[196:199], v142 offset:54272
	ds_read_b128 v[200:203], v142 offset:55296
	ds_read_b128 v[206:209], v142 offset:56320
	global_load_lds_dwordx4 v[210:211], off
	v_lshl_add_u64 v[210:211], v[212:213], 0, s[8:9]
	s_mov_b32 m0, s79
	s_nop 0
	global_load_lds_dwordx4 v[210:211], off
	v_lshl_add_u64 v[210:211], s[46:47], 0, v[136:137]
	s_mov_b32 m0, s80
	s_nop 0
	global_load_lds_dwordx4 v[210:211], off
	v_lshl_add_u64 v[210:211], s[46:47], 0, v[134:135]
	s_mov_b32 m0, s78
	s_nop 0
	global_load_lds_dwordx4 v[210:211], off
	v_lshl_add_u64 v[210:211], v[214:215], 0, s[8:9]
	s_mov_b32 m0, s30
	s_nop 0
	global_load_lds_dwordx4 v[210:211], off
	v_lshl_add_u64 v[210:211], v[216:217], 0, s[8:9]
	s_mov_b32 m0, s31
	s_nop 0
	global_load_lds_dwordx4 v[210:211], off
	s_waitcnt vmcnt(8)
	s_waitcnt lgkmcnt(0)
	s_setprio 1
	s_barrier
	v_mfma_f32_16x16x32_bf16 v[62:65], v[144:147], v[176:179], v[62:65]
	v_mfma_f32_16x16x32_bf16 v[58:61], v[152:155], v[176:179], v[58:61]
	v_mfma_f32_16x16x32_bf16 v[54:57], v[144:147], v[184:187], v[54:57]
	v_mfma_f32_16x16x32_bf16 v[50:53], v[152:155], v[184:187], v[50:53]
	v_mfma_f32_16x16x32_bf16 v[38:41], v[144:147], v[192:195], v[38:41]
	v_mfma_f32_16x16x32_bf16 v[34:37], v[152:155], v[192:195], v[34:37]
	v_mfma_f32_16x16x32_bf16 v[22:25], v[144:147], v[200:203], v[22:25]
	v_mfma_f32_16x16x32_bf16 v[18:21], v[152:155], v[200:203], v[18:21]
	v_mfma_f32_16x16x32_bf16 v[62:65], v[148:151], v[180:183], v[62:65]
	v_mfma_f32_16x16x32_bf16 v[58:61], v[156:159], v[180:183], v[58:61]
	v_mfma_f32_16x16x32_bf16 v[54:57], v[148:151], v[188:191], v[54:57]
	v_mfma_f32_16x16x32_bf16 v[50:53], v[156:159], v[188:191], v[50:53]
	v_mfma_f32_16x16x32_bf16 v[38:41], v[148:151], v[196:199], v[38:41]
	v_mfma_f32_16x16x32_bf16 v[34:37], v[156:159], v[196:199], v[34:37]
	v_mfma_f32_16x16x32_bf16 v[22:25], v[148:151], v[206:209], v[22:25]
	v_mfma_f32_16x16x32_bf16 v[18:21], v[156:159], v[206:209], v[18:21]
	v_mfma_f32_16x16x32_bf16 v[46:49], v[160:163], v[176:179], v[46:49]
	v_mfma_f32_16x16x32_bf16 v[42:45], v[168:171], v[176:179], v[42:45]
	v_mfma_f32_16x16x32_bf16 v[30:33], v[160:163], v[184:187], v[30:33]
	v_mfma_f32_16x16x32_bf16 v[26:29], v[168:171], v[184:187], v[26:29]
	v_mfma_f32_16x16x32_bf16 v[14:17], v[160:163], v[192:195], v[14:17]
	v_mfma_f32_16x16x32_bf16 v[10:13], v[168:171], v[192:195], v[10:13]
	v_mfma_f32_16x16x32_bf16 v[6:9], v[160:163], v[200:203], v[6:9]
	v_mfma_f32_16x16x32_bf16 v[2:5], v[168:171], v[200:203], v[2:5]
	v_mfma_f32_16x16x32_bf16 v[46:49], v[164:167], v[180:183], v[46:49]
	v_mfma_f32_16x16x32_bf16 v[42:45], v[172:175], v[180:183], v[42:45]
	v_mfma_f32_16x16x32_bf16 v[30:33], v[164:167], v[188:191], v[30:33]
	v_mfma_f32_16x16x32_bf16 v[26:29], v[172:175], v[188:191], v[26:29]
	v_mfma_f32_16x16x32_bf16 v[14:17], v[164:167], v[196:199], v[14:17]
	v_mfma_f32_16x16x32_bf16 v[10:13], v[172:175], v[196:199], v[10:13]
	v_mfma_f32_16x16x32_bf16 v[6:9], v[164:167], v[206:209], v[6:9]
	v_mfma_f32_16x16x32_bf16 v[2:5], v[172:175], v[206:209], v[2:5]
	s_barrier
	s_setprio 0
	s_movk_i32 s48, 0x100
	s_andn2_b64 vcc, exec, s[44:45]
	s_mov_b64 s[46:47], -1
	s_mov_b64 s[44:45], 0
	s_cbranch_vccz .LBB0_313
	s_and_b64 vcc, exec, s[10:11]
	s_cbranch_vccz .LBB0_316
	s_barrier

.LBB0_383:
	s_add_u32 s26, s0, s22
	s_addc_u32 s27, s1, s23
	s_and_b64 s[44:45], s[36:37], exec
	s_cselect_b32 s15, s27, s43
	s_cselect_b32 s39, s26, s42
	s_add_u32 s66, s42, 0x100
	s_addc_u32 s67, s43, 0
	s_mov_b32 s68, -2
	s_mov_b64 s[42:43], 0
	ds_read_b128 v[152:155], v146
	ds_read_b128 v[156:159], v146 offset:1024
	ds_read_b128 v[160:163], v146 offset:2048
	ds_read_b128 v[164:167], v146 offset:3072
	ds_read_b128 v[168:171], v147
	ds_read_b128 v[172:175], v147 offset:1024
	ds_read_b128 v[176:179], v147 offset:2048
	ds_read_b128 v[180:183], v147 offset:3072
	s_add_u32 s44, s42, 0x100
	s_addc_u32 s45, s43, 0
	s_add_u32 s46, s66, s42
	s_addc_u32 s47, s67, s43
	s_cmp_eq_u32 s68, 4
	s_cselect_b32 s48, 0, s44
	s_cselect_b32 s49, 0, s45
	s_cselect_b32 s46, s39, s46
	s_cselect_b32 s47, s15, s47
	s_add_u32 s48, s6, s48
	s_addc_u32 s49, s7, s49
	s_mov_b32 m0, s29
	v_lshl_add_u64 v[218:219], v[138:139], 0, s[42:43]
	ds_read_b128 v[184:187], v148
	ds_read_b128 v[188:191], v148 offset:1024
	ds_read_b128 v[192:195], v148 offset:2048
	ds_read_b128 v[196:199], v148 offset:3072
	ds_read_b128 v[200:203], v148 offset:4096
	ds_read_b128 v[206:209], v148 offset:5120
	ds_read_b128 v[210:213], v148 offset:6144
	ds_read_b128 v[214:217], v148 offset:7168
	global_load_lds_dwordx4 v[218:219], off
	v_lshl_add_u64 v[218:219], v[140:141], 0, s[42:43]
	s_mov_b32 m0, s30
	s_nop 0
	global_load_lds_dwordx4 v[218:219], off
	s_waitcnt vmcnt(8)
	s_waitcnt lgkmcnt(0)
	s_setprio 1
	s_barrier
	v_mfma_f32_16x16x32_bf16 v[126:129], v[152:155], v[184:187], 0
	v_mfma_f32_16x16x32_bf16 v[122:125], v[160:163], v[184:187], 0
	v_mfma_f32_16x16x32_bf16 v[118:121], v[152:155], v[192:195], 0
	v_mfma_f32_16x16x32_bf16 v[114:117], v[160:163], v[192:195], 0
	v_mfma_f32_16x16x32_bf16 v[102:105], v[152:155], v[200:203], 0
	v_mfma_f32_16x16x32_bf16 v[98:101], v[160:163], v[200:203], 0
	v_mfma_f32_16x16x32_bf16 v[86:89], v[152:155], v[210:213], 0
	v_mfma_f32_16x16x32_bf16 v[82:85], v[160:163], v[210:213], 0
	v_mfma_f32_16x16x32_bf16 v[126:129], v[156:159], v[188:191], v[126:129]
	v_mfma_f32_16x16x32_bf16 v[122:125], v[164:167], v[188:191], v[122:125]
	v_mfma_f32_16x16x32_bf16 v[118:121], v[156:159], v[196:199], v[118:121]
	v_mfma_f32_16x16x32_bf16 v[114:117], v[164:167], v[196:199], v[114:117]
	v_mfma_f32_16x16x32_bf16 v[102:105], v[156:159], v[206:209], v[102:105]
	v_mfma_f32_16x16x32_bf16 v[98:101], v[164:167], v[206:209], v[98:101]
	v_mfma_f32_16x16x32_bf16 v[86:89], v[156:159], v[214:217], v[86:89]
	v_mfma_f32_16x16x32_bf16 v[82:85], v[164:167], v[214:217], v[82:85]
	v_mfma_f32_16x16x32_bf16 v[110:113], v[168:171], v[184:187], 0
	v_mfma_f32_16x16x32_bf16 v[106:109], v[176:179], v[184:187], 0
	v_mfma_f32_16x16x32_bf16 v[94:97], v[168:171], v[192:195], 0
	v_mfma_f32_16x16x32_bf16 v[90:93], v[176:179], v[192:195], 0
	v_mfma_f32_16x16x32_bf16 v[78:81], v[168:171], v[200:203], 0
	v_mfma_f32_16x16x32_bf16 v[74:77], v[176:179], v[200:203], 0
	v_mfma_f32_16x16x32_bf16 v[70:73], v[168:171], v[210:213], 0
	v_mfma_f32_16x16x32_bf16 v[66:69], v[176:179], v[210:213], 0
	v_mfma_f32_16x16x32_bf16 v[110:113], v[172:175], v[188:191], v[110:113]
	v_mfma_f32_16x16x32_bf16 v[106:109], v[180:183], v[188:191], v[106:109]
	v_mfma_f32_16x16x32_bf16 v[94:97], v[172:175], v[196:199], v[94:97]
	v_mfma_f32_16x16x32_bf16 v[90:93], v[180:183], v[196:199], v[90:93]
	v_mfma_f32_16x16x32_bf16 v[78:81], v[172:175], v[206:209], v[78:81]
	v_mfma_f32_16x16x32_bf16 v[74:77], v[180:183], v[206:209], v[74:77]
	v_mfma_f32_16x16x32_bf16 v[70:73], v[172:175], v[214:217], v[70:73]
	v_mfma_f32_16x16x32_bf16 v[66:69], v[180:183], v[214:217], v[66:69]
	s_barrier
	s_setprio 0
	s_mov_b32 m0, s31
	v_lshl_add_u64 v[218:219], s[46:47], 0, v[134:135]
	s_add_u32 s42, s46, 0x20000
	ds_read_b128 v[184:187], v148 offset:16384
	ds_read_b128 v[188:191], v148 offset:17408
	ds_read_b128 v[192:195], v148 offset:18432
	ds_read_b128 v[196:199], v148 offset:19456
	ds_read_b128 v[200:203], v148 offset:20480
	ds_read_b128 v[206:209], v148 offset:21504
	ds_read_b128 v[210:213], v148 offset:22528
	ds_read_b128 v[214:217], v148 offset:23552
	global_load_lds_dwordx4 v[218:219], off
	v_lshl_add_u64 v[220:221], s[46:47], 0, v[130:131]
	s_mov_b32 m0, s33
	s_addc_u32 s43, s47, 0
	global_load_lds_dwordx4 v[220:221], off
	v_lshl_add_u64 v[222:223], s[42:43], 0, v[134:135]
	s_mov_b32 m0, s34
	v_lshl_add_u64 v[224:225], s[48:49], 0, v[132:133]
	global_load_lds_dwordx4 v[222:223], off
	v_lshl_add_u64 v[222:223], s[42:43], 0, v[130:131]
	s_mov_b32 m0, s35
	s_nop 0
	global_load_lds_dwordx4 v[222:223], off
	v_lshl_add_u64 v[222:223], s[48:49], 0, v[136:137]
	s_mov_b32 m0, s2
	s_nop 0
	global_load_lds_dwordx4 v[222:223], off
	s_mov_b32 m0, s3
	s_nop 0
	global_load_lds_dwordx4 v[224:225], off
	s_waitcnt vmcnt(8)
	s_waitcnt lgkmcnt(0)
	s_setprio 1
	s_barrier
	v_mfma_f32_16x16x32_bf16 v[62:65], v[152:155], v[184:187], 0
	v_mfma_f32_16x16x32_bf16 v[58:61], v[160:163], v[184:187], 0
	v_mfma_f32_16x16x32_bf16 v[54:57], v[152:155], v[192:195], 0
	v_mfma_f32_16x16x32_bf16 v[50:53], v[160:163], v[192:195], 0
	v_mfma_f32_16x16x32_bf16 v[38:41], v[152:155], v[200:203], 0
	v_mfma_f32_16x16x32_bf16 v[34:37], v[160:163], v[200:203], 0
	v_mfma_f32_16x16x32_bf16 v[22:25], v[152:155], v[210:213], 0
	v_mfma_f32_16x16x32_bf16 v[18:21], v[160:163], v[210:213], 0
	v_mfma_f32_16x16x32_bf16 v[62:65], v[156:159], v[188:191], v[62:65]
	v_mfma_f32_16x16x32_bf16 v[58:61], v[164:167], v[188:191], v[58:61]
	v_mfma_f32_16x16x32_bf16 v[54:57], v[156:159], v[196:199], v[54:57]
	v_mfma_f32_16x16x32_bf16 v[50:53], v[164:167], v[196:199], v[50:53]
	v_mfma_f32_16x16x32_bf16 v[38:41], v[156:159], v[206:209], v[38:41]
	v_mfma_f32_16x16x32_bf16 v[34:37], v[164:167], v[206:209], v[34:37]
	v_mfma_f32_16x16x32_bf16 v[22:25], v[156:159], v[214:217], v[22:25]
	v_mfma_f32_16x16x32_bf16 v[18:21], v[164:167], v[214:217], v[18:21]
	v_mfma_f32_16x16x32_bf16 v[46:49], v[168:171], v[184:187], 0
	v_mfma_f32_16x16x32_bf16 v[42:45], v[176:179], v[184:187], 0
	v_mfma_f32_16x16x32_bf16 v[30:33], v[168:171], v[192:195], 0
	v_mfma_f32_16x16x32_bf16 v[26:29], v[176:179], v[192:195], 0
	v_mfma_f32_16x16x32_bf16 v[14:17], v[168:171], v[200:203], 0
	v_mfma_f32_16x16x32_bf16 v[10:13], v[176:179], v[200:203], 0
	v_mfma_f32_16x16x32_bf16 v[6:9], v[168:171], v[210:213], 0
	v_mfma_f32_16x16x32_bf16 v[2:5], v[176:179], v[210:213], 0
	v_mfma_f32_16x16x32_bf16 v[46:49], v[172:175], v[188:191], v[46:49]
	v_mfma_f32_16x16x32_bf16 v[42:45], v[180:183], v[188:191], v[42:45]
	v_mfma_f32_16x16x32_bf16 v[30:33], v[172:175], v[196:199], v[30:33]
	v_mfma_f32_16x16x32_bf16 v[26:29], v[180:183], v[196:199], v[26:29]
	v_mfma_f32_16x16x32_bf16 v[14:17], v[172:175], v[206:209], v[14:17]
	v_mfma_f32_16x16x32_bf16 v[10:13], v[180:183], v[206:209], v[10:13]
	v_mfma_f32_16x16x32_bf16 v[6:9], v[172:175], v[214:217], v[6:9]
	v_mfma_f32_16x16x32_bf16 v[2:5], v[180:183], v[214:217], v[2:5]
	s_barrier
	s_setprio 0
	ds_read_b128 v[152:155], v149
	ds_read_b128 v[156:159], v149 offset:1024
	ds_read_b128 v[160:163], v149 offset:2048
	ds_read_b128 v[164:167], v149 offset:3072
	ds_read_b128 v[168:171], v150
	ds_read_b128 v[172:175], v150 offset:1024
	ds_read_b128 v[176:179], v150 offset:2048
	ds_read_b128 v[180:183], v150 offset:3072
	s_add_u32 s42, s48, 0x20000
	s_addc_u32 s43, s49, 0
	s_mov_b32 m0, s16
	v_lshl_add_u64 v[226:227], s[42:43], 0, v[136:137]
	ds_read_b128 v[184:187], v148 offset:32768
	ds_read_b128 v[188:191], v148 offset:33792
	ds_read_b128 v[192:195], v148 offset:34816
	ds_read_b128 v[196:199], v148 offset:35840
	ds_read_b128 v[200:203], v148 offset:36864
	ds_read_b128 v[206:209], v148 offset:37888
	ds_read_b128 v[210:213], v148 offset:38912
	ds_read_b128 v[214:217], v148 offset:39936
	global_load_lds_dwordx4 v[226:227], off
	v_lshl_add_u64 v[226:227], s[42:43], 0, v[132:133]
	s_mov_b32 m0, s17
	s_nop 0
	global_load_lds_dwordx4 v[226:227], off
	s_waitcnt vmcnt(8)
	s_waitcnt lgkmcnt(0)
	s_setprio 1
	s_barrier
	v_mfma_f32_16x16x32_bf16 v[126:129], v[152:155], v[184:187], v[126:129]
	v_mfma_f32_16x16x32_bf16 v[122:125], v[160:163], v[184:187], v[122:125]
	v_mfma_f32_16x16x32_bf16 v[118:121], v[152:155], v[192:195], v[118:121]
	v_mfma_f32_16x16x32_bf16 v[114:117], v[160:163], v[192:195], v[114:117]
	v_mfma_f32_16x16x32_bf16 v[102:105], v[152:155], v[200:203], v[102:105]
	v_mfma_f32_16x16x32_bf16 v[98:101], v[160:163], v[200:203], v[98:101]
	v_mfma_f32_16x16x32_bf16 v[86:89], v[152:155], v[210:213], v[86:89]
	v_mfma_f32_16x16x32_bf16 v[82:85], v[160:163], v[210:213], v[82:85]
	v_mfma_f32_16x16x32_bf16 v[126:129], v[156:159], v[188:191], v[126:129]
	v_mfma_f32_16x16x32_bf16 v[122:125], v[164:167], v[188:191], v[122:125]
	v_mfma_f32_16x16x32_bf16 v[118:121], v[156:159], v[196:199], v[118:121]
	v_mfma_f32_16x16x32_bf16 v[114:117], v[164:167], v[196:199], v[114:117]
	v_mfma_f32_16x16x32_bf16 v[102:105], v[156:159], v[206:209], v[102:105]
	v_mfma_f32_16x16x32_bf16 v[98:101], v[164:167], v[206:209], v[98:101]
	v_mfma_f32_16x16x32_bf16 v[86:89], v[156:159], v[214:217], v[86:89]
	v_mfma_f32_16x16x32_bf16 v[82:85], v[164:167], v[214:217], v[82:85]
	v_mfma_f32_16x16x32_bf16 v[110:113], v[168:171], v[184:187], v[110:113]
	v_mfma_f32_16x16x32_bf16 v[106:109], v[176:179], v[184:187], v[106:109]
	v_mfma_f32_16x16x32_bf16 v[94:97], v[168:171], v[192:195], v[94:97]
	v_mfma_f32_16x16x32_bf16 v[90:93], v[176:179], v[192:195], v[90:93]
	v_mfma_f32_16x16x32_bf16 v[78:81], v[168:171], v[200:203], v[78:81]
	v_mfma_f32_16x16x32_bf16 v[74:77], v[176:179], v[200:203], v[74:77]
	v_mfma_f32_16x16x32_bf16 v[70:73], v[168:171], v[210:213], v[70:73]
	v_mfma_f32_16x16x32_bf16 v[66:69], v[176:179], v[210:213], v[66:69]
	v_mfma_f32_16x16x32_bf16 v[110:113], v[172:175], v[188:191], v[110:113]
	v_mfma_f32_16x16x32_bf16 v[106:109], v[180:183], v[188:191], v[106:109]
	v_mfma_f32_16x16x32_bf16 v[94:97], v[172:175], v[196:199], v[94:97]
	v_mfma_f32_16x16x32_bf16 v[90:93], v[180:183], v[196:199], v[90:93]
	v_mfma_f32_16x16x32_bf16 v[78:81], v[172:175], v[206:209], v[78:81]
	v_mfma_f32_16x16x32_bf16 v[74:77], v[180:183], v[206:209], v[74:77]
	v_mfma_f32_16x16x32_bf16 v[70:73], v[172:175], v[214:217], v[70:73]
	v_mfma_f32_16x16x32_bf16 v[66:69], v[180:183], v[214:217], v[66:69]
	s_barrier
	s_setprio 0
	s_mov_b32 m0, s62
	v_lshl_add_u64 v[218:219], v[218:219], 0, s[10:11]
	s_add_u32 s42, s46, 0x20080
	ds_read_b128 v[184:187], v148 offset:49152
	ds_read_b128 v[188:191], v148 offset:50176
	ds_read_b128 v[192:195], v148 offset:51200
	ds_read_b128 v[196:199], v148 offset:52224
	ds_read_b128 v[200:203], v148 offset:53248
	ds_read_b128 v[206:209], v148 offset:54272
	ds_read_b128 v[210:213], v148 offset:55296
	ds_read_b128 v[214:217], v148 offset:56320
	global_load_lds_dwordx4 v[218:219], off
	v_lshl_add_u64 v[218:219], v[220:221], 0, s[10:11]
	s_mov_b32 m0, s63
	s_addc_u32 s43, s47, 0
	global_load_lds_dwordx4 v[218:219], off
	v_lshl_add_u64 v[218:219], s[42:43], 0, v[134:135]
	s_mov_b32 m0, s64
	s_nop 0
	global_load_lds_dwordx4 v[218:219], off
	v_lshl_add_u64 v[218:219], s[42:43], 0, v[130:131]
	s_mov_b32 m0, s65
	s_nop 0
	global_load_lds_dwordx4 v[218:219], off
	v_lshl_add_u64 v[218:219], v[222:223], 0, s[10:11]
	s_mov_b32 m0, s25
	s_nop 0
	global_load_lds_dwordx4 v[218:219], off
	v_lshl_add_u64 v[218:219], v[224:225], 0, s[10:11]
	s_mov_b32 m0, s28
	s_nop 0
	global_load_lds_dwordx4 v[218:219], off
	s_waitcnt vmcnt(8)
	s_waitcnt lgkmcnt(0)
	s_setprio 1
	s_barrier
	v_mfma_f32_16x16x32_bf16 v[62:65], v[152:155], v[184:187], v[62:65]
	v_mfma_f32_16x16x32_bf16 v[58:61], v[160:163], v[184:187], v[58:61]
	v_mfma_f32_16x16x32_bf16 v[54:57], v[152:155], v[192:195], v[54:57]
	v_mfma_f32_16x16x32_bf16 v[50:53], v[160:163], v[192:195], v[50:53]
	v_mfma_f32_16x16x32_bf16 v[38:41], v[152:155], v[200:203], v[38:41]
	v_mfma_f32_16x16x32_bf16 v[34:37], v[160:163], v[200:203], v[34:37]
	v_mfma_f32_16x16x32_bf16 v[22:25], v[152:155], v[210:213], v[22:25]
	v_mfma_f32_16x16x32_bf16 v[18:21], v[160:163], v[210:213], v[18:21]
	v_mfma_f32_16x16x32_bf16 v[62:65], v[156:159], v[188:191], v[62:65]
	v_mfma_f32_16x16x32_bf16 v[58:61], v[164:167], v[188:191], v[58:61]
	v_mfma_f32_16x16x32_bf16 v[54:57], v[156:159], v[196:199], v[54:57]
	v_mfma_f32_16x16x32_bf16 v[50:53], v[164:167], v[196:199], v[50:53]
	v_mfma_f32_16x16x32_bf16 v[38:41], v[156:159], v[206:209], v[38:41]
	v_mfma_f32_16x16x32_bf16 v[34:37], v[164:167], v[206:209], v[34:37]
	v_mfma_f32_16x16x32_bf16 v[22:25], v[156:159], v[214:217], v[22:25]
	v_mfma_f32_16x16x32_bf16 v[18:21], v[164:167], v[214:217], v[18:21]
	v_mfma_f32_16x16x32_bf16 v[46:49], v[168:171], v[184:187], v[46:49]
	v_mfma_f32_16x16x32_bf16 v[42:45], v[176:179], v[184:187], v[42:45]
	v_mfma_f32_16x16x32_bf16 v[30:33], v[168:171], v[192:195], v[30:33]
	v_mfma_f32_16x16x32_bf16 v[26:29], v[176:179], v[192:195], v[26:29]
	v_mfma_f32_16x16x32_bf16 v[14:17], v[168:171], v[200:203], v[14:17]
	v_mfma_f32_16x16x32_bf16 v[10:13], v[176:179], v[200:203], v[10:13]
	v_mfma_f32_16x16x32_bf16 v[6:9], v[168:171], v[210:213], v[6:9]
	v_mfma_f32_16x16x32_bf16 v[2:5], v[176:179], v[210:213], v[2:5]
	v_mfma_f32_16x16x32_bf16 v[46:49], v[172:175], v[188:191], v[46:49]
	v_mfma_f32_16x16x32_bf16 v[42:45], v[180:183], v[188:191], v[42:45]
	v_mfma_f32_16x16x32_bf16 v[30:33], v[172:175], v[196:199], v[30:33]
	v_mfma_f32_16x16x32_bf16 v[26:29], v[180:183], v[196:199], v[26:29]
	v_mfma_f32_16x16x32_bf16 v[14:17], v[172:175], v[206:209], v[14:17]
	v_mfma_f32_16x16x32_bf16 v[10:13], v[180:183], v[206:209], v[10:13]
	v_mfma_f32_16x16x32_bf16 v[6:9], v[172:175], v[214:217], v[6:9]
	v_mfma_f32_16x16x32_bf16 v[2:5], v[180:183], v[214:217], v[2:5]
	s_barrier
	s_setprio 0
	s_add_i32 s68, s68, 2
	s_cmp_gt_u32 s68, 5
	s_mov_b64 s[42:43], s[44:45]
.LBB0_384:
	ds_read_b128 v[152:155], v146
	ds_read_b128 v[156:159], v146 offset:1024
	ds_read_b128 v[160:163], v146 offset:2048
	ds_read_b128 v[164:167], v146 offset:3072
	ds_read_b128 v[168:171], v147
	ds_read_b128 v[172:175], v147 offset:1024
	ds_read_b128 v[176:179], v147 offset:2048
	ds_read_b128 v[180:183], v147 offset:3072
	s_add_u32 s44, s42, 0x100
	s_addc_u32 s45, s43, 0
	s_add_u32 s46, s66, s42
	s_addc_u32 s47, s67, s43
	s_cmp_eq_u32 s68, 4
	s_cselect_b32 s48, 0, s44
	s_cselect_b32 s49, 0, s45
	s_cselect_b32 s46, s39, s46
	s_cselect_b32 s47, s15, s47
	s_add_u32 s48, s6, s48
	s_addc_u32 s49, s7, s49
	s_mov_b32 m0, s29
	v_lshl_add_u64 v[218:219], v[138:139], 0, s[42:43]
	ds_read_b128 v[184:187], v148
	ds_read_b128 v[188:191], v148 offset:1024
	ds_read_b128 v[192:195], v148 offset:2048
	ds_read_b128 v[196:199], v148 offset:3072
	ds_read_b128 v[200:203], v148 offset:4096
	ds_read_b128 v[206:209], v148 offset:5120
	ds_read_b128 v[210:213], v148 offset:6144
	ds_read_b128 v[214:217], v148 offset:7168
	global_load_lds_dwordx4 v[218:219], off
	v_lshl_add_u64 v[218:219], v[140:141], 0, s[42:43]
	s_mov_b32 m0, s30
	s_nop 0
	global_load_lds_dwordx4 v[218:219], off
	s_waitcnt vmcnt(8)
	s_waitcnt lgkmcnt(0)
	s_setprio 1
	s_barrier
	v_mfma_f32_16x16x32_bf16 v[126:129], v[152:155], v[184:187], v[126:129]
	v_mfma_f32_16x16x32_bf16 v[122:125], v[160:163], v[184:187], v[122:125]
	v_mfma_f32_16x16x32_bf16 v[118:121], v[152:155], v[192:195], v[118:121]
	v_mfma_f32_16x16x32_bf16 v[114:117], v[160:163], v[192:195], v[114:117]
	v_mfma_f32_16x16x32_bf16 v[102:105], v[152:155], v[200:203], v[102:105]
	v_mfma_f32_16x16x32_bf16 v[98:101], v[160:163], v[200:203], v[98:101]
	v_mfma_f32_16x16x32_bf16 v[86:89], v[152:155], v[210:213], v[86:89]
	v_mfma_f32_16x16x32_bf16 v[82:85], v[160:163], v[210:213], v[82:85]
	v_mfma_f32_16x16x32_bf16 v[126:129], v[156:159], v[188:191], v[126:129]
	v_mfma_f32_16x16x32_bf16 v[122:125], v[164:167], v[188:191], v[122:125]
	v_mfma_f32_16x16x32_bf16 v[118:121], v[156:159], v[196:199], v[118:121]
	v_mfma_f32_16x16x32_bf16 v[114:117], v[164:167], v[196:199], v[114:117]
	v_mfma_f32_16x16x32_bf16 v[102:105], v[156:159], v[206:209], v[102:105]
	v_mfma_f32_16x16x32_bf16 v[98:101], v[164:167], v[206:209], v[98:101]
	v_mfma_f32_16x16x32_bf16 v[86:89], v[156:159], v[214:217], v[86:89]
	v_mfma_f32_16x16x32_bf16 v[82:85], v[164:167], v[214:217], v[82:85]
	v_mfma_f32_16x16x32_bf16 v[110:113], v[168:171], v[184:187], v[110:113]
	v_mfma_f32_16x16x32_bf16 v[106:109], v[176:179], v[184:187], v[106:109]
	v_mfma_f32_16x16x32_bf16 v[94:97], v[168:171], v[192:195], v[94:97]
	v_mfma_f32_16x16x32_bf16 v[90:93], v[176:179], v[192:195], v[90:93]
	v_mfma_f32_16x16x32_bf16 v[78:81], v[168:171], v[200:203], v[78:81]
	v_mfma_f32_16x16x32_bf16 v[74:77], v[176:179], v[200:203], v[74:77]
	v_mfma_f32_16x16x32_bf16 v[70:73], v[168:171], v[210:213], v[70:73]
	v_mfma_f32_16x16x32_bf16 v[66:69], v[176:179], v[210:213], v[66:69]
	v_mfma_f32_16x16x32_bf16 v[110:113], v[172:175], v[188:191], v[110:113]
	v_mfma_f32_16x16x32_bf16 v[106:109], v[180:183], v[188:191], v[106:109]
	v_mfma_f32_16x16x32_bf16 v[94:97], v[172:175], v[196:199], v[94:97]
	v_mfma_f32_16x16x32_bf16 v[90:93], v[180:183], v[196:199], v[90:93]
	v_mfma_f32_16x16x32_bf16 v[78:81], v[172:175], v[206:209], v[78:81]
	v_mfma_f32_16x16x32_bf16 v[74:77], v[180:183], v[206:209], v[74:77]
	v_mfma_f32_16x16x32_bf16 v[70:73], v[172:175], v[214:217], v[70:73]
	v_mfma_f32_16x16x32_bf16 v[66:69], v[180:183], v[214:217], v[66:69]
	s_barrier
	s_setprio 0
	s_mov_b32 m0, s31
	v_lshl_add_u64 v[218:219], s[46:47], 0, v[134:135]
	s_add_u32 s42, s46, 0x20000
	ds_read_b128 v[184:187], v148 offset:16384
	ds_read_b128 v[188:191], v148 offset:17408
	ds_read_b128 v[192:195], v148 offset:18432
	ds_read_b128 v[196:199], v148 offset:19456
	ds_read_b128 v[200:203], v148 offset:20480
	ds_read_b128 v[206:209], v148 offset:21504
	ds_read_b128 v[210:213], v148 offset:22528
	ds_read_b128 v[214:217], v148 offset:23552
	global_load_lds_dwordx4 v[218:219], off
	v_lshl_add_u64 v[220:221], s[46:47], 0, v[130:131]
	s_mov_b32 m0, s33
	s_addc_u32 s43, s47, 0
	global_load_lds_dwordx4 v[220:221], off
	v_lshl_add_u64 v[222:223], s[42:43], 0, v[134:135]
	s_mov_b32 m0, s34
	v_lshl_add_u64 v[224:225], s[48:49], 0, v[132:133]
	global_load_lds_dwordx4 v[222:223], off
	v_lshl_add_u64 v[222:223], s[42:43], 0, v[130:131]
	s_mov_b32 m0, s35
	s_nop 0
	global_load_lds_dwordx4 v[222:223], off
	v_lshl_add_u64 v[222:223], s[48:49], 0, v[136:137]
	s_mov_b32 m0, s2
	s_nop 0
	global_load_lds_dwordx4 v[222:223], off
	s_mov_b32 m0, s3
	s_nop 0
	global_load_lds_dwordx4 v[224:225], off
	s_waitcnt vmcnt(8)
	s_waitcnt lgkmcnt(0)
	s_setprio 1
	s_barrier
	v_mfma_f32_16x16x32_bf16 v[62:65], v[152:155], v[184:187], v[62:65]
	v_mfma_f32_16x16x32_bf16 v[58:61], v[160:163], v[184:187], v[58:61]
	v_mfma_f32_16x16x32_bf16 v[54:57], v[152:155], v[192:195], v[54:57]
	v_mfma_f32_16x16x32_bf16 v[50:53], v[160:163], v[192:195], v[50:53]
	v_mfma_f32_16x16x32_bf16 v[38:41], v[152:155], v[200:203], v[38:41]
	v_mfma_f32_16x16x32_bf16 v[34:37], v[160:163], v[200:203], v[34:37]
	v_mfma_f32_16x16x32_bf16 v[22:25], v[152:155], v[210:213], v[22:25]
	v_mfma_f32_16x16x32_bf16 v[18:21], v[160:163], v[210:213], v[18:21]
	v_mfma_f32_16x16x32_bf16 v[62:65], v[156:159], v[188:191], v[62:65]
	v_mfma_f32_16x16x32_bf16 v[58:61], v[164:167], v[188:191], v[58:61]
	v_mfma_f32_16x16x32_bf16 v[54:57], v[156:159], v[196:199], v[54:57]
	v_mfma_f32_16x16x32_bf16 v[50:53], v[164:167], v[196:199], v[50:53]
	v_mfma_f32_16x16x32_bf16 v[38:41], v[156:159], v[206:209], v[38:41]
	v_mfma_f32_16x16x32_bf16 v[34:37], v[164:167], v[206:209], v[34:37]
	v_mfma_f32_16x16x32_bf16 v[22:25], v[156:159], v[214:217], v[22:25]
	v_mfma_f32_16x16x32_bf16 v[18:21], v[164:167], v[214:217], v[18:21]
	v_mfma_f32_16x16x32_bf16 v[46:49], v[168:171], v[184:187], v[46:49]
	v_mfma_f32_16x16x32_bf16 v[42:45], v[176:179], v[184:187], v[42:45]
	v_mfma_f32_16x16x32_bf16 v[30:33], v[168:171], v[192:195], v[30:33]
	v_mfma_f32_16x16x32_bf16 v[26:29], v[176:179], v[192:195], v[26:29]
	v_mfma_f32_16x16x32_bf16 v[14:17], v[168:171], v[200:203], v[14:17]
	v_mfma_f32_16x16x32_bf16 v[10:13], v[176:179], v[200:203], v[10:13]
	v_mfma_f32_16x16x32_bf16 v[6:9], v[168:171], v[210:213], v[6:9]
	v_mfma_f32_16x16x32_bf16 v[2:5], v[176:179], v[210:213], v[2:5]
	v_mfma_f32_16x16x32_bf16 v[46:49], v[172:175], v[188:191], v[46:49]
	v_mfma_f32_16x16x32_bf16 v[42:45], v[180:183], v[188:191], v[42:45]
	v_mfma_f32_16x16x32_bf16 v[30:33], v[172:175], v[196:199], v[30:33]
	v_mfma_f32_16x16x32_bf16 v[26:29], v[180:183], v[196:199], v[26:29]
	v_mfma_f32_16x16x32_bf16 v[14:17], v[172:175], v[206:209], v[14:17]
	v_mfma_f32_16x16x32_bf16 v[10:13], v[180:183], v[206:209], v[10:13]
	v_mfma_f32_16x16x32_bf16 v[6:9], v[172:175], v[214:217], v[6:9]
	v_mfma_f32_16x16x32_bf16 v[2:5], v[180:183], v[214:217], v[2:5]
	s_barrier
	s_setprio 0
	ds_read_b128 v[152:155], v149
	ds_read_b128 v[156:159], v149 offset:1024
	ds_read_b128 v[160:163], v149 offset:2048
	ds_read_b128 v[164:167], v149 offset:3072
	ds_read_b128 v[168:171], v150
	ds_read_b128 v[172:175], v150 offset:1024
	ds_read_b128 v[176:179], v150 offset:2048
	ds_read_b128 v[180:183], v150 offset:3072
	s_add_u32 s42, s48, 0x20000
	s_addc_u32 s43, s49, 0
	s_mov_b32 m0, s16
	v_lshl_add_u64 v[226:227], s[42:43], 0, v[136:137]
	ds_read_b128 v[184:187], v148 offset:32768
	ds_read_b128 v[188:191], v148 offset:33792
	ds_read_b128 v[192:195], v148 offset:34816
	ds_read_b128 v[196:199], v148 offset:35840
	ds_read_b128 v[200:203], v148 offset:36864
	ds_read_b128 v[206:209], v148 offset:37888
	ds_read_b128 v[210:213], v148 offset:38912
	ds_read_b128 v[214:217], v148 offset:39936
	global_load_lds_dwordx4 v[226:227], off
	v_lshl_add_u64 v[226:227], s[42:43], 0, v[132:133]
	s_mov_b32 m0, s17
	s_nop 0
	global_load_lds_dwordx4 v[226:227], off
	s_waitcnt vmcnt(8)
	s_waitcnt lgkmcnt(0)
	s_setprio 1
	s_barrier
	v_mfma_f32_16x16x32_bf16 v[126:129], v[152:155], v[184:187], v[126:129]
	v_mfma_f32_16x16x32_bf16 v[122:125], v[160:163], v[184:187], v[122:125]
	v_mfma_f32_16x16x32_bf16 v[118:121], v[152:155], v[192:195], v[118:121]
	v_mfma_f32_16x16x32_bf16 v[114:117], v[160:163], v[192:195], v[114:117]
	v_mfma_f32_16x16x32_bf16 v[102:105], v[152:155], v[200:203], v[102:105]
	v_mfma_f32_16x16x32_bf16 v[98:101], v[160:163], v[200:203], v[98:101]
	v_mfma_f32_16x16x32_bf16 v[86:89], v[152:155], v[210:213], v[86:89]
	v_mfma_f32_16x16x32_bf16 v[82:85], v[160:163], v[210:213], v[82:85]
	v_mfma_f32_16x16x32_bf16 v[126:129], v[156:159], v[188:191], v[126:129]
	v_mfma_f32_16x16x32_bf16 v[122:125], v[164:167], v[188:191], v[122:125]
	v_mfma_f32_16x16x32_bf16 v[118:121], v[156:159], v[196:199], v[118:121]
	v_mfma_f32_16x16x32_bf16 v[114:117], v[164:167], v[196:199], v[114:117]
	v_mfma_f32_16x16x32_bf16 v[102:105], v[156:159], v[206:209], v[102:105]
	v_mfma_f32_16x16x32_bf16 v[98:101], v[164:167], v[206:209], v[98:101]
	v_mfma_f32_16x16x32_bf16 v[86:89], v[156:159], v[214:217], v[86:89]
	v_mfma_f32_16x16x32_bf16 v[82:85], v[164:167], v[214:217], v[82:85]
	v_mfma_f32_16x16x32_bf16 v[110:113], v[168:171], v[184:187], v[110:113]
	v_mfma_f32_16x16x32_bf16 v[106:109], v[176:179], v[184:187], v[106:109]
	v_mfma_f32_16x16x32_bf16 v[94:97], v[168:171], v[192:195], v[94:97]
	v_mfma_f32_16x16x32_bf16 v[90:93], v[176:179], v[192:195], v[90:93]
	v_mfma_f32_16x16x32_bf16 v[78:81], v[168:171], v[200:203], v[78:81]
	v_mfma_f32_16x16x32_bf16 v[74:77], v[176:179], v[200:203], v[74:77]
	v_mfma_f32_16x16x32_bf16 v[70:73], v[168:171], v[210:213], v[70:73]
	v_mfma_f32_16x16x32_bf16 v[66:69], v[176:179], v[210:213], v[66:69]
	v_mfma_f32_16x16x32_bf16 v[110:113], v[172:175], v[188:191], v[110:113]
	v_mfma_f32_16x16x32_bf16 v[106:109], v[180:183], v[188:191], v[106:109]
	v_mfma_f32_16x16x32_bf16 v[94:97], v[172:175], v[196:199], v[94:97]
	v_mfma_f32_16x16x32_bf16 v[90:93], v[180:183], v[196:199], v[90:93]
	v_mfma_f32_16x16x32_bf16 v[78:81], v[172:175], v[206:209], v[78:81]
	v_mfma_f32_16x16x32_bf16 v[74:77], v[180:183], v[206:209], v[74:77]
	v_mfma_f32_16x16x32_bf16 v[70:73], v[172:175], v[214:217], v[70:73]
	v_mfma_f32_16x16x32_bf16 v[66:69], v[180:183], v[214:217], v[66:69]
	s_barrier
	s_setprio 0
	s_mov_b32 m0, s62
	v_lshl_add_u64 v[218:219], v[218:219], 0, s[10:11]
	s_add_u32 s42, s46, 0x20080
	ds_read_b128 v[184:187], v148 offset:49152
	ds_read_b128 v[188:191], v148 offset:50176
	ds_read_b128 v[192:195], v148 offset:51200
	ds_read_b128 v[196:199], v148 offset:52224
	ds_read_b128 v[200:203], v148 offset:53248
	ds_read_b128 v[206:209], v148 offset:54272
	ds_read_b128 v[210:213], v148 offset:55296
	ds_read_b128 v[214:217], v148 offset:56320
	global_load_lds_dwordx4 v[218:219], off
	v_lshl_add_u64 v[218:219], v[220:221], 0, s[10:11]
	s_mov_b32 m0, s63
	s_addc_u32 s43, s47, 0
	global_load_lds_dwordx4 v[218:219], off
	v_lshl_add_u64 v[218:219], s[42:43], 0, v[134:135]
	s_mov_b32 m0, s64
	s_nop 0
	global_load_lds_dwordx4 v[218:219], off
	v_lshl_add_u64 v[218:219], s[42:43], 0, v[130:131]
	s_mov_b32 m0, s65
	s_nop 0
	global_load_lds_dwordx4 v[218:219], off
	v_lshl_add_u64 v[218:219], v[222:223], 0, s[10:11]
	s_mov_b32 m0, s25
	s_nop 0
	global_load_lds_dwordx4 v[218:219], off
	v_lshl_add_u64 v[218:219], v[224:225], 0, s[10:11]
	s_mov_b32 m0, s28
	s_nop 0
	global_load_lds_dwordx4 v[218:219], off
	s_waitcnt vmcnt(8)
	s_waitcnt lgkmcnt(0)
	s_setprio 1
	s_barrier
	v_mfma_f32_16x16x32_bf16 v[62:65], v[152:155], v[184:187], v[62:65]
	v_mfma_f32_16x16x32_bf16 v[58:61], v[160:163], v[184:187], v[58:61]
	v_mfma_f32_16x16x32_bf16 v[54:57], v[152:155], v[192:195], v[54:57]
	v_mfma_f32_16x16x32_bf16 v[50:53], v[160:163], v[192:195], v[50:53]
	v_mfma_f32_16x16x32_bf16 v[38:41], v[152:155], v[200:203], v[38:41]
	v_mfma_f32_16x16x32_bf16 v[34:37], v[160:163], v[200:203], v[34:37]
	v_mfma_f32_16x16x32_bf16 v[22:25], v[152:155], v[210:213], v[22:25]
	v_mfma_f32_16x16x32_bf16 v[18:21], v[160:163], v[210:213], v[18:21]
	v_mfma_f32_16x16x32_bf16 v[62:65], v[156:159], v[188:191], v[62:65]
	v_mfma_f32_16x16x32_bf16 v[58:61], v[164:167], v[188:191], v[58:61]
	v_mfma_f32_16x16x32_bf16 v[54:57], v[156:159], v[196:199], v[54:57]
	v_mfma_f32_16x16x32_bf16 v[50:53], v[164:167], v[196:199], v[50:53]
	v_mfma_f32_16x16x32_bf16 v[38:41], v[156:159], v[206:209], v[38:41]
	v_mfma_f32_16x16x32_bf16 v[34:37], v[164:167], v[206:209], v[34:37]
	v_mfma_f32_16x16x32_bf16 v[22:25], v[156:159], v[214:217], v[22:25]
	v_mfma_f32_16x16x32_bf16 v[18:21], v[164:167], v[214:217], v[18:21]
	v_mfma_f32_16x16x32_bf16 v[46:49], v[168:171], v[184:187], v[46:49]
	v_mfma_f32_16x16x32_bf16 v[42:45], v[176:179], v[184:187], v[42:45]
	v_mfma_f32_16x16x32_bf16 v[30:33], v[168:171], v[192:195], v[30:33]
	v_mfma_f32_16x16x32_bf16 v[26:29], v[176:179], v[192:195], v[26:29]
	v_mfma_f32_16x16x32_bf16 v[14:17], v[168:171], v[200:203], v[14:17]
	v_mfma_f32_16x16x32_bf16 v[10:13], v[176:179], v[200:203], v[10:13]
	v_mfma_f32_16x16x32_bf16 v[6:9], v[168:171], v[210:213], v[6:9]
	v_mfma_f32_16x16x32_bf16 v[2:5], v[176:179], v[210:213], v[2:5]
	v_mfma_f32_16x16x32_bf16 v[46:49], v[172:175], v[188:191], v[46:49]
	v_mfma_f32_16x16x32_bf16 v[42:45], v[180:183], v[188:191], v[42:45]
	v_mfma_f32_16x16x32_bf16 v[30:33], v[172:175], v[196:199], v[30:33]
	v_mfma_f32_16x16x32_bf16 v[26:29], v[180:183], v[196:199], v[26:29]
	v_mfma_f32_16x16x32_bf16 v[14:17], v[172:175], v[206:209], v[14:17]
	v_mfma_f32_16x16x32_bf16 v[10:13], v[180:183], v[206:209], v[10:13]
	v_mfma_f32_16x16x32_bf16 v[6:9], v[172:175], v[214:217], v[6:9]
	v_mfma_f32_16x16x32_bf16 v[2:5], v[180:183], v[214:217], v[2:5]
	s_barrier
	s_setprio 0
	s_add_i32 s68, s68, 2
	s_cmp_gt_u32 s68, 5
	s_mov_b64 s[42:43], s[44:45]
	s_cbranch_scc0 .LBB0_384
	s_and_b64 vcc, exec, s[12:13]
	s_cbranch_vccz .LBB0_387
	s_barrier

.LBB0_406:
	s_lshl_b32 s74, s12, 7
	s_add_i32 s12, s12, 2
	v_cndmask_b32_e64 v138, 0, 1, s[66:67]
	s_lshl_b64 s[66:67], s[12:13], 7
	s_and_b64 s[68:69], s[64:65], exec
	s_cselect_b32 s66, 0, s66
	s_cselect_b32 s67, 0, s67
	s_add_u32 s70, s8, s66
	s_addc_u32 s71, s9, s67
	s_lshl_b64 s[66:67], s[12:13], 12
	s_add_u32 s12, s48, s66
	s_addc_u32 s66, s49, s67
	s_and_b64 s[64:65], s[64:65], exec
	s_cselect_b32 s73, s14, s66
	s_cselect_b32 s72, s15, s12
	s_add_u32 s76, s10, s74
	s_addc_u32 s77, s11, 0
	s_add_i32 s91, s62, s16
	s_add_i32 m0, s17, 0xc000
	s_add_i32 s92, s17, 0xe000
	s_add_i32 s88, s91, 0x2000
	s_add_u32 s74, s72, 0x10000
	ds_read_b128 v[146:149], v141
	ds_read_b128 v[150:153], v141 offset:1024
	ds_read_b128 v[154:157], v141 offset:2048
	ds_read_b128 v[158:161], v141 offset:3072
	ds_read_b128 v[162:165], v143
	ds_read_b128 v[166:169], v143 offset:1024
	ds_read_b128 v[170:173], v143 offset:2048
	ds_read_b128 v[174:177], v143 offset:3072
	s_addc_u32 s75, s73, 0
	s_add_i32 s90, s63, s16
	s_add_i32 s89, s90, 0x2000
	s_add_i32 s87, 0, 0x18000
	s_add_i32 s86, 0, 0x1c000
	s_add_u32 s68, s70, 0x10000
	s_addc_u32 s69, s71, 0
	s_add_u32 s64, s72, 0x1000
	s_addc_u32 s65, s73, 0
	s_add_i32 s85, s87, s16
	s_add_i32 s83, s85, 0x2000
	s_add_u32 s66, s72, 0x11000
	s_addc_u32 s67, s73, 0
	s_add_i32 s84, s86, s16
	s_add_i32 s12, s84, 0x2000
	v_cmp_ne_u32_e32 vcc, 1, v138
	v_lshl_add_u64 v[202:203], s[76:77], 0, v[136:137]
	v_lshl_add_u64 v[202:203], v[202:203], 0, s[36:37]
	ds_read_b128 v[178:181], v144
	ds_read_b128 v[182:185], v144 offset:1024
	ds_read_b128 v[186:189], v144 offset:2048
	ds_read_b128 v[190:193], v144 offset:3072
	ds_read_b128 v[194:197], v144 offset:4096
	ds_read_b128 v[198:201], v144 offset:5120
	ds_read_b128 v[206:209], v144 offset:6144
	ds_read_b128 v[210:213], v144 offset:7168
	global_load_lds_dwordx4 v[202:203], off
	v_lshl_add_u64 v[202:203], s[76:77], 0, v[132:133]
	v_lshl_add_u64 v[202:203], v[202:203], 0, s[36:37]
	s_mov_b32 m0, s92
	s_nop 0
	global_load_lds_dwordx4 v[202:203], off
	s_waitcnt vmcnt(8)
	s_waitcnt lgkmcnt(0)
	s_setprio 1
	s_barrier
	v_mfma_f32_16x16x32_bf16 v[126:129], v[146:149], v[178:181], v[126:129]
	v_mfma_f32_16x16x32_bf16 v[122:125], v[154:157], v[178:181], v[122:125]
	v_mfma_f32_16x16x32_bf16 v[118:121], v[146:149], v[186:189], v[118:121]
	v_mfma_f32_16x16x32_bf16 v[110:113], v[154:157], v[186:189], v[110:113]
	v_mfma_f32_16x16x32_bf16 v[102:105], v[146:149], v[194:197], v[102:105]
	v_mfma_f32_16x16x32_bf16 v[98:101], v[154:157], v[194:197], v[98:101]
	v_mfma_f32_16x16x32_bf16 v[86:89], v[146:149], v[206:209], v[86:89]
	v_mfma_f32_16x16x32_bf16 v[82:85], v[154:157], v[206:209], v[82:85]
	v_mfma_f32_16x16x32_bf16 v[126:129], v[150:153], v[182:185], v[126:129]
	v_mfma_f32_16x16x32_bf16 v[122:125], v[158:161], v[182:185], v[122:125]
	v_mfma_f32_16x16x32_bf16 v[118:121], v[150:153], v[190:193], v[118:121]
	v_mfma_f32_16x16x32_bf16 v[110:113], v[158:161], v[190:193], v[110:113]
	v_mfma_f32_16x16x32_bf16 v[102:105], v[150:153], v[198:201], v[102:105]
	v_mfma_f32_16x16x32_bf16 v[98:101], v[158:161], v[198:201], v[98:101]
	v_mfma_f32_16x16x32_bf16 v[86:89], v[150:153], v[210:213], v[86:89]
	v_mfma_f32_16x16x32_bf16 v[82:85], v[158:161], v[210:213], v[82:85]
	v_mfma_f32_16x16x32_bf16 v[114:117], v[162:165], v[178:181], v[114:117]
	v_mfma_f32_16x16x32_bf16 v[106:109], v[170:173], v[178:181], v[106:109]
	v_mfma_f32_16x16x32_bf16 v[94:97], v[162:165], v[186:189], v[94:97]
	v_mfma_f32_16x16x32_bf16 v[90:93], v[170:173], v[186:189], v[90:93]
	v_mfma_f32_16x16x32_bf16 v[78:81], v[162:165], v[194:197], v[78:81]
	v_mfma_f32_16x16x32_bf16 v[74:77], v[170:173], v[194:197], v[74:77]
	v_mfma_f32_16x16x32_bf16 v[70:73], v[162:165], v[206:209], v[70:73]
	v_mfma_f32_16x16x32_bf16 v[66:69], v[170:173], v[206:209], v[66:69]
	v_mfma_f32_16x16x32_bf16 v[114:117], v[166:169], v[182:185], v[114:117]
	v_mfma_f32_16x16x32_bf16 v[106:109], v[174:177], v[182:185], v[106:109]
	v_mfma_f32_16x16x32_bf16 v[94:97], v[166:169], v[190:193], v[94:97]
	v_mfma_f32_16x16x32_bf16 v[90:93], v[174:177], v[190:193], v[90:93]
	v_mfma_f32_16x16x32_bf16 v[78:81], v[166:169], v[198:201], v[78:81]
	v_mfma_f32_16x16x32_bf16 v[74:77], v[174:177], v[198:201], v[74:77]
	v_mfma_f32_16x16x32_bf16 v[70:73], v[166:169], v[210:213], v[70:73]
	v_mfma_f32_16x16x32_bf16 v[66:69], v[174:177], v[210:213], v[66:69]
	s_barrier
	s_setprio 0
	s_mov_b32 m0, s91
	v_lshl_add_u64 v[202:203], s[72:73], 0, v[134:135]
	ds_read_b128 v[178:181], v144 offset:16384
	ds_read_b128 v[182:185], v144 offset:17408
	ds_read_b128 v[186:189], v144 offset:18432
	ds_read_b128 v[190:193], v144 offset:19456
	ds_read_b128 v[194:197], v144 offset:20480
	ds_read_b128 v[198:201], v144 offset:21504
	ds_read_b128 v[206:209], v144 offset:22528
	ds_read_b128 v[210:213], v144 offset:23552
	global_load_lds_dwordx4 v[202:203], off
	v_lshl_add_u64 v[202:203], s[72:73], 0, v[130:131]
	s_mov_b32 m0, s88
	v_lshl_add_u64 v[214:215], s[70:71], 0, v[132:133]
	global_load_lds_dwordx4 v[202:203], off
	v_lshl_add_u64 v[202:203], s[74:75], 0, v[134:135]
	s_mov_b32 m0, s90
	s_nop 0
	global_load_lds_dwordx4 v[202:203], off
	v_lshl_add_u64 v[202:203], s[74:75], 0, v[130:131]
	s_mov_b32 m0, s89
	s_nop 0
	global_load_lds_dwordx4 v[202:203], off
	v_lshl_add_u64 v[202:203], s[70:71], 0, v[136:137]
	s_mov_b32 m0, s17
	s_nop 0
	global_load_lds_dwordx4 v[202:203], off
	s_mov_b32 m0, s18
	s_nop 0
	global_load_lds_dwordx4 v[214:215], off
	s_waitcnt vmcnt(8)
	s_waitcnt lgkmcnt(0)
	s_setprio 1
	s_barrier
	v_mfma_f32_16x16x32_bf16 v[62:65], v[146:149], v[178:181], v[62:65]
	v_mfma_f32_16x16x32_bf16 v[58:61], v[154:157], v[178:181], v[58:61]
	v_mfma_f32_16x16x32_bf16 v[54:57], v[146:149], v[186:189], v[54:57]
	v_mfma_f32_16x16x32_bf16 v[50:53], v[154:157], v[186:189], v[50:53]
	v_mfma_f32_16x16x32_bf16 v[38:41], v[146:149], v[194:197], v[38:41]
	v_mfma_f32_16x16x32_bf16 v[34:37], v[154:157], v[194:197], v[34:37]
	v_mfma_f32_16x16x32_bf16 v[22:25], v[146:149], v[206:209], v[22:25]
	v_mfma_f32_16x16x32_bf16 v[18:21], v[154:157], v[206:209], v[18:21]
	v_mfma_f32_16x16x32_bf16 v[62:65], v[150:153], v[182:185], v[62:65]
	v_mfma_f32_16x16x32_bf16 v[58:61], v[158:161], v[182:185], v[58:61]
	v_mfma_f32_16x16x32_bf16 v[54:57], v[150:153], v[190:193], v[54:57]
	v_mfma_f32_16x16x32_bf16 v[50:53], v[158:161], v[190:193], v[50:53]
	v_mfma_f32_16x16x32_bf16 v[38:41], v[150:153], v[198:201], v[38:41]
	v_mfma_f32_16x16x32_bf16 v[34:37], v[158:161], v[198:201], v[34:37]
	v_mfma_f32_16x16x32_bf16 v[22:25], v[150:153], v[210:213], v[22:25]
	v_mfma_f32_16x16x32_bf16 v[18:21], v[158:161], v[210:213], v[18:21]
	v_mfma_f32_16x16x32_bf16 v[46:49], v[162:165], v[178:181], v[46:49]
	v_mfma_f32_16x16x32_bf16 v[42:45], v[170:173], v[178:181], v[42:45]
	v_mfma_f32_16x16x32_bf16 v[30:33], v[162:165], v[186:189], v[30:33]
	v_mfma_f32_16x16x32_bf16 v[26:29], v[170:173], v[186:189], v[26:29]
	v_mfma_f32_16x16x32_bf16 v[14:17], v[162:165], v[194:197], v[14:17]
	v_mfma_f32_16x16x32_bf16 v[10:13], v[170:173], v[194:197], v[10:13]
	v_mfma_f32_16x16x32_bf16 v[6:9], v[162:165], v[206:209], v[6:9]
	v_mfma_f32_16x16x32_bf16 v[2:5], v[170:173], v[206:209], v[2:5]
	v_mfma_f32_16x16x32_bf16 v[46:49], v[166:169], v[182:185], v[46:49]
	v_mfma_f32_16x16x32_bf16 v[42:45], v[174:177], v[182:185], v[42:45]
	v_mfma_f32_16x16x32_bf16 v[30:33], v[166:169], v[190:193], v[30:33]
	v_mfma_f32_16x16x32_bf16 v[26:29], v[174:177], v[190:193], v[26:29]
	v_mfma_f32_16x16x32_bf16 v[14:17], v[166:169], v[198:201], v[14:17]
	v_mfma_f32_16x16x32_bf16 v[10:13], v[174:177], v[198:201], v[10:13]
	v_mfma_f32_16x16x32_bf16 v[6:9], v[166:169], v[210:213], v[6:9]
	v_mfma_f32_16x16x32_bf16 v[2:5], v[174:177], v[210:213], v[2:5]
	s_barrier
	s_setprio 0
	v_add_u32_e32 v138, s87, v140
	ds_read_b128 v[146:149], v138
	ds_read_b128 v[150:153], v138 offset:1024
	ds_read_b128 v[154:157], v138 offset:2048
	ds_read_b128 v[158:161], v138 offset:3072
	v_add_u32_e32 v138, s86, v140
	ds_read_b128 v[162:165], v138
	ds_read_b128 v[166:169], v138 offset:1024
	ds_read_b128 v[170:173], v138 offset:2048
	ds_read_b128 v[174:177], v138 offset:3072
	s_mov_b32 m0, s19
	v_lshl_add_u64 v[216:217], s[68:69], 0, v[136:137]
	ds_read_b128 v[178:181], v144 offset:32768
	ds_read_b128 v[182:185], v144 offset:33792
	ds_read_b128 v[186:189], v144 offset:34816
	ds_read_b128 v[190:193], v144 offset:35840
	ds_read_b128 v[194:197], v144 offset:36864
	ds_read_b128 v[198:201], v144 offset:37888
	ds_read_b128 v[206:209], v144 offset:38912
	ds_read_b128 v[210:213], v144 offset:39936
	global_load_lds_dwordx4 v[216:217], off
	v_lshl_add_u64 v[216:217], s[68:69], 0, v[132:133]
	s_mov_b32 m0, s24
	s_nop 0
	global_load_lds_dwordx4 v[216:217], off
	s_waitcnt vmcnt(8)
	s_waitcnt lgkmcnt(0)
	s_setprio 1
	s_barrier
	v_mfma_f32_16x16x32_bf16 v[126:129], v[146:149], v[178:181], v[126:129]
	v_mfma_f32_16x16x32_bf16 v[122:125], v[154:157], v[178:181], v[122:125]
	v_mfma_f32_16x16x32_bf16 v[118:121], v[146:149], v[186:189], v[118:121]
	v_mfma_f32_16x16x32_bf16 v[110:113], v[154:157], v[186:189], v[110:113]
	v_mfma_f32_16x16x32_bf16 v[102:105], v[146:149], v[194:197], v[102:105]
	v_mfma_f32_16x16x32_bf16 v[98:101], v[154:157], v[194:197], v[98:101]
	v_mfma_f32_16x16x32_bf16 v[86:89], v[146:149], v[206:209], v[86:89]
	v_mfma_f32_16x16x32_bf16 v[82:85], v[154:157], v[206:209], v[82:85]
	v_mfma_f32_16x16x32_bf16 v[126:129], v[150:153], v[182:185], v[126:129]
	v_mfma_f32_16x16x32_bf16 v[122:125], v[158:161], v[182:185], v[122:125]
	v_mfma_f32_16x16x32_bf16 v[118:121], v[150:153], v[190:193], v[118:121]
	v_mfma_f32_16x16x32_bf16 v[110:113], v[158:161], v[190:193], v[110:113]
	v_mfma_f32_16x16x32_bf16 v[102:105], v[150:153], v[198:201], v[102:105]
	v_mfma_f32_16x16x32_bf16 v[98:101], v[158:161], v[198:201], v[98:101]
	v_mfma_f32_16x16x32_bf16 v[86:89], v[150:153], v[210:213], v[86:89]
	v_mfma_f32_16x16x32_bf16 v[82:85], v[158:161], v[210:213], v[82:85]
	v_mfma_f32_16x16x32_bf16 v[114:117], v[162:165], v[178:181], v[114:117]
	v_mfma_f32_16x16x32_bf16 v[106:109], v[170:173], v[178:181], v[106:109]
	v_mfma_f32_16x16x32_bf16 v[94:97], v[162:165], v[186:189], v[94:97]
	v_mfma_f32_16x16x32_bf16 v[90:93], v[170:173], v[186:189], v[90:93]
	v_mfma_f32_16x16x32_bf16 v[78:81], v[162:165], v[194:197], v[78:81]
	v_mfma_f32_16x16x32_bf16 v[74:77], v[170:173], v[194:197], v[74:77]
	v_mfma_f32_16x16x32_bf16 v[70:73], v[162:165], v[206:209], v[70:73]
	v_mfma_f32_16x16x32_bf16 v[66:69], v[170:173], v[206:209], v[66:69]
	v_mfma_f32_16x16x32_bf16 v[114:117], v[166:169], v[182:185], v[114:117]
	v_mfma_f32_16x16x32_bf16 v[106:109], v[174:177], v[182:185], v[106:109]
	v_mfma_f32_16x16x32_bf16 v[94:97], v[166:169], v[190:193], v[94:97]
	v_mfma_f32_16x16x32_bf16 v[90:93], v[174:177], v[190:193], v[90:93]
	v_mfma_f32_16x16x32_bf16 v[78:81], v[166:169], v[198:201], v[78:81]
	v_mfma_f32_16x16x32_bf16 v[74:77], v[174:177], v[198:201], v[74:77]
	v_mfma_f32_16x16x32_bf16 v[70:73], v[166:169], v[210:213], v[70:73]
	v_mfma_f32_16x16x32_bf16 v[66:69], v[174:177], v[210:213], v[66:69]
	s_barrier
	s_setprio 0
	s_mov_b32 m0, s85
	v_lshl_add_u64 v[216:217], s[64:65], 0, v[134:135]
	ds_read_b128 v[178:181], v144 offset:49152
	ds_read_b128 v[182:185], v144 offset:50176
	ds_read_b128 v[186:189], v144 offset:51200
	ds_read_b128 v[190:193], v144 offset:52224
	ds_read_b128 v[194:197], v144 offset:53248
	ds_read_b128 v[198:201], v144 offset:54272
	ds_read_b128 v[206:209], v144 offset:55296
	ds_read_b128 v[210:213], v144 offset:56320
	global_load_lds_dwordx4 v[216:217], off
	v_lshl_add_u64 v[216:217], s[64:65], 0, v[130:131]
	s_mov_b32 m0, s83
	v_lshl_add_u64 v[202:203], v[202:203], 0, s[36:37]
	global_load_lds_dwordx4 v[216:217], off
	v_lshl_add_u64 v[216:217], s[66:67], 0, v[134:135]
	s_mov_b32 m0, s84
	s_nop 0
	global_load_lds_dwordx4 v[216:217], off
	v_lshl_add_u64 v[216:217], s[66:67], 0, v[130:131]
	s_mov_b32 m0, s12
	s_nop 0
	global_load_lds_dwordx4 v[216:217], off
	s_mov_b32 m0, s31
	s_nop 0
	global_load_lds_dwordx4 v[202:203], off
	v_lshl_add_u64 v[202:203], v[214:215], 0, s[36:37]
	s_mov_b32 m0, s33
	s_nop 0
	global_load_lds_dwordx4 v[202:203], off
	s_waitcnt vmcnt(8)
	s_waitcnt lgkmcnt(0)
	s_setprio 1
	s_barrier
	v_mfma_f32_16x16x32_bf16 v[62:65], v[146:149], v[178:181], v[62:65]
	v_mfma_f32_16x16x32_bf16 v[58:61], v[154:157], v[178:181], v[58:61]
	v_mfma_f32_16x16x32_bf16 v[54:57], v[146:149], v[186:189], v[54:57]
	v_mfma_f32_16x16x32_bf16 v[50:53], v[154:157], v[186:189], v[50:53]
	v_mfma_f32_16x16x32_bf16 v[38:41], v[146:149], v[194:197], v[38:41]
	v_mfma_f32_16x16x32_bf16 v[34:37], v[154:157], v[194:197], v[34:37]
	v_mfma_f32_16x16x32_bf16 v[22:25], v[146:149], v[206:209], v[22:25]
	v_mfma_f32_16x16x32_bf16 v[18:21], v[154:157], v[206:209], v[18:21]
	v_mfma_f32_16x16x32_bf16 v[62:65], v[150:153], v[182:185], v[62:65]
	v_mfma_f32_16x16x32_bf16 v[58:61], v[158:161], v[182:185], v[58:61]
	v_mfma_f32_16x16x32_bf16 v[54:57], v[150:153], v[190:193], v[54:57]
	v_mfma_f32_16x16x32_bf16 v[50:53], v[158:161], v[190:193], v[50:53]
	v_mfma_f32_16x16x32_bf16 v[38:41], v[150:153], v[198:201], v[38:41]
	v_mfma_f32_16x16x32_bf16 v[34:37], v[158:161], v[198:201], v[34:37]
	v_mfma_f32_16x16x32_bf16 v[22:25], v[150:153], v[210:213], v[22:25]
	v_mfma_f32_16x16x32_bf16 v[18:21], v[158:161], v[210:213], v[18:21]
	v_mfma_f32_16x16x32_bf16 v[46:49], v[162:165], v[178:181], v[46:49]
	v_mfma_f32_16x16x32_bf16 v[42:45], v[170:173], v[178:181], v[42:45]
	v_mfma_f32_16x16x32_bf16 v[30:33], v[162:165], v[186:189], v[30:33]
	v_mfma_f32_16x16x32_bf16 v[26:29], v[170:173], v[186:189], v[26:29]
	v_mfma_f32_16x16x32_bf16 v[14:17], v[162:165], v[194:197], v[14:17]
	v_mfma_f32_16x16x32_bf16 v[10:13], v[170:173], v[194:197], v[10:13]
	v_mfma_f32_16x16x32_bf16 v[6:9], v[162:165], v[206:209], v[6:9]
	v_mfma_f32_16x16x32_bf16 v[2:5], v[170:173], v[206:209], v[2:5]
	v_mfma_f32_16x16x32_bf16 v[46:49], v[166:169], v[182:185], v[46:49]
	v_mfma_f32_16x16x32_bf16 v[42:45], v[174:177], v[182:185], v[42:45]
	v_mfma_f32_16x16x32_bf16 v[30:33], v[166:169], v[190:193], v[30:33]
	v_mfma_f32_16x16x32_bf16 v[26:29], v[174:177], v[190:193], v[26:29]
	v_mfma_f32_16x16x32_bf16 v[14:17], v[166:169], v[198:201], v[14:17]
	v_mfma_f32_16x16x32_bf16 v[10:13], v[174:177], v[198:201], v[10:13]
	v_mfma_f32_16x16x32_bf16 v[6:9], v[166:169], v[210:213], v[6:9]
	v_mfma_f32_16x16x32_bf16 v[2:5], v[174:177], v[210:213], v[2:5]
	s_barrier
	s_setprio 0
	s_mov_b64 s[66:67], 0
	s_mov_b64 s[64:65], -1
	s_mov_b32 s12, 2
	s_cbranch_vccz .LBB0_406
	s_and_b64 vcc, exec, s[22:23]
	s_cbranch_vccz .LBB0_409
	s_barrier

.LBB0_476:
	s_add_u32 s22, s2, s49
	s_addc_u32 s23, s3, s29
	s_and_b64 s[26:27], s[20:21], exec
	s_cselect_b32 s63, s23, s37
	s_cselect_b32 s64, s22, s36
	s_add_u32 s26, s16, s12
	s_addc_u32 s27, s17, s13
	s_and_b64 s[42:43], s[20:21], exec
	s_cselect_b32 s65, s27, s39
	s_cselect_b32 s66, s26, s38
	s_add_u32 s36, s36, 0x20080
	s_addc_u32 s37, s37, 0
	s_add_u32 s67, s38, 0x100
	s_addc_u32 s68, s39, 0
	s_mov_b32 s69, -2
	ds_read_b128 v[148:151], v144
	ds_read_b128 v[152:155], v144 offset:1024
	ds_read_b128 v[156:159], v144 offset:2048
	ds_read_b128 v[160:163], v144 offset:3072
	ds_read_b128 v[164:167], v145
	ds_read_b128 v[168:171], v145 offset:1024
	ds_read_b128 v[172:175], v145 offset:2048
	ds_read_b128 v[176:179], v145 offset:3072
	s_add_u32 s38, s36, 0xfffe0080
	s_addc_u32 s39, s37, -1
	s_cmp_eq_u32 s69, 4
	s_cselect_b32 s43, s63, s39
	s_cselect_b32 s42, s64, s38
	s_cselect_b32 s39, s65, s68
	s_cselect_b32 s38, s66, s67
	v_lshl_add_u64 v[214:215], s[36:37], 0, v[138:139]
	s_add_i32 m0, s19, 0xc000
	ds_read_b128 v[180:183], v146
	ds_read_b128 v[184:187], v146 offset:1024
	ds_read_b128 v[188:191], v146 offset:2048
	ds_read_b128 v[192:195], v146 offset:3072
	ds_read_b128 v[196:199], v146 offset:4096
	ds_read_b128 v[200:203], v146 offset:5120
	ds_read_b128 v[206:209], v146 offset:6144
	ds_read_b128 v[210:213], v146 offset:7168
	global_load_lds_dwordx4 v[214:215], off
	v_lshl_add_u64 v[214:215], s[36:37], 0, v[140:141]
	s_add_i32 m0, s19, 0xe000
	s_nop 0
	global_load_lds_dwordx4 v[214:215], off
	s_waitcnt vmcnt(8)
	s_waitcnt lgkmcnt(0)
	s_setprio 1
	s_barrier
	v_mfma_f32_16x16x32_bf16 v[126:129], v[148:151], v[180:183], 0
	v_mfma_f32_16x16x32_bf16 v[122:125], v[156:159], v[180:183], 0
	v_mfma_f32_16x16x32_bf16 v[118:121], v[148:151], v[188:191], 0
	v_mfma_f32_16x16x32_bf16 v[114:117], v[156:159], v[188:191], 0
	v_mfma_f32_16x16x32_bf16 v[102:105], v[148:151], v[196:199], 0
	v_mfma_f32_16x16x32_bf16 v[98:101], v[156:159], v[196:199], 0
	v_mfma_f32_16x16x32_bf16 v[86:89], v[148:151], v[206:209], 0
	v_mfma_f32_16x16x32_bf16 v[82:85], v[156:159], v[206:209], 0
	v_mfma_f32_16x16x32_bf16 v[126:129], v[152:155], v[184:187], v[126:129]
	v_mfma_f32_16x16x32_bf16 v[122:125], v[160:163], v[184:187], v[122:125]
	v_mfma_f32_16x16x32_bf16 v[118:121], v[152:155], v[192:195], v[118:121]
	v_mfma_f32_16x16x32_bf16 v[114:117], v[160:163], v[192:195], v[114:117]
	v_mfma_f32_16x16x32_bf16 v[102:105], v[152:155], v[200:203], v[102:105]
	v_mfma_f32_16x16x32_bf16 v[98:101], v[160:163], v[200:203], v[98:101]
	v_mfma_f32_16x16x32_bf16 v[86:89], v[152:155], v[210:213], v[86:89]
	v_mfma_f32_16x16x32_bf16 v[82:85], v[160:163], v[210:213], v[82:85]
	v_mfma_f32_16x16x32_bf16 v[110:113], v[164:167], v[180:183], 0
	v_mfma_f32_16x16x32_bf16 v[106:109], v[172:175], v[180:183], 0
	v_mfma_f32_16x16x32_bf16 v[94:97], v[164:167], v[188:191], 0
	v_mfma_f32_16x16x32_bf16 v[90:93], v[172:175], v[188:191], 0
	v_mfma_f32_16x16x32_bf16 v[78:81], v[164:167], v[196:199], 0
	v_mfma_f32_16x16x32_bf16 v[74:77], v[172:175], v[196:199], 0
	v_mfma_f32_16x16x32_bf16 v[70:73], v[164:167], v[206:209], 0
	v_mfma_f32_16x16x32_bf16 v[66:69], v[172:175], v[206:209], 0
	v_mfma_f32_16x16x32_bf16 v[110:113], v[168:171], v[184:187], v[110:113]
	v_mfma_f32_16x16x32_bf16 v[106:109], v[176:179], v[184:187], v[106:109]
	v_mfma_f32_16x16x32_bf16 v[94:97], v[168:171], v[192:195], v[94:97]
	v_mfma_f32_16x16x32_bf16 v[90:93], v[176:179], v[192:195], v[90:93]
	v_mfma_f32_16x16x32_bf16 v[78:81], v[168:171], v[200:203], v[78:81]
	v_mfma_f32_16x16x32_bf16 v[74:77], v[176:179], v[200:203], v[74:77]
	v_mfma_f32_16x16x32_bf16 v[70:73], v[168:171], v[210:213], v[70:73]
	v_mfma_f32_16x16x32_bf16 v[66:69], v[176:179], v[210:213], v[66:69]
	s_barrier
	s_setprio 0
	s_add_i32 s70, s35, s18
	v_lshl_add_u64 v[214:215], s[38:39], 0, v[134:135]
	s_mov_b32 m0, s70
	ds_read_b128 v[180:183], v146 offset:16384
	ds_read_b128 v[184:187], v146 offset:17408
	ds_read_b128 v[188:191], v146 offset:18432
	ds_read_b128 v[192:195], v146 offset:19456
	ds_read_b128 v[196:199], v146 offset:20480
	ds_read_b128 v[200:203], v146 offset:21504
	ds_read_b128 v[206:209], v146 offset:22528
	ds_read_b128 v[210:213], v146 offset:23552
	global_load_lds_dwordx4 v[214:215], off
	s_add_i32 m0, s70, 0x2000
	s_add_u32 s70, s38, 0x200000
	v_lshl_add_u64 v[216:217], s[38:39], 0, v[130:131]
	s_addc_u32 s71, s39, 0
	s_add_i32 s72, s44, s18
	global_load_lds_dwordx4 v[216:217], off
	v_lshl_add_u64 v[218:219], s[70:71], 0, v[134:135]
	s_mov_b32 m0, s72
	v_lshl_add_u64 v[220:221], s[42:43], 0, v[132:133]
	global_load_lds_dwordx4 v[218:219], off
	v_lshl_add_u64 v[218:219], s[70:71], 0, v[130:131]
	s_add_i32 m0, s72, 0x2000
	s_nop 0
	global_load_lds_dwordx4 v[218:219], off
	v_lshl_add_u64 v[218:219], s[42:43], 0, v[136:137]
	s_mov_b32 m0, s19
	s_nop 0
	global_load_lds_dwordx4 v[218:219], off
	s_mov_b32 m0, s24
	s_nop 0
	global_load_lds_dwordx4 v[220:221], off
	s_waitcnt vmcnt(8)
	s_waitcnt lgkmcnt(0)
	s_setprio 1
	s_barrier
	v_mfma_f32_16x16x32_bf16 v[62:65], v[148:151], v[180:183], 0
	v_mfma_f32_16x16x32_bf16 v[58:61], v[156:159], v[180:183], 0
	v_mfma_f32_16x16x32_bf16 v[54:57], v[148:151], v[188:191], 0
	v_mfma_f32_16x16x32_bf16 v[50:53], v[156:159], v[188:191], 0
	v_mfma_f32_16x16x32_bf16 v[38:41], v[148:151], v[196:199], 0
	v_mfma_f32_16x16x32_bf16 v[34:37], v[156:159], v[196:199], 0
	v_mfma_f32_16x16x32_bf16 v[22:25], v[148:151], v[206:209], 0
	v_mfma_f32_16x16x32_bf16 v[18:21], v[156:159], v[206:209], 0
	v_mfma_f32_16x16x32_bf16 v[62:65], v[152:155], v[184:187], v[62:65]
	v_mfma_f32_16x16x32_bf16 v[58:61], v[160:163], v[184:187], v[58:61]
	v_mfma_f32_16x16x32_bf16 v[54:57], v[152:155], v[192:195], v[54:57]
	v_mfma_f32_16x16x32_bf16 v[50:53], v[160:163], v[192:195], v[50:53]
	v_mfma_f32_16x16x32_bf16 v[38:41], v[152:155], v[200:203], v[38:41]
	v_mfma_f32_16x16x32_bf16 v[34:37], v[160:163], v[200:203], v[34:37]
	v_mfma_f32_16x16x32_bf16 v[22:25], v[152:155], v[210:213], v[22:25]
	v_mfma_f32_16x16x32_bf16 v[18:21], v[160:163], v[210:213], v[18:21]
	v_mfma_f32_16x16x32_bf16 v[46:49], v[164:167], v[180:183], 0
	v_mfma_f32_16x16x32_bf16 v[42:45], v[172:175], v[180:183], 0
	v_mfma_f32_16x16x32_bf16 v[30:33], v[164:167], v[188:191], 0
	v_mfma_f32_16x16x32_bf16 v[26:29], v[172:175], v[188:191], 0
	v_mfma_f32_16x16x32_bf16 v[14:17], v[164:167], v[196:199], 0
	v_mfma_f32_16x16x32_bf16 v[10:13], v[172:175], v[196:199], 0
	v_mfma_f32_16x16x32_bf16 v[6:9], v[164:167], v[206:209], 0
	v_mfma_f32_16x16x32_bf16 v[2:5], v[172:175], v[206:209], 0
	v_mfma_f32_16x16x32_bf16 v[46:49], v[168:171], v[184:187], v[46:49]
	v_mfma_f32_16x16x32_bf16 v[42:45], v[176:179], v[184:187], v[42:45]
	v_mfma_f32_16x16x32_bf16 v[30:33], v[168:171], v[192:195], v[30:33]
	v_mfma_f32_16x16x32_bf16 v[26:29], v[176:179], v[192:195], v[26:29]
	v_mfma_f32_16x16x32_bf16 v[14:17], v[168:171], v[200:203], v[14:17]
	v_mfma_f32_16x16x32_bf16 v[10:13], v[176:179], v[200:203], v[10:13]
	v_mfma_f32_16x16x32_bf16 v[6:9], v[168:171], v[210:213], v[6:9]
	v_mfma_f32_16x16x32_bf16 v[2:5], v[176:179], v[210:213], v[2:5]
	s_barrier
	s_setprio 0
	s_add_i32 s70, 0, 0x18000
	v_add_u32_e32 v147, s70, v143
	s_add_i32 s71, 0, 0x1c000
	ds_read_b128 v[148:151], v147
	ds_read_b128 v[152:155], v147 offset:1024
	ds_read_b128 v[156:159], v147 offset:2048
	ds_read_b128 v[160:163], v147 offset:3072
	v_add_u32_e32 v147, s71, v143
	ds_read_b128 v[164:167], v147
	ds_read_b128 v[168:171], v147 offset:1024
	ds_read_b128 v[172:175], v147 offset:2048
	ds_read_b128 v[176:179], v147 offset:3072
	s_add_u32 s42, s42, 0x20000
	s_addc_u32 s43, s43, 0
	s_mov_b32 m0, s25
	v_lshl_add_u64 v[222:223], s[42:43], 0, v[136:137]
	ds_read_b128 v[180:183], v146 offset:32768
	ds_read_b128 v[184:187], v146 offset:33792
	ds_read_b128 v[188:191], v146 offset:34816
	ds_read_b128 v[192:195], v146 offset:35840
	ds_read_b128 v[196:199], v146 offset:36864
	ds_read_b128 v[200:203], v146 offset:37888
	ds_read_b128 v[206:209], v146 offset:38912
	ds_read_b128 v[210:213], v146 offset:39936
	global_load_lds_dwordx4 v[222:223], off
	v_lshl_add_u64 v[222:223], s[42:43], 0, v[132:133]
	s_mov_b32 m0, s28
	s_nop 0
	global_load_lds_dwordx4 v[222:223], off
	s_waitcnt vmcnt(8)
	s_waitcnt lgkmcnt(0)
	s_setprio 1
	s_barrier
	v_mfma_f32_16x16x32_bf16 v[126:129], v[148:151], v[180:183], v[126:129]
	v_mfma_f32_16x16x32_bf16 v[122:125], v[156:159], v[180:183], v[122:125]
	v_mfma_f32_16x16x32_bf16 v[118:121], v[148:151], v[188:191], v[118:121]
	v_mfma_f32_16x16x32_bf16 v[114:117], v[156:159], v[188:191], v[114:117]
	v_mfma_f32_16x16x32_bf16 v[102:105], v[148:151], v[196:199], v[102:105]
	v_mfma_f32_16x16x32_bf16 v[98:101], v[156:159], v[196:199], v[98:101]
	v_mfma_f32_16x16x32_bf16 v[86:89], v[148:151], v[206:209], v[86:89]
	v_mfma_f32_16x16x32_bf16 v[82:85], v[156:159], v[206:209], v[82:85]
	v_mfma_f32_16x16x32_bf16 v[126:129], v[152:155], v[184:187], v[126:129]
	v_mfma_f32_16x16x32_bf16 v[122:125], v[160:163], v[184:187], v[122:125]
	v_mfma_f32_16x16x32_bf16 v[118:121], v[152:155], v[192:195], v[118:121]
	v_mfma_f32_16x16x32_bf16 v[114:117], v[160:163], v[192:195], v[114:117]
	v_mfma_f32_16x16x32_bf16 v[102:105], v[152:155], v[200:203], v[102:105]
	v_mfma_f32_16x16x32_bf16 v[98:101], v[160:163], v[200:203], v[98:101]
	v_mfma_f32_16x16x32_bf16 v[86:89], v[152:155], v[210:213], v[86:89]
	v_mfma_f32_16x16x32_bf16 v[82:85], v[160:163], v[210:213], v[82:85]
	v_mfma_f32_16x16x32_bf16 v[110:113], v[164:167], v[180:183], v[110:113]
	v_mfma_f32_16x16x32_bf16 v[106:109], v[172:175], v[180:183], v[106:109]
	v_mfma_f32_16x16x32_bf16 v[94:97], v[164:167], v[188:191], v[94:97]
	v_mfma_f32_16x16x32_bf16 v[90:93], v[172:175], v[188:191], v[90:93]
	v_mfma_f32_16x16x32_bf16 v[78:81], v[164:167], v[196:199], v[78:81]
	v_mfma_f32_16x16x32_bf16 v[74:77], v[172:175], v[196:199], v[74:77]
	v_mfma_f32_16x16x32_bf16 v[70:73], v[164:167], v[206:209], v[70:73]
	v_mfma_f32_16x16x32_bf16 v[66:69], v[172:175], v[206:209], v[66:69]
	v_mfma_f32_16x16x32_bf16 v[110:113], v[168:171], v[184:187], v[110:113]
	v_mfma_f32_16x16x32_bf16 v[106:109], v[176:179], v[184:187], v[106:109]
	v_mfma_f32_16x16x32_bf16 v[94:97], v[168:171], v[192:195], v[94:97]
	v_mfma_f32_16x16x32_bf16 v[90:93], v[176:179], v[192:195], v[90:93]
	v_mfma_f32_16x16x32_bf16 v[78:81], v[168:171], v[200:203], v[78:81]
	v_mfma_f32_16x16x32_bf16 v[74:77], v[176:179], v[200:203], v[74:77]
	v_mfma_f32_16x16x32_bf16 v[70:73], v[168:171], v[210:213], v[70:73]
	v_mfma_f32_16x16x32_bf16 v[66:69], v[176:179], v[210:213], v[66:69]
	s_barrier
	s_setprio 0
	s_add_i32 s42, s70, s18
	v_lshl_add_u64 v[214:215], v[214:215], 0, s[8:9]
	s_mov_b32 m0, s42
	ds_read_b128 v[180:183], v146 offset:49152
	ds_read_b128 v[184:187], v146 offset:50176
	ds_read_b128 v[188:191], v146 offset:51200
	ds_read_b128 v[192:195], v146 offset:52224
	ds_read_b128 v[196:199], v146 offset:53248
	ds_read_b128 v[200:203], v146 offset:54272
	ds_read_b128 v[206:209], v146 offset:55296
	ds_read_b128 v[210:213], v146 offset:56320
	global_load_lds_dwordx4 v[214:215], off
	s_add_i32 m0, s42, 0x2000
	s_add_u32 s38, s38, 0x200080
	v_lshl_add_u64 v[214:215], v[216:217], 0, s[8:9]
	s_addc_u32 s39, s39, 0
	s_add_i32 s42, s71, s18
	global_load_lds_dwordx4 v[214:215], off
	v_lshl_add_u64 v[214:215], s[38:39], 0, v[134:135]
	s_mov_b32 m0, s42
	s_nop 0
	global_load_lds_dwordx4 v[214:215], off
	v_lshl_add_u64 v[214:215], s[38:39], 0, v[130:131]
	s_add_i32 m0, s42, 0x2000
	s_nop 0
	global_load_lds_dwordx4 v[214:215], off
	v_lshl_add_u64 v[214:215], v[218:219], 0, s[8:9]
	s_mov_b32 m0, s33
	s_nop 0
	global_load_lds_dwordx4 v[214:215], off
	v_lshl_add_u64 v[214:215], v[220:221], 0, s[8:9]
	s_mov_b32 m0, s34
	s_nop 0
	global_load_lds_dwordx4 v[214:215], off
	s_waitcnt vmcnt(8)
	s_waitcnt lgkmcnt(0)
	s_setprio 1
	s_barrier
	v_mfma_f32_16x16x32_bf16 v[62:65], v[148:151], v[180:183], v[62:65]
	v_mfma_f32_16x16x32_bf16 v[58:61], v[156:159], v[180:183], v[58:61]
	v_mfma_f32_16x16x32_bf16 v[54:57], v[148:151], v[188:191], v[54:57]
	v_mfma_f32_16x16x32_bf16 v[50:53], v[156:159], v[188:191], v[50:53]
	v_mfma_f32_16x16x32_bf16 v[38:41], v[148:151], v[196:199], v[38:41]
	v_mfma_f32_16x16x32_bf16 v[34:37], v[156:159], v[196:199], v[34:37]
	v_mfma_f32_16x16x32_bf16 v[22:25], v[148:151], v[206:209], v[22:25]
	v_mfma_f32_16x16x32_bf16 v[18:21], v[156:159], v[206:209], v[18:21]
	v_mfma_f32_16x16x32_bf16 v[62:65], v[152:155], v[184:187], v[62:65]
	v_mfma_f32_16x16x32_bf16 v[58:61], v[160:163], v[184:187], v[58:61]
	v_mfma_f32_16x16x32_bf16 v[54:57], v[152:155], v[192:195], v[54:57]
	v_mfma_f32_16x16x32_bf16 v[50:53], v[160:163], v[192:195], v[50:53]
	v_mfma_f32_16x16x32_bf16 v[38:41], v[152:155], v[200:203], v[38:41]
	v_mfma_f32_16x16x32_bf16 v[34:37], v[160:163], v[200:203], v[34:37]
	v_mfma_f32_16x16x32_bf16 v[22:25], v[152:155], v[210:213], v[22:25]
	v_mfma_f32_16x16x32_bf16 v[18:21], v[160:163], v[210:213], v[18:21]
	v_mfma_f32_16x16x32_bf16 v[46:49], v[164:167], v[180:183], v[46:49]
	v_mfma_f32_16x16x32_bf16 v[42:45], v[172:175], v[180:183], v[42:45]
	v_mfma_f32_16x16x32_bf16 v[30:33], v[164:167], v[188:191], v[30:33]
	v_mfma_f32_16x16x32_bf16 v[26:29], v[172:175], v[188:191], v[26:29]
	v_mfma_f32_16x16x32_bf16 v[14:17], v[164:167], v[196:199], v[14:17]
	v_mfma_f32_16x16x32_bf16 v[10:13], v[172:175], v[196:199], v[10:13]
	v_mfma_f32_16x16x32_bf16 v[6:9], v[164:167], v[206:209], v[6:9]
	v_mfma_f32_16x16x32_bf16 v[2:5], v[172:175], v[206:209], v[2:5]
	v_mfma_f32_16x16x32_bf16 v[46:49], v[168:171], v[184:187], v[46:49]
	v_mfma_f32_16x16x32_bf16 v[42:45], v[176:179], v[184:187], v[42:45]
	v_mfma_f32_16x16x32_bf16 v[30:33], v[168:171], v[192:195], v[30:33]
	v_mfma_f32_16x16x32_bf16 v[26:29], v[176:179], v[192:195], v[26:29]
	v_mfma_f32_16x16x32_bf16 v[14:17], v[168:171], v[200:203], v[14:17]
	v_mfma_f32_16x16x32_bf16 v[10:13], v[176:179], v[200:203], v[10:13]
	v_mfma_f32_16x16x32_bf16 v[6:9], v[168:171], v[210:213], v[6:9]
	v_mfma_f32_16x16x32_bf16 v[2:5], v[176:179], v[210:213], v[2:5]
	s_barrier
	s_setprio 0
	s_add_i32 s69, s69, 2
	s_add_u32 s36, s36, 0x100
	s_addc_u32 s37, s37, 0
	s_add_u32 s67, s67, 0x100
	s_addc_u32 s68, s68, 0
	s_cmp_gt_u32 s69, 5
.LBB0_477:
	ds_read_b128 v[148:151], v144
	ds_read_b128 v[152:155], v144 offset:1024
	ds_read_b128 v[156:159], v144 offset:2048
	ds_read_b128 v[160:163], v144 offset:3072
	ds_read_b128 v[164:167], v145
	ds_read_b128 v[168:171], v145 offset:1024
	ds_read_b128 v[172:175], v145 offset:2048
	ds_read_b128 v[176:179], v145 offset:3072
	s_add_u32 s38, s36, 0xfffe0080
	s_addc_u32 s39, s37, -1
	s_cmp_eq_u32 s69, 4
	s_cselect_b32 s43, s63, s39
	s_cselect_b32 s42, s64, s38
	s_cselect_b32 s39, s65, s68
	s_cselect_b32 s38, s66, s67
	v_lshl_add_u64 v[214:215], s[36:37], 0, v[138:139]
	s_add_i32 m0, s19, 0xc000
	ds_read_b128 v[180:183], v146
	ds_read_b128 v[184:187], v146 offset:1024
	ds_read_b128 v[188:191], v146 offset:2048
	ds_read_b128 v[192:195], v146 offset:3072
	ds_read_b128 v[196:199], v146 offset:4096
	ds_read_b128 v[200:203], v146 offset:5120
	ds_read_b128 v[206:209], v146 offset:6144
	ds_read_b128 v[210:213], v146 offset:7168
	global_load_lds_dwordx4 v[214:215], off
	v_lshl_add_u64 v[214:215], s[36:37], 0, v[140:141]
	s_add_i32 m0, s19, 0xe000
	s_nop 0
	global_load_lds_dwordx4 v[214:215], off
	s_waitcnt vmcnt(8)
	s_waitcnt lgkmcnt(0)
	s_setprio 1
	s_barrier
	v_mfma_f32_16x16x32_bf16 v[126:129], v[148:151], v[180:183], v[126:129]
	v_mfma_f32_16x16x32_bf16 v[122:125], v[156:159], v[180:183], v[122:125]
	v_mfma_f32_16x16x32_bf16 v[118:121], v[148:151], v[188:191], v[118:121]
	v_mfma_f32_16x16x32_bf16 v[114:117], v[156:159], v[188:191], v[114:117]
	v_mfma_f32_16x16x32_bf16 v[102:105], v[148:151], v[196:199], v[102:105]
	v_mfma_f32_16x16x32_bf16 v[98:101], v[156:159], v[196:199], v[98:101]
	v_mfma_f32_16x16x32_bf16 v[86:89], v[148:151], v[206:209], v[86:89]
	v_mfma_f32_16x16x32_bf16 v[82:85], v[156:159], v[206:209], v[82:85]
	v_mfma_f32_16x16x32_bf16 v[126:129], v[152:155], v[184:187], v[126:129]
	v_mfma_f32_16x16x32_bf16 v[122:125], v[160:163], v[184:187], v[122:125]
	v_mfma_f32_16x16x32_bf16 v[118:121], v[152:155], v[192:195], v[118:121]
	v_mfma_f32_16x16x32_bf16 v[114:117], v[160:163], v[192:195], v[114:117]
	v_mfma_f32_16x16x32_bf16 v[102:105], v[152:155], v[200:203], v[102:105]
	v_mfma_f32_16x16x32_bf16 v[98:101], v[160:163], v[200:203], v[98:101]
	v_mfma_f32_16x16x32_bf16 v[86:89], v[152:155], v[210:213], v[86:89]
	v_mfma_f32_16x16x32_bf16 v[82:85], v[160:163], v[210:213], v[82:85]
	v_mfma_f32_16x16x32_bf16 v[110:113], v[164:167], v[180:183], v[110:113]
	v_mfma_f32_16x16x32_bf16 v[106:109], v[172:175], v[180:183], v[106:109]
	v_mfma_f32_16x16x32_bf16 v[94:97], v[164:167], v[188:191], v[94:97]
	v_mfma_f32_16x16x32_bf16 v[90:93], v[172:175], v[188:191], v[90:93]
	v_mfma_f32_16x16x32_bf16 v[78:81], v[164:167], v[196:199], v[78:81]
	v_mfma_f32_16x16x32_bf16 v[74:77], v[172:175], v[196:199], v[74:77]
	v_mfma_f32_16x16x32_bf16 v[70:73], v[164:167], v[206:209], v[70:73]
	v_mfma_f32_16x16x32_bf16 v[66:69], v[172:175], v[206:209], v[66:69]
	v_mfma_f32_16x16x32_bf16 v[110:113], v[168:171], v[184:187], v[110:113]
	v_mfma_f32_16x16x32_bf16 v[106:109], v[176:179], v[184:187], v[106:109]
	v_mfma_f32_16x16x32_bf16 v[94:97], v[168:171], v[192:195], v[94:97]
	v_mfma_f32_16x16x32_bf16 v[90:93], v[176:179], v[192:195], v[90:93]
	v_mfma_f32_16x16x32_bf16 v[78:81], v[168:171], v[200:203], v[78:81]
	v_mfma_f32_16x16x32_bf16 v[74:77], v[176:179], v[200:203], v[74:77]
	v_mfma_f32_16x16x32_bf16 v[70:73], v[168:171], v[210:213], v[70:73]
	v_mfma_f32_16x16x32_bf16 v[66:69], v[176:179], v[210:213], v[66:69]
	s_barrier
	s_setprio 0
	s_add_i32 s70, s35, s18
	v_lshl_add_u64 v[214:215], s[38:39], 0, v[134:135]
	s_mov_b32 m0, s70
	ds_read_b128 v[180:183], v146 offset:16384
	ds_read_b128 v[184:187], v146 offset:17408
	ds_read_b128 v[188:191], v146 offset:18432
	ds_read_b128 v[192:195], v146 offset:19456
	ds_read_b128 v[196:199], v146 offset:20480
	ds_read_b128 v[200:203], v146 offset:21504
	ds_read_b128 v[206:209], v146 offset:22528
	ds_read_b128 v[210:213], v146 offset:23552
	global_load_lds_dwordx4 v[214:215], off
	s_add_i32 m0, s70, 0x2000
	s_add_u32 s70, s38, 0x200000
	v_lshl_add_u64 v[216:217], s[38:39], 0, v[130:131]
	s_addc_u32 s71, s39, 0
	s_add_i32 s72, s44, s18
	global_load_lds_dwordx4 v[216:217], off
	v_lshl_add_u64 v[218:219], s[70:71], 0, v[134:135]
	s_mov_b32 m0, s72
	v_lshl_add_u64 v[220:221], s[42:43], 0, v[132:133]
	global_load_lds_dwordx4 v[218:219], off
	v_lshl_add_u64 v[218:219], s[70:71], 0, v[130:131]
	s_add_i32 m0, s72, 0x2000
	s_nop 0
	global_load_lds_dwordx4 v[218:219], off
	v_lshl_add_u64 v[218:219], s[42:43], 0, v[136:137]
	s_mov_b32 m0, s19
	s_nop 0
	global_load_lds_dwordx4 v[218:219], off
	s_mov_b32 m0, s24
	s_nop 0
	global_load_lds_dwordx4 v[220:221], off
	s_waitcnt vmcnt(8)
	s_waitcnt lgkmcnt(0)
	s_setprio 1
	s_barrier
	v_mfma_f32_16x16x32_bf16 v[62:65], v[148:151], v[180:183], v[62:65]
	v_mfma_f32_16x16x32_bf16 v[58:61], v[156:159], v[180:183], v[58:61]
	v_mfma_f32_16x16x32_bf16 v[54:57], v[148:151], v[188:191], v[54:57]
	v_mfma_f32_16x16x32_bf16 v[50:53], v[156:159], v[188:191], v[50:53]
	v_mfma_f32_16x16x32_bf16 v[38:41], v[148:151], v[196:199], v[38:41]
	v_mfma_f32_16x16x32_bf16 v[34:37], v[156:159], v[196:199], v[34:37]
	v_mfma_f32_16x16x32_bf16 v[22:25], v[148:151], v[206:209], v[22:25]
	v_mfma_f32_16x16x32_bf16 v[18:21], v[156:159], v[206:209], v[18:21]
	v_mfma_f32_16x16x32_bf16 v[62:65], v[152:155], v[184:187], v[62:65]
	v_mfma_f32_16x16x32_bf16 v[58:61], v[160:163], v[184:187], v[58:61]
	v_mfma_f32_16x16x32_bf16 v[54:57], v[152:155], v[192:195], v[54:57]
	v_mfma_f32_16x16x32_bf16 v[50:53], v[160:163], v[192:195], v[50:53]
	v_mfma_f32_16x16x32_bf16 v[38:41], v[152:155], v[200:203], v[38:41]
	v_mfma_f32_16x16x32_bf16 v[34:37], v[160:163], v[200:203], v[34:37]
	v_mfma_f32_16x16x32_bf16 v[22:25], v[152:155], v[210:213], v[22:25]
	v_mfma_f32_16x16x32_bf16 v[18:21], v[160:163], v[210:213], v[18:21]
	v_mfma_f32_16x16x32_bf16 v[46:49], v[164:167], v[180:183], v[46:49]
	v_mfma_f32_16x16x32_bf16 v[42:45], v[172:175], v[180:183], v[42:45]
	v_mfma_f32_16x16x32_bf16 v[30:33], v[164:167], v[188:191], v[30:33]
	v_mfma_f32_16x16x32_bf16 v[26:29], v[172:175], v[188:191], v[26:29]
	v_mfma_f32_16x16x32_bf16 v[14:17], v[164:167], v[196:199], v[14:17]
	v_mfma_f32_16x16x32_bf16 v[10:13], v[172:175], v[196:199], v[10:13]
	v_mfma_f32_16x16x32_bf16 v[6:9], v[164:167], v[206:209], v[6:9]
	v_mfma_f32_16x16x32_bf16 v[2:5], v[172:175], v[206:209], v[2:5]
	v_mfma_f32_16x16x32_bf16 v[46:49], v[168:171], v[184:187], v[46:49]
	v_mfma_f32_16x16x32_bf16 v[42:45], v[176:179], v[184:187], v[42:45]
	v_mfma_f32_16x16x32_bf16 v[30:33], v[168:171], v[192:195], v[30:33]
	v_mfma_f32_16x16x32_bf16 v[26:29], v[176:179], v[192:195], v[26:29]
	v_mfma_f32_16x16x32_bf16 v[14:17], v[168:171], v[200:203], v[14:17]
	v_mfma_f32_16x16x32_bf16 v[10:13], v[176:179], v[200:203], v[10:13]
	v_mfma_f32_16x16x32_bf16 v[6:9], v[168:171], v[210:213], v[6:9]
	v_mfma_f32_16x16x32_bf16 v[2:5], v[176:179], v[210:213], v[2:5]
	s_barrier
	s_setprio 0
	s_add_i32 s70, 0, 0x18000
	v_add_u32_e32 v147, s70, v143
	s_add_i32 s71, 0, 0x1c000
	ds_read_b128 v[148:151], v147
	ds_read_b128 v[152:155], v147 offset:1024
	ds_read_b128 v[156:159], v147 offset:2048
	ds_read_b128 v[160:163], v147 offset:3072
	v_add_u32_e32 v147, s71, v143
	ds_read_b128 v[164:167], v147
	ds_read_b128 v[168:171], v147 offset:1024
	ds_read_b128 v[172:175], v147 offset:2048
	ds_read_b128 v[176:179], v147 offset:3072
	s_add_u32 s42, s42, 0x20000
	s_addc_u32 s43, s43, 0
	s_mov_b32 m0, s25
	v_lshl_add_u64 v[222:223], s[42:43], 0, v[136:137]
	ds_read_b128 v[180:183], v146 offset:32768
	ds_read_b128 v[184:187], v146 offset:33792
	ds_read_b128 v[188:191], v146 offset:34816
	ds_read_b128 v[192:195], v146 offset:35840
	ds_read_b128 v[196:199], v146 offset:36864
	ds_read_b128 v[200:203], v146 offset:37888
	ds_read_b128 v[206:209], v146 offset:38912
	ds_read_b128 v[210:213], v146 offset:39936
	global_load_lds_dwordx4 v[222:223], off
	v_lshl_add_u64 v[222:223], s[42:43], 0, v[132:133]
	s_mov_b32 m0, s28
	s_nop 0
	global_load_lds_dwordx4 v[222:223], off
	s_waitcnt vmcnt(8)
	s_waitcnt lgkmcnt(0)
	s_setprio 1
	s_barrier
	v_mfma_f32_16x16x32_bf16 v[126:129], v[148:151], v[180:183], v[126:129]
	v_mfma_f32_16x16x32_bf16 v[122:125], v[156:159], v[180:183], v[122:125]
	v_mfma_f32_16x16x32_bf16 v[118:121], v[148:151], v[188:191], v[118:121]
	v_mfma_f32_16x16x32_bf16 v[114:117], v[156:159], v[188:191], v[114:117]
	v_mfma_f32_16x16x32_bf16 v[102:105], v[148:151], v[196:199], v[102:105]
	v_mfma_f32_16x16x32_bf16 v[98:101], v[156:159], v[196:199], v[98:101]
	v_mfma_f32_16x16x32_bf16 v[86:89], v[148:151], v[206:209], v[86:89]
	v_mfma_f32_16x16x32_bf16 v[82:85], v[156:159], v[206:209], v[82:85]
	v_mfma_f32_16x16x32_bf16 v[126:129], v[152:155], v[184:187], v[126:129]
	v_mfma_f32_16x16x32_bf16 v[122:125], v[160:163], v[184:187], v[122:125]
	v_mfma_f32_16x16x32_bf16 v[118:121], v[152:155], v[192:195], v[118:121]
	v_mfma_f32_16x16x32_bf16 v[114:117], v[160:163], v[192:195], v[114:117]
	v_mfma_f32_16x16x32_bf16 v[102:105], v[152:155], v[200:203], v[102:105]
	v_mfma_f32_16x16x32_bf16 v[98:101], v[160:163], v[200:203], v[98:101]
	v_mfma_f32_16x16x32_bf16 v[86:89], v[152:155], v[210:213], v[86:89]
	v_mfma_f32_16x16x32_bf16 v[82:85], v[160:163], v[210:213], v[82:85]
	v_mfma_f32_16x16x32_bf16 v[110:113], v[164:167], v[180:183], v[110:113]
	v_mfma_f32_16x16x32_bf16 v[106:109], v[172:175], v[180:183], v[106:109]
	v_mfma_f32_16x16x32_bf16 v[94:97], v[164:167], v[188:191], v[94:97]
	v_mfma_f32_16x16x32_bf16 v[90:93], v[172:175], v[188:191], v[90:93]
	v_mfma_f32_16x16x32_bf16 v[78:81], v[164:167], v[196:199], v[78:81]
	v_mfma_f32_16x16x32_bf16 v[74:77], v[172:175], v[196:199], v[74:77]
	v_mfma_f32_16x16x32_bf16 v[70:73], v[164:167], v[206:209], v[70:73]
	v_mfma_f32_16x16x32_bf16 v[66:69], v[172:175], v[206:209], v[66:69]
	v_mfma_f32_16x16x32_bf16 v[110:113], v[168:171], v[184:187], v[110:113]
	v_mfma_f32_16x16x32_bf16 v[106:109], v[176:179], v[184:187], v[106:109]
	v_mfma_f32_16x16x32_bf16 v[94:97], v[168:171], v[192:195], v[94:97]
	v_mfma_f32_16x16x32_bf16 v[90:93], v[176:179], v[192:195], v[90:93]
	v_mfma_f32_16x16x32_bf16 v[78:81], v[168:171], v[200:203], v[78:81]
	v_mfma_f32_16x16x32_bf16 v[74:77], v[176:179], v[200:203], v[74:77]
	v_mfma_f32_16x16x32_bf16 v[70:73], v[168:171], v[210:213], v[70:73]
	v_mfma_f32_16x16x32_bf16 v[66:69], v[176:179], v[210:213], v[66:69]
	s_barrier
	s_setprio 0
	s_add_i32 s42, s70, s18
	v_lshl_add_u64 v[214:215], v[214:215], 0, s[8:9]
	s_mov_b32 m0, s42
	ds_read_b128 v[180:183], v146 offset:49152
	ds_read_b128 v[184:187], v146 offset:50176
	ds_read_b128 v[188:191], v146 offset:51200
	ds_read_b128 v[192:195], v146 offset:52224
	ds_read_b128 v[196:199], v146 offset:53248
	ds_read_b128 v[200:203], v146 offset:54272
	ds_read_b128 v[206:209], v146 offset:55296
	ds_read_b128 v[210:213], v146 offset:56320
	global_load_lds_dwordx4 v[214:215], off
	s_add_i32 m0, s42, 0x2000
	s_add_u32 s38, s38, 0x200080
	v_lshl_add_u64 v[214:215], v[216:217], 0, s[8:9]
	s_addc_u32 s39, s39, 0
	s_add_i32 s42, s71, s18
	global_load_lds_dwordx4 v[214:215], off
	v_lshl_add_u64 v[214:215], s[38:39], 0, v[134:135]
	s_mov_b32 m0, s42
	s_nop 0
	global_load_lds_dwordx4 v[214:215], off
	v_lshl_add_u64 v[214:215], s[38:39], 0, v[130:131]
	s_add_i32 m0, s42, 0x2000
	s_nop 0
	global_load_lds_dwordx4 v[214:215], off
	v_lshl_add_u64 v[214:215], v[218:219], 0, s[8:9]
	s_mov_b32 m0, s33
	s_nop 0
	global_load_lds_dwordx4 v[214:215], off
	v_lshl_add_u64 v[214:215], v[220:221], 0, s[8:9]
	s_mov_b32 m0, s34
	s_nop 0
	global_load_lds_dwordx4 v[214:215], off
	s_waitcnt vmcnt(8)
	s_waitcnt lgkmcnt(0)
	s_setprio 1
	s_barrier
	v_mfma_f32_16x16x32_bf16 v[62:65], v[148:151], v[180:183], v[62:65]
	v_mfma_f32_16x16x32_bf16 v[58:61], v[156:159], v[180:183], v[58:61]
	v_mfma_f32_16x16x32_bf16 v[54:57], v[148:151], v[188:191], v[54:57]
	v_mfma_f32_16x16x32_bf16 v[50:53], v[156:159], v[188:191], v[50:53]
	v_mfma_f32_16x16x32_bf16 v[38:41], v[148:151], v[196:199], v[38:41]
	v_mfma_f32_16x16x32_bf16 v[34:37], v[156:159], v[196:199], v[34:37]
	v_mfma_f32_16x16x32_bf16 v[22:25], v[148:151], v[206:209], v[22:25]
	v_mfma_f32_16x16x32_bf16 v[18:21], v[156:159], v[206:209], v[18:21]
	v_mfma_f32_16x16x32_bf16 v[62:65], v[152:155], v[184:187], v[62:65]
	v_mfma_f32_16x16x32_bf16 v[58:61], v[160:163], v[184:187], v[58:61]
	v_mfma_f32_16x16x32_bf16 v[54:57], v[152:155], v[192:195], v[54:57]
	v_mfma_f32_16x16x32_bf16 v[50:53], v[160:163], v[192:195], v[50:53]
	v_mfma_f32_16x16x32_bf16 v[38:41], v[152:155], v[200:203], v[38:41]
	v_mfma_f32_16x16x32_bf16 v[34:37], v[160:163], v[200:203], v[34:37]
	v_mfma_f32_16x16x32_bf16 v[22:25], v[152:155], v[210:213], v[22:25]
	v_mfma_f32_16x16x32_bf16 v[18:21], v[160:163], v[210:213], v[18:21]
	v_mfma_f32_16x16x32_bf16 v[46:49], v[164:167], v[180:183], v[46:49]
	v_mfma_f32_16x16x32_bf16 v[42:45], v[172:175], v[180:183], v[42:45]
	v_mfma_f32_16x16x32_bf16 v[30:33], v[164:167], v[188:191], v[30:33]
	v_mfma_f32_16x16x32_bf16 v[26:29], v[172:175], v[188:191], v[26:29]
	v_mfma_f32_16x16x32_bf16 v[14:17], v[164:167], v[196:199], v[14:17]
	v_mfma_f32_16x16x32_bf16 v[10:13], v[172:175], v[196:199], v[10:13]
	v_mfma_f32_16x16x32_bf16 v[6:9], v[164:167], v[206:209], v[6:9]
	v_mfma_f32_16x16x32_bf16 v[2:5], v[172:175], v[206:209], v[2:5]
	v_mfma_f32_16x16x32_bf16 v[46:49], v[168:171], v[184:187], v[46:49]
	v_mfma_f32_16x16x32_bf16 v[42:45], v[176:179], v[184:187], v[42:45]
	v_mfma_f32_16x16x32_bf16 v[30:33], v[168:171], v[192:195], v[30:33]
	v_mfma_f32_16x16x32_bf16 v[26:29], v[176:179], v[192:195], v[26:29]
	v_mfma_f32_16x16x32_bf16 v[14:17], v[168:171], v[200:203], v[14:17]
	v_mfma_f32_16x16x32_bf16 v[10:13], v[176:179], v[200:203], v[10:13]
	v_mfma_f32_16x16x32_bf16 v[6:9], v[168:171], v[210:213], v[6:9]
	v_mfma_f32_16x16x32_bf16 v[2:5], v[176:179], v[210:213], v[2:5]
	s_barrier
	s_setprio 0
	s_add_i32 s69, s69, 2
	s_add_u32 s36, s36, 0x100
	s_addc_u32 s37, s37, 0
	s_add_u32 s67, s67, 0x100
	s_addc_u32 s68, s68, 0
	s_cmp_gt_u32 s69, 5
	s_cbranch_scc0 .LBB0_477
	s_and_b64 vcc, exec, s[10:11]
	s_cbranch_vccz .LBB0_480
	s_barrier

.LBB0_565:
	v_readlane_b32 s62, v249, 27
	v_readlane_b32 s63, v249, 28
	s_add_u32 s72, s62, s68
	s_addc_u32 s73, s63, s69
	s_and_b64 s[62:63], s[70:71], exec
	s_cselect_b32 s31, s73, s77
	s_cselect_b32 s33, s72, s76
	s_add_u32 s74, s35, s66
	s_addc_u32 s75, s85, s67
	s_and_b64 s[62:63], s[70:71], exec
	s_cselect_b32 s34, s75, s79
	s_cselect_b32 s39, s74, s78
	s_add_i32 s45, s7, -2
	s_add_u32 s76, s76, 0x40080
	s_addc_u32 s77, s77, 0
	s_add_u32 s47, s78, 0x100
	s_addc_u32 s62, s79, 0
	s_mov_b32 s63, 0
	s_waitcnt vmcnt(0)
	ds_read_b128 v[114:117], v190
	ds_read_b128 v[118:121], v190 offset:1024
	ds_read_b128 v[122:125], v190 offset:2048
	ds_read_b128 v[126:129], v190 offset:3072
	ds_read_b128 v[146:149], v191
	ds_read_b128 v[150:153], v191 offset:1024
	ds_read_b128 v[154:157], v191 offset:2048
	ds_read_b128 v[158:161], v191 offset:3072
	s_add_i32 s82, s63, 2
	s_add_u32 s78, s76, 0xfffc0080
	s_addc_u32 s79, s77, -1
	s_cmp_eq_u32 s45, s63
	s_cselect_b32 s81, s31, s79
	s_cselect_b32 s80, s33, s78
	s_cselect_b32 s79, s34, s62
	s_cselect_b32 s78, s39, s47
	v_lshl_add_u64 v[186:187], s[76:77], 0, v[180:181]
	s_add_i32 m0, s87, 0xc000
	ds_read_b128 v[162:165], v192
	ds_read_b128 v[166:169], v192 offset:1024
	ds_read_b128 v[194:197], v192 offset:2048
	ds_read_b128 v[198:201], v192 offset:3072
	ds_read_b128 v[206:209], v192 offset:4096
	ds_read_b128 v[210:213], v192 offset:5120
	ds_read_b128 v[214:217], v192 offset:6144
	ds_read_b128 v[218:221], v192 offset:7168
	global_load_lds_dwordx4 v[186:187], off
	v_lshl_add_u64 v[186:187], s[76:77], 0, v[182:183]
	s_add_i32 m0, s87, 0xe000
	s_nop 0
	global_load_lds_dwordx4 v[186:187], off
	s_waitcnt vmcnt(8)
	s_waitcnt lgkmcnt(0)
	s_setprio 1
	s_barrier
	v_mfma_f32_16x16x32_bf16 v[142:145], v[114:117], v[162:165], 0
	v_mfma_f32_16x16x32_bf16 v[138:141], v[122:125], v[162:165], 0
	v_mfma_f32_16x16x32_bf16 v[110:113], v[114:117], v[194:197], 0
	v_mfma_f32_16x16x32_bf16 v[106:109], v[122:125], v[194:197], 0
	v_mfma_f32_16x16x32_bf16 v[98:101], v[114:117], v[206:209], 0
	v_mfma_f32_16x16x32_bf16 v[90:93], v[122:125], v[206:209], 0
	v_mfma_f32_16x16x32_bf16 v[82:85], v[114:117], v[214:217], 0
	v_mfma_f32_16x16x32_bf16 v[74:77], v[122:125], v[214:217], 0
	v_mfma_f32_16x16x32_bf16 v[142:145], v[118:121], v[166:169], v[142:145]
	v_mfma_f32_16x16x32_bf16 v[138:141], v[126:129], v[166:169], v[138:141]
	v_mfma_f32_16x16x32_bf16 v[110:113], v[118:121], v[198:201], v[110:113]
	v_mfma_f32_16x16x32_bf16 v[106:109], v[126:129], v[198:201], v[106:109]
	v_mfma_f32_16x16x32_bf16 v[98:101], v[118:121], v[210:213], v[98:101]
	v_mfma_f32_16x16x32_bf16 v[90:93], v[126:129], v[210:213], v[90:93]
	v_mfma_f32_16x16x32_bf16 v[82:85], v[118:121], v[218:221], v[82:85]
	v_mfma_f32_16x16x32_bf16 v[74:77], v[126:129], v[218:221], v[74:77]
	v_mfma_f32_16x16x32_bf16 v[134:137], v[146:149], v[162:165], 0
	v_mfma_f32_16x16x32_bf16 v[130:133], v[154:157], v[162:165], 0
	v_mfma_f32_16x16x32_bf16 v[102:105], v[146:149], v[194:197], 0
	v_mfma_f32_16x16x32_bf16 v[94:97], v[154:157], v[194:197], 0
	v_mfma_f32_16x16x32_bf16 v[86:89], v[146:149], v[206:209], 0
	v_mfma_f32_16x16x32_bf16 v[78:81], v[154:157], v[206:209], 0
	v_mfma_f32_16x16x32_bf16 v[70:73], v[146:149], v[214:217], 0
	v_mfma_f32_16x16x32_bf16 v[66:69], v[154:157], v[214:217], 0
	v_mfma_f32_16x16x32_bf16 v[134:137], v[150:153], v[166:169], v[134:137]
	v_mfma_f32_16x16x32_bf16 v[130:133], v[158:161], v[166:169], v[130:133]
	v_mfma_f32_16x16x32_bf16 v[102:105], v[150:153], v[198:201], v[102:105]
	v_mfma_f32_16x16x32_bf16 v[94:97], v[158:161], v[198:201], v[94:97]
	v_mfma_f32_16x16x32_bf16 v[86:89], v[150:153], v[210:213], v[86:89]
	v_mfma_f32_16x16x32_bf16 v[78:81], v[158:161], v[210:213], v[78:81]
	v_mfma_f32_16x16x32_bf16 v[70:73], v[150:153], v[218:221], v[70:73]
	v_mfma_f32_16x16x32_bf16 v[66:69], v[158:161], v[218:221], v[66:69]
	s_barrier
	s_setprio 0
	s_add_i32 s63, s24, s86
	v_lshl_add_u64 v[186:187], s[78:79], 0, v[172:173]
	s_mov_b32 m0, s63
	ds_read_b128 v[162:165], v192 offset:16384
	ds_read_b128 v[166:169], v192 offset:17408
	ds_read_b128 v[194:197], v192 offset:18432
	ds_read_b128 v[198:201], v192 offset:19456
	ds_read_b128 v[206:209], v192 offset:20480
	ds_read_b128 v[210:213], v192 offset:21504
	ds_read_b128 v[214:217], v192 offset:22528
	ds_read_b128 v[218:221], v192 offset:23552
	global_load_lds_dwordx4 v[186:187], off
	s_add_i32 m0, s63, 0x2000
	s_add_u32 vcc_lo, s78, 0x40000
	v_lshl_add_u64 v[202:203], s[78:79], 0, v[176:177]
	s_addc_u32 vcc_hi, s79, 0
	s_add_i32 s63, s25, s86
	global_load_lds_dwordx4 v[202:203], off
	v_lshl_add_u64 v[222:223], vcc, 0, v[172:173]
	s_mov_b32 m0, s63
	v_lshl_add_u64 v[224:225], s[80:81], 0, v[174:175]
	global_load_lds_dwordx4 v[222:223], off
	v_lshl_add_u64 v[222:223], vcc, 0, v[176:177]
	s_add_i32 m0, s63, 0x2000
	s_nop 0
	global_load_lds_dwordx4 v[222:223], off
	v_lshl_add_u64 v[222:223], s[80:81], 0, v[170:171]
	s_mov_b32 m0, s87
	s_nop 0
	global_load_lds_dwordx4 v[222:223], off
	s_mov_b32 m0, s88
	s_nop 0
	global_load_lds_dwordx4 v[224:225], off
	s_waitcnt vmcnt(8)
	s_waitcnt lgkmcnt(0)
	s_setprio 1
	s_barrier
	v_mfma_f32_16x16x32_bf16 v[62:65], v[114:117], v[162:165], 0
	v_mfma_f32_16x16x32_bf16 v[58:61], v[122:125], v[162:165], 0
	v_mfma_f32_16x16x32_bf16 v[50:53], v[114:117], v[194:197], 0
	v_mfma_f32_16x16x32_bf16 v[42:45], v[122:125], v[194:197], 0
	v_mfma_f32_16x16x32_bf16 v[34:37], v[114:117], v[206:209], 0
	v_mfma_f32_16x16x32_bf16 v[26:29], v[122:125], v[206:209], 0
	v_mfma_f32_16x16x32_bf16 v[18:21], v[114:117], v[214:217], 0
	v_mfma_f32_16x16x32_bf16 v[10:13], v[122:125], v[214:217], 0
	v_mfma_f32_16x16x32_bf16 v[62:65], v[118:121], v[166:169], v[62:65]
	v_mfma_f32_16x16x32_bf16 v[58:61], v[126:129], v[166:169], v[58:61]
	v_mfma_f32_16x16x32_bf16 v[50:53], v[118:121], v[198:201], v[50:53]
	v_mfma_f32_16x16x32_bf16 v[42:45], v[126:129], v[198:201], v[42:45]
	v_mfma_f32_16x16x32_bf16 v[34:37], v[118:121], v[210:213], v[34:37]
	v_mfma_f32_16x16x32_bf16 v[26:29], v[126:129], v[210:213], v[26:29]
	v_mfma_f32_16x16x32_bf16 v[18:21], v[118:121], v[218:221], v[18:21]
	v_mfma_f32_16x16x32_bf16 v[10:13], v[126:129], v[218:221], v[10:13]
	v_mfma_f32_16x16x32_bf16 v[54:57], v[146:149], v[162:165], 0
	v_mfma_f32_16x16x32_bf16 v[46:49], v[154:157], v[162:165], 0
	v_mfma_f32_16x16x32_bf16 v[38:41], v[146:149], v[194:197], 0
	v_mfma_f32_16x16x32_bf16 v[30:33], v[154:157], v[194:197], 0
	v_mfma_f32_16x16x32_bf16 v[22:25], v[146:149], v[206:209], 0
	v_mfma_f32_16x16x32_bf16 v[14:17], v[154:157], v[206:209], 0
	v_mfma_f32_16x16x32_bf16 v[6:9], v[146:149], v[214:217], 0
	v_mfma_f32_16x16x32_bf16 v[2:5], v[154:157], v[214:217], 0
	v_mfma_f32_16x16x32_bf16 v[54:57], v[150:153], v[166:169], v[54:57]
	v_mfma_f32_16x16x32_bf16 v[46:49], v[158:161], v[166:169], v[46:49]
	v_mfma_f32_16x16x32_bf16 v[38:41], v[150:153], v[198:201], v[38:41]
	v_mfma_f32_16x16x32_bf16 v[30:33], v[158:161], v[198:201], v[30:33]
	v_mfma_f32_16x16x32_bf16 v[22:25], v[150:153], v[210:213], v[22:25]
	v_mfma_f32_16x16x32_bf16 v[14:17], v[158:161], v[210:213], v[14:17]
	v_mfma_f32_16x16x32_bf16 v[6:9], v[150:153], v[218:221], v[6:9]
	v_mfma_f32_16x16x32_bf16 v[2:5], v[158:161], v[218:221], v[2:5]
	s_barrier
	s_setprio 0
	s_add_i32 s63, 0, 0x18000
	s_add_i32 s83, 0, 0x1c000
	v_add_u32_e32 v126, s63, v189
	v_add_u32_e32 v158, s83, v189
	ds_read_b128 v[114:117], v126
	ds_read_b128 v[118:121], v126 offset:1024
	ds_read_b128 v[122:125], v126 offset:2048
	ds_read_b128 v[126:129], v126 offset:3072
	ds_read_b128 v[146:149], v158
	ds_read_b128 v[150:153], v158 offset:1024
	ds_read_b128 v[154:157], v158 offset:2048
	ds_read_b128 v[158:161], v158 offset:3072
	s_add_u32 s80, s80, 0x40000
	s_addc_u32 s81, s81, 0
	s_mov_b32 m0, s89
	v_lshl_add_u64 v[226:227], s[80:81], 0, v[170:171]
	ds_read_b128 v[162:165], v192 offset:32768
	ds_read_b128 v[166:169], v192 offset:33792
	ds_read_b128 v[194:197], v192 offset:34816
	ds_read_b128 v[198:201], v192 offset:35840
	ds_read_b128 v[206:209], v192 offset:36864
	ds_read_b128 v[210:213], v192 offset:37888
	ds_read_b128 v[214:217], v192 offset:38912
	ds_read_b128 v[218:221], v192 offset:39936
	global_load_lds_dwordx4 v[226:227], off
	v_lshl_add_u64 v[226:227], s[80:81], 0, v[174:175]
	s_mov_b32 m0, s90
	s_nop 0
	global_load_lds_dwordx4 v[226:227], off
	s_waitcnt vmcnt(8)
	s_waitcnt lgkmcnt(0)
	s_setprio 1
	s_barrier
	v_mfma_f32_16x16x32_bf16 v[142:145], v[114:117], v[162:165], v[142:145]
	v_mfma_f32_16x16x32_bf16 v[138:141], v[122:125], v[162:165], v[138:141]
	v_mfma_f32_16x16x32_bf16 v[110:113], v[114:117], v[194:197], v[110:113]
	v_mfma_f32_16x16x32_bf16 v[106:109], v[122:125], v[194:197], v[106:109]
	v_mfma_f32_16x16x32_bf16 v[98:101], v[114:117], v[206:209], v[98:101]
	v_mfma_f32_16x16x32_bf16 v[90:93], v[122:125], v[206:209], v[90:93]
	v_mfma_f32_16x16x32_bf16 v[82:85], v[114:117], v[214:217], v[82:85]
	v_mfma_f32_16x16x32_bf16 v[74:77], v[122:125], v[214:217], v[74:77]
	v_mfma_f32_16x16x32_bf16 v[142:145], v[118:121], v[166:169], v[142:145]
	v_mfma_f32_16x16x32_bf16 v[138:141], v[126:129], v[166:169], v[138:141]
	v_mfma_f32_16x16x32_bf16 v[110:113], v[118:121], v[198:201], v[110:113]
	v_mfma_f32_16x16x32_bf16 v[106:109], v[126:129], v[198:201], v[106:109]
	v_mfma_f32_16x16x32_bf16 v[98:101], v[118:121], v[210:213], v[98:101]
	v_mfma_f32_16x16x32_bf16 v[90:93], v[126:129], v[210:213], v[90:93]
	v_mfma_f32_16x16x32_bf16 v[82:85], v[118:121], v[218:221], v[82:85]
	v_mfma_f32_16x16x32_bf16 v[74:77], v[126:129], v[218:221], v[74:77]
	v_mfma_f32_16x16x32_bf16 v[134:137], v[146:149], v[162:165], v[134:137]
	v_mfma_f32_16x16x32_bf16 v[130:133], v[154:157], v[162:165], v[130:133]
	v_mfma_f32_16x16x32_bf16 v[102:105], v[146:149], v[194:197], v[102:105]
	v_mfma_f32_16x16x32_bf16 v[94:97], v[154:157], v[194:197], v[94:97]
	v_mfma_f32_16x16x32_bf16 v[86:89], v[146:149], v[206:209], v[86:89]
	v_mfma_f32_16x16x32_bf16 v[78:81], v[154:157], v[206:209], v[78:81]
	v_mfma_f32_16x16x32_bf16 v[70:73], v[146:149], v[214:217], v[70:73]
	v_mfma_f32_16x16x32_bf16 v[66:69], v[154:157], v[214:217], v[66:69]
	v_mfma_f32_16x16x32_bf16 v[134:137], v[150:153], v[166:169], v[134:137]
	v_mfma_f32_16x16x32_bf16 v[130:133], v[158:161], v[166:169], v[130:133]
	v_mfma_f32_16x16x32_bf16 v[102:105], v[150:153], v[198:201], v[102:105]
	v_mfma_f32_16x16x32_bf16 v[94:97], v[158:161], v[198:201], v[94:97]
	v_mfma_f32_16x16x32_bf16 v[86:89], v[150:153], v[210:213], v[86:89]
	v_mfma_f32_16x16x32_bf16 v[78:81], v[158:161], v[210:213], v[78:81]
	v_mfma_f32_16x16x32_bf16 v[70:73], v[150:153], v[218:221], v[70:73]
	v_mfma_f32_16x16x32_bf16 v[66:69], v[158:161], v[218:221], v[66:69]
	s_barrier
	s_setprio 0
	s_add_i32 s63, s63, s86
	v_lshl_add_u64 v[186:187], v[186:187], 0, s[22:23]
	s_mov_b32 m0, s63
	ds_read_b128 v[162:165], v192 offset:49152
	ds_read_b128 v[166:169], v192 offset:50176
	ds_read_b128 v[194:197], v192 offset:51200
	ds_read_b128 v[198:201], v192 offset:52224
	ds_read_b128 v[206:209], v192 offset:53248
	ds_read_b128 v[210:213], v192 offset:54272
	ds_read_b128 v[214:217], v192 offset:55296
	ds_read_b128 v[218:221], v192 offset:56320
	global_load_lds_dwordx4 v[186:187], off
	s_add_i32 m0, s63, 0x2000
	s_add_u32 s78, s78, 0x40080
	v_lshl_add_u64 v[186:187], v[202:203], 0, s[22:23]
	s_addc_u32 s79, s79, 0
	s_add_i32 s63, s83, s86
	global_load_lds_dwordx4 v[186:187], off
	v_lshl_add_u64 v[186:187], s[78:79], 0, v[172:173]
	s_mov_b32 m0, s63
	s_nop 0
	global_load_lds_dwordx4 v[186:187], off
	v_lshl_add_u64 v[186:187], s[78:79], 0, v[176:177]
	s_add_i32 m0, s63, 0x2000
	s_nop 0
	global_load_lds_dwordx4 v[186:187], off
	v_lshl_add_u64 v[186:187], v[222:223], 0, s[22:23]
	s_mov_b32 m0, s95
	s_nop 0
	global_load_lds_dwordx4 v[186:187], off
	v_lshl_add_u64 v[186:187], v[224:225], 0, s[22:23]
	s_mov_b32 m0, s96
	s_nop 0
	global_load_lds_dwordx4 v[186:187], off
	s_waitcnt vmcnt(8)
	s_waitcnt lgkmcnt(0)
	s_setprio 1
	s_barrier
	v_mfma_f32_16x16x32_bf16 v[62:65], v[114:117], v[162:165], v[62:65]
	v_mfma_f32_16x16x32_bf16 v[58:61], v[122:125], v[162:165], v[58:61]
	v_mfma_f32_16x16x32_bf16 v[50:53], v[114:117], v[194:197], v[50:53]
	v_mfma_f32_16x16x32_bf16 v[42:45], v[122:125], v[194:197], v[42:45]
	v_mfma_f32_16x16x32_bf16 v[34:37], v[114:117], v[206:209], v[34:37]
	v_mfma_f32_16x16x32_bf16 v[26:29], v[122:125], v[206:209], v[26:29]
	v_mfma_f32_16x16x32_bf16 v[18:21], v[114:117], v[214:217], v[18:21]
	v_mfma_f32_16x16x32_bf16 v[10:13], v[122:125], v[214:217], v[10:13]
	v_mfma_f32_16x16x32_bf16 v[62:65], v[118:121], v[166:169], v[62:65]
	v_mfma_f32_16x16x32_bf16 v[58:61], v[126:129], v[166:169], v[58:61]
	v_mfma_f32_16x16x32_bf16 v[50:53], v[118:121], v[198:201], v[50:53]
	v_mfma_f32_16x16x32_bf16 v[42:45], v[126:129], v[198:201], v[42:45]
	v_mfma_f32_16x16x32_bf16 v[34:37], v[118:121], v[210:213], v[34:37]
	v_mfma_f32_16x16x32_bf16 v[26:29], v[126:129], v[210:213], v[26:29]
	v_mfma_f32_16x16x32_bf16 v[18:21], v[118:121], v[218:221], v[18:21]
	v_mfma_f32_16x16x32_bf16 v[10:13], v[126:129], v[218:221], v[10:13]
	v_mfma_f32_16x16x32_bf16 v[54:57], v[146:149], v[162:165], v[54:57]
	v_mfma_f32_16x16x32_bf16 v[46:49], v[154:157], v[162:165], v[46:49]
	v_mfma_f32_16x16x32_bf16 v[38:41], v[146:149], v[194:197], v[38:41]
	v_mfma_f32_16x16x32_bf16 v[30:33], v[154:157], v[194:197], v[30:33]
	v_mfma_f32_16x16x32_bf16 v[22:25], v[146:149], v[206:209], v[22:25]
	v_mfma_f32_16x16x32_bf16 v[14:17], v[154:157], v[206:209], v[14:17]
	v_mfma_f32_16x16x32_bf16 v[6:9], v[146:149], v[214:217], v[6:9]
	v_mfma_f32_16x16x32_bf16 v[2:5], v[154:157], v[214:217], v[2:5]
	v_mfma_f32_16x16x32_bf16 v[54:57], v[150:153], v[166:169], v[54:57]
	v_mfma_f32_16x16x32_bf16 v[46:49], v[158:161], v[166:169], v[46:49]
	v_mfma_f32_16x16x32_bf16 v[38:41], v[150:153], v[198:201], v[38:41]
	v_mfma_f32_16x16x32_bf16 v[30:33], v[158:161], v[198:201], v[30:33]
	v_mfma_f32_16x16x32_bf16 v[22:25], v[150:153], v[210:213], v[22:25]
	v_mfma_f32_16x16x32_bf16 v[14:17], v[158:161], v[210:213], v[14:17]
	v_mfma_f32_16x16x32_bf16 v[6:9], v[150:153], v[218:221], v[6:9]
	v_mfma_f32_16x16x32_bf16 v[2:5], v[158:161], v[218:221], v[2:5]
	s_barrier
	s_setprio 0
	s_add_u32 s76, s76, 0x100
	s_addc_u32 s77, s77, 0
	s_add_u32 s47, s47, 0x100
	s_addc_u32 s62, s62, 0
	s_cmp_ge_i32 s82, s7
	s_mov_b32 s63, s82
.LBB0_566:
	s_waitcnt vmcnt(0)
	ds_read_b128 v[114:117], v190
	ds_read_b128 v[118:121], v190 offset:1024
	ds_read_b128 v[122:125], v190 offset:2048
	ds_read_b128 v[126:129], v190 offset:3072
	ds_read_b128 v[146:149], v191
	ds_read_b128 v[150:153], v191 offset:1024
	ds_read_b128 v[154:157], v191 offset:2048
	ds_read_b128 v[158:161], v191 offset:3072
	s_add_i32 s82, s63, 2
	s_add_u32 s78, s76, 0xfffc0080
	s_addc_u32 s79, s77, -1
	s_cmp_eq_u32 s45, s63
	s_cselect_b32 s81, s31, s79
	s_cselect_b32 s80, s33, s78
	s_cselect_b32 s79, s34, s62
	s_cselect_b32 s78, s39, s47
	v_lshl_add_u64 v[186:187], s[76:77], 0, v[180:181]
	s_add_i32 m0, s87, 0xc000
	ds_read_b128 v[162:165], v192
	ds_read_b128 v[166:169], v192 offset:1024
	ds_read_b128 v[194:197], v192 offset:2048
	ds_read_b128 v[198:201], v192 offset:3072
	ds_read_b128 v[206:209], v192 offset:4096
	ds_read_b128 v[210:213], v192 offset:5120
	ds_read_b128 v[214:217], v192 offset:6144
	ds_read_b128 v[218:221], v192 offset:7168
	global_load_lds_dwordx4 v[186:187], off
	v_lshl_add_u64 v[186:187], s[76:77], 0, v[182:183]
	s_add_i32 m0, s87, 0xe000
	s_nop 0
	global_load_lds_dwordx4 v[186:187], off
	s_waitcnt vmcnt(8)
	s_waitcnt lgkmcnt(0)
	s_setprio 1
	s_barrier
	v_mfma_f32_16x16x32_bf16 v[142:145], v[114:117], v[162:165], v[142:145]
	v_mfma_f32_16x16x32_bf16 v[138:141], v[122:125], v[162:165], v[138:141]
	v_mfma_f32_16x16x32_bf16 v[110:113], v[114:117], v[194:197], v[110:113]
	v_mfma_f32_16x16x32_bf16 v[106:109], v[122:125], v[194:197], v[106:109]
	v_mfma_f32_16x16x32_bf16 v[98:101], v[114:117], v[206:209], v[98:101]
	v_mfma_f32_16x16x32_bf16 v[90:93], v[122:125], v[206:209], v[90:93]
	v_mfma_f32_16x16x32_bf16 v[82:85], v[114:117], v[214:217], v[82:85]
	v_mfma_f32_16x16x32_bf16 v[74:77], v[122:125], v[214:217], v[74:77]
	v_mfma_f32_16x16x32_bf16 v[142:145], v[118:121], v[166:169], v[142:145]
	v_mfma_f32_16x16x32_bf16 v[138:141], v[126:129], v[166:169], v[138:141]
	v_mfma_f32_16x16x32_bf16 v[110:113], v[118:121], v[198:201], v[110:113]
	v_mfma_f32_16x16x32_bf16 v[106:109], v[126:129], v[198:201], v[106:109]
	v_mfma_f32_16x16x32_bf16 v[98:101], v[118:121], v[210:213], v[98:101]
	v_mfma_f32_16x16x32_bf16 v[90:93], v[126:129], v[210:213], v[90:93]
	v_mfma_f32_16x16x32_bf16 v[82:85], v[118:121], v[218:221], v[82:85]
	v_mfma_f32_16x16x32_bf16 v[74:77], v[126:129], v[218:221], v[74:77]
	v_mfma_f32_16x16x32_bf16 v[134:137], v[146:149], v[162:165], v[134:137]
	v_mfma_f32_16x16x32_bf16 v[130:133], v[154:157], v[162:165], v[130:133]
	v_mfma_f32_16x16x32_bf16 v[102:105], v[146:149], v[194:197], v[102:105]
	v_mfma_f32_16x16x32_bf16 v[94:97], v[154:157], v[194:197], v[94:97]
	v_mfma_f32_16x16x32_bf16 v[86:89], v[146:149], v[206:209], v[86:89]
	v_mfma_f32_16x16x32_bf16 v[78:81], v[154:157], v[206:209], v[78:81]
	v_mfma_f32_16x16x32_bf16 v[70:73], v[146:149], v[214:217], v[70:73]
	v_mfma_f32_16x16x32_bf16 v[66:69], v[154:157], v[214:217], v[66:69]
	v_mfma_f32_16x16x32_bf16 v[134:137], v[150:153], v[166:169], v[134:137]
	v_mfma_f32_16x16x32_bf16 v[130:133], v[158:161], v[166:169], v[130:133]
	v_mfma_f32_16x16x32_bf16 v[102:105], v[150:153], v[198:201], v[102:105]
	v_mfma_f32_16x16x32_bf16 v[94:97], v[158:161], v[198:201], v[94:97]
	v_mfma_f32_16x16x32_bf16 v[86:89], v[150:153], v[210:213], v[86:89]
	v_mfma_f32_16x16x32_bf16 v[78:81], v[158:161], v[210:213], v[78:81]
	v_mfma_f32_16x16x32_bf16 v[70:73], v[150:153], v[218:221], v[70:73]
	v_mfma_f32_16x16x32_bf16 v[66:69], v[158:161], v[218:221], v[66:69]
	s_barrier
	s_setprio 0
	s_add_i32 s63, s24, s86
	v_lshl_add_u64 v[186:187], s[78:79], 0, v[172:173]
	s_mov_b32 m0, s63
	ds_read_b128 v[162:165], v192 offset:16384
	ds_read_b128 v[166:169], v192 offset:17408
	ds_read_b128 v[194:197], v192 offset:18432
	ds_read_b128 v[198:201], v192 offset:19456
	ds_read_b128 v[206:209], v192 offset:20480
	ds_read_b128 v[210:213], v192 offset:21504
	ds_read_b128 v[214:217], v192 offset:22528
	ds_read_b128 v[218:221], v192 offset:23552
	global_load_lds_dwordx4 v[186:187], off
	s_add_i32 m0, s63, 0x2000
	s_add_u32 vcc_lo, s78, 0x40000
	v_lshl_add_u64 v[202:203], s[78:79], 0, v[176:177]
	s_addc_u32 vcc_hi, s79, 0
	s_add_i32 s63, s25, s86
	global_load_lds_dwordx4 v[202:203], off
	v_lshl_add_u64 v[222:223], vcc, 0, v[172:173]
	s_mov_b32 m0, s63
	v_lshl_add_u64 v[224:225], s[80:81], 0, v[174:175]
	global_load_lds_dwordx4 v[222:223], off
	v_lshl_add_u64 v[222:223], vcc, 0, v[176:177]
	s_add_i32 m0, s63, 0x2000
	s_nop 0
	global_load_lds_dwordx4 v[222:223], off
	v_lshl_add_u64 v[222:223], s[80:81], 0, v[170:171]
	s_mov_b32 m0, s87
	s_nop 0
	global_load_lds_dwordx4 v[222:223], off
	s_mov_b32 m0, s88
	s_nop 0
	global_load_lds_dwordx4 v[224:225], off
	s_waitcnt vmcnt(8)
	s_waitcnt lgkmcnt(0)
	s_setprio 1
	s_barrier
	v_mfma_f32_16x16x32_bf16 v[62:65], v[114:117], v[162:165], v[62:65]
	v_mfma_f32_16x16x32_bf16 v[58:61], v[122:125], v[162:165], v[58:61]
	v_mfma_f32_16x16x32_bf16 v[50:53], v[114:117], v[194:197], v[50:53]
	v_mfma_f32_16x16x32_bf16 v[42:45], v[122:125], v[194:197], v[42:45]
	v_mfma_f32_16x16x32_bf16 v[34:37], v[114:117], v[206:209], v[34:37]
	v_mfma_f32_16x16x32_bf16 v[26:29], v[122:125], v[206:209], v[26:29]
	v_mfma_f32_16x16x32_bf16 v[18:21], v[114:117], v[214:217], v[18:21]
	v_mfma_f32_16x16x32_bf16 v[10:13], v[122:125], v[214:217], v[10:13]
	v_mfma_f32_16x16x32_bf16 v[62:65], v[118:121], v[166:169], v[62:65]
	v_mfma_f32_16x16x32_bf16 v[58:61], v[126:129], v[166:169], v[58:61]
	v_mfma_f32_16x16x32_bf16 v[50:53], v[118:121], v[198:201], v[50:53]
	v_mfma_f32_16x16x32_bf16 v[42:45], v[126:129], v[198:201], v[42:45]
	v_mfma_f32_16x16x32_bf16 v[34:37], v[118:121], v[210:213], v[34:37]
	v_mfma_f32_16x16x32_bf16 v[26:29], v[126:129], v[210:213], v[26:29]
	v_mfma_f32_16x16x32_bf16 v[18:21], v[118:121], v[218:221], v[18:21]
	v_mfma_f32_16x16x32_bf16 v[10:13], v[126:129], v[218:221], v[10:13]
	v_mfma_f32_16x16x32_bf16 v[54:57], v[146:149], v[162:165], v[54:57]
	v_mfma_f32_16x16x32_bf16 v[46:49], v[154:157], v[162:165], v[46:49]
	v_mfma_f32_16x16x32_bf16 v[38:41], v[146:149], v[194:197], v[38:41]
	v_mfma_f32_16x16x32_bf16 v[30:33], v[154:157], v[194:197], v[30:33]
	v_mfma_f32_16x16x32_bf16 v[22:25], v[146:149], v[206:209], v[22:25]
	v_mfma_f32_16x16x32_bf16 v[14:17], v[154:157], v[206:209], v[14:17]
	v_mfma_f32_16x16x32_bf16 v[6:9], v[146:149], v[214:217], v[6:9]
	v_mfma_f32_16x16x32_bf16 v[2:5], v[154:157], v[214:217], v[2:5]
	v_mfma_f32_16x16x32_bf16 v[54:57], v[150:153], v[166:169], v[54:57]
	v_mfma_f32_16x16x32_bf16 v[46:49], v[158:161], v[166:169], v[46:49]
	v_mfma_f32_16x16x32_bf16 v[38:41], v[150:153], v[198:201], v[38:41]
	v_mfma_f32_16x16x32_bf16 v[30:33], v[158:161], v[198:201], v[30:33]
	v_mfma_f32_16x16x32_bf16 v[22:25], v[150:153], v[210:213], v[22:25]
	v_mfma_f32_16x16x32_bf16 v[14:17], v[158:161], v[210:213], v[14:17]
	v_mfma_f32_16x16x32_bf16 v[6:9], v[150:153], v[218:221], v[6:9]
	v_mfma_f32_16x16x32_bf16 v[2:5], v[158:161], v[218:221], v[2:5]
	s_barrier
	s_setprio 0
	s_add_i32 s63, 0, 0x18000
	s_add_i32 s83, 0, 0x1c000
	v_add_u32_e32 v126, s63, v189
	v_add_u32_e32 v158, s83, v189
	ds_read_b128 v[114:117], v126
	ds_read_b128 v[118:121], v126 offset:1024
	ds_read_b128 v[122:125], v126 offset:2048
	ds_read_b128 v[126:129], v126 offset:3072
	ds_read_b128 v[146:149], v158
	ds_read_b128 v[150:153], v158 offset:1024
	ds_read_b128 v[154:157], v158 offset:2048
	ds_read_b128 v[158:161], v158 offset:3072
	s_add_u32 s80, s80, 0x40000
	s_addc_u32 s81, s81, 0
	s_mov_b32 m0, s89
	v_lshl_add_u64 v[226:227], s[80:81], 0, v[170:171]
	ds_read_b128 v[162:165], v192 offset:32768
	ds_read_b128 v[166:169], v192 offset:33792
	ds_read_b128 v[194:197], v192 offset:34816
	ds_read_b128 v[198:201], v192 offset:35840
	ds_read_b128 v[206:209], v192 offset:36864
	ds_read_b128 v[210:213], v192 offset:37888
	ds_read_b128 v[214:217], v192 offset:38912
	ds_read_b128 v[218:221], v192 offset:39936
	global_load_lds_dwordx4 v[226:227], off
	v_lshl_add_u64 v[226:227], s[80:81], 0, v[174:175]
	s_mov_b32 m0, s90
	s_nop 0
	global_load_lds_dwordx4 v[226:227], off
	s_waitcnt vmcnt(8)
	s_waitcnt lgkmcnt(0)
	s_setprio 1
	s_barrier
	v_mfma_f32_16x16x32_bf16 v[142:145], v[114:117], v[162:165], v[142:145]
	v_mfma_f32_16x16x32_bf16 v[138:141], v[122:125], v[162:165], v[138:141]
	v_mfma_f32_16x16x32_bf16 v[110:113], v[114:117], v[194:197], v[110:113]
	v_mfma_f32_16x16x32_bf16 v[106:109], v[122:125], v[194:197], v[106:109]
	v_mfma_f32_16x16x32_bf16 v[98:101], v[114:117], v[206:209], v[98:101]
	v_mfma_f32_16x16x32_bf16 v[90:93], v[122:125], v[206:209], v[90:93]
	v_mfma_f32_16x16x32_bf16 v[82:85], v[114:117], v[214:217], v[82:85]
	v_mfma_f32_16x16x32_bf16 v[74:77], v[122:125], v[214:217], v[74:77]
	v_mfma_f32_16x16x32_bf16 v[142:145], v[118:121], v[166:169], v[142:145]
	v_mfma_f32_16x16x32_bf16 v[138:141], v[126:129], v[166:169], v[138:141]
	v_mfma_f32_16x16x32_bf16 v[110:113], v[118:121], v[198:201], v[110:113]
	v_mfma_f32_16x16x32_bf16 v[106:109], v[126:129], v[198:201], v[106:109]
	v_mfma_f32_16x16x32_bf16 v[98:101], v[118:121], v[210:213], v[98:101]
	v_mfma_f32_16x16x32_bf16 v[90:93], v[126:129], v[210:213], v[90:93]
	v_mfma_f32_16x16x32_bf16 v[82:85], v[118:121], v[218:221], v[82:85]
	v_mfma_f32_16x16x32_bf16 v[74:77], v[126:129], v[218:221], v[74:77]
	v_mfma_f32_16x16x32_bf16 v[134:137], v[146:149], v[162:165], v[134:137]
	v_mfma_f32_16x16x32_bf16 v[130:133], v[154:157], v[162:165], v[130:133]
	v_mfma_f32_16x16x32_bf16 v[102:105], v[146:149], v[194:197], v[102:105]
	v_mfma_f32_16x16x32_bf16 v[94:97], v[154:157], v[194:197], v[94:97]
	v_mfma_f32_16x16x32_bf16 v[86:89], v[146:149], v[206:209], v[86:89]
	v_mfma_f32_16x16x32_bf16 v[78:81], v[154:157], v[206:209], v[78:81]
	v_mfma_f32_16x16x32_bf16 v[70:73], v[146:149], v[214:217], v[70:73]
	v_mfma_f32_16x16x32_bf16 v[66:69], v[154:157], v[214:217], v[66:69]
	v_mfma_f32_16x16x32_bf16 v[134:137], v[150:153], v[166:169], v[134:137]
	v_mfma_f32_16x16x32_bf16 v[130:133], v[158:161], v[166:169], v[130:133]
	v_mfma_f32_16x16x32_bf16 v[102:105], v[150:153], v[198:201], v[102:105]
	v_mfma_f32_16x16x32_bf16 v[94:97], v[158:161], v[198:201], v[94:97]
	v_mfma_f32_16x16x32_bf16 v[86:89], v[150:153], v[210:213], v[86:89]
	v_mfma_f32_16x16x32_bf16 v[78:81], v[158:161], v[210:213], v[78:81]
	v_mfma_f32_16x16x32_bf16 v[70:73], v[150:153], v[218:221], v[70:73]
	v_mfma_f32_16x16x32_bf16 v[66:69], v[158:161], v[218:221], v[66:69]
	s_barrier
	s_setprio 0
	s_add_i32 s63, s63, s86
	v_lshl_add_u64 v[186:187], v[186:187], 0, s[22:23]
	s_mov_b32 m0, s63
	ds_read_b128 v[162:165], v192 offset:49152
	ds_read_b128 v[166:169], v192 offset:50176
	ds_read_b128 v[194:197], v192 offset:51200
	ds_read_b128 v[198:201], v192 offset:52224
	ds_read_b128 v[206:209], v192 offset:53248
	ds_read_b128 v[210:213], v192 offset:54272
	ds_read_b128 v[214:217], v192 offset:55296
	ds_read_b128 v[218:221], v192 offset:56320
	global_load_lds_dwordx4 v[186:187], off
	s_add_i32 m0, s63, 0x2000
	s_add_u32 s78, s78, 0x40080
	v_lshl_add_u64 v[186:187], v[202:203], 0, s[22:23]
	s_addc_u32 s79, s79, 0
	s_add_i32 s63, s83, s86
	global_load_lds_dwordx4 v[186:187], off
	v_lshl_add_u64 v[186:187], s[78:79], 0, v[172:173]
	s_mov_b32 m0, s63
	s_nop 0
	global_load_lds_dwordx4 v[186:187], off
	v_lshl_add_u64 v[186:187], s[78:79], 0, v[176:177]
	s_add_i32 m0, s63, 0x2000
	s_nop 0
	global_load_lds_dwordx4 v[186:187], off
	v_lshl_add_u64 v[186:187], v[222:223], 0, s[22:23]
	s_mov_b32 m0, s95
	s_nop 0
	global_load_lds_dwordx4 v[186:187], off
	v_lshl_add_u64 v[186:187], v[224:225], 0, s[22:23]
	s_mov_b32 m0, s96
	s_nop 0
	global_load_lds_dwordx4 v[186:187], off
	s_waitcnt vmcnt(8)
	s_waitcnt lgkmcnt(0)
	s_setprio 1
	s_barrier
	v_mfma_f32_16x16x32_bf16 v[62:65], v[114:117], v[162:165], v[62:65]
	v_mfma_f32_16x16x32_bf16 v[58:61], v[122:125], v[162:165], v[58:61]
	v_mfma_f32_16x16x32_bf16 v[50:53], v[114:117], v[194:197], v[50:53]
	v_mfma_f32_16x16x32_bf16 v[42:45], v[122:125], v[194:197], v[42:45]
	v_mfma_f32_16x16x32_bf16 v[34:37], v[114:117], v[206:209], v[34:37]
	v_mfma_f32_16x16x32_bf16 v[26:29], v[122:125], v[206:209], v[26:29]
	v_mfma_f32_16x16x32_bf16 v[18:21], v[114:117], v[214:217], v[18:21]
	v_mfma_f32_16x16x32_bf16 v[10:13], v[122:125], v[214:217], v[10:13]
	v_mfma_f32_16x16x32_bf16 v[62:65], v[118:121], v[166:169], v[62:65]
	v_mfma_f32_16x16x32_bf16 v[58:61], v[126:129], v[166:169], v[58:61]
	v_mfma_f32_16x16x32_bf16 v[50:53], v[118:121], v[198:201], v[50:53]
	v_mfma_f32_16x16x32_bf16 v[42:45], v[126:129], v[198:201], v[42:45]
	v_mfma_f32_16x16x32_bf16 v[34:37], v[118:121], v[210:213], v[34:37]
	v_mfma_f32_16x16x32_bf16 v[26:29], v[126:129], v[210:213], v[26:29]
	v_mfma_f32_16x16x32_bf16 v[18:21], v[118:121], v[218:221], v[18:21]
	v_mfma_f32_16x16x32_bf16 v[10:13], v[126:129], v[218:221], v[10:13]
	v_mfma_f32_16x16x32_bf16 v[54:57], v[146:149], v[162:165], v[54:57]
	v_mfma_f32_16x16x32_bf16 v[46:49], v[154:157], v[162:165], v[46:49]
	v_mfma_f32_16x16x32_bf16 v[38:41], v[146:149], v[194:197], v[38:41]
	v_mfma_f32_16x16x32_bf16 v[30:33], v[154:157], v[194:197], v[30:33]
	v_mfma_f32_16x16x32_bf16 v[22:25], v[146:149], v[206:209], v[22:25]
	v_mfma_f32_16x16x32_bf16 v[14:17], v[154:157], v[206:209], v[14:17]
	v_mfma_f32_16x16x32_bf16 v[6:9], v[146:149], v[214:217], v[6:9]
	v_mfma_f32_16x16x32_bf16 v[2:5], v[154:157], v[214:217], v[2:5]
	v_mfma_f32_16x16x32_bf16 v[54:57], v[150:153], v[166:169], v[54:57]
	v_mfma_f32_16x16x32_bf16 v[46:49], v[158:161], v[166:169], v[46:49]
	v_mfma_f32_16x16x32_bf16 v[38:41], v[150:153], v[198:201], v[38:41]
	v_mfma_f32_16x16x32_bf16 v[30:33], v[158:161], v[198:201], v[30:33]
	v_mfma_f32_16x16x32_bf16 v[22:25], v[150:153], v[210:213], v[22:25]
	v_mfma_f32_16x16x32_bf16 v[14:17], v[158:161], v[210:213], v[14:17]
	v_mfma_f32_16x16x32_bf16 v[6:9], v[150:153], v[218:221], v[6:9]
	v_mfma_f32_16x16x32_bf16 v[2:5], v[158:161], v[218:221], v[2:5]
	s_barrier
	s_setprio 0
	s_add_u32 s76, s76, 0x100
	s_addc_u32 s77, s77, 0
	s_add_u32 s47, s47, 0x100
	s_addc_u32 s62, s62, 0
	s_cmp_ge_i32 s82, s7
	s_mov_b32 s63, s82
	s_cbranch_scc0 .LBB0_566
	s_and_b64 vcc, exec, s[26:27]
	s_cbranch_vccz .LBB0_569
	s_barrier

.LBB0_744:
	s_add_u32 s36, s96, s22
	s_addc_u32 s37, s97, s23
	s_and_b64 s[14:15], s[4:5], exec
	s_cselect_b32 s14, s37, s43
	s_cselect_b32 s15, s36, s42
	s_add_u32 s38, s2, s26
	s_addc_u32 s39, s3, s27
	s_and_b64 s[46:47], s[4:5], exec
	s_cselect_b32 s21, s39, s45
	s_cselect_b32 s65, s38, s44
	s_add_u32 s42, s42, 0x40080
	s_addc_u32 s43, s43, 0
	s_add_u32 s66, s44, 0x100
	s_addc_u32 s67, s45, 0
	s_mov_b32 s68, -2
	ds_read_b128 v[154:157], v150
	ds_read_b128 v[158:161], v150 offset:1024
	ds_read_b128 v[162:165], v150 offset:2048
	ds_read_b128 v[166:169], v150 offset:3072
	ds_read_b128 v[170:173], v151
	ds_read_b128 v[174:177], v151 offset:1024
	ds_read_b128 v[178:181], v151 offset:2048
	ds_read_b128 v[182:185], v151 offset:3072
	s_add_u32 s44, s42, 0xfffc0080
	s_addc_u32 s45, s43, -1
	s_cmp_eq_u32 s68, 12
	s_cselect_b32 s47, s14, s45
	s_cselect_b32 s46, s15, s44
	s_cselect_b32 s45, s21, s67
	s_cselect_b32 s44, s65, s66
	v_lshl_add_u64 v[146:147], s[42:43], 0, v[138:139]
	s_add_i32 m0, s19, 0xc000
	ds_read_b128 v[186:189], v152
	ds_read_b128 v[190:193], v152 offset:1024
	ds_read_b128 v[194:197], v152 offset:2048
	ds_read_b128 v[198:201], v152 offset:3072
	ds_read_b128 v[206:209], v152 offset:4096
	ds_read_b128 v[210:213], v152 offset:5120
	ds_read_b128 v[214:217], v152 offset:6144
	ds_read_b128 v[218:221], v152 offset:7168
	global_load_lds_dwordx4 v[146:147], off
	v_lshl_add_u64 v[146:147], s[42:43], 0, v[140:141]
	s_add_i32 m0, s19, 0xe000
	s_nop 0
	global_load_lds_dwordx4 v[146:147], off
	s_waitcnt vmcnt(8)
	s_waitcnt lgkmcnt(0)
	s_setprio 1
	s_barrier
	v_mfma_f32_16x16x32_bf16 v[126:129], v[154:157], v[186:189], 0
	v_mfma_f32_16x16x32_bf16 v[122:125], v[162:165], v[186:189], 0
	v_mfma_f32_16x16x32_bf16 v[110:113], v[154:157], v[194:197], 0
	v_mfma_f32_16x16x32_bf16 v[106:109], v[162:165], v[194:197], 0
	v_mfma_f32_16x16x32_bf16 v[94:97], v[154:157], v[206:209], 0
	v_mfma_f32_16x16x32_bf16 v[90:93], v[162:165], v[206:209], 0
	v_mfma_f32_16x16x32_bf16 v[78:81], v[154:157], v[214:217], 0
	v_mfma_f32_16x16x32_bf16 v[74:77], v[162:165], v[214:217], 0
	v_mfma_f32_16x16x32_bf16 v[126:129], v[158:161], v[190:193], v[126:129]
	v_mfma_f32_16x16x32_bf16 v[122:125], v[166:169], v[190:193], v[122:125]
	v_mfma_f32_16x16x32_bf16 v[110:113], v[158:161], v[198:201], v[110:113]
	v_mfma_f32_16x16x32_bf16 v[106:109], v[166:169], v[198:201], v[106:109]
	v_mfma_f32_16x16x32_bf16 v[94:97], v[158:161], v[210:213], v[94:97]
	v_mfma_f32_16x16x32_bf16 v[90:93], v[166:169], v[210:213], v[90:93]
	v_mfma_f32_16x16x32_bf16 v[78:81], v[158:161], v[218:221], v[78:81]
	v_mfma_f32_16x16x32_bf16 v[74:77], v[166:169], v[218:221], v[74:77]
	v_mfma_f32_16x16x32_bf16 v[118:121], v[170:173], v[186:189], 0
	v_mfma_f32_16x16x32_bf16 v[114:117], v[178:181], v[186:189], 0
	v_mfma_f32_16x16x32_bf16 v[102:105], v[170:173], v[194:197], 0
	v_mfma_f32_16x16x32_bf16 v[98:101], v[178:181], v[194:197], 0
	v_mfma_f32_16x16x32_bf16 v[86:89], v[170:173], v[206:209], 0
	v_mfma_f32_16x16x32_bf16 v[82:85], v[178:181], v[206:209], 0
	v_mfma_f32_16x16x32_bf16 v[70:73], v[170:173], v[214:217], 0
	v_mfma_f32_16x16x32_bf16 v[66:69], v[178:181], v[214:217], 0
	v_mfma_f32_16x16x32_bf16 v[118:121], v[174:177], v[190:193], v[118:121]
	v_mfma_f32_16x16x32_bf16 v[114:117], v[182:185], v[190:193], v[114:117]
	v_mfma_f32_16x16x32_bf16 v[102:105], v[174:177], v[198:201], v[102:105]
	v_mfma_f32_16x16x32_bf16 v[98:101], v[182:185], v[198:201], v[98:101]
	v_mfma_f32_16x16x32_bf16 v[86:89], v[174:177], v[210:213], v[86:89]
	v_mfma_f32_16x16x32_bf16 v[82:85], v[182:185], v[210:213], v[82:85]
	v_mfma_f32_16x16x32_bf16 v[70:73], v[174:177], v[218:221], v[70:73]
	v_mfma_f32_16x16x32_bf16 v[66:69], v[182:185], v[218:221], v[66:69]
	s_barrier
	s_setprio 0
	s_add_i32 s69, s49, s16
	v_lshl_add_u64 v[146:147], s[44:45], 0, v[134:135]
	s_mov_b32 m0, s69
	ds_read_b128 v[186:189], v152 offset:16384
	ds_read_b128 v[190:193], v152 offset:17408
	ds_read_b128 v[194:197], v152 offset:18432
	ds_read_b128 v[198:201], v152 offset:19456
	ds_read_b128 v[206:209], v152 offset:20480
	ds_read_b128 v[210:213], v152 offset:21504
	ds_read_b128 v[214:217], v152 offset:22528
	ds_read_b128 v[218:221], v152 offset:23552
	global_load_lds_dwordx4 v[146:147], off
	s_add_i32 m0, s69, 0x2000
	s_add_u32 s70, s44, 0x40000
	v_lshl_add_u64 v[202:203], s[44:45], 0, v[130:131]
	s_addc_u32 s71, s45, 0
	s_add_i32 s69, s62, s16
	global_load_lds_dwordx4 v[202:203], off
	v_lshl_add_u64 v[222:223], s[70:71], 0, v[134:135]
	s_mov_b32 m0, s69
	v_lshl_add_u64 v[224:225], s[46:47], 0, v[132:133]
	global_load_lds_dwordx4 v[222:223], off
	v_lshl_add_u64 v[222:223], s[70:71], 0, v[130:131]
	s_add_i32 m0, s69, 0x2000
	s_nop 0
	global_load_lds_dwordx4 v[222:223], off
	v_lshl_add_u64 v[222:223], s[46:47], 0, v[136:137]
	s_mov_b32 m0, s19
	s_nop 0
	global_load_lds_dwordx4 v[222:223], off
	s_mov_b32 m0, s24
	s_nop 0
	global_load_lds_dwordx4 v[224:225], off
	s_waitcnt vmcnt(8)
	s_waitcnt lgkmcnt(0)
	s_setprio 1
	s_barrier
	v_mfma_f32_16x16x32_bf16 v[62:65], v[154:157], v[186:189], 0
	v_mfma_f32_16x16x32_bf16 v[58:61], v[162:165], v[186:189], 0
	v_mfma_f32_16x16x32_bf16 v[46:49], v[154:157], v[194:197], 0
	v_mfma_f32_16x16x32_bf16 v[42:45], v[162:165], v[194:197], 0
	v_mfma_f32_16x16x32_bf16 v[30:33], v[154:157], v[206:209], 0
	v_mfma_f32_16x16x32_bf16 v[26:29], v[162:165], v[206:209], 0
	v_mfma_f32_16x16x32_bf16 v[14:17], v[154:157], v[214:217], 0
	v_mfma_f32_16x16x32_bf16 v[10:13], v[162:165], v[214:217], 0
	v_mfma_f32_16x16x32_bf16 v[62:65], v[158:161], v[190:193], v[62:65]
	v_mfma_f32_16x16x32_bf16 v[58:61], v[166:169], v[190:193], v[58:61]
	v_mfma_f32_16x16x32_bf16 v[46:49], v[158:161], v[198:201], v[46:49]
	v_mfma_f32_16x16x32_bf16 v[42:45], v[166:169], v[198:201], v[42:45]
	v_mfma_f32_16x16x32_bf16 v[30:33], v[158:161], v[210:213], v[30:33]
	v_mfma_f32_16x16x32_bf16 v[26:29], v[166:169], v[210:213], v[26:29]
	v_mfma_f32_16x16x32_bf16 v[14:17], v[158:161], v[218:221], v[14:17]
	v_mfma_f32_16x16x32_bf16 v[10:13], v[166:169], v[218:221], v[10:13]
	v_mfma_f32_16x16x32_bf16 v[54:57], v[170:173], v[186:189], 0
	v_mfma_f32_16x16x32_bf16 v[50:53], v[178:181], v[186:189], 0
	v_mfma_f32_16x16x32_bf16 v[38:41], v[170:173], v[194:197], 0
	v_mfma_f32_16x16x32_bf16 v[34:37], v[178:181], v[194:197], 0
	v_mfma_f32_16x16x32_bf16 v[22:25], v[170:173], v[206:209], 0
	v_mfma_f32_16x16x32_bf16 v[18:21], v[178:181], v[206:209], 0
	v_mfma_f32_16x16x32_bf16 v[6:9], v[170:173], v[214:217], 0
	v_mfma_f32_16x16x32_bf16 v[2:5], v[178:181], v[214:217], 0
	v_mfma_f32_16x16x32_bf16 v[54:57], v[174:177], v[190:193], v[54:57]
	v_mfma_f32_16x16x32_bf16 v[50:53], v[182:185], v[190:193], v[50:53]
	v_mfma_f32_16x16x32_bf16 v[38:41], v[174:177], v[198:201], v[38:41]
	v_mfma_f32_16x16x32_bf16 v[34:37], v[182:185], v[198:201], v[34:37]
	v_mfma_f32_16x16x32_bf16 v[22:25], v[174:177], v[210:213], v[22:25]
	v_mfma_f32_16x16x32_bf16 v[18:21], v[182:185], v[210:213], v[18:21]
	v_mfma_f32_16x16x32_bf16 v[6:9], v[174:177], v[218:221], v[6:9]
	v_mfma_f32_16x16x32_bf16 v[2:5], v[182:185], v[218:221], v[2:5]
	s_barrier
	s_setprio 0
	s_add_i32 s69, 0, 0x18000
	v_add_u32_e32 v153, s69, v149
	s_add_i32 s70, 0, 0x1c000
	ds_read_b128 v[154:157], v153
	ds_read_b128 v[158:161], v153 offset:1024
	ds_read_b128 v[162:165], v153 offset:2048
	ds_read_b128 v[166:169], v153 offset:3072
	v_add_u32_e32 v153, s70, v149
	ds_read_b128 v[170:173], v153
	ds_read_b128 v[174:177], v153 offset:1024
	ds_read_b128 v[178:181], v153 offset:2048
	ds_read_b128 v[182:185], v153 offset:3072
	s_add_u32 s46, s46, 0x40000
	s_addc_u32 s47, s47, 0
	s_mov_b32 m0, s25
	v_lshl_add_u64 v[226:227], s[46:47], 0, v[136:137]
	ds_read_b128 v[186:189], v152 offset:32768
	ds_read_b128 v[190:193], v152 offset:33792
	ds_read_b128 v[194:197], v152 offset:34816
	ds_read_b128 v[198:201], v152 offset:35840
	ds_read_b128 v[206:209], v152 offset:36864
	ds_read_b128 v[210:213], v152 offset:37888
	ds_read_b128 v[214:217], v152 offset:38912
	ds_read_b128 v[218:221], v152 offset:39936
	global_load_lds_dwordx4 v[226:227], off
	v_lshl_add_u64 v[226:227], s[46:47], 0, v[132:133]
	s_mov_b32 m0, s28
	s_nop 0
	global_load_lds_dwordx4 v[226:227], off
	s_waitcnt vmcnt(8)
	s_waitcnt lgkmcnt(0)
	s_setprio 1
	s_barrier
	v_mfma_f32_16x16x32_bf16 v[126:129], v[154:157], v[186:189], v[126:129]
	v_mfma_f32_16x16x32_bf16 v[122:125], v[162:165], v[186:189], v[122:125]
	v_mfma_f32_16x16x32_bf16 v[110:113], v[154:157], v[194:197], v[110:113]
	v_mfma_f32_16x16x32_bf16 v[106:109], v[162:165], v[194:197], v[106:109]
	v_mfma_f32_16x16x32_bf16 v[94:97], v[154:157], v[206:209], v[94:97]
	v_mfma_f32_16x16x32_bf16 v[90:93], v[162:165], v[206:209], v[90:93]
	v_mfma_f32_16x16x32_bf16 v[78:81], v[154:157], v[214:217], v[78:81]
	v_mfma_f32_16x16x32_bf16 v[74:77], v[162:165], v[214:217], v[74:77]
	v_mfma_f32_16x16x32_bf16 v[126:129], v[158:161], v[190:193], v[126:129]
	v_mfma_f32_16x16x32_bf16 v[122:125], v[166:169], v[190:193], v[122:125]
	v_mfma_f32_16x16x32_bf16 v[110:113], v[158:161], v[198:201], v[110:113]
	v_mfma_f32_16x16x32_bf16 v[106:109], v[166:169], v[198:201], v[106:109]
	v_mfma_f32_16x16x32_bf16 v[94:97], v[158:161], v[210:213], v[94:97]
	v_mfma_f32_16x16x32_bf16 v[90:93], v[166:169], v[210:213], v[90:93]
	v_mfma_f32_16x16x32_bf16 v[78:81], v[158:161], v[218:221], v[78:81]
	v_mfma_f32_16x16x32_bf16 v[74:77], v[166:169], v[218:221], v[74:77]
	v_mfma_f32_16x16x32_bf16 v[118:121], v[170:173], v[186:189], v[118:121]
	v_mfma_f32_16x16x32_bf16 v[114:117], v[178:181], v[186:189], v[114:117]
	v_mfma_f32_16x16x32_bf16 v[102:105], v[170:173], v[194:197], v[102:105]
	v_mfma_f32_16x16x32_bf16 v[98:101], v[178:181], v[194:197], v[98:101]
	v_mfma_f32_16x16x32_bf16 v[86:89], v[170:173], v[206:209], v[86:89]
	v_mfma_f32_16x16x32_bf16 v[82:85], v[178:181], v[206:209], v[82:85]
	v_mfma_f32_16x16x32_bf16 v[70:73], v[170:173], v[214:217], v[70:73]
	v_mfma_f32_16x16x32_bf16 v[66:69], v[178:181], v[214:217], v[66:69]
	v_mfma_f32_16x16x32_bf16 v[118:121], v[174:177], v[190:193], v[118:121]
	v_mfma_f32_16x16x32_bf16 v[114:117], v[182:185], v[190:193], v[114:117]
	v_mfma_f32_16x16x32_bf16 v[102:105], v[174:177], v[198:201], v[102:105]
	v_mfma_f32_16x16x32_bf16 v[98:101], v[182:185], v[198:201], v[98:101]
	v_mfma_f32_16x16x32_bf16 v[86:89], v[174:177], v[210:213], v[86:89]
	v_mfma_f32_16x16x32_bf16 v[82:85], v[182:185], v[210:213], v[82:85]
	v_mfma_f32_16x16x32_bf16 v[70:73], v[174:177], v[218:221], v[70:73]
	v_mfma_f32_16x16x32_bf16 v[66:69], v[182:185], v[218:221], v[66:69]
	s_barrier
	s_setprio 0
	s_add_i32 s46, s69, s16
	v_lshl_add_u64 v[146:147], v[146:147], 0, s[10:11]
	s_mov_b32 m0, s46
	ds_read_b128 v[186:189], v152 offset:49152
	ds_read_b128 v[190:193], v152 offset:50176
	ds_read_b128 v[194:197], v152 offset:51200
	ds_read_b128 v[198:201], v152 offset:52224
	ds_read_b128 v[206:209], v152 offset:53248
	ds_read_b128 v[210:213], v152 offset:54272
	ds_read_b128 v[214:217], v152 offset:55296
	ds_read_b128 v[218:221], v152 offset:56320
	global_load_lds_dwordx4 v[146:147], off
	s_add_i32 m0, s46, 0x2000
	s_add_u32 s44, s44, 0x40080
	v_lshl_add_u64 v[146:147], v[202:203], 0, s[10:11]
	s_addc_u32 s45, s45, 0
	s_add_i32 s46, s70, s16
	global_load_lds_dwordx4 v[146:147], off
	v_lshl_add_u64 v[146:147], s[44:45], 0, v[134:135]
	s_mov_b32 m0, s46
	s_nop 0
	global_load_lds_dwordx4 v[146:147], off
	v_lshl_add_u64 v[146:147], s[44:45], 0, v[130:131]
	s_add_i32 m0, s46, 0x2000
	s_nop 0
	global_load_lds_dwordx4 v[146:147], off
	v_lshl_add_u64 v[146:147], v[222:223], 0, s[10:11]
	s_mov_b32 m0, s33
	s_nop 0
	global_load_lds_dwordx4 v[146:147], off
	v_lshl_add_u64 v[146:147], v[224:225], 0, s[10:11]
	s_mov_b32 m0, s35
	s_nop 0
	global_load_lds_dwordx4 v[146:147], off
	s_waitcnt vmcnt(8)
	s_waitcnt lgkmcnt(0)
	s_setprio 1
	s_barrier
	v_mfma_f32_16x16x32_bf16 v[62:65], v[154:157], v[186:189], v[62:65]
	v_mfma_f32_16x16x32_bf16 v[58:61], v[162:165], v[186:189], v[58:61]
	v_mfma_f32_16x16x32_bf16 v[46:49], v[154:157], v[194:197], v[46:49]
	v_mfma_f32_16x16x32_bf16 v[42:45], v[162:165], v[194:197], v[42:45]
	v_mfma_f32_16x16x32_bf16 v[30:33], v[154:157], v[206:209], v[30:33]
	v_mfma_f32_16x16x32_bf16 v[26:29], v[162:165], v[206:209], v[26:29]
	v_mfma_f32_16x16x32_bf16 v[14:17], v[154:157], v[214:217], v[14:17]
	v_mfma_f32_16x16x32_bf16 v[10:13], v[162:165], v[214:217], v[10:13]
	v_mfma_f32_16x16x32_bf16 v[62:65], v[158:161], v[190:193], v[62:65]
	v_mfma_f32_16x16x32_bf16 v[58:61], v[166:169], v[190:193], v[58:61]
	v_mfma_f32_16x16x32_bf16 v[46:49], v[158:161], v[198:201], v[46:49]
	v_mfma_f32_16x16x32_bf16 v[42:45], v[166:169], v[198:201], v[42:45]
	v_mfma_f32_16x16x32_bf16 v[30:33], v[158:161], v[210:213], v[30:33]
	v_mfma_f32_16x16x32_bf16 v[26:29], v[166:169], v[210:213], v[26:29]
	v_mfma_f32_16x16x32_bf16 v[14:17], v[158:161], v[218:221], v[14:17]
	v_mfma_f32_16x16x32_bf16 v[10:13], v[166:169], v[218:221], v[10:13]
	v_mfma_f32_16x16x32_bf16 v[54:57], v[170:173], v[186:189], v[54:57]
	v_mfma_f32_16x16x32_bf16 v[50:53], v[178:181], v[186:189], v[50:53]
	v_mfma_f32_16x16x32_bf16 v[38:41], v[170:173], v[194:197], v[38:41]
	v_mfma_f32_16x16x32_bf16 v[34:37], v[178:181], v[194:197], v[34:37]
	v_mfma_f32_16x16x32_bf16 v[22:25], v[170:173], v[206:209], v[22:25]
	v_mfma_f32_16x16x32_bf16 v[18:21], v[178:181], v[206:209], v[18:21]
	v_mfma_f32_16x16x32_bf16 v[6:9], v[170:173], v[214:217], v[6:9]
	v_mfma_f32_16x16x32_bf16 v[2:5], v[178:181], v[214:217], v[2:5]
	v_mfma_f32_16x16x32_bf16 v[54:57], v[174:177], v[190:193], v[54:57]
	v_mfma_f32_16x16x32_bf16 v[50:53], v[182:185], v[190:193], v[50:53]
	v_mfma_f32_16x16x32_bf16 v[38:41], v[174:177], v[198:201], v[38:41]
	v_mfma_f32_16x16x32_bf16 v[34:37], v[182:185], v[198:201], v[34:37]
	v_mfma_f32_16x16x32_bf16 v[22:25], v[174:177], v[210:213], v[22:25]
	v_mfma_f32_16x16x32_bf16 v[18:21], v[182:185], v[210:213], v[18:21]
	v_mfma_f32_16x16x32_bf16 v[6:9], v[174:177], v[218:221], v[6:9]
	v_mfma_f32_16x16x32_bf16 v[2:5], v[182:185], v[218:221], v[2:5]
	s_barrier
	s_setprio 0
	s_add_i32 s68, s68, 2
	s_add_u32 s42, s42, 0x100
	s_addc_u32 s43, s43, 0
	s_add_u32 s66, s66, 0x100
	s_addc_u32 s67, s67, 0
	s_cmp_gt_u32 s68, 13
.LBB0_745:
	ds_read_b128 v[154:157], v150
	ds_read_b128 v[158:161], v150 offset:1024
	ds_read_b128 v[162:165], v150 offset:2048
	ds_read_b128 v[166:169], v150 offset:3072
	ds_read_b128 v[170:173], v151
	ds_read_b128 v[174:177], v151 offset:1024
	ds_read_b128 v[178:181], v151 offset:2048
	ds_read_b128 v[182:185], v151 offset:3072
	s_add_u32 s44, s42, 0xfffc0080
	s_addc_u32 s45, s43, -1
	s_cmp_eq_u32 s68, 12
	s_cselect_b32 s47, s14, s45
	s_cselect_b32 s46, s15, s44
	s_cselect_b32 s45, s21, s67
	s_cselect_b32 s44, s65, s66
	v_lshl_add_u64 v[146:147], s[42:43], 0, v[138:139]
	s_add_i32 m0, s19, 0xc000
	ds_read_b128 v[186:189], v152
	ds_read_b128 v[190:193], v152 offset:1024
	ds_read_b128 v[194:197], v152 offset:2048
	ds_read_b128 v[198:201], v152 offset:3072
	ds_read_b128 v[206:209], v152 offset:4096
	ds_read_b128 v[210:213], v152 offset:5120
	ds_read_b128 v[214:217], v152 offset:6144
	ds_read_b128 v[218:221], v152 offset:7168
	global_load_lds_dwordx4 v[146:147], off
	v_lshl_add_u64 v[146:147], s[42:43], 0, v[140:141]
	s_add_i32 m0, s19, 0xe000
	s_nop 0
	global_load_lds_dwordx4 v[146:147], off
	s_waitcnt vmcnt(8)
	s_waitcnt lgkmcnt(0)
	s_setprio 1
	s_barrier
	v_mfma_f32_16x16x32_bf16 v[126:129], v[154:157], v[186:189], v[126:129]
	v_mfma_f32_16x16x32_bf16 v[122:125], v[162:165], v[186:189], v[122:125]
	v_mfma_f32_16x16x32_bf16 v[110:113], v[154:157], v[194:197], v[110:113]
	v_mfma_f32_16x16x32_bf16 v[106:109], v[162:165], v[194:197], v[106:109]
	v_mfma_f32_16x16x32_bf16 v[94:97], v[154:157], v[206:209], v[94:97]
	v_mfma_f32_16x16x32_bf16 v[90:93], v[162:165], v[206:209], v[90:93]
	v_mfma_f32_16x16x32_bf16 v[78:81], v[154:157], v[214:217], v[78:81]
	v_mfma_f32_16x16x32_bf16 v[74:77], v[162:165], v[214:217], v[74:77]
	v_mfma_f32_16x16x32_bf16 v[126:129], v[158:161], v[190:193], v[126:129]
	v_mfma_f32_16x16x32_bf16 v[122:125], v[166:169], v[190:193], v[122:125]
	v_mfma_f32_16x16x32_bf16 v[110:113], v[158:161], v[198:201], v[110:113]
	v_mfma_f32_16x16x32_bf16 v[106:109], v[166:169], v[198:201], v[106:109]
	v_mfma_f32_16x16x32_bf16 v[94:97], v[158:161], v[210:213], v[94:97]
	v_mfma_f32_16x16x32_bf16 v[90:93], v[166:169], v[210:213], v[90:93]
	v_mfma_f32_16x16x32_bf16 v[78:81], v[158:161], v[218:221], v[78:81]
	v_mfma_f32_16x16x32_bf16 v[74:77], v[166:169], v[218:221], v[74:77]
	v_mfma_f32_16x16x32_bf16 v[118:121], v[170:173], v[186:189], v[118:121]
	v_mfma_f32_16x16x32_bf16 v[114:117], v[178:181], v[186:189], v[114:117]
	v_mfma_f32_16x16x32_bf16 v[102:105], v[170:173], v[194:197], v[102:105]
	v_mfma_f32_16x16x32_bf16 v[98:101], v[178:181], v[194:197], v[98:101]
	v_mfma_f32_16x16x32_bf16 v[86:89], v[170:173], v[206:209], v[86:89]
	v_mfma_f32_16x16x32_bf16 v[82:85], v[178:181], v[206:209], v[82:85]
	v_mfma_f32_16x16x32_bf16 v[70:73], v[170:173], v[214:217], v[70:73]
	v_mfma_f32_16x16x32_bf16 v[66:69], v[178:181], v[214:217], v[66:69]
	v_mfma_f32_16x16x32_bf16 v[118:121], v[174:177], v[190:193], v[118:121]
	v_mfma_f32_16x16x32_bf16 v[114:117], v[182:185], v[190:193], v[114:117]
	v_mfma_f32_16x16x32_bf16 v[102:105], v[174:177], v[198:201], v[102:105]
	v_mfma_f32_16x16x32_bf16 v[98:101], v[182:185], v[198:201], v[98:101]
	v_mfma_f32_16x16x32_bf16 v[86:89], v[174:177], v[210:213], v[86:89]
	v_mfma_f32_16x16x32_bf16 v[82:85], v[182:185], v[210:213], v[82:85]
	v_mfma_f32_16x16x32_bf16 v[70:73], v[174:177], v[218:221], v[70:73]
	v_mfma_f32_16x16x32_bf16 v[66:69], v[182:185], v[218:221], v[66:69]
	s_barrier
	s_setprio 0
	s_add_i32 s69, s49, s16
	v_lshl_add_u64 v[146:147], s[44:45], 0, v[134:135]
	s_mov_b32 m0, s69
	ds_read_b128 v[186:189], v152 offset:16384
	ds_read_b128 v[190:193], v152 offset:17408
	ds_read_b128 v[194:197], v152 offset:18432
	ds_read_b128 v[198:201], v152 offset:19456
	ds_read_b128 v[206:209], v152 offset:20480
	ds_read_b128 v[210:213], v152 offset:21504
	ds_read_b128 v[214:217], v152 offset:22528
	ds_read_b128 v[218:221], v152 offset:23552
	global_load_lds_dwordx4 v[146:147], off
	s_add_i32 m0, s69, 0x2000
	s_add_u32 s70, s44, 0x40000
	v_lshl_add_u64 v[202:203], s[44:45], 0, v[130:131]
	s_addc_u32 s71, s45, 0
	s_add_i32 s69, s62, s16
	global_load_lds_dwordx4 v[202:203], off
	v_lshl_add_u64 v[222:223], s[70:71], 0, v[134:135]
	s_mov_b32 m0, s69
	v_lshl_add_u64 v[224:225], s[46:47], 0, v[132:133]
	global_load_lds_dwordx4 v[222:223], off
	v_lshl_add_u64 v[222:223], s[70:71], 0, v[130:131]
	s_add_i32 m0, s69, 0x2000
	s_nop 0
	global_load_lds_dwordx4 v[222:223], off
	v_lshl_add_u64 v[222:223], s[46:47], 0, v[136:137]
	s_mov_b32 m0, s19
	s_nop 0
	global_load_lds_dwordx4 v[222:223], off
	s_mov_b32 m0, s24
	s_nop 0
	global_load_lds_dwordx4 v[224:225], off
	s_waitcnt vmcnt(8)
	s_waitcnt lgkmcnt(0)
	s_setprio 1
	s_barrier
	v_mfma_f32_16x16x32_bf16 v[62:65], v[154:157], v[186:189], v[62:65]
	v_mfma_f32_16x16x32_bf16 v[58:61], v[162:165], v[186:189], v[58:61]
	v_mfma_f32_16x16x32_bf16 v[46:49], v[154:157], v[194:197], v[46:49]
	v_mfma_f32_16x16x32_bf16 v[42:45], v[162:165], v[194:197], v[42:45]
	v_mfma_f32_16x16x32_bf16 v[30:33], v[154:157], v[206:209], v[30:33]
	v_mfma_f32_16x16x32_bf16 v[26:29], v[162:165], v[206:209], v[26:29]
	v_mfma_f32_16x16x32_bf16 v[14:17], v[154:157], v[214:217], v[14:17]
	v_mfma_f32_16x16x32_bf16 v[10:13], v[162:165], v[214:217], v[10:13]
	v_mfma_f32_16x16x32_bf16 v[62:65], v[158:161], v[190:193], v[62:65]
	v_mfma_f32_16x16x32_bf16 v[58:61], v[166:169], v[190:193], v[58:61]
	v_mfma_f32_16x16x32_bf16 v[46:49], v[158:161], v[198:201], v[46:49]
	v_mfma_f32_16x16x32_bf16 v[42:45], v[166:169], v[198:201], v[42:45]
	v_mfma_f32_16x16x32_bf16 v[30:33], v[158:161], v[210:213], v[30:33]
	v_mfma_f32_16x16x32_bf16 v[26:29], v[166:169], v[210:213], v[26:29]
	v_mfma_f32_16x16x32_bf16 v[14:17], v[158:161], v[218:221], v[14:17]
	v_mfma_f32_16x16x32_bf16 v[10:13], v[166:169], v[218:221], v[10:13]
	v_mfma_f32_16x16x32_bf16 v[54:57], v[170:173], v[186:189], v[54:57]
	v_mfma_f32_16x16x32_bf16 v[50:53], v[178:181], v[186:189], v[50:53]
	v_mfma_f32_16x16x32_bf16 v[38:41], v[170:173], v[194:197], v[38:41]
	v_mfma_f32_16x16x32_bf16 v[34:37], v[178:181], v[194:197], v[34:37]
	v_mfma_f32_16x16x32_bf16 v[22:25], v[170:173], v[206:209], v[22:25]
	v_mfma_f32_16x16x32_bf16 v[18:21], v[178:181], v[206:209], v[18:21]
	v_mfma_f32_16x16x32_bf16 v[6:9], v[170:173], v[214:217], v[6:9]
	v_mfma_f32_16x16x32_bf16 v[2:5], v[178:181], v[214:217], v[2:5]
	v_mfma_f32_16x16x32_bf16 v[54:57], v[174:177], v[190:193], v[54:57]
	v_mfma_f32_16x16x32_bf16 v[50:53], v[182:185], v[190:193], v[50:53]
	v_mfma_f32_16x16x32_bf16 v[38:41], v[174:177], v[198:201], v[38:41]
	v_mfma_f32_16x16x32_bf16 v[34:37], v[182:185], v[198:201], v[34:37]
	v_mfma_f32_16x16x32_bf16 v[22:25], v[174:177], v[210:213], v[22:25]
	v_mfma_f32_16x16x32_bf16 v[18:21], v[182:185], v[210:213], v[18:21]
	v_mfma_f32_16x16x32_bf16 v[6:9], v[174:177], v[218:221], v[6:9]
	v_mfma_f32_16x16x32_bf16 v[2:5], v[182:185], v[218:221], v[2:5]
	s_barrier
	s_setprio 0
	s_add_i32 s69, 0, 0x18000
	v_add_u32_e32 v153, s69, v149
	s_add_i32 s70, 0, 0x1c000
	ds_read_b128 v[154:157], v153
	ds_read_b128 v[158:161], v153 offset:1024
	ds_read_b128 v[162:165], v153 offset:2048
	ds_read_b128 v[166:169], v153 offset:3072
	v_add_u32_e32 v153, s70, v149
	ds_read_b128 v[170:173], v153
	ds_read_b128 v[174:177], v153 offset:1024
	ds_read_b128 v[178:181], v153 offset:2048
	ds_read_b128 v[182:185], v153 offset:3072
	s_add_u32 s46, s46, 0x40000
	s_addc_u32 s47, s47, 0
	s_mov_b32 m0, s25
	v_lshl_add_u64 v[226:227], s[46:47], 0, v[136:137]
	ds_read_b128 v[186:189], v152 offset:32768
	ds_read_b128 v[190:193], v152 offset:33792
	ds_read_b128 v[194:197], v152 offset:34816
	ds_read_b128 v[198:201], v152 offset:35840
	ds_read_b128 v[206:209], v152 offset:36864
	ds_read_b128 v[210:213], v152 offset:37888
	ds_read_b128 v[214:217], v152 offset:38912
	ds_read_b128 v[218:221], v152 offset:39936
	global_load_lds_dwordx4 v[226:227], off
	v_lshl_add_u64 v[226:227], s[46:47], 0, v[132:133]
	s_mov_b32 m0, s28
	s_nop 0
	global_load_lds_dwordx4 v[226:227], off
	s_waitcnt vmcnt(8)
	s_waitcnt lgkmcnt(0)
	s_setprio 1
	s_barrier
	v_mfma_f32_16x16x32_bf16 v[126:129], v[154:157], v[186:189], v[126:129]
	v_mfma_f32_16x16x32_bf16 v[122:125], v[162:165], v[186:189], v[122:125]
	v_mfma_f32_16x16x32_bf16 v[110:113], v[154:157], v[194:197], v[110:113]
	v_mfma_f32_16x16x32_bf16 v[106:109], v[162:165], v[194:197], v[106:109]
	v_mfma_f32_16x16x32_bf16 v[94:97], v[154:157], v[206:209], v[94:97]
	v_mfma_f32_16x16x32_bf16 v[90:93], v[162:165], v[206:209], v[90:93]
	v_mfma_f32_16x16x32_bf16 v[78:81], v[154:157], v[214:217], v[78:81]
	v_mfma_f32_16x16x32_bf16 v[74:77], v[162:165], v[214:217], v[74:77]
	v_mfma_f32_16x16x32_bf16 v[126:129], v[158:161], v[190:193], v[126:129]
	v_mfma_f32_16x16x32_bf16 v[122:125], v[166:169], v[190:193], v[122:125]
	v_mfma_f32_16x16x32_bf16 v[110:113], v[158:161], v[198:201], v[110:113]
	v_mfma_f32_16x16x32_bf16 v[106:109], v[166:169], v[198:201], v[106:109]
	v_mfma_f32_16x16x32_bf16 v[94:97], v[158:161], v[210:213], v[94:97]
	v_mfma_f32_16x16x32_bf16 v[90:93], v[166:169], v[210:213], v[90:93]
	v_mfma_f32_16x16x32_bf16 v[78:81], v[158:161], v[218:221], v[78:81]
	v_mfma_f32_16x16x32_bf16 v[74:77], v[166:169], v[218:221], v[74:77]
	v_mfma_f32_16x16x32_bf16 v[118:121], v[170:173], v[186:189], v[118:121]
	v_mfma_f32_16x16x32_bf16 v[114:117], v[178:181], v[186:189], v[114:117]
	v_mfma_f32_16x16x32_bf16 v[102:105], v[170:173], v[194:197], v[102:105]
	v_mfma_f32_16x16x32_bf16 v[98:101], v[178:181], v[194:197], v[98:101]
	v_mfma_f32_16x16x32_bf16 v[86:89], v[170:173], v[206:209], v[86:89]
	v_mfma_f32_16x16x32_bf16 v[82:85], v[178:181], v[206:209], v[82:85]
	v_mfma_f32_16x16x32_bf16 v[70:73], v[170:173], v[214:217], v[70:73]
	v_mfma_f32_16x16x32_bf16 v[66:69], v[178:181], v[214:217], v[66:69]
	v_mfma_f32_16x16x32_bf16 v[118:121], v[174:177], v[190:193], v[118:121]
	v_mfma_f32_16x16x32_bf16 v[114:117], v[182:185], v[190:193], v[114:117]
	v_mfma_f32_16x16x32_bf16 v[102:105], v[174:177], v[198:201], v[102:105]
	v_mfma_f32_16x16x32_bf16 v[98:101], v[182:185], v[198:201], v[98:101]
	v_mfma_f32_16x16x32_bf16 v[86:89], v[174:177], v[210:213], v[86:89]
	v_mfma_f32_16x16x32_bf16 v[82:85], v[182:185], v[210:213], v[82:85]
	v_mfma_f32_16x16x32_bf16 v[70:73], v[174:177], v[218:221], v[70:73]
	v_mfma_f32_16x16x32_bf16 v[66:69], v[182:185], v[218:221], v[66:69]
	s_barrier
	s_setprio 0
	s_add_i32 s46, s69, s16
	v_lshl_add_u64 v[146:147], v[146:147], 0, s[10:11]
	s_mov_b32 m0, s46
	ds_read_b128 v[186:189], v152 offset:49152
	ds_read_b128 v[190:193], v152 offset:50176
	ds_read_b128 v[194:197], v152 offset:51200
	ds_read_b128 v[198:201], v152 offset:52224
	ds_read_b128 v[206:209], v152 offset:53248
	ds_read_b128 v[210:213], v152 offset:54272
	ds_read_b128 v[214:217], v152 offset:55296
	ds_read_b128 v[218:221], v152 offset:56320
	global_load_lds_dwordx4 v[146:147], off
	s_add_i32 m0, s46, 0x2000
	s_add_u32 s44, s44, 0x40080
	v_lshl_add_u64 v[146:147], v[202:203], 0, s[10:11]
	s_addc_u32 s45, s45, 0
	s_add_i32 s46, s70, s16
	global_load_lds_dwordx4 v[146:147], off
	v_lshl_add_u64 v[146:147], s[44:45], 0, v[134:135]
	s_mov_b32 m0, s46
	s_nop 0
	global_load_lds_dwordx4 v[146:147], off
	v_lshl_add_u64 v[146:147], s[44:45], 0, v[130:131]
	s_add_i32 m0, s46, 0x2000
	s_nop 0
	global_load_lds_dwordx4 v[146:147], off
	v_lshl_add_u64 v[146:147], v[222:223], 0, s[10:11]
	s_mov_b32 m0, s33
	s_nop 0
	global_load_lds_dwordx4 v[146:147], off
	v_lshl_add_u64 v[146:147], v[224:225], 0, s[10:11]
	s_mov_b32 m0, s35
	s_nop 0
	global_load_lds_dwordx4 v[146:147], off
	s_waitcnt vmcnt(8)
	s_waitcnt lgkmcnt(0)
	s_setprio 1
	s_barrier
	v_mfma_f32_16x16x32_bf16 v[62:65], v[154:157], v[186:189], v[62:65]
	v_mfma_f32_16x16x32_bf16 v[58:61], v[162:165], v[186:189], v[58:61]
	v_mfma_f32_16x16x32_bf16 v[46:49], v[154:157], v[194:197], v[46:49]
	v_mfma_f32_16x16x32_bf16 v[42:45], v[162:165], v[194:197], v[42:45]
	v_mfma_f32_16x16x32_bf16 v[30:33], v[154:157], v[206:209], v[30:33]
	v_mfma_f32_16x16x32_bf16 v[26:29], v[162:165], v[206:209], v[26:29]
	v_mfma_f32_16x16x32_bf16 v[14:17], v[154:157], v[214:217], v[14:17]
	v_mfma_f32_16x16x32_bf16 v[10:13], v[162:165], v[214:217], v[10:13]
	v_mfma_f32_16x16x32_bf16 v[62:65], v[158:161], v[190:193], v[62:65]
	v_mfma_f32_16x16x32_bf16 v[58:61], v[166:169], v[190:193], v[58:61]
	v_mfma_f32_16x16x32_bf16 v[46:49], v[158:161], v[198:201], v[46:49]
	v_mfma_f32_16x16x32_bf16 v[42:45], v[166:169], v[198:201], v[42:45]
	v_mfma_f32_16x16x32_bf16 v[30:33], v[158:161], v[210:213], v[30:33]
	v_mfma_f32_16x16x32_bf16 v[26:29], v[166:169], v[210:213], v[26:29]
	v_mfma_f32_16x16x32_bf16 v[14:17], v[158:161], v[218:221], v[14:17]
	v_mfma_f32_16x16x32_bf16 v[10:13], v[166:169], v[218:221], v[10:13]
	v_mfma_f32_16x16x32_bf16 v[54:57], v[170:173], v[186:189], v[54:57]
	v_mfma_f32_16x16x32_bf16 v[50:53], v[178:181], v[186:189], v[50:53]
	v_mfma_f32_16x16x32_bf16 v[38:41], v[170:173], v[194:197], v[38:41]
	v_mfma_f32_16x16x32_bf16 v[34:37], v[178:181], v[194:197], v[34:37]
	v_mfma_f32_16x16x32_bf16 v[22:25], v[170:173], v[206:209], v[22:25]
	v_mfma_f32_16x16x32_bf16 v[18:21], v[178:181], v[206:209], v[18:21]
	v_mfma_f32_16x16x32_bf16 v[6:9], v[170:173], v[214:217], v[6:9]
	v_mfma_f32_16x16x32_bf16 v[2:5], v[178:181], v[214:217], v[2:5]
	v_mfma_f32_16x16x32_bf16 v[54:57], v[174:177], v[190:193], v[54:57]
	v_mfma_f32_16x16x32_bf16 v[50:53], v[182:185], v[190:193], v[50:53]
	v_mfma_f32_16x16x32_bf16 v[38:41], v[174:177], v[198:201], v[38:41]
	v_mfma_f32_16x16x32_bf16 v[34:37], v[182:185], v[198:201], v[34:37]
	v_mfma_f32_16x16x32_bf16 v[22:25], v[174:177], v[210:213], v[22:25]
	v_mfma_f32_16x16x32_bf16 v[18:21], v[182:185], v[210:213], v[18:21]
	v_mfma_f32_16x16x32_bf16 v[6:9], v[174:177], v[218:221], v[6:9]
	v_mfma_f32_16x16x32_bf16 v[2:5], v[182:185], v[218:221], v[2:5]
	s_barrier
	s_setprio 0
	s_add_i32 s68, s68, 2
	s_add_u32 s42, s42, 0x100
	s_addc_u32 s43, s43, 0
	s_add_u32 s66, s66, 0x100
	s_addc_u32 s67, s67, 0
	s_cmp_gt_u32 s68, 13
	s_cbranch_scc0 .LBB0_745
	s_and_b64 vcc, exec, s[12:13]
	s_cbranch_vccz .LBB0_748
	s_barrier

.LBB0_833:
	s_add_u32 s72, s0, s68
	s_addc_u32 s73, s1, s69
	s_and_b64 s[62:63], s[70:71], exec
	s_cselect_b32 s15, s73, s77
	s_cselect_b32 s33, s72, s76
	s_add_u32 s74, s35, s66
	s_addc_u32 s75, s85, s67
	s_and_b64 s[62:63], s[70:71], exec
	s_cselect_b32 s34, s75, s79
	s_cselect_b32 s39, s74, s78
	s_add_i32 s45, s7, -2
	s_add_u32 s76, s76, 0x100080
	s_addc_u32 s77, s77, 0
	s_add_u32 s47, s78, 0x100
	s_addc_u32 s62, s79, 0
	s_mov_b32 s63, 0
	s_waitcnt vmcnt(0)
	ds_read_b128 v[114:117], v190
	ds_read_b128 v[118:121], v190 offset:1024
	ds_read_b128 v[122:125], v190 offset:2048
	ds_read_b128 v[126:129], v190 offset:3072
	ds_read_b128 v[146:149], v191
	ds_read_b128 v[150:153], v191 offset:1024
	ds_read_b128 v[154:157], v191 offset:2048
	ds_read_b128 v[158:161], v191 offset:3072
	s_add_i32 s82, s63, 2
	s_add_u32 s78, s76, 0xfff00080
	s_addc_u32 s79, s77, -1
	s_cmp_eq_u32 s45, s63
	s_cselect_b32 s81, s15, s79
	s_cselect_b32 s80, s33, s78
	s_cselect_b32 s79, s34, s62
	s_cselect_b32 s78, s39, s47
	v_lshl_add_u64 v[186:187], s[76:77], 0, v[180:181]
	s_add_i32 m0, s87, 0xc000
	ds_read_b128 v[162:165], v192
	ds_read_b128 v[166:169], v192 offset:1024
	ds_read_b128 v[194:197], v192 offset:2048
	ds_read_b128 v[198:201], v192 offset:3072
	ds_read_b128 v[206:209], v192 offset:4096
	ds_read_b128 v[210:213], v192 offset:5120
	ds_read_b128 v[214:217], v192 offset:6144
	ds_read_b128 v[218:221], v192 offset:7168
	global_load_lds_dwordx4 v[186:187], off
	v_lshl_add_u64 v[186:187], s[76:77], 0, v[182:183]
	s_add_i32 m0, s87, 0xe000
	s_nop 0
	global_load_lds_dwordx4 v[186:187], off
	s_waitcnt vmcnt(8)
	s_waitcnt lgkmcnt(0)
	s_setprio 1
	s_barrier
	v_mfma_f32_16x16x32_bf16 v[142:145], v[114:117], v[162:165], 0
	v_mfma_f32_16x16x32_bf16 v[138:141], v[122:125], v[162:165], 0
	v_mfma_f32_16x16x32_bf16 v[110:113], v[114:117], v[194:197], 0
	v_mfma_f32_16x16x32_bf16 v[106:109], v[122:125], v[194:197], 0
	v_mfma_f32_16x16x32_bf16 v[98:101], v[114:117], v[206:209], 0
	v_mfma_f32_16x16x32_bf16 v[90:93], v[122:125], v[206:209], 0
	v_mfma_f32_16x16x32_bf16 v[82:85], v[114:117], v[214:217], 0
	v_mfma_f32_16x16x32_bf16 v[74:77], v[122:125], v[214:217], 0
	v_mfma_f32_16x16x32_bf16 v[142:145], v[118:121], v[166:169], v[142:145]
	v_mfma_f32_16x16x32_bf16 v[138:141], v[126:129], v[166:169], v[138:141]
	v_mfma_f32_16x16x32_bf16 v[110:113], v[118:121], v[198:201], v[110:113]
	v_mfma_f32_16x16x32_bf16 v[106:109], v[126:129], v[198:201], v[106:109]
	v_mfma_f32_16x16x32_bf16 v[98:101], v[118:121], v[210:213], v[98:101]
	v_mfma_f32_16x16x32_bf16 v[90:93], v[126:129], v[210:213], v[90:93]
	v_mfma_f32_16x16x32_bf16 v[82:85], v[118:121], v[218:221], v[82:85]
	v_mfma_f32_16x16x32_bf16 v[74:77], v[126:129], v[218:221], v[74:77]
	v_mfma_f32_16x16x32_bf16 v[134:137], v[146:149], v[162:165], 0
	v_mfma_f32_16x16x32_bf16 v[130:133], v[154:157], v[162:165], 0
	v_mfma_f32_16x16x32_bf16 v[102:105], v[146:149], v[194:197], 0
	v_mfma_f32_16x16x32_bf16 v[94:97], v[154:157], v[194:197], 0
	v_mfma_f32_16x16x32_bf16 v[86:89], v[146:149], v[206:209], 0
	v_mfma_f32_16x16x32_bf16 v[78:81], v[154:157], v[206:209], 0
	v_mfma_f32_16x16x32_bf16 v[70:73], v[146:149], v[214:217], 0
	v_mfma_f32_16x16x32_bf16 v[66:69], v[154:157], v[214:217], 0
	v_mfma_f32_16x16x32_bf16 v[134:137], v[150:153], v[166:169], v[134:137]
	v_mfma_f32_16x16x32_bf16 v[130:133], v[158:161], v[166:169], v[130:133]
	v_mfma_f32_16x16x32_bf16 v[102:105], v[150:153], v[198:201], v[102:105]
	v_mfma_f32_16x16x32_bf16 v[94:97], v[158:161], v[198:201], v[94:97]
	v_mfma_f32_16x16x32_bf16 v[86:89], v[150:153], v[210:213], v[86:89]
	v_mfma_f32_16x16x32_bf16 v[78:81], v[158:161], v[210:213], v[78:81]
	v_mfma_f32_16x16x32_bf16 v[70:73], v[150:153], v[218:221], v[70:73]
	v_mfma_f32_16x16x32_bf16 v[66:69], v[158:161], v[218:221], v[66:69]
	s_barrier
	s_setprio 0
	s_add_i32 s63, s24, s86
	v_lshl_add_u64 v[186:187], s[78:79], 0, v[172:173]
	s_mov_b32 m0, s63
	ds_read_b128 v[162:165], v192 offset:16384
	ds_read_b128 v[166:169], v192 offset:17408
	ds_read_b128 v[194:197], v192 offset:18432
	ds_read_b128 v[198:201], v192 offset:19456
	ds_read_b128 v[206:209], v192 offset:20480
	ds_read_b128 v[210:213], v192 offset:21504
	ds_read_b128 v[214:217], v192 offset:22528
	ds_read_b128 v[218:221], v192 offset:23552
	global_load_lds_dwordx4 v[186:187], off
	s_add_i32 m0, s63, 0x2000
	s_add_u32 vcc_lo, s78, 0x100000
	v_lshl_add_u64 v[202:203], s[78:79], 0, v[176:177]
	s_addc_u32 vcc_hi, s79, 0
	s_add_i32 s63, s25, s86
	global_load_lds_dwordx4 v[202:203], off
	v_lshl_add_u64 v[222:223], vcc, 0, v[172:173]
	s_mov_b32 m0, s63
	v_lshl_add_u64 v[224:225], s[80:81], 0, v[174:175]
	global_load_lds_dwordx4 v[222:223], off
	v_lshl_add_u64 v[222:223], vcc, 0, v[176:177]
	s_add_i32 m0, s63, 0x2000
	s_nop 0
	global_load_lds_dwordx4 v[222:223], off
	v_lshl_add_u64 v[222:223], s[80:81], 0, v[170:171]
	s_mov_b32 m0, s87
	s_nop 0
	global_load_lds_dwordx4 v[222:223], off
	s_mov_b32 m0, s88
	s_nop 0
	global_load_lds_dwordx4 v[224:225], off
	s_waitcnt vmcnt(8)
	s_waitcnt lgkmcnt(0)
	s_setprio 1
	s_barrier
	v_mfma_f32_16x16x32_bf16 v[62:65], v[114:117], v[162:165], 0
	v_mfma_f32_16x16x32_bf16 v[58:61], v[122:125], v[162:165], 0
	v_mfma_f32_16x16x32_bf16 v[50:53], v[114:117], v[194:197], 0
	v_mfma_f32_16x16x32_bf16 v[42:45], v[122:125], v[194:197], 0
	v_mfma_f32_16x16x32_bf16 v[34:37], v[114:117], v[206:209], 0
	v_mfma_f32_16x16x32_bf16 v[26:29], v[122:125], v[206:209], 0
	v_mfma_f32_16x16x32_bf16 v[18:21], v[114:117], v[214:217], 0
	v_mfma_f32_16x16x32_bf16 v[10:13], v[122:125], v[214:217], 0
	v_mfma_f32_16x16x32_bf16 v[62:65], v[118:121], v[166:169], v[62:65]
	v_mfma_f32_16x16x32_bf16 v[58:61], v[126:129], v[166:169], v[58:61]
	v_mfma_f32_16x16x32_bf16 v[50:53], v[118:121], v[198:201], v[50:53]
	v_mfma_f32_16x16x32_bf16 v[42:45], v[126:129], v[198:201], v[42:45]
	v_mfma_f32_16x16x32_bf16 v[34:37], v[118:121], v[210:213], v[34:37]
	v_mfma_f32_16x16x32_bf16 v[26:29], v[126:129], v[210:213], v[26:29]
	v_mfma_f32_16x16x32_bf16 v[18:21], v[118:121], v[218:221], v[18:21]
	v_mfma_f32_16x16x32_bf16 v[10:13], v[126:129], v[218:221], v[10:13]
	v_mfma_f32_16x16x32_bf16 v[54:57], v[146:149], v[162:165], 0
	v_mfma_f32_16x16x32_bf16 v[46:49], v[154:157], v[162:165], 0
	v_mfma_f32_16x16x32_bf16 v[38:41], v[146:149], v[194:197], 0
	v_mfma_f32_16x16x32_bf16 v[30:33], v[154:157], v[194:197], 0
	v_mfma_f32_16x16x32_bf16 v[22:25], v[146:149], v[206:209], 0
	v_mfma_f32_16x16x32_bf16 v[14:17], v[154:157], v[206:209], 0
	v_mfma_f32_16x16x32_bf16 v[6:9], v[146:149], v[214:217], 0
	v_mfma_f32_16x16x32_bf16 v[2:5], v[154:157], v[214:217], 0
	v_mfma_f32_16x16x32_bf16 v[54:57], v[150:153], v[166:169], v[54:57]
	v_mfma_f32_16x16x32_bf16 v[46:49], v[158:161], v[166:169], v[46:49]
	v_mfma_f32_16x16x32_bf16 v[38:41], v[150:153], v[198:201], v[38:41]
	v_mfma_f32_16x16x32_bf16 v[30:33], v[158:161], v[198:201], v[30:33]
	v_mfma_f32_16x16x32_bf16 v[22:25], v[150:153], v[210:213], v[22:25]
	v_mfma_f32_16x16x32_bf16 v[14:17], v[158:161], v[210:213], v[14:17]
	v_mfma_f32_16x16x32_bf16 v[6:9], v[150:153], v[218:221], v[6:9]
	v_mfma_f32_16x16x32_bf16 v[2:5], v[158:161], v[218:221], v[2:5]
	s_barrier
	s_setprio 0
	s_add_i32 s63, 0, 0x18000
	s_add_i32 s83, 0, 0x1c000
	v_add_u32_e32 v126, s63, v189
	v_add_u32_e32 v158, s83, v189
	ds_read_b128 v[114:117], v126
	ds_read_b128 v[118:121], v126 offset:1024
	ds_read_b128 v[122:125], v126 offset:2048
	ds_read_b128 v[126:129], v126 offset:3072
	ds_read_b128 v[146:149], v158
	ds_read_b128 v[150:153], v158 offset:1024
	ds_read_b128 v[154:157], v158 offset:2048
	ds_read_b128 v[158:161], v158 offset:3072
	s_add_u32 s80, s80, 0x100000
	s_addc_u32 s81, s81, 0
	s_mov_b32 m0, s89
	v_lshl_add_u64 v[226:227], s[80:81], 0, v[170:171]
	ds_read_b128 v[162:165], v192 offset:32768
	ds_read_b128 v[166:169], v192 offset:33792
	ds_read_b128 v[194:197], v192 offset:34816
	ds_read_b128 v[198:201], v192 offset:35840
	ds_read_b128 v[206:209], v192 offset:36864
	ds_read_b128 v[210:213], v192 offset:37888
	ds_read_b128 v[214:217], v192 offset:38912
	ds_read_b128 v[218:221], v192 offset:39936
	global_load_lds_dwordx4 v[226:227], off
	v_lshl_add_u64 v[226:227], s[80:81], 0, v[174:175]
	s_mov_b32 m0, s90
	s_nop 0
	global_load_lds_dwordx4 v[226:227], off
	s_waitcnt vmcnt(8)
	s_waitcnt lgkmcnt(0)
	s_setprio 1
	s_barrier
	v_mfma_f32_16x16x32_bf16 v[142:145], v[114:117], v[162:165], v[142:145]
	v_mfma_f32_16x16x32_bf16 v[138:141], v[122:125], v[162:165], v[138:141]
	v_mfma_f32_16x16x32_bf16 v[110:113], v[114:117], v[194:197], v[110:113]
	v_mfma_f32_16x16x32_bf16 v[106:109], v[122:125], v[194:197], v[106:109]
	v_mfma_f32_16x16x32_bf16 v[98:101], v[114:117], v[206:209], v[98:101]
	v_mfma_f32_16x16x32_bf16 v[90:93], v[122:125], v[206:209], v[90:93]
	v_mfma_f32_16x16x32_bf16 v[82:85], v[114:117], v[214:217], v[82:85]
	v_mfma_f32_16x16x32_bf16 v[74:77], v[122:125], v[214:217], v[74:77]
	v_mfma_f32_16x16x32_bf16 v[142:145], v[118:121], v[166:169], v[142:145]
	v_mfma_f32_16x16x32_bf16 v[138:141], v[126:129], v[166:169], v[138:141]
	v_mfma_f32_16x16x32_bf16 v[110:113], v[118:121], v[198:201], v[110:113]
	v_mfma_f32_16x16x32_bf16 v[106:109], v[126:129], v[198:201], v[106:109]
	v_mfma_f32_16x16x32_bf16 v[98:101], v[118:121], v[210:213], v[98:101]
	v_mfma_f32_16x16x32_bf16 v[90:93], v[126:129], v[210:213], v[90:93]
	v_mfma_f32_16x16x32_bf16 v[82:85], v[118:121], v[218:221], v[82:85]
	v_mfma_f32_16x16x32_bf16 v[74:77], v[126:129], v[218:221], v[74:77]
	v_mfma_f32_16x16x32_bf16 v[134:137], v[146:149], v[162:165], v[134:137]
	v_mfma_f32_16x16x32_bf16 v[130:133], v[154:157], v[162:165], v[130:133]
	v_mfma_f32_16x16x32_bf16 v[102:105], v[146:149], v[194:197], v[102:105]
	v_mfma_f32_16x16x32_bf16 v[94:97], v[154:157], v[194:197], v[94:97]
	v_mfma_f32_16x16x32_bf16 v[86:89], v[146:149], v[206:209], v[86:89]
	v_mfma_f32_16x16x32_bf16 v[78:81], v[154:157], v[206:209], v[78:81]
	v_mfma_f32_16x16x32_bf16 v[70:73], v[146:149], v[214:217], v[70:73]
	v_mfma_f32_16x16x32_bf16 v[66:69], v[154:157], v[214:217], v[66:69]
	v_mfma_f32_16x16x32_bf16 v[134:137], v[150:153], v[166:169], v[134:137]
	v_mfma_f32_16x16x32_bf16 v[130:133], v[158:161], v[166:169], v[130:133]
	v_mfma_f32_16x16x32_bf16 v[102:105], v[150:153], v[198:201], v[102:105]
	v_mfma_f32_16x16x32_bf16 v[94:97], v[158:161], v[198:201], v[94:97]
	v_mfma_f32_16x16x32_bf16 v[86:89], v[150:153], v[210:213], v[86:89]
	v_mfma_f32_16x16x32_bf16 v[78:81], v[158:161], v[210:213], v[78:81]
	v_mfma_f32_16x16x32_bf16 v[70:73], v[150:153], v[218:221], v[70:73]
	v_mfma_f32_16x16x32_bf16 v[66:69], v[158:161], v[218:221], v[66:69]
	s_barrier
	s_setprio 0
	s_add_i32 s63, s63, s86
	v_lshl_add_u64 v[186:187], v[186:187], 0, s[22:23]
	s_mov_b32 m0, s63
	ds_read_b128 v[162:165], v192 offset:49152
	ds_read_b128 v[166:169], v192 offset:50176
	ds_read_b128 v[194:197], v192 offset:51200
	ds_read_b128 v[198:201], v192 offset:52224
	ds_read_b128 v[206:209], v192 offset:53248
	ds_read_b128 v[210:213], v192 offset:54272
	ds_read_b128 v[214:217], v192 offset:55296
	ds_read_b128 v[218:221], v192 offset:56320
	global_load_lds_dwordx4 v[186:187], off
	s_add_i32 m0, s63, 0x2000
	s_add_u32 s78, s78, 0x100080
	v_lshl_add_u64 v[186:187], v[202:203], 0, s[22:23]
	s_addc_u32 s79, s79, 0
	s_add_i32 s63, s83, s86
	global_load_lds_dwordx4 v[186:187], off
	v_lshl_add_u64 v[186:187], s[78:79], 0, v[172:173]
	s_mov_b32 m0, s63
	s_nop 0
	global_load_lds_dwordx4 v[186:187], off
	v_lshl_add_u64 v[186:187], s[78:79], 0, v[176:177]
	s_add_i32 m0, s63, 0x2000
	s_nop 0
	global_load_lds_dwordx4 v[186:187], off
	v_lshl_add_u64 v[186:187], v[222:223], 0, s[22:23]
	s_mov_b32 m0, s95
	s_nop 0
	global_load_lds_dwordx4 v[186:187], off
	v_lshl_add_u64 v[186:187], v[224:225], 0, s[22:23]
	s_mov_b32 m0, s96
	s_nop 0
	global_load_lds_dwordx4 v[186:187], off
	s_waitcnt vmcnt(8)
	s_waitcnt lgkmcnt(0)
	s_setprio 1
	s_barrier
	v_mfma_f32_16x16x32_bf16 v[62:65], v[114:117], v[162:165], v[62:65]
	v_mfma_f32_16x16x32_bf16 v[58:61], v[122:125], v[162:165], v[58:61]
	v_mfma_f32_16x16x32_bf16 v[50:53], v[114:117], v[194:197], v[50:53]
	v_mfma_f32_16x16x32_bf16 v[42:45], v[122:125], v[194:197], v[42:45]
	v_mfma_f32_16x16x32_bf16 v[34:37], v[114:117], v[206:209], v[34:37]
	v_mfma_f32_16x16x32_bf16 v[26:29], v[122:125], v[206:209], v[26:29]
	v_mfma_f32_16x16x32_bf16 v[18:21], v[114:117], v[214:217], v[18:21]
	v_mfma_f32_16x16x32_bf16 v[10:13], v[122:125], v[214:217], v[10:13]
	v_mfma_f32_16x16x32_bf16 v[62:65], v[118:121], v[166:169], v[62:65]
	v_mfma_f32_16x16x32_bf16 v[58:61], v[126:129], v[166:169], v[58:61]
	v_mfma_f32_16x16x32_bf16 v[50:53], v[118:121], v[198:201], v[50:53]
	v_mfma_f32_16x16x32_bf16 v[42:45], v[126:129], v[198:201], v[42:45]
	v_mfma_f32_16x16x32_bf16 v[34:37], v[118:121], v[210:213], v[34:37]
	v_mfma_f32_16x16x32_bf16 v[26:29], v[126:129], v[210:213], v[26:29]
	v_mfma_f32_16x16x32_bf16 v[18:21], v[118:121], v[218:221], v[18:21]
	v_mfma_f32_16x16x32_bf16 v[10:13], v[126:129], v[218:221], v[10:13]
	v_mfma_f32_16x16x32_bf16 v[54:57], v[146:149], v[162:165], v[54:57]
	v_mfma_f32_16x16x32_bf16 v[46:49], v[154:157], v[162:165], v[46:49]
	v_mfma_f32_16x16x32_bf16 v[38:41], v[146:149], v[194:197], v[38:41]
	v_mfma_f32_16x16x32_bf16 v[30:33], v[154:157], v[194:197], v[30:33]
	v_mfma_f32_16x16x32_bf16 v[22:25], v[146:149], v[206:209], v[22:25]
	v_mfma_f32_16x16x32_bf16 v[14:17], v[154:157], v[206:209], v[14:17]
	v_mfma_f32_16x16x32_bf16 v[6:9], v[146:149], v[214:217], v[6:9]
	v_mfma_f32_16x16x32_bf16 v[2:5], v[154:157], v[214:217], v[2:5]
	v_mfma_f32_16x16x32_bf16 v[54:57], v[150:153], v[166:169], v[54:57]
	v_mfma_f32_16x16x32_bf16 v[46:49], v[158:161], v[166:169], v[46:49]
	v_mfma_f32_16x16x32_bf16 v[38:41], v[150:153], v[198:201], v[38:41]
	v_mfma_f32_16x16x32_bf16 v[30:33], v[158:161], v[198:201], v[30:33]
	v_mfma_f32_16x16x32_bf16 v[22:25], v[150:153], v[210:213], v[22:25]
	v_mfma_f32_16x16x32_bf16 v[14:17], v[158:161], v[210:213], v[14:17]
	v_mfma_f32_16x16x32_bf16 v[6:9], v[150:153], v[218:221], v[6:9]
	v_mfma_f32_16x16x32_bf16 v[2:5], v[158:161], v[218:221], v[2:5]
	s_barrier
	s_setprio 0
	s_add_u32 s76, s76, 0x100
	s_addc_u32 s77, s77, 0
	s_add_u32 s47, s47, 0x100
	s_addc_u32 s62, s62, 0
	s_cmp_ge_i32 s82, s7
	s_mov_b32 s63, s82
.LBB0_834:
	ds_read_b128 v[114:117], v190
	ds_read_b128 v[118:121], v190 offset:1024
	ds_read_b128 v[122:125], v190 offset:2048
	ds_read_b128 v[126:129], v190 offset:3072
	ds_read_b128 v[146:149], v191
	ds_read_b128 v[150:153], v191 offset:1024
	ds_read_b128 v[154:157], v191 offset:2048
	ds_read_b128 v[158:161], v191 offset:3072
	s_add_i32 s82, s63, 2
	s_add_u32 s78, s76, 0xfff00080
	s_addc_u32 s79, s77, -1
	s_cmp_eq_u32 s45, s63
	s_cselect_b32 s81, s15, s79
	s_cselect_b32 s80, s33, s78
	s_cselect_b32 s79, s34, s62
	s_cselect_b32 s78, s39, s47
	v_lshl_add_u64 v[186:187], s[76:77], 0, v[180:181]
	s_add_i32 m0, s87, 0xc000
	ds_read_b128 v[162:165], v192
	ds_read_b128 v[166:169], v192 offset:1024
	ds_read_b128 v[194:197], v192 offset:2048
	ds_read_b128 v[198:201], v192 offset:3072
	ds_read_b128 v[206:209], v192 offset:4096
	ds_read_b128 v[210:213], v192 offset:5120
	ds_read_b128 v[214:217], v192 offset:6144
	ds_read_b128 v[218:221], v192 offset:7168
	global_load_lds_dwordx4 v[186:187], off
	v_lshl_add_u64 v[186:187], s[76:77], 0, v[182:183]
	s_add_i32 m0, s87, 0xe000
	s_nop 0
	global_load_lds_dwordx4 v[186:187], off
	s_waitcnt vmcnt(8)
	s_waitcnt lgkmcnt(0)
	s_setprio 1
	s_barrier
	v_mfma_f32_16x16x32_bf16 v[142:145], v[114:117], v[162:165], v[142:145]
	v_mfma_f32_16x16x32_bf16 v[138:141], v[122:125], v[162:165], v[138:141]
	v_mfma_f32_16x16x32_bf16 v[110:113], v[114:117], v[194:197], v[110:113]
	v_mfma_f32_16x16x32_bf16 v[106:109], v[122:125], v[194:197], v[106:109]
	v_mfma_f32_16x16x32_bf16 v[98:101], v[114:117], v[206:209], v[98:101]
	v_mfma_f32_16x16x32_bf16 v[90:93], v[122:125], v[206:209], v[90:93]
	v_mfma_f32_16x16x32_bf16 v[82:85], v[114:117], v[214:217], v[82:85]
	v_mfma_f32_16x16x32_bf16 v[74:77], v[122:125], v[214:217], v[74:77]
	v_mfma_f32_16x16x32_bf16 v[142:145], v[118:121], v[166:169], v[142:145]
	v_mfma_f32_16x16x32_bf16 v[138:141], v[126:129], v[166:169], v[138:141]
	v_mfma_f32_16x16x32_bf16 v[110:113], v[118:121], v[198:201], v[110:113]
	v_mfma_f32_16x16x32_bf16 v[106:109], v[126:129], v[198:201], v[106:109]
	v_mfma_f32_16x16x32_bf16 v[98:101], v[118:121], v[210:213], v[98:101]
	v_mfma_f32_16x16x32_bf16 v[90:93], v[126:129], v[210:213], v[90:93]
	v_mfma_f32_16x16x32_bf16 v[82:85], v[118:121], v[218:221], v[82:85]
	v_mfma_f32_16x16x32_bf16 v[74:77], v[126:129], v[218:221], v[74:77]
	v_mfma_f32_16x16x32_bf16 v[134:137], v[146:149], v[162:165], v[134:137]
	v_mfma_f32_16x16x32_bf16 v[130:133], v[154:157], v[162:165], v[130:133]
	v_mfma_f32_16x16x32_bf16 v[102:105], v[146:149], v[194:197], v[102:105]
	v_mfma_f32_16x16x32_bf16 v[94:97], v[154:157], v[194:197], v[94:97]
	v_mfma_f32_16x16x32_bf16 v[86:89], v[146:149], v[206:209], v[86:89]
	v_mfma_f32_16x16x32_bf16 v[78:81], v[154:157], v[206:209], v[78:81]
	v_mfma_f32_16x16x32_bf16 v[70:73], v[146:149], v[214:217], v[70:73]
	v_mfma_f32_16x16x32_bf16 v[66:69], v[154:157], v[214:217], v[66:69]
	v_mfma_f32_16x16x32_bf16 v[134:137], v[150:153], v[166:169], v[134:137]
	v_mfma_f32_16x16x32_bf16 v[130:133], v[158:161], v[166:169], v[130:133]
	v_mfma_f32_16x16x32_bf16 v[102:105], v[150:153], v[198:201], v[102:105]
	v_mfma_f32_16x16x32_bf16 v[94:97], v[158:161], v[198:201], v[94:97]
	v_mfma_f32_16x16x32_bf16 v[86:89], v[150:153], v[210:213], v[86:89]
	v_mfma_f32_16x16x32_bf16 v[78:81], v[158:161], v[210:213], v[78:81]
	v_mfma_f32_16x16x32_bf16 v[70:73], v[150:153], v[218:221], v[70:73]
	v_mfma_f32_16x16x32_bf16 v[66:69], v[158:161], v[218:221], v[66:69]
	s_barrier
	s_setprio 0
	s_add_i32 s63, s24, s86
	v_lshl_add_u64 v[186:187], s[78:79], 0, v[172:173]
	s_mov_b32 m0, s63
	ds_read_b128 v[162:165], v192 offset:16384
	ds_read_b128 v[166:169], v192 offset:17408
	ds_read_b128 v[194:197], v192 offset:18432
	ds_read_b128 v[198:201], v192 offset:19456
	ds_read_b128 v[206:209], v192 offset:20480
	ds_read_b128 v[210:213], v192 offset:21504
	ds_read_b128 v[214:217], v192 offset:22528
	ds_read_b128 v[218:221], v192 offset:23552
	global_load_lds_dwordx4 v[186:187], off
	s_add_i32 m0, s63, 0x2000
	s_add_u32 vcc_lo, s78, 0x100000
	v_lshl_add_u64 v[202:203], s[78:79], 0, v[176:177]
	s_addc_u32 vcc_hi, s79, 0
	s_add_i32 s63, s25, s86
	global_load_lds_dwordx4 v[202:203], off
	v_lshl_add_u64 v[222:223], vcc, 0, v[172:173]
	s_mov_b32 m0, s63
	v_lshl_add_u64 v[224:225], s[80:81], 0, v[174:175]
	global_load_lds_dwordx4 v[222:223], off
	v_lshl_add_u64 v[222:223], vcc, 0, v[176:177]
	s_add_i32 m0, s63, 0x2000
	s_nop 0
	global_load_lds_dwordx4 v[222:223], off
	v_lshl_add_u64 v[222:223], s[80:81], 0, v[170:171]
	s_mov_b32 m0, s87
	s_nop 0
	global_load_lds_dwordx4 v[222:223], off
	s_mov_b32 m0, s88
	s_nop 0
	global_load_lds_dwordx4 v[224:225], off
	s_waitcnt vmcnt(8)
	s_waitcnt lgkmcnt(0)
	s_setprio 1
	s_barrier
	v_mfma_f32_16x16x32_bf16 v[62:65], v[114:117], v[162:165], v[62:65]
	v_mfma_f32_16x16x32_bf16 v[58:61], v[122:125], v[162:165], v[58:61]
	v_mfma_f32_16x16x32_bf16 v[50:53], v[114:117], v[194:197], v[50:53]
	v_mfma_f32_16x16x32_bf16 v[42:45], v[122:125], v[194:197], v[42:45]
	v_mfma_f32_16x16x32_bf16 v[34:37], v[114:117], v[206:209], v[34:37]
	v_mfma_f32_16x16x32_bf16 v[26:29], v[122:125], v[206:209], v[26:29]
	v_mfma_f32_16x16x32_bf16 v[18:21], v[114:117], v[214:217], v[18:21]
	v_mfma_f32_16x16x32_bf16 v[10:13], v[122:125], v[214:217], v[10:13]
	v_mfma_f32_16x16x32_bf16 v[62:65], v[118:121], v[166:169], v[62:65]
	v_mfma_f32_16x16x32_bf16 v[58:61], v[126:129], v[166:169], v[58:61]
	v_mfma_f32_16x16x32_bf16 v[50:53], v[118:121], v[198:201], v[50:53]
	v_mfma_f32_16x16x32_bf16 v[42:45], v[126:129], v[198:201], v[42:45]
	v_mfma_f32_16x16x32_bf16 v[34:37], v[118:121], v[210:213], v[34:37]
	v_mfma_f32_16x16x32_bf16 v[26:29], v[126:129], v[210:213], v[26:29]
	v_mfma_f32_16x16x32_bf16 v[18:21], v[118:121], v[218:221], v[18:21]
	v_mfma_f32_16x16x32_bf16 v[10:13], v[126:129], v[218:221], v[10:13]
	v_mfma_f32_16x16x32_bf16 v[54:57], v[146:149], v[162:165], v[54:57]
	v_mfma_f32_16x16x32_bf16 v[46:49], v[154:157], v[162:165], v[46:49]
	v_mfma_f32_16x16x32_bf16 v[38:41], v[146:149], v[194:197], v[38:41]
	v_mfma_f32_16x16x32_bf16 v[30:33], v[154:157], v[194:197], v[30:33]
	v_mfma_f32_16x16x32_bf16 v[22:25], v[146:149], v[206:209], v[22:25]
	v_mfma_f32_16x16x32_bf16 v[14:17], v[154:157], v[206:209], v[14:17]
	v_mfma_f32_16x16x32_bf16 v[6:9], v[146:149], v[214:217], v[6:9]
	v_mfma_f32_16x16x32_bf16 v[2:5], v[154:157], v[214:217], v[2:5]
	v_mfma_f32_16x16x32_bf16 v[54:57], v[150:153], v[166:169], v[54:57]
	v_mfma_f32_16x16x32_bf16 v[46:49], v[158:161], v[166:169], v[46:49]
	v_mfma_f32_16x16x32_bf16 v[38:41], v[150:153], v[198:201], v[38:41]
	v_mfma_f32_16x16x32_bf16 v[30:33], v[158:161], v[198:201], v[30:33]
	v_mfma_f32_16x16x32_bf16 v[22:25], v[150:153], v[210:213], v[22:25]
	v_mfma_f32_16x16x32_bf16 v[14:17], v[158:161], v[210:213], v[14:17]
	v_mfma_f32_16x16x32_bf16 v[6:9], v[150:153], v[218:221], v[6:9]
	v_mfma_f32_16x16x32_bf16 v[2:5], v[158:161], v[218:221], v[2:5]
	s_barrier
	s_setprio 0
	s_add_i32 s63, 0, 0x18000
	s_add_i32 s83, 0, 0x1c000
	v_add_u32_e32 v126, s63, v189
	v_add_u32_e32 v158, s83, v189
	ds_read_b128 v[114:117], v126
	ds_read_b128 v[118:121], v126 offset:1024
	ds_read_b128 v[122:125], v126 offset:2048
	ds_read_b128 v[126:129], v126 offset:3072
	ds_read_b128 v[146:149], v158
	ds_read_b128 v[150:153], v158 offset:1024
	ds_read_b128 v[154:157], v158 offset:2048
	ds_read_b128 v[158:161], v158 offset:3072
	s_add_u32 s80, s80, 0x100000
	s_addc_u32 s81, s81, 0
	s_mov_b32 m0, s89
	v_lshl_add_u64 v[226:227], s[80:81], 0, v[170:171]
	ds_read_b128 v[162:165], v192 offset:32768
	ds_read_b128 v[166:169], v192 offset:33792
	ds_read_b128 v[194:197], v192 offset:34816
	ds_read_b128 v[198:201], v192 offset:35840
	ds_read_b128 v[206:209], v192 offset:36864
	ds_read_b128 v[210:213], v192 offset:37888
	ds_read_b128 v[214:217], v192 offset:38912
	ds_read_b128 v[218:221], v192 offset:39936
	global_load_lds_dwordx4 v[226:227], off
	v_lshl_add_u64 v[226:227], s[80:81], 0, v[174:175]
	s_mov_b32 m0, s90
	s_nop 0
	global_load_lds_dwordx4 v[226:227], off
	s_waitcnt vmcnt(8)
	s_waitcnt lgkmcnt(0)
	s_setprio 1
	s_barrier
	v_mfma_f32_16x16x32_bf16 v[142:145], v[114:117], v[162:165], v[142:145]
	v_mfma_f32_16x16x32_bf16 v[138:141], v[122:125], v[162:165], v[138:141]
	v_mfma_f32_16x16x32_bf16 v[110:113], v[114:117], v[194:197], v[110:113]
	v_mfma_f32_16x16x32_bf16 v[106:109], v[122:125], v[194:197], v[106:109]
	v_mfma_f32_16x16x32_bf16 v[98:101], v[114:117], v[206:209], v[98:101]
	v_mfma_f32_16x16x32_bf16 v[90:93], v[122:125], v[206:209], v[90:93]
	v_mfma_f32_16x16x32_bf16 v[82:85], v[114:117], v[214:217], v[82:85]
	v_mfma_f32_16x16x32_bf16 v[74:77], v[122:125], v[214:217], v[74:77]
	v_mfma_f32_16x16x32_bf16 v[142:145], v[118:121], v[166:169], v[142:145]
	v_mfma_f32_16x16x32_bf16 v[138:141], v[126:129], v[166:169], v[138:141]
	v_mfma_f32_16x16x32_bf16 v[110:113], v[118:121], v[198:201], v[110:113]
	v_mfma_f32_16x16x32_bf16 v[106:109], v[126:129], v[198:201], v[106:109]
	v_mfma_f32_16x16x32_bf16 v[98:101], v[118:121], v[210:213], v[98:101]
	v_mfma_f32_16x16x32_bf16 v[90:93], v[126:129], v[210:213], v[90:93]
	v_mfma_f32_16x16x32_bf16 v[82:85], v[118:121], v[218:221], v[82:85]
	v_mfma_f32_16x16x32_bf16 v[74:77], v[126:129], v[218:221], v[74:77]
	v_mfma_f32_16x16x32_bf16 v[134:137], v[146:149], v[162:165], v[134:137]
	v_mfma_f32_16x16x32_bf16 v[130:133], v[154:157], v[162:165], v[130:133]
	v_mfma_f32_16x16x32_bf16 v[102:105], v[146:149], v[194:197], v[102:105]
	v_mfma_f32_16x16x32_bf16 v[94:97], v[154:157], v[194:197], v[94:97]
	v_mfma_f32_16x16x32_bf16 v[86:89], v[146:149], v[206:209], v[86:89]
	v_mfma_f32_16x16x32_bf16 v[78:81], v[154:157], v[206:209], v[78:81]
	v_mfma_f32_16x16x32_bf16 v[70:73], v[146:149], v[214:217], v[70:73]
	v_mfma_f32_16x16x32_bf16 v[66:69], v[154:157], v[214:217], v[66:69]
	v_mfma_f32_16x16x32_bf16 v[134:137], v[150:153], v[166:169], v[134:137]
	v_mfma_f32_16x16x32_bf16 v[130:133], v[158:161], v[166:169], v[130:133]
	v_mfma_f32_16x16x32_bf16 v[102:105], v[150:153], v[198:201], v[102:105]
	v_mfma_f32_16x16x32_bf16 v[94:97], v[158:161], v[198:201], v[94:97]
	v_mfma_f32_16x16x32_bf16 v[86:89], v[150:153], v[210:213], v[86:89]
	v_mfma_f32_16x16x32_bf16 v[78:81], v[158:161], v[210:213], v[78:81]
	v_mfma_f32_16x16x32_bf16 v[70:73], v[150:153], v[218:221], v[70:73]
	v_mfma_f32_16x16x32_bf16 v[66:69], v[158:161], v[218:221], v[66:69]
	s_barrier
	s_setprio 0
	s_add_i32 s63, s63, s86
	v_lshl_add_u64 v[186:187], v[186:187], 0, s[22:23]
	s_mov_b32 m0, s63
	ds_read_b128 v[162:165], v192 offset:49152
	ds_read_b128 v[166:169], v192 offset:50176
	ds_read_b128 v[194:197], v192 offset:51200
	ds_read_b128 v[198:201], v192 offset:52224
	ds_read_b128 v[206:209], v192 offset:53248
	ds_read_b128 v[210:213], v192 offset:54272
	ds_read_b128 v[214:217], v192 offset:55296
	ds_read_b128 v[218:221], v192 offset:56320
	global_load_lds_dwordx4 v[186:187], off
	s_add_i32 m0, s63, 0x2000
	s_add_u32 s78, s78, 0x100080
	v_lshl_add_u64 v[186:187], v[202:203], 0, s[22:23]
	s_addc_u32 s79, s79, 0
	s_add_i32 s63, s83, s86
	global_load_lds_dwordx4 v[186:187], off
	v_lshl_add_u64 v[186:187], s[78:79], 0, v[172:173]
	s_mov_b32 m0, s63
	s_nop 0
	global_load_lds_dwordx4 v[186:187], off
	v_lshl_add_u64 v[186:187], s[78:79], 0, v[176:177]
	s_add_i32 m0, s63, 0x2000
	s_nop 0
	global_load_lds_dwordx4 v[186:187], off
	v_lshl_add_u64 v[186:187], v[222:223], 0, s[22:23]
	s_mov_b32 m0, s95
	s_nop 0
	global_load_lds_dwordx4 v[186:187], off
	v_lshl_add_u64 v[186:187], v[224:225], 0, s[22:23]
	s_mov_b32 m0, s96
	s_nop 0
	global_load_lds_dwordx4 v[186:187], off
	s_waitcnt vmcnt(8)
	s_waitcnt lgkmcnt(0)
	s_setprio 1
	s_barrier
	v_mfma_f32_16x16x32_bf16 v[62:65], v[114:117], v[162:165], v[62:65]
	v_mfma_f32_16x16x32_bf16 v[58:61], v[122:125], v[162:165], v[58:61]
	v_mfma_f32_16x16x32_bf16 v[50:53], v[114:117], v[194:197], v[50:53]
	v_mfma_f32_16x16x32_bf16 v[42:45], v[122:125], v[194:197], v[42:45]
	v_mfma_f32_16x16x32_bf16 v[34:37], v[114:117], v[206:209], v[34:37]
	v_mfma_f32_16x16x32_bf16 v[26:29], v[122:125], v[206:209], v[26:29]
	v_mfma_f32_16x16x32_bf16 v[18:21], v[114:117], v[214:217], v[18:21]
	v_mfma_f32_16x16x32_bf16 v[10:13], v[122:125], v[214:217], v[10:13]
	v_mfma_f32_16x16x32_bf16 v[62:65], v[118:121], v[166:169], v[62:65]
	v_mfma_f32_16x16x32_bf16 v[58:61], v[126:129], v[166:169], v[58:61]
	v_mfma_f32_16x16x32_bf16 v[50:53], v[118:121], v[198:201], v[50:53]
	v_mfma_f32_16x16x32_bf16 v[42:45], v[126:129], v[198:201], v[42:45]
	v_mfma_f32_16x16x32_bf16 v[34:37], v[118:121], v[210:213], v[34:37]
	v_mfma_f32_16x16x32_bf16 v[26:29], v[126:129], v[210:213], v[26:29]
	v_mfma_f32_16x16x32_bf16 v[18:21], v[118:121], v[218:221], v[18:21]
	v_mfma_f32_16x16x32_bf16 v[10:13], v[126:129], v[218:221], v[10:13]
	v_mfma_f32_16x16x32_bf16 v[54:57], v[146:149], v[162:165], v[54:57]
	v_mfma_f32_16x16x32_bf16 v[46:49], v[154:157], v[162:165], v[46:49]
	v_mfma_f32_16x16x32_bf16 v[38:41], v[146:149], v[194:197], v[38:41]
	v_mfma_f32_16x16x32_bf16 v[30:33], v[154:157], v[194:197], v[30:33]
	v_mfma_f32_16x16x32_bf16 v[22:25], v[146:149], v[206:209], v[22:25]
	v_mfma_f32_16x16x32_bf16 v[14:17], v[154:157], v[206:209], v[14:17]
	v_mfma_f32_16x16x32_bf16 v[6:9], v[146:149], v[214:217], v[6:9]
	v_mfma_f32_16x16x32_bf16 v[2:5], v[154:157], v[214:217], v[2:5]
	v_mfma_f32_16x16x32_bf16 v[54:57], v[150:153], v[166:169], v[54:57]
	v_mfma_f32_16x16x32_bf16 v[46:49], v[158:161], v[166:169], v[46:49]
	v_mfma_f32_16x16x32_bf16 v[38:41], v[150:153], v[198:201], v[38:41]
	v_mfma_f32_16x16x32_bf16 v[30:33], v[158:161], v[198:201], v[30:33]
	v_mfma_f32_16x16x32_bf16 v[22:25], v[150:153], v[210:213], v[22:25]
	v_mfma_f32_16x16x32_bf16 v[14:17], v[158:161], v[210:213], v[14:17]
	v_mfma_f32_16x16x32_bf16 v[6:9], v[150:153], v[218:221], v[6:9]
	v_mfma_f32_16x16x32_bf16 v[2:5], v[158:161], v[218:221], v[2:5]
	s_barrier
	s_setprio 0
	s_add_u32 s76, s76, 0x100
	s_addc_u32 s77, s77, 0
	s_add_u32 s47, s47, 0x100
	s_addc_u32 s62, s62, 0
	s_cmp_ge_i32 s82, s7
	s_mov_b32 s63, s82
	s_cbranch_scc0 .LBB0_834
	s_and_b64 vcc, exec, s[26:27]
	s_cbranch_vccz .LBB0_837
	s_barrier

.LBB0_1012:
	s_add_u32 s48, s96, s44
	s_addc_u32 s49, s97, s45
	s_and_b64 s[14:15], s[4:5], exec
	s_cselect_b32 s6, s49, s65
	s_cselect_b32 s14, s48, s64
	s_add_u32 s50, s3, s46
	s_addc_u32 s51, s35, s47
	s_and_b64 s[18:19], s[4:5], exec
	s_cselect_b32 s15, s51, s67
	s_cselect_b32 s17, s50, s66
	s_add_u32 s64, s64, 0x40080
	s_addc_u32 s65, s65, 0
	s_add_u32 s18, s66, 0x100
	s_addc_u32 s19, s67, 0
	s_mov_b32 s24, -2
	s_waitcnt vmcnt(0)
	ds_read_b128 v[130:133], v172
	ds_read_b128 v[134:137], v172 offset:1024
	ds_read_b128 v[138:141], v172 offset:2048
	ds_read_b128 v[142:145], v172 offset:3072
	ds_read_b128 v[164:167], v173
	ds_read_b128 v[176:179], v173 offset:1024
	ds_read_b128 v[180:183], v173 offset:2048
	ds_read_b128 v[184:187], v173 offset:3072
	s_add_u32 s25, s64, 0xfffc0080
	s_addc_u32 s28, s65, -1
	s_cmp_eq_u32 s24, 12
	s_cselect_b32 s69, s6, s28
	s_cselect_b32 s68, s14, s25
	s_cselect_b32 s67, s15, s19
	s_cselect_b32 s66, s17, s18
	v_lshl_add_u64 v[168:169], s[64:65], 0, v[156:157]
	s_add_i32 m0, s73, 0xc000
	ds_read_b128 v[188:191], v174
	ds_read_b128 v[192:195], v174 offset:1024
	ds_read_b128 v[196:199], v174 offset:2048
	ds_read_b128 v[200:203], v174 offset:3072
	ds_read_b128 v[206:209], v174 offset:4096
	ds_read_b128 v[210:213], v174 offset:5120
	ds_read_b128 v[214:217], v174 offset:6144
	ds_read_b128 v[218:221], v174 offset:7168
	global_load_lds_dwordx4 v[168:169], off
	v_lshl_add_u64 v[168:169], s[64:65], 0, v[158:159]
	s_add_i32 m0, s73, 0xe000
	s_nop 0
	global_load_lds_dwordx4 v[168:169], off
	s_waitcnt vmcnt(8)
	s_waitcnt lgkmcnt(0)
	s_setprio 1
	s_barrier
	v_mfma_f32_16x16x32_bf16 v[126:129], v[130:133], v[188:191], 0
	v_mfma_f32_16x16x32_bf16 v[122:125], v[138:141], v[188:191], 0
	v_mfma_f32_16x16x32_bf16 v[110:113], v[130:133], v[196:199], 0
	v_mfma_f32_16x16x32_bf16 v[106:109], v[138:141], v[196:199], 0
	v_mfma_f32_16x16x32_bf16 v[94:97], v[130:133], v[206:209], 0
	v_mfma_f32_16x16x32_bf16 v[90:93], v[138:141], v[206:209], 0
	v_mfma_f32_16x16x32_bf16 v[78:81], v[130:133], v[214:217], 0
	v_mfma_f32_16x16x32_bf16 v[74:77], v[138:141], v[214:217], 0
	v_mfma_f32_16x16x32_bf16 v[126:129], v[134:137], v[192:195], v[126:129]
	v_mfma_f32_16x16x32_bf16 v[122:125], v[142:145], v[192:195], v[122:125]
	v_mfma_f32_16x16x32_bf16 v[110:113], v[134:137], v[200:203], v[110:113]
	v_mfma_f32_16x16x32_bf16 v[106:109], v[142:145], v[200:203], v[106:109]
	v_mfma_f32_16x16x32_bf16 v[94:97], v[134:137], v[210:213], v[94:97]
	v_mfma_f32_16x16x32_bf16 v[90:93], v[142:145], v[210:213], v[90:93]
	v_mfma_f32_16x16x32_bf16 v[78:81], v[134:137], v[218:221], v[78:81]
	v_mfma_f32_16x16x32_bf16 v[74:77], v[142:145], v[218:221], v[74:77]
	v_mfma_f32_16x16x32_bf16 v[118:121], v[164:167], v[188:191], 0
	v_mfma_f32_16x16x32_bf16 v[114:117], v[180:183], v[188:191], 0
	v_mfma_f32_16x16x32_bf16 v[102:105], v[164:167], v[196:199], 0
	v_mfma_f32_16x16x32_bf16 v[98:101], v[180:183], v[196:199], 0
	v_mfma_f32_16x16x32_bf16 v[86:89], v[164:167], v[206:209], 0
	v_mfma_f32_16x16x32_bf16 v[82:85], v[180:183], v[206:209], 0
	v_mfma_f32_16x16x32_bf16 v[70:73], v[164:167], v[214:217], 0
	v_mfma_f32_16x16x32_bf16 v[66:69], v[180:183], v[214:217], 0
	v_mfma_f32_16x16x32_bf16 v[118:121], v[176:179], v[192:195], v[118:121]
	v_mfma_f32_16x16x32_bf16 v[114:117], v[184:187], v[192:195], v[114:117]
	v_mfma_f32_16x16x32_bf16 v[102:105], v[176:179], v[200:203], v[102:105]
	v_mfma_f32_16x16x32_bf16 v[98:101], v[184:187], v[200:203], v[98:101]
	v_mfma_f32_16x16x32_bf16 v[86:89], v[176:179], v[210:213], v[86:89]
	v_mfma_f32_16x16x32_bf16 v[82:85], v[184:187], v[210:213], v[82:85]
	v_mfma_f32_16x16x32_bf16 v[70:73], v[176:179], v[218:221], v[70:73]
	v_mfma_f32_16x16x32_bf16 v[66:69], v[184:187], v[218:221], v[66:69]
	s_barrier
	s_setprio 0
	s_add_i32 s25, s82, s70
	v_lshl_add_u64 v[168:169], s[66:67], 0, v[150:151]
	s_mov_b32 m0, s25
	ds_read_b128 v[188:191], v174 offset:16384
	ds_read_b128 v[192:195], v174 offset:17408
	ds_read_b128 v[196:199], v174 offset:18432
	ds_read_b128 v[200:203], v174 offset:19456
	ds_read_b128 v[206:209], v174 offset:20480
	ds_read_b128 v[210:213], v174 offset:21504
	ds_read_b128 v[214:217], v174 offset:22528
	ds_read_b128 v[218:221], v174 offset:23552
	global_load_lds_dwordx4 v[168:169], off
	s_add_i32 m0, s25, 0x2000
	s_add_u32 s28, s66, 0x40000
	v_lshl_add_u64 v[222:223], s[66:67], 0, v[146:147]
	s_addc_u32 s29, s67, 0
	s_add_i32 s25, s83, s70
	global_load_lds_dwordx4 v[222:223], off
	v_lshl_add_u64 v[224:225], s[28:29], 0, v[150:151]
	s_mov_b32 m0, s25
	v_lshl_add_u64 v[226:227], s[68:69], 0, v[148:149]
	global_load_lds_dwordx4 v[224:225], off
	v_lshl_add_u64 v[224:225], s[28:29], 0, v[146:147]
	s_add_i32 m0, s25, 0x2000
	s_nop 0
	global_load_lds_dwordx4 v[224:225], off
	v_lshl_add_u64 v[224:225], s[68:69], 0, v[152:153]
	s_mov_b32 m0, s73
	s_nop 0
	global_load_lds_dwordx4 v[224:225], off
	s_mov_b32 m0, s74
	s_nop 0
	global_load_lds_dwordx4 v[226:227], off
	s_waitcnt vmcnt(8)
	s_waitcnt lgkmcnt(0)
	s_setprio 1
	s_barrier
	v_mfma_f32_16x16x32_bf16 v[62:65], v[130:133], v[188:191], 0
	v_mfma_f32_16x16x32_bf16 v[58:61], v[138:141], v[188:191], 0
	v_mfma_f32_16x16x32_bf16 v[46:49], v[130:133], v[196:199], 0
	v_mfma_f32_16x16x32_bf16 v[42:45], v[138:141], v[196:199], 0
	v_mfma_f32_16x16x32_bf16 v[30:33], v[130:133], v[206:209], 0
	v_mfma_f32_16x16x32_bf16 v[26:29], v[138:141], v[206:209], 0
	v_mfma_f32_16x16x32_bf16 v[14:17], v[130:133], v[214:217], 0
	v_mfma_f32_16x16x32_bf16 v[10:13], v[138:141], v[214:217], 0
	v_mfma_f32_16x16x32_bf16 v[62:65], v[134:137], v[192:195], v[62:65]
	v_mfma_f32_16x16x32_bf16 v[58:61], v[142:145], v[192:195], v[58:61]
	v_mfma_f32_16x16x32_bf16 v[46:49], v[134:137], v[200:203], v[46:49]
	v_mfma_f32_16x16x32_bf16 v[42:45], v[142:145], v[200:203], v[42:45]
	v_mfma_f32_16x16x32_bf16 v[30:33], v[134:137], v[210:213], v[30:33]
	v_mfma_f32_16x16x32_bf16 v[26:29], v[142:145], v[210:213], v[26:29]
	v_mfma_f32_16x16x32_bf16 v[14:17], v[134:137], v[218:221], v[14:17]
	v_mfma_f32_16x16x32_bf16 v[10:13], v[142:145], v[218:221], v[10:13]
	v_mfma_f32_16x16x32_bf16 v[54:57], v[164:167], v[188:191], 0
	v_mfma_f32_16x16x32_bf16 v[50:53], v[180:183], v[188:191], 0
	v_mfma_f32_16x16x32_bf16 v[38:41], v[164:167], v[196:199], 0
	v_mfma_f32_16x16x32_bf16 v[34:37], v[180:183], v[196:199], 0
	v_mfma_f32_16x16x32_bf16 v[22:25], v[164:167], v[206:209], 0
	v_mfma_f32_16x16x32_bf16 v[18:21], v[180:183], v[206:209], 0
	v_mfma_f32_16x16x32_bf16 v[6:9], v[164:167], v[214:217], 0
	v_mfma_f32_16x16x32_bf16 v[2:5], v[180:183], v[214:217], 0
	v_mfma_f32_16x16x32_bf16 v[54:57], v[176:179], v[192:195], v[54:57]
	v_mfma_f32_16x16x32_bf16 v[50:53], v[184:187], v[192:195], v[50:53]
	v_mfma_f32_16x16x32_bf16 v[38:41], v[176:179], v[200:203], v[38:41]
	v_mfma_f32_16x16x32_bf16 v[34:37], v[184:187], v[200:203], v[34:37]
	v_mfma_f32_16x16x32_bf16 v[22:25], v[176:179], v[210:213], v[22:25]
	v_mfma_f32_16x16x32_bf16 v[18:21], v[184:187], v[210:213], v[18:21]
	v_mfma_f32_16x16x32_bf16 v[6:9], v[176:179], v[218:221], v[6:9]
	v_mfma_f32_16x16x32_bf16 v[2:5], v[184:187], v[218:221], v[2:5]
	s_barrier
	s_setprio 0
	s_add_i32 s25, 0, 0x18000
	s_add_i32 s30, 0, 0x1c000
	v_add_u32_e32 v142, s25, v171
	v_add_u32_e32 v175, s30, v171
	ds_read_b128 v[130:133], v142
	ds_read_b128 v[134:137], v142 offset:1024
	ds_read_b128 v[138:141], v142 offset:2048
	ds_read_b128 v[142:145], v142 offset:3072
	ds_read_b128 v[164:167], v175
	ds_read_b128 v[176:179], v175 offset:1024
	ds_read_b128 v[180:183], v175 offset:2048
	ds_read_b128 v[184:187], v175 offset:3072
	s_add_u32 s28, s68, 0x40000
	s_addc_u32 s29, s69, 0
	s_mov_b32 m0, s75
	v_lshl_add_u64 v[228:229], s[28:29], 0, v[152:153]
	ds_read_b128 v[188:191], v174 offset:32768
	ds_read_b128 v[192:195], v174 offset:33792
	ds_read_b128 v[196:199], v174 offset:34816
	ds_read_b128 v[200:203], v174 offset:35840
	ds_read_b128 v[206:209], v174 offset:36864
	ds_read_b128 v[210:213], v174 offset:37888
	ds_read_b128 v[214:217], v174 offset:38912
	ds_read_b128 v[218:221], v174 offset:39936
	global_load_lds_dwordx4 v[228:229], off
	v_lshl_add_u64 v[228:229], s[28:29], 0, v[148:149]
	s_mov_b32 m0, s76
	s_nop 0
	global_load_lds_dwordx4 v[228:229], off
	s_waitcnt vmcnt(8)
	s_waitcnt lgkmcnt(0)
	s_setprio 1
	s_barrier
	v_mfma_f32_16x16x32_bf16 v[126:129], v[130:133], v[188:191], v[126:129]
	v_mfma_f32_16x16x32_bf16 v[122:125], v[138:141], v[188:191], v[122:125]
	v_mfma_f32_16x16x32_bf16 v[110:113], v[130:133], v[196:199], v[110:113]
	v_mfma_f32_16x16x32_bf16 v[106:109], v[138:141], v[196:199], v[106:109]
	v_mfma_f32_16x16x32_bf16 v[94:97], v[130:133], v[206:209], v[94:97]
	v_mfma_f32_16x16x32_bf16 v[90:93], v[138:141], v[206:209], v[90:93]
	v_mfma_f32_16x16x32_bf16 v[78:81], v[130:133], v[214:217], v[78:81]
	v_mfma_f32_16x16x32_bf16 v[74:77], v[138:141], v[214:217], v[74:77]
	v_mfma_f32_16x16x32_bf16 v[126:129], v[134:137], v[192:195], v[126:129]
	v_mfma_f32_16x16x32_bf16 v[122:125], v[142:145], v[192:195], v[122:125]
	v_mfma_f32_16x16x32_bf16 v[110:113], v[134:137], v[200:203], v[110:113]
	v_mfma_f32_16x16x32_bf16 v[106:109], v[142:145], v[200:203], v[106:109]
	v_mfma_f32_16x16x32_bf16 v[94:97], v[134:137], v[210:213], v[94:97]
	v_mfma_f32_16x16x32_bf16 v[90:93], v[142:145], v[210:213], v[90:93]
	v_mfma_f32_16x16x32_bf16 v[78:81], v[134:137], v[218:221], v[78:81]
	v_mfma_f32_16x16x32_bf16 v[74:77], v[142:145], v[218:221], v[74:77]
	v_mfma_f32_16x16x32_bf16 v[118:121], v[164:167], v[188:191], v[118:121]
	v_mfma_f32_16x16x32_bf16 v[114:117], v[180:183], v[188:191], v[114:117]
	v_mfma_f32_16x16x32_bf16 v[102:105], v[164:167], v[196:199], v[102:105]
	v_mfma_f32_16x16x32_bf16 v[98:101], v[180:183], v[196:199], v[98:101]
	v_mfma_f32_16x16x32_bf16 v[86:89], v[164:167], v[206:209], v[86:89]
	v_mfma_f32_16x16x32_bf16 v[82:85], v[180:183], v[206:209], v[82:85]
	v_mfma_f32_16x16x32_bf16 v[70:73], v[164:167], v[214:217], v[70:73]
	v_mfma_f32_16x16x32_bf16 v[66:69], v[180:183], v[214:217], v[66:69]
	v_mfma_f32_16x16x32_bf16 v[118:121], v[176:179], v[192:195], v[118:121]
	v_mfma_f32_16x16x32_bf16 v[114:117], v[184:187], v[192:195], v[114:117]
	v_mfma_f32_16x16x32_bf16 v[102:105], v[176:179], v[200:203], v[102:105]
	v_mfma_f32_16x16x32_bf16 v[98:101], v[184:187], v[200:203], v[98:101]
	v_mfma_f32_16x16x32_bf16 v[86:89], v[176:179], v[210:213], v[86:89]
	v_mfma_f32_16x16x32_bf16 v[82:85], v[184:187], v[210:213], v[82:85]
	v_mfma_f32_16x16x32_bf16 v[70:73], v[176:179], v[218:221], v[70:73]
	v_mfma_f32_16x16x32_bf16 v[66:69], v[184:187], v[218:221], v[66:69]
	s_barrier
	s_setprio 0
	s_add_i32 s25, s25, s70
	v_lshl_add_u64 v[168:169], v[168:169], 0, s[36:37]
	s_mov_b32 m0, s25
	ds_read_b128 v[188:191], v174 offset:49152
	ds_read_b128 v[192:195], v174 offset:50176
	ds_read_b128 v[196:199], v174 offset:51200
	ds_read_b128 v[200:203], v174 offset:52224
	ds_read_b128 v[206:209], v174 offset:53248
	ds_read_b128 v[210:213], v174 offset:54272
	ds_read_b128 v[214:217], v174 offset:55296
	ds_read_b128 v[218:221], v174 offset:56320
	global_load_lds_dwordx4 v[168:169], off
	s_add_i32 m0, s25, 0x2000
	s_add_u32 s28, s66, 0x40080
	v_lshl_add_u64 v[168:169], v[222:223], 0, s[36:37]
	s_addc_u32 s29, s67, 0
	s_add_i32 s25, s30, s70
	global_load_lds_dwordx4 v[168:169], off
	v_lshl_add_u64 v[168:169], s[28:29], 0, v[150:151]
	s_mov_b32 m0, s25
	s_nop 0
	global_load_lds_dwordx4 v[168:169], off
	v_lshl_add_u64 v[168:169], s[28:29], 0, v[146:147]
	s_add_i32 m0, s25, 0x2000
	s_nop 0
	global_load_lds_dwordx4 v[168:169], off
	v_lshl_add_u64 v[168:169], v[224:225], 0, s[36:37]
	s_mov_b32 m0, s79
	s_nop 0
	global_load_lds_dwordx4 v[168:169], off
	v_lshl_add_u64 v[168:169], v[226:227], 0, s[36:37]
	s_mov_b32 m0, s80
	s_nop 0
	global_load_lds_dwordx4 v[168:169], off
	s_waitcnt vmcnt(8)
	s_waitcnt lgkmcnt(0)
	s_setprio 1
	s_barrier
	v_mfma_f32_16x16x32_bf16 v[62:65], v[130:133], v[188:191], v[62:65]
	v_mfma_f32_16x16x32_bf16 v[58:61], v[138:141], v[188:191], v[58:61]
	v_mfma_f32_16x16x32_bf16 v[46:49], v[130:133], v[196:199], v[46:49]
	v_mfma_f32_16x16x32_bf16 v[42:45], v[138:141], v[196:199], v[42:45]
	v_mfma_f32_16x16x32_bf16 v[30:33], v[130:133], v[206:209], v[30:33]
	v_mfma_f32_16x16x32_bf16 v[26:29], v[138:141], v[206:209], v[26:29]
	v_mfma_f32_16x16x32_bf16 v[14:17], v[130:133], v[214:217], v[14:17]
	v_mfma_f32_16x16x32_bf16 v[10:13], v[138:141], v[214:217], v[10:13]
	v_mfma_f32_16x16x32_bf16 v[62:65], v[134:137], v[192:195], v[62:65]
	v_mfma_f32_16x16x32_bf16 v[58:61], v[142:145], v[192:195], v[58:61]
	v_mfma_f32_16x16x32_bf16 v[46:49], v[134:137], v[200:203], v[46:49]
	v_mfma_f32_16x16x32_bf16 v[42:45], v[142:145], v[200:203], v[42:45]
	v_mfma_f32_16x16x32_bf16 v[30:33], v[134:137], v[210:213], v[30:33]
	v_mfma_f32_16x16x32_bf16 v[26:29], v[142:145], v[210:213], v[26:29]
	v_mfma_f32_16x16x32_bf16 v[14:17], v[134:137], v[218:221], v[14:17]
	v_mfma_f32_16x16x32_bf16 v[10:13], v[142:145], v[218:221], v[10:13]
	v_mfma_f32_16x16x32_bf16 v[54:57], v[164:167], v[188:191], v[54:57]
	v_mfma_f32_16x16x32_bf16 v[50:53], v[180:183], v[188:191], v[50:53]
	v_mfma_f32_16x16x32_bf16 v[38:41], v[164:167], v[196:199], v[38:41]
	v_mfma_f32_16x16x32_bf16 v[34:37], v[180:183], v[196:199], v[34:37]
	v_mfma_f32_16x16x32_bf16 v[22:25], v[164:167], v[206:209], v[22:25]
	v_mfma_f32_16x16x32_bf16 v[18:21], v[180:183], v[206:209], v[18:21]
	v_mfma_f32_16x16x32_bf16 v[6:9], v[164:167], v[214:217], v[6:9]
	v_mfma_f32_16x16x32_bf16 v[2:5], v[180:183], v[214:217], v[2:5]
	v_mfma_f32_16x16x32_bf16 v[54:57], v[176:179], v[192:195], v[54:57]
	v_mfma_f32_16x16x32_bf16 v[50:53], v[184:187], v[192:195], v[50:53]
	v_mfma_f32_16x16x32_bf16 v[38:41], v[176:179], v[200:203], v[38:41]
	v_mfma_f32_16x16x32_bf16 v[34:37], v[184:187], v[200:203], v[34:37]
	v_mfma_f32_16x16x32_bf16 v[22:25], v[176:179], v[210:213], v[22:25]
	v_mfma_f32_16x16x32_bf16 v[18:21], v[184:187], v[210:213], v[18:21]
	v_mfma_f32_16x16x32_bf16 v[6:9], v[176:179], v[218:221], v[6:9]
	v_mfma_f32_16x16x32_bf16 v[2:5], v[184:187], v[218:221], v[2:5]
	s_barrier
	s_setprio 0
	s_add_i32 s24, s24, 2
	s_add_u32 s64, s64, 0x100
	s_addc_u32 s65, s65, 0
	s_add_u32 s18, s18, 0x100
	s_addc_u32 s19, s19, 0
	s_cmp_gt_u32 s24, 13
.LBB0_1013:
	ds_read_b128 v[130:133], v172
	ds_read_b128 v[134:137], v172 offset:1024
	ds_read_b128 v[138:141], v172 offset:2048
	ds_read_b128 v[142:145], v172 offset:3072
	ds_read_b128 v[164:167], v173
	ds_read_b128 v[176:179], v173 offset:1024
	ds_read_b128 v[180:183], v173 offset:2048
	ds_read_b128 v[184:187], v173 offset:3072
	s_add_u32 s25, s64, 0xfffc0080
	s_addc_u32 s28, s65, -1
	s_cmp_eq_u32 s24, 12
	s_cselect_b32 s69, s6, s28
	s_cselect_b32 s68, s14, s25
	s_cselect_b32 s67, s15, s19
	s_cselect_b32 s66, s17, s18
	v_lshl_add_u64 v[168:169], s[64:65], 0, v[156:157]
	s_add_i32 m0, s73, 0xc000
	ds_read_b128 v[188:191], v174
	ds_read_b128 v[192:195], v174 offset:1024
	ds_read_b128 v[196:199], v174 offset:2048
	ds_read_b128 v[200:203], v174 offset:3072
	ds_read_b128 v[206:209], v174 offset:4096
	ds_read_b128 v[210:213], v174 offset:5120
	ds_read_b128 v[214:217], v174 offset:6144
	ds_read_b128 v[218:221], v174 offset:7168
	global_load_lds_dwordx4 v[168:169], off
	v_lshl_add_u64 v[168:169], s[64:65], 0, v[158:159]
	s_add_i32 m0, s73, 0xe000
	s_nop 0
	global_load_lds_dwordx4 v[168:169], off
	s_waitcnt vmcnt(8)
	s_waitcnt lgkmcnt(0)
	s_setprio 1
	s_barrier
	v_mfma_f32_16x16x32_bf16 v[126:129], v[130:133], v[188:191], v[126:129]
	v_mfma_f32_16x16x32_bf16 v[122:125], v[138:141], v[188:191], v[122:125]
	v_mfma_f32_16x16x32_bf16 v[110:113], v[130:133], v[196:199], v[110:113]
	v_mfma_f32_16x16x32_bf16 v[106:109], v[138:141], v[196:199], v[106:109]
	v_mfma_f32_16x16x32_bf16 v[94:97], v[130:133], v[206:209], v[94:97]
	v_mfma_f32_16x16x32_bf16 v[90:93], v[138:141], v[206:209], v[90:93]
	v_mfma_f32_16x16x32_bf16 v[78:81], v[130:133], v[214:217], v[78:81]
	v_mfma_f32_16x16x32_bf16 v[74:77], v[138:141], v[214:217], v[74:77]
	v_mfma_f32_16x16x32_bf16 v[126:129], v[134:137], v[192:195], v[126:129]
	v_mfma_f32_16x16x32_bf16 v[122:125], v[142:145], v[192:195], v[122:125]
	v_mfma_f32_16x16x32_bf16 v[110:113], v[134:137], v[200:203], v[110:113]
	v_mfma_f32_16x16x32_bf16 v[106:109], v[142:145], v[200:203], v[106:109]
	v_mfma_f32_16x16x32_bf16 v[94:97], v[134:137], v[210:213], v[94:97]
	v_mfma_f32_16x16x32_bf16 v[90:93], v[142:145], v[210:213], v[90:93]
	v_mfma_f32_16x16x32_bf16 v[78:81], v[134:137], v[218:221], v[78:81]
	v_mfma_f32_16x16x32_bf16 v[74:77], v[142:145], v[218:221], v[74:77]
	v_mfma_f32_16x16x32_bf16 v[118:121], v[164:167], v[188:191], v[118:121]
	v_mfma_f32_16x16x32_bf16 v[114:117], v[180:183], v[188:191], v[114:117]
	v_mfma_f32_16x16x32_bf16 v[102:105], v[164:167], v[196:199], v[102:105]
	v_mfma_f32_16x16x32_bf16 v[98:101], v[180:183], v[196:199], v[98:101]
	v_mfma_f32_16x16x32_bf16 v[86:89], v[164:167], v[206:209], v[86:89]
	v_mfma_f32_16x16x32_bf16 v[82:85], v[180:183], v[206:209], v[82:85]
	v_mfma_f32_16x16x32_bf16 v[70:73], v[164:167], v[214:217], v[70:73]
	v_mfma_f32_16x16x32_bf16 v[66:69], v[180:183], v[214:217], v[66:69]
	v_mfma_f32_16x16x32_bf16 v[118:121], v[176:179], v[192:195], v[118:121]
	v_mfma_f32_16x16x32_bf16 v[114:117], v[184:187], v[192:195], v[114:117]
	v_mfma_f32_16x16x32_bf16 v[102:105], v[176:179], v[200:203], v[102:105]
	v_mfma_f32_16x16x32_bf16 v[98:101], v[184:187], v[200:203], v[98:101]
	v_mfma_f32_16x16x32_bf16 v[86:89], v[176:179], v[210:213], v[86:89]
	v_mfma_f32_16x16x32_bf16 v[82:85], v[184:187], v[210:213], v[82:85]
	v_mfma_f32_16x16x32_bf16 v[70:73], v[176:179], v[218:221], v[70:73]
	v_mfma_f32_16x16x32_bf16 v[66:69], v[184:187], v[218:221], v[66:69]
	s_barrier
	s_setprio 0
	s_add_i32 s25, s82, s70
	v_lshl_add_u64 v[168:169], s[66:67], 0, v[150:151]
	s_mov_b32 m0, s25
	ds_read_b128 v[188:191], v174 offset:16384
	ds_read_b128 v[192:195], v174 offset:17408
	ds_read_b128 v[196:199], v174 offset:18432
	ds_read_b128 v[200:203], v174 offset:19456
	ds_read_b128 v[206:209], v174 offset:20480
	ds_read_b128 v[210:213], v174 offset:21504
	ds_read_b128 v[214:217], v174 offset:22528
	ds_read_b128 v[218:221], v174 offset:23552
	global_load_lds_dwordx4 v[168:169], off
	s_add_i32 m0, s25, 0x2000
	s_add_u32 s28, s66, 0x40000
	v_lshl_add_u64 v[222:223], s[66:67], 0, v[146:147]
	s_addc_u32 s29, s67, 0
	s_add_i32 s25, s83, s70
	global_load_lds_dwordx4 v[222:223], off
	v_lshl_add_u64 v[224:225], s[28:29], 0, v[150:151]
	s_mov_b32 m0, s25
	v_lshl_add_u64 v[226:227], s[68:69], 0, v[148:149]
	global_load_lds_dwordx4 v[224:225], off
	v_lshl_add_u64 v[224:225], s[28:29], 0, v[146:147]
	s_add_i32 m0, s25, 0x2000
	s_nop 0
	global_load_lds_dwordx4 v[224:225], off
	v_lshl_add_u64 v[224:225], s[68:69], 0, v[152:153]
	s_mov_b32 m0, s73
	s_nop 0
	global_load_lds_dwordx4 v[224:225], off
	s_mov_b32 m0, s74
	s_nop 0
	global_load_lds_dwordx4 v[226:227], off
	s_waitcnt vmcnt(8)
	s_waitcnt lgkmcnt(0)
	s_setprio 1
	s_barrier
	v_mfma_f32_16x16x32_bf16 v[62:65], v[130:133], v[188:191], v[62:65]
	v_mfma_f32_16x16x32_bf16 v[58:61], v[138:141], v[188:191], v[58:61]
	v_mfma_f32_16x16x32_bf16 v[46:49], v[130:133], v[196:199], v[46:49]
	v_mfma_f32_16x16x32_bf16 v[42:45], v[138:141], v[196:199], v[42:45]
	v_mfma_f32_16x16x32_bf16 v[30:33], v[130:133], v[206:209], v[30:33]
	v_mfma_f32_16x16x32_bf16 v[26:29], v[138:141], v[206:209], v[26:29]
	v_mfma_f32_16x16x32_bf16 v[14:17], v[130:133], v[214:217], v[14:17]
	v_mfma_f32_16x16x32_bf16 v[10:13], v[138:141], v[214:217], v[10:13]
	v_mfma_f32_16x16x32_bf16 v[62:65], v[134:137], v[192:195], v[62:65]
	v_mfma_f32_16x16x32_bf16 v[58:61], v[142:145], v[192:195], v[58:61]
	v_mfma_f32_16x16x32_bf16 v[46:49], v[134:137], v[200:203], v[46:49]
	v_mfma_f32_16x16x32_bf16 v[42:45], v[142:145], v[200:203], v[42:45]
	v_mfma_f32_16x16x32_bf16 v[30:33], v[134:137], v[210:213], v[30:33]
	v_mfma_f32_16x16x32_bf16 v[26:29], v[142:145], v[210:213], v[26:29]
	v_mfma_f32_16x16x32_bf16 v[14:17], v[134:137], v[218:221], v[14:17]
	v_mfma_f32_16x16x32_bf16 v[10:13], v[142:145], v[218:221], v[10:13]
	v_mfma_f32_16x16x32_bf16 v[54:57], v[164:167], v[188:191], v[54:57]
	v_mfma_f32_16x16x32_bf16 v[50:53], v[180:183], v[188:191], v[50:53]
	v_mfma_f32_16x16x32_bf16 v[38:41], v[164:167], v[196:199], v[38:41]
	v_mfma_f32_16x16x32_bf16 v[34:37], v[180:183], v[196:199], v[34:37]
	v_mfma_f32_16x16x32_bf16 v[22:25], v[164:167], v[206:209], v[22:25]
	v_mfma_f32_16x16x32_bf16 v[18:21], v[180:183], v[206:209], v[18:21]
	v_mfma_f32_16x16x32_bf16 v[6:9], v[164:167], v[214:217], v[6:9]
	v_mfma_f32_16x16x32_bf16 v[2:5], v[180:183], v[214:217], v[2:5]
	v_mfma_f32_16x16x32_bf16 v[54:57], v[176:179], v[192:195], v[54:57]
	v_mfma_f32_16x16x32_bf16 v[50:53], v[184:187], v[192:195], v[50:53]
	v_mfma_f32_16x16x32_bf16 v[38:41], v[176:179], v[200:203], v[38:41]
	v_mfma_f32_16x16x32_bf16 v[34:37], v[184:187], v[200:203], v[34:37]
	v_mfma_f32_16x16x32_bf16 v[22:25], v[176:179], v[210:213], v[22:25]
	v_mfma_f32_16x16x32_bf16 v[18:21], v[184:187], v[210:213], v[18:21]
	v_mfma_f32_16x16x32_bf16 v[6:9], v[176:179], v[218:221], v[6:9]
	v_mfma_f32_16x16x32_bf16 v[2:5], v[184:187], v[218:221], v[2:5]
	s_barrier
	s_setprio 0
	s_add_i32 s25, 0, 0x18000
	s_add_i32 s30, 0, 0x1c000
	v_add_u32_e32 v142, s25, v171
	v_add_u32_e32 v175, s30, v171
	ds_read_b128 v[130:133], v142
	ds_read_b128 v[134:137], v142 offset:1024
	ds_read_b128 v[138:141], v142 offset:2048
	ds_read_b128 v[142:145], v142 offset:3072
	ds_read_b128 v[164:167], v175
	ds_read_b128 v[176:179], v175 offset:1024
	ds_read_b128 v[180:183], v175 offset:2048
	ds_read_b128 v[184:187], v175 offset:3072
	s_add_u32 s28, s68, 0x40000
	s_addc_u32 s29, s69, 0
	s_mov_b32 m0, s75
	v_lshl_add_u64 v[228:229], s[28:29], 0, v[152:153]
	ds_read_b128 v[188:191], v174 offset:32768
	ds_read_b128 v[192:195], v174 offset:33792
	ds_read_b128 v[196:199], v174 offset:34816
	ds_read_b128 v[200:203], v174 offset:35840
	ds_read_b128 v[206:209], v174 offset:36864
	ds_read_b128 v[210:213], v174 offset:37888
	ds_read_b128 v[214:217], v174 offset:38912
	ds_read_b128 v[218:221], v174 offset:39936
	global_load_lds_dwordx4 v[228:229], off
	v_lshl_add_u64 v[228:229], s[28:29], 0, v[148:149]
	s_mov_b32 m0, s76
	s_nop 0
	global_load_lds_dwordx4 v[228:229], off
	s_waitcnt vmcnt(8)
	s_waitcnt lgkmcnt(0)
	s_setprio 1
	s_barrier
	v_mfma_f32_16x16x32_bf16 v[126:129], v[130:133], v[188:191], v[126:129]
	v_mfma_f32_16x16x32_bf16 v[122:125], v[138:141], v[188:191], v[122:125]
	v_mfma_f32_16x16x32_bf16 v[110:113], v[130:133], v[196:199], v[110:113]
	v_mfma_f32_16x16x32_bf16 v[106:109], v[138:141], v[196:199], v[106:109]
	v_mfma_f32_16x16x32_bf16 v[94:97], v[130:133], v[206:209], v[94:97]
	v_mfma_f32_16x16x32_bf16 v[90:93], v[138:141], v[206:209], v[90:93]
	v_mfma_f32_16x16x32_bf16 v[78:81], v[130:133], v[214:217], v[78:81]
	v_mfma_f32_16x16x32_bf16 v[74:77], v[138:141], v[214:217], v[74:77]
	v_mfma_f32_16x16x32_bf16 v[126:129], v[134:137], v[192:195], v[126:129]
	v_mfma_f32_16x16x32_bf16 v[122:125], v[142:145], v[192:195], v[122:125]
	v_mfma_f32_16x16x32_bf16 v[110:113], v[134:137], v[200:203], v[110:113]
	v_mfma_f32_16x16x32_bf16 v[106:109], v[142:145], v[200:203], v[106:109]
	v_mfma_f32_16x16x32_bf16 v[94:97], v[134:137], v[210:213], v[94:97]
	v_mfma_f32_16x16x32_bf16 v[90:93], v[142:145], v[210:213], v[90:93]
	v_mfma_f32_16x16x32_bf16 v[78:81], v[134:137], v[218:221], v[78:81]
	v_mfma_f32_16x16x32_bf16 v[74:77], v[142:145], v[218:221], v[74:77]
	v_mfma_f32_16x16x32_bf16 v[118:121], v[164:167], v[188:191], v[118:121]
	v_mfma_f32_16x16x32_bf16 v[114:117], v[180:183], v[188:191], v[114:117]
	v_mfma_f32_16x16x32_bf16 v[102:105], v[164:167], v[196:199], v[102:105]
	v_mfma_f32_16x16x32_bf16 v[98:101], v[180:183], v[196:199], v[98:101]
	v_mfma_f32_16x16x32_bf16 v[86:89], v[164:167], v[206:209], v[86:89]
	v_mfma_f32_16x16x32_bf16 v[82:85], v[180:183], v[206:209], v[82:85]
	v_mfma_f32_16x16x32_bf16 v[70:73], v[164:167], v[214:217], v[70:73]
	v_mfma_f32_16x16x32_bf16 v[66:69], v[180:183], v[214:217], v[66:69]
	v_mfma_f32_16x16x32_bf16 v[118:121], v[176:179], v[192:195], v[118:121]
	v_mfma_f32_16x16x32_bf16 v[114:117], v[184:187], v[192:195], v[114:117]
	v_mfma_f32_16x16x32_bf16 v[102:105], v[176:179], v[200:203], v[102:105]
	v_mfma_f32_16x16x32_bf16 v[98:101], v[184:187], v[200:203], v[98:101]
	v_mfma_f32_16x16x32_bf16 v[86:89], v[176:179], v[210:213], v[86:89]
	v_mfma_f32_16x16x32_bf16 v[82:85], v[184:187], v[210:213], v[82:85]
	v_mfma_f32_16x16x32_bf16 v[70:73], v[176:179], v[218:221], v[70:73]
	v_mfma_f32_16x16x32_bf16 v[66:69], v[184:187], v[218:221], v[66:69]
	s_barrier
	s_setprio 0
	s_add_i32 s25, s25, s70
	v_lshl_add_u64 v[168:169], v[168:169], 0, s[36:37]
	s_mov_b32 m0, s25
	ds_read_b128 v[188:191], v174 offset:49152
	ds_read_b128 v[192:195], v174 offset:50176
	ds_read_b128 v[196:199], v174 offset:51200
	ds_read_b128 v[200:203], v174 offset:52224
	ds_read_b128 v[206:209], v174 offset:53248
	ds_read_b128 v[210:213], v174 offset:54272
	ds_read_b128 v[214:217], v174 offset:55296
	ds_read_b128 v[218:221], v174 offset:56320
	global_load_lds_dwordx4 v[168:169], off
	s_add_i32 m0, s25, 0x2000
	s_add_u32 s28, s66, 0x40080
	v_lshl_add_u64 v[168:169], v[222:223], 0, s[36:37]
	s_addc_u32 s29, s67, 0
	s_add_i32 s25, s30, s70
	global_load_lds_dwordx4 v[168:169], off
	v_lshl_add_u64 v[168:169], s[28:29], 0, v[150:151]
	s_mov_b32 m0, s25
	s_nop 0
	global_load_lds_dwordx4 v[168:169], off
	v_lshl_add_u64 v[168:169], s[28:29], 0, v[146:147]
	s_add_i32 m0, s25, 0x2000
	s_nop 0
	global_load_lds_dwordx4 v[168:169], off
	v_lshl_add_u64 v[168:169], v[224:225], 0, s[36:37]
	s_mov_b32 m0, s79
	s_nop 0
	global_load_lds_dwordx4 v[168:169], off
	v_lshl_add_u64 v[168:169], v[226:227], 0, s[36:37]
	s_mov_b32 m0, s80
	s_nop 0
	global_load_lds_dwordx4 v[168:169], off
	s_waitcnt vmcnt(8)
	s_waitcnt lgkmcnt(0)
	s_setprio 1
	s_barrier
	v_mfma_f32_16x16x32_bf16 v[62:65], v[130:133], v[188:191], v[62:65]
	v_mfma_f32_16x16x32_bf16 v[58:61], v[138:141], v[188:191], v[58:61]
	v_mfma_f32_16x16x32_bf16 v[46:49], v[130:133], v[196:199], v[46:49]
	v_mfma_f32_16x16x32_bf16 v[42:45], v[138:141], v[196:199], v[42:45]
	v_mfma_f32_16x16x32_bf16 v[30:33], v[130:133], v[206:209], v[30:33]
	v_mfma_f32_16x16x32_bf16 v[26:29], v[138:141], v[206:209], v[26:29]
	v_mfma_f32_16x16x32_bf16 v[14:17], v[130:133], v[214:217], v[14:17]
	v_mfma_f32_16x16x32_bf16 v[10:13], v[138:141], v[214:217], v[10:13]
	v_mfma_f32_16x16x32_bf16 v[62:65], v[134:137], v[192:195], v[62:65]
	v_mfma_f32_16x16x32_bf16 v[58:61], v[142:145], v[192:195], v[58:61]
	v_mfma_f32_16x16x32_bf16 v[46:49], v[134:137], v[200:203], v[46:49]
	v_mfma_f32_16x16x32_bf16 v[42:45], v[142:145], v[200:203], v[42:45]
	v_mfma_f32_16x16x32_bf16 v[30:33], v[134:137], v[210:213], v[30:33]
	v_mfma_f32_16x16x32_bf16 v[26:29], v[142:145], v[210:213], v[26:29]
	v_mfma_f32_16x16x32_bf16 v[14:17], v[134:137], v[218:221], v[14:17]
	v_mfma_f32_16x16x32_bf16 v[10:13], v[142:145], v[218:221], v[10:13]
	v_mfma_f32_16x16x32_bf16 v[54:57], v[164:167], v[188:191], v[54:57]
	v_mfma_f32_16x16x32_bf16 v[50:53], v[180:183], v[188:191], v[50:53]
	v_mfma_f32_16x16x32_bf16 v[38:41], v[164:167], v[196:199], v[38:41]
	v_mfma_f32_16x16x32_bf16 v[34:37], v[180:183], v[196:199], v[34:37]
	v_mfma_f32_16x16x32_bf16 v[22:25], v[164:167], v[206:209], v[22:25]
	v_mfma_f32_16x16x32_bf16 v[18:21], v[180:183], v[206:209], v[18:21]
	v_mfma_f32_16x16x32_bf16 v[6:9], v[164:167], v[214:217], v[6:9]
	v_mfma_f32_16x16x32_bf16 v[2:5], v[180:183], v[214:217], v[2:5]
	v_mfma_f32_16x16x32_bf16 v[54:57], v[176:179], v[192:195], v[54:57]
	v_mfma_f32_16x16x32_bf16 v[50:53], v[184:187], v[192:195], v[50:53]
	v_mfma_f32_16x16x32_bf16 v[38:41], v[176:179], v[200:203], v[38:41]
	v_mfma_f32_16x16x32_bf16 v[34:37], v[184:187], v[200:203], v[34:37]
	v_mfma_f32_16x16x32_bf16 v[22:25], v[176:179], v[210:213], v[22:25]
	v_mfma_f32_16x16x32_bf16 v[18:21], v[184:187], v[210:213], v[18:21]
	v_mfma_f32_16x16x32_bf16 v[6:9], v[176:179], v[218:221], v[6:9]
	v_mfma_f32_16x16x32_bf16 v[2:5], v[184:187], v[218:221], v[2:5]
	s_barrier
	s_setprio 0
	s_add_i32 s24, s24, 2
	s_add_u32 s64, s64, 0x100
	s_addc_u32 s65, s65, 0
	s_add_u32 s18, s18, 0x100
	s_addc_u32 s19, s19, 0
	s_cmp_gt_u32 s24, 13
	s_cbranch_scc0 .LBB0_1013
	s_and_b64 vcc, exec, s[38:39]
	s_cbranch_vccz .LBB0_1016
	s_barrier

.LBB0_1427:
	s_add_u32 s90, s35, s86
	s_addc_u32 s91, s64, s87
	s_and_b64 s[14:15], s[88:89], exec
	s_cselect_b32 s14, s91, s11
	s_cselect_b32 s15, s90, s10
	s_add_u32 s92, s65, s74
	s_addc_u32 s93, s68, s75
	s_and_b64 s[66:67], s[88:89], exec
	s_cselect_b32 s51, s93, s95
	s_cselect_b32 s84, s92, s94
	s_add_i32 s85, s18, -2
	s_add_u32 s10, s10, 0x40080
	s_addc_u32 s11, s11, 0
	s_add_u32 vcc_lo, s94, 0x100
	s_addc_u32 vcc_hi, s95, 0
	s_mov_b32 s94, 0
	s_waitcnt vmcnt(0)
	s_add_i32 s66, s94, 2
	s_add_u32 s67, s10, 0xfffc0080
	s_addc_u32 s72, s11, -1
	s_cmp_eq_u32 s85, s94
	s_cselect_b32 s97, s14, s72
	s_cselect_b32 s96, s15, s67
	s_cselect_b32 s95, s51, vcc_hi
	s_cselect_b32 s94, s84, vcc_lo
	s_add_i32 s67, 0, 0x10000
	s_add_i32 s62, 0, 0x14000
	v_add_u32_e32 v126, s67, v199
	v_add_u32_e32 v158, s62, v199
	ds_read_b128 v[114:117], v126
	ds_read_b128 v[118:121], v126 offset:1024
	ds_read_b128 v[122:125], v126 offset:2048
	ds_read_b128 v[126:129], v126 offset:3072
	ds_read_b128 v[146:149], v158
	ds_read_b128 v[150:153], v158 offset:1024
	ds_read_b128 v[154:157], v158 offset:2048
	ds_read_b128 v[158:161], v158 offset:3072
	v_lshl_add_u64 v[202:203], s[10:11], 0, v[196:197]
	s_add_i32 m0, s28, 0xc000
	ds_read_b128 v[162:165], v214
	ds_read_b128 v[166:169], v214 offset:1024
	ds_read_b128 v[216:219], v214 offset:2048
	ds_read_b128 v[220:223], v214 offset:3072
	ds_read_b128 v[224:227], v214 offset:4096
	ds_read_b128 v[228:231], v214 offset:5120
	ds_read_b128 v[232:235], v214 offset:6144
	ds_read_b128 v[236:239], v214 offset:7168
	global_load_lds_dwordx4 v[202:203], off
	v_lshl_add_u64 v[202:203], s[10:11], 0, v[176:177]
	s_add_i32 m0, s28, 0xe000
	s_nop 0
	global_load_lds_dwordx4 v[202:203], off
	s_waitcnt vmcnt(8)
	s_waitcnt lgkmcnt(0)
	s_setprio 1
	s_barrier
	v_mfma_f32_16x16x32_bf16 v[142:145], v[114:117], v[162:165], 0
	v_mfma_f32_16x16x32_bf16 v[138:141], v[122:125], v[162:165], 0
	v_mfma_f32_16x16x32_bf16 v[110:113], v[114:117], v[216:219], 0
	v_mfma_f32_16x16x32_bf16 v[106:109], v[122:125], v[216:219], 0
	v_mfma_f32_16x16x32_bf16 v[98:101], v[114:117], v[224:227], 0
	v_mfma_f32_16x16x32_bf16 v[90:93], v[122:125], v[224:227], 0
	v_mfma_f32_16x16x32_bf16 v[82:85], v[114:117], v[232:235], 0
	v_mfma_f32_16x16x32_bf16 v[74:77], v[122:125], v[232:235], 0
	v_mfma_f32_16x16x32_bf16 v[142:145], v[118:121], v[166:169], v[142:145]
	v_mfma_f32_16x16x32_bf16 v[138:141], v[126:129], v[166:169], v[138:141]
	v_mfma_f32_16x16x32_bf16 v[110:113], v[118:121], v[220:223], v[110:113]
	v_mfma_f32_16x16x32_bf16 v[106:109], v[126:129], v[220:223], v[106:109]
	v_mfma_f32_16x16x32_bf16 v[98:101], v[118:121], v[228:231], v[98:101]
	v_mfma_f32_16x16x32_bf16 v[90:93], v[126:129], v[228:231], v[90:93]
	v_mfma_f32_16x16x32_bf16 v[82:85], v[118:121], v[236:239], v[82:85]
	v_mfma_f32_16x16x32_bf16 v[74:77], v[126:129], v[236:239], v[74:77]
	v_mfma_f32_16x16x32_bf16 v[134:137], v[146:149], v[162:165], 0
	v_mfma_f32_16x16x32_bf16 v[130:133], v[154:157], v[162:165], 0
	v_mfma_f32_16x16x32_bf16 v[102:105], v[146:149], v[216:219], 0
	v_mfma_f32_16x16x32_bf16 v[94:97], v[154:157], v[216:219], 0
	v_mfma_f32_16x16x32_bf16 v[86:89], v[146:149], v[224:227], 0
	v_mfma_f32_16x16x32_bf16 v[78:81], v[154:157], v[224:227], 0
	v_mfma_f32_16x16x32_bf16 v[70:73], v[146:149], v[232:235], 0
	v_mfma_f32_16x16x32_bf16 v[66:69], v[154:157], v[232:235], 0
	v_mfma_f32_16x16x32_bf16 v[134:137], v[150:153], v[166:169], v[134:137]
	v_mfma_f32_16x16x32_bf16 v[130:133], v[158:161], v[166:169], v[130:133]
	v_mfma_f32_16x16x32_bf16 v[102:105], v[150:153], v[220:223], v[102:105]
	v_mfma_f32_16x16x32_bf16 v[94:97], v[158:161], v[220:223], v[94:97]
	v_mfma_f32_16x16x32_bf16 v[86:89], v[150:153], v[228:231], v[86:89]
	v_mfma_f32_16x16x32_bf16 v[78:81], v[158:161], v[228:231], v[78:81]
	v_mfma_f32_16x16x32_bf16 v[70:73], v[150:153], v[236:239], v[70:73]
	v_mfma_f32_16x16x32_bf16 v[66:69], v[158:161], v[236:239], v[66:69]
	s_barrier
	s_setprio 0
	s_add_i32 s63, s67, s17
	v_lshl_add_u64 v[202:203], s[94:95], 0, v[174:175]
	s_mov_b32 m0, s63
	ds_read_b128 v[162:165], v214 offset:16384
	ds_read_b128 v[166:169], v214 offset:17408
	ds_read_b128 v[216:219], v214 offset:18432
	ds_read_b128 v[220:223], v214 offset:19456
	ds_read_b128 v[224:227], v214 offset:20480
	ds_read_b128 v[228:231], v214 offset:21504
	ds_read_b128 v[232:235], v214 offset:22528
	ds_read_b128 v[236:239], v214 offset:23552
	global_load_lds_dwordx4 v[202:203], off
	s_add_i32 m0, s63, 0x2000
	s_add_u32 s72, s94, 0x40000
	v_lshl_add_u64 v[240:241], s[94:95], 0, v[178:179]
	s_addc_u32 s73, s95, 0
	s_add_i32 s62, s62, s17
	global_load_lds_dwordx4 v[240:241], off
	v_lshl_add_u64 v[242:243], s[72:73], 0, v[174:175]
	s_mov_b32 m0, s62
	v_lshl_add_u64 v[244:245], s[96:97], 0, v[176:177]
	global_load_lds_dwordx4 v[242:243], off
	v_lshl_add_u64 v[242:243], s[72:73], 0, v[178:179]
	s_add_i32 m0, s62, 0x2000
	s_nop 0
	global_load_lds_dwordx4 v[242:243], off
	v_lshl_add_u64 v[242:243], s[96:97], 0, v[172:173]
	s_mov_b32 m0, s28
	s_nop 0
	global_load_lds_dwordx4 v[242:243], off
	s_mov_b32 m0, s29
	s_nop 0
	global_load_lds_dwordx4 v[244:245], off
	s_waitcnt vmcnt(8)
	s_waitcnt lgkmcnt(0)
	s_setprio 1
	s_barrier
	v_mfma_f32_16x16x32_bf16 v[62:65], v[114:117], v[162:165], 0
	v_mfma_f32_16x16x32_bf16 v[58:61], v[122:125], v[162:165], 0
	v_mfma_f32_16x16x32_bf16 v[50:53], v[114:117], v[216:219], 0
	v_mfma_f32_16x16x32_bf16 v[42:45], v[122:125], v[216:219], 0
	v_mfma_f32_16x16x32_bf16 v[34:37], v[114:117], v[224:227], 0
	v_mfma_f32_16x16x32_bf16 v[26:29], v[122:125], v[224:227], 0
	v_mfma_f32_16x16x32_bf16 v[18:21], v[114:117], v[232:235], 0
	v_mfma_f32_16x16x32_bf16 v[10:13], v[122:125], v[232:235], 0
	v_mfma_f32_16x16x32_bf16 v[62:65], v[118:121], v[166:169], v[62:65]
	v_mfma_f32_16x16x32_bf16 v[58:61], v[126:129], v[166:169], v[58:61]
	v_mfma_f32_16x16x32_bf16 v[50:53], v[118:121], v[220:223], v[50:53]
	v_mfma_f32_16x16x32_bf16 v[42:45], v[126:129], v[220:223], v[42:45]
	v_mfma_f32_16x16x32_bf16 v[34:37], v[118:121], v[228:231], v[34:37]
	v_mfma_f32_16x16x32_bf16 v[26:29], v[126:129], v[228:231], v[26:29]
	v_mfma_f32_16x16x32_bf16 v[18:21], v[118:121], v[236:239], v[18:21]
	v_mfma_f32_16x16x32_bf16 v[10:13], v[126:129], v[236:239], v[10:13]
	v_mfma_f32_16x16x32_bf16 v[54:57], v[146:149], v[162:165], 0
	v_mfma_f32_16x16x32_bf16 v[46:49], v[154:157], v[162:165], 0
	v_mfma_f32_16x16x32_bf16 v[38:41], v[146:149], v[216:219], 0
	v_mfma_f32_16x16x32_bf16 v[30:33], v[154:157], v[216:219], 0
	v_mfma_f32_16x16x32_bf16 v[22:25], v[146:149], v[224:227], 0
	v_mfma_f32_16x16x32_bf16 v[14:17], v[154:157], v[224:227], 0
	v_mfma_f32_16x16x32_bf16 v[6:9], v[146:149], v[232:235], 0
	v_mfma_f32_16x16x32_bf16 v[2:5], v[154:157], v[232:235], 0
	v_mfma_f32_16x16x32_bf16 v[54:57], v[150:153], v[166:169], v[54:57]
	v_mfma_f32_16x16x32_bf16 v[46:49], v[158:161], v[166:169], v[46:49]
	v_mfma_f32_16x16x32_bf16 v[38:41], v[150:153], v[220:223], v[38:41]
	v_mfma_f32_16x16x32_bf16 v[30:33], v[158:161], v[220:223], v[30:33]
	v_mfma_f32_16x16x32_bf16 v[22:25], v[150:153], v[228:231], v[22:25]
	v_mfma_f32_16x16x32_bf16 v[14:17], v[158:161], v[228:231], v[14:17]
	v_mfma_f32_16x16x32_bf16 v[6:9], v[150:153], v[236:239], v[6:9]
	v_mfma_f32_16x16x32_bf16 v[2:5], v[158:161], v[236:239], v[2:5]
	s_barrier
	s_setprio 0
	s_add_i32 s62, 0, 0x18000
	s_add_i32 s63, 0, 0x1c000
	v_add_u32_e32 v126, s62, v199
	v_add_u32_e32 v158, s63, v199
	ds_read_b128 v[114:117], v126
	ds_read_b128 v[118:121], v126 offset:1024
	ds_read_b128 v[122:125], v126 offset:2048
	ds_read_b128 v[126:129], v126 offset:3072
	ds_read_b128 v[146:149], v158
	ds_read_b128 v[150:153], v158 offset:1024
	ds_read_b128 v[154:157], v158 offset:2048
	ds_read_b128 v[158:161], v158 offset:3072
	s_add_u32 s72, s96, 0x40000
	s_addc_u32 s73, s97, 0
	s_mov_b32 m0, s30
	v_lshl_add_u64 v[246:247], s[72:73], 0, v[172:173]
	ds_read_b128 v[162:165], v214 offset:32768
	ds_read_b128 v[166:169], v214 offset:33792
	ds_read_b128 v[216:219], v214 offset:34816
	ds_read_b128 v[220:223], v214 offset:35840
	ds_read_b128 v[224:227], v214 offset:36864
	ds_read_b128 v[228:231], v214 offset:37888
	ds_read_b128 v[232:235], v214 offset:38912
	ds_read_b128 v[236:239], v214 offset:39936
	global_load_lds_dwordx4 v[246:247], off
	v_lshl_add_u64 v[246:247], s[72:73], 0, v[176:177]
	s_mov_b32 m0, s31
	s_nop 0
	global_load_lds_dwordx4 v[246:247], off
	s_waitcnt vmcnt(8)
	s_waitcnt lgkmcnt(0)
	s_setprio 1
	s_barrier
	v_mfma_f32_16x16x32_bf16 v[142:145], v[114:117], v[162:165], v[142:145]
	v_mfma_f32_16x16x32_bf16 v[138:141], v[122:125], v[162:165], v[138:141]
	v_mfma_f32_16x16x32_bf16 v[110:113], v[114:117], v[216:219], v[110:113]
	v_mfma_f32_16x16x32_bf16 v[106:109], v[122:125], v[216:219], v[106:109]
	v_mfma_f32_16x16x32_bf16 v[98:101], v[114:117], v[224:227], v[98:101]
	v_mfma_f32_16x16x32_bf16 v[90:93], v[122:125], v[224:227], v[90:93]
	v_mfma_f32_16x16x32_bf16 v[82:85], v[114:117], v[232:235], v[82:85]
	v_mfma_f32_16x16x32_bf16 v[74:77], v[122:125], v[232:235], v[74:77]
	v_mfma_f32_16x16x32_bf16 v[142:145], v[118:121], v[166:169], v[142:145]
	v_mfma_f32_16x16x32_bf16 v[138:141], v[126:129], v[166:169], v[138:141]
	v_mfma_f32_16x16x32_bf16 v[110:113], v[118:121], v[220:223], v[110:113]
	v_mfma_f32_16x16x32_bf16 v[106:109], v[126:129], v[220:223], v[106:109]
	v_mfma_f32_16x16x32_bf16 v[98:101], v[118:121], v[228:231], v[98:101]
	v_mfma_f32_16x16x32_bf16 v[90:93], v[126:129], v[228:231], v[90:93]
	v_mfma_f32_16x16x32_bf16 v[82:85], v[118:121], v[236:239], v[82:85]
	v_mfma_f32_16x16x32_bf16 v[74:77], v[126:129], v[236:239], v[74:77]
	v_mfma_f32_16x16x32_bf16 v[134:137], v[146:149], v[162:165], v[134:137]
	v_mfma_f32_16x16x32_bf16 v[130:133], v[154:157], v[162:165], v[130:133]
	v_mfma_f32_16x16x32_bf16 v[102:105], v[146:149], v[216:219], v[102:105]
	v_mfma_f32_16x16x32_bf16 v[94:97], v[154:157], v[216:219], v[94:97]
	v_mfma_f32_16x16x32_bf16 v[86:89], v[146:149], v[224:227], v[86:89]
	v_mfma_f32_16x16x32_bf16 v[78:81], v[154:157], v[224:227], v[78:81]
	v_mfma_f32_16x16x32_bf16 v[70:73], v[146:149], v[232:235], v[70:73]
	v_mfma_f32_16x16x32_bf16 v[66:69], v[154:157], v[232:235], v[66:69]
	v_mfma_f32_16x16x32_bf16 v[134:137], v[150:153], v[166:169], v[134:137]
	v_mfma_f32_16x16x32_bf16 v[130:133], v[158:161], v[166:169], v[130:133]
	v_mfma_f32_16x16x32_bf16 v[102:105], v[150:153], v[220:223], v[102:105]
	v_mfma_f32_16x16x32_bf16 v[94:97], v[158:161], v[220:223], v[94:97]
	v_mfma_f32_16x16x32_bf16 v[86:89], v[150:153], v[228:231], v[86:89]
	v_mfma_f32_16x16x32_bf16 v[78:81], v[158:161], v[228:231], v[78:81]
	v_mfma_f32_16x16x32_bf16 v[70:73], v[150:153], v[236:239], v[70:73]
	v_mfma_f32_16x16x32_bf16 v[66:69], v[158:161], v[236:239], v[66:69]
	s_barrier
	s_setprio 0
	s_add_i32 s62, s62, s17
	v_lshl_add_u64 v[202:203], v[202:203], 0, s[76:77]
	s_mov_b32 m0, s62
	ds_read_b128 v[162:165], v214 offset:49152
	ds_read_b128 v[166:169], v214 offset:50176
	ds_read_b128 v[216:219], v214 offset:51200
	ds_read_b128 v[220:223], v214 offset:52224
	ds_read_b128 v[224:227], v214 offset:53248
	ds_read_b128 v[228:231], v214 offset:54272
	ds_read_b128 v[232:235], v214 offset:55296
	ds_read_b128 v[236:239], v214 offset:56320
	global_load_lds_dwordx4 v[202:203], off
	s_add_i32 m0, s62, 0x2000
	s_add_u32 s72, s94, 0x40080
	v_lshl_add_u64 v[202:203], v[240:241], 0, s[76:77]
	s_addc_u32 s73, s95, 0
	s_add_i32 s62, s63, s17
	global_load_lds_dwordx4 v[202:203], off
	v_lshl_add_u64 v[202:203], s[72:73], 0, v[174:175]
	s_mov_b32 m0, s62
	s_nop 0
	global_load_lds_dwordx4 v[202:203], off
	v_lshl_add_u64 v[202:203], s[72:73], 0, v[178:179]
	s_add_i32 m0, s62, 0x2000
	s_nop 0
	global_load_lds_dwordx4 v[202:203], off
	v_lshl_add_u64 v[202:203], v[242:243], 0, s[76:77]
	s_mov_b32 m0, s44
	s_nop 0
	global_load_lds_dwordx4 v[202:203], off
	v_lshl_add_u64 v[202:203], v[244:245], 0, s[76:77]
	s_mov_b32 m0, s36
	s_nop 0
	global_load_lds_dwordx4 v[202:203], off
	s_waitcnt vmcnt(8)
	s_waitcnt lgkmcnt(0)
	s_setprio 1
	s_barrier
	v_mfma_f32_16x16x32_bf16 v[62:65], v[114:117], v[162:165], v[62:65]
	v_mfma_f32_16x16x32_bf16 v[58:61], v[122:125], v[162:165], v[58:61]
	v_mfma_f32_16x16x32_bf16 v[50:53], v[114:117], v[216:219], v[50:53]
	v_mfma_f32_16x16x32_bf16 v[42:45], v[122:125], v[216:219], v[42:45]
	v_mfma_f32_16x16x32_bf16 v[34:37], v[114:117], v[224:227], v[34:37]
	v_mfma_f32_16x16x32_bf16 v[26:29], v[122:125], v[224:227], v[26:29]
	v_mfma_f32_16x16x32_bf16 v[18:21], v[114:117], v[232:235], v[18:21]
	v_mfma_f32_16x16x32_bf16 v[10:13], v[122:125], v[232:235], v[10:13]
	v_mfma_f32_16x16x32_bf16 v[62:65], v[118:121], v[166:169], v[62:65]
	v_mfma_f32_16x16x32_bf16 v[58:61], v[126:129], v[166:169], v[58:61]
	v_mfma_f32_16x16x32_bf16 v[50:53], v[118:121], v[220:223], v[50:53]
	v_mfma_f32_16x16x32_bf16 v[42:45], v[126:129], v[220:223], v[42:45]
	v_mfma_f32_16x16x32_bf16 v[34:37], v[118:121], v[228:231], v[34:37]
	v_mfma_f32_16x16x32_bf16 v[26:29], v[126:129], v[228:231], v[26:29]
	v_mfma_f32_16x16x32_bf16 v[18:21], v[118:121], v[236:239], v[18:21]
	v_mfma_f32_16x16x32_bf16 v[10:13], v[126:129], v[236:239], v[10:13]
	v_mfma_f32_16x16x32_bf16 v[54:57], v[146:149], v[162:165], v[54:57]
	v_mfma_f32_16x16x32_bf16 v[46:49], v[154:157], v[162:165], v[46:49]
	v_mfma_f32_16x16x32_bf16 v[38:41], v[146:149], v[216:219], v[38:41]
	v_mfma_f32_16x16x32_bf16 v[30:33], v[154:157], v[216:219], v[30:33]
	v_mfma_f32_16x16x32_bf16 v[22:25], v[146:149], v[224:227], v[22:25]
	v_mfma_f32_16x16x32_bf16 v[14:17], v[154:157], v[224:227], v[14:17]
	v_mfma_f32_16x16x32_bf16 v[6:9], v[146:149], v[232:235], v[6:9]
	v_mfma_f32_16x16x32_bf16 v[2:5], v[154:157], v[232:235], v[2:5]
	v_mfma_f32_16x16x32_bf16 v[54:57], v[150:153], v[166:169], v[54:57]
	v_mfma_f32_16x16x32_bf16 v[46:49], v[158:161], v[166:169], v[46:49]
	v_mfma_f32_16x16x32_bf16 v[38:41], v[150:153], v[220:223], v[38:41]
	v_mfma_f32_16x16x32_bf16 v[30:33], v[158:161], v[220:223], v[30:33]
	v_mfma_f32_16x16x32_bf16 v[22:25], v[150:153], v[228:231], v[22:25]
	v_mfma_f32_16x16x32_bf16 v[14:17], v[158:161], v[228:231], v[14:17]
	v_mfma_f32_16x16x32_bf16 v[6:9], v[150:153], v[236:239], v[6:9]
	v_mfma_f32_16x16x32_bf16 v[2:5], v[158:161], v[236:239], v[2:5]
	s_barrier
	s_setprio 0
	s_add_u32 s10, s10, 0x100
	s_addc_u32 s11, s11, 0
	s_add_u32 vcc_lo, vcc_lo, 0x100
	s_addc_u32 vcc_hi, vcc_hi, 0
	s_cmp_ge_i32 s66, s18
	s_mov_b32 s94, s66
.LBB0_1428:
	s_add_i32 s66, s94, 2
	s_add_u32 s67, s10, 0xfffc0080
	s_addc_u32 s72, s11, -1
	s_cmp_eq_u32 s85, s94
	s_cselect_b32 s97, s14, s72
	s_cselect_b32 s96, s15, s67
	s_cselect_b32 s95, s51, vcc_hi
	s_cselect_b32 s94, s84, vcc_lo
	s_add_i32 s67, 0, 0x10000
	s_add_i32 s62, 0, 0x14000
	v_add_u32_e32 v126, s67, v199
	v_add_u32_e32 v158, s62, v199
	ds_read_b128 v[114:117], v126
	ds_read_b128 v[118:121], v126 offset:1024
	ds_read_b128 v[122:125], v126 offset:2048
	ds_read_b128 v[126:129], v126 offset:3072
	ds_read_b128 v[146:149], v158
	ds_read_b128 v[150:153], v158 offset:1024
	ds_read_b128 v[154:157], v158 offset:2048
	ds_read_b128 v[158:161], v158 offset:3072
	v_lshl_add_u64 v[202:203], s[10:11], 0, v[196:197]
	s_add_i32 m0, s28, 0xc000
	ds_read_b128 v[162:165], v214
	ds_read_b128 v[166:169], v214 offset:1024
	ds_read_b128 v[216:219], v214 offset:2048
	ds_read_b128 v[220:223], v214 offset:3072
	ds_read_b128 v[224:227], v214 offset:4096
	ds_read_b128 v[228:231], v214 offset:5120
	ds_read_b128 v[232:235], v214 offset:6144
	ds_read_b128 v[236:239], v214 offset:7168
	global_load_lds_dwordx4 v[202:203], off
	v_lshl_add_u64 v[202:203], s[10:11], 0, v[176:177]
	s_add_i32 m0, s28, 0xe000
	s_nop 0
	global_load_lds_dwordx4 v[202:203], off
	s_waitcnt vmcnt(8)
	s_waitcnt lgkmcnt(0)
	s_setprio 1
	s_barrier
	v_mfma_f32_16x16x32_bf16 v[142:145], v[114:117], v[162:165], v[142:145]
	v_mfma_f32_16x16x32_bf16 v[138:141], v[122:125], v[162:165], v[138:141]
	v_mfma_f32_16x16x32_bf16 v[110:113], v[114:117], v[216:219], v[110:113]
	v_mfma_f32_16x16x32_bf16 v[106:109], v[122:125], v[216:219], v[106:109]
	v_mfma_f32_16x16x32_bf16 v[98:101], v[114:117], v[224:227], v[98:101]
	v_mfma_f32_16x16x32_bf16 v[90:93], v[122:125], v[224:227], v[90:93]
	v_mfma_f32_16x16x32_bf16 v[82:85], v[114:117], v[232:235], v[82:85]
	v_mfma_f32_16x16x32_bf16 v[74:77], v[122:125], v[232:235], v[74:77]
	v_mfma_f32_16x16x32_bf16 v[142:145], v[118:121], v[166:169], v[142:145]
	v_mfma_f32_16x16x32_bf16 v[138:141], v[126:129], v[166:169], v[138:141]
	v_mfma_f32_16x16x32_bf16 v[110:113], v[118:121], v[220:223], v[110:113]
	v_mfma_f32_16x16x32_bf16 v[106:109], v[126:129], v[220:223], v[106:109]
	v_mfma_f32_16x16x32_bf16 v[98:101], v[118:121], v[228:231], v[98:101]
	v_mfma_f32_16x16x32_bf16 v[90:93], v[126:129], v[228:231], v[90:93]
	v_mfma_f32_16x16x32_bf16 v[82:85], v[118:121], v[236:239], v[82:85]
	v_mfma_f32_16x16x32_bf16 v[74:77], v[126:129], v[236:239], v[74:77]
	v_mfma_f32_16x16x32_bf16 v[134:137], v[146:149], v[162:165], v[134:137]
	v_mfma_f32_16x16x32_bf16 v[130:133], v[154:157], v[162:165], v[130:133]
	v_mfma_f32_16x16x32_bf16 v[102:105], v[146:149], v[216:219], v[102:105]
	v_mfma_f32_16x16x32_bf16 v[94:97], v[154:157], v[216:219], v[94:97]
	v_mfma_f32_16x16x32_bf16 v[86:89], v[146:149], v[224:227], v[86:89]
	v_mfma_f32_16x16x32_bf16 v[78:81], v[154:157], v[224:227], v[78:81]
	v_mfma_f32_16x16x32_bf16 v[70:73], v[146:149], v[232:235], v[70:73]
	v_mfma_f32_16x16x32_bf16 v[66:69], v[154:157], v[232:235], v[66:69]
	v_mfma_f32_16x16x32_bf16 v[134:137], v[150:153], v[166:169], v[134:137]
	v_mfma_f32_16x16x32_bf16 v[130:133], v[158:161], v[166:169], v[130:133]
	v_mfma_f32_16x16x32_bf16 v[102:105], v[150:153], v[220:223], v[102:105]
	v_mfma_f32_16x16x32_bf16 v[94:97], v[158:161], v[220:223], v[94:97]
	v_mfma_f32_16x16x32_bf16 v[86:89], v[150:153], v[228:231], v[86:89]
	v_mfma_f32_16x16x32_bf16 v[78:81], v[158:161], v[228:231], v[78:81]
	v_mfma_f32_16x16x32_bf16 v[70:73], v[150:153], v[236:239], v[70:73]
	v_mfma_f32_16x16x32_bf16 v[66:69], v[158:161], v[236:239], v[66:69]
	s_barrier
	s_setprio 0
	s_add_i32 s63, s67, s17
	v_lshl_add_u64 v[202:203], s[94:95], 0, v[174:175]
	s_mov_b32 m0, s63
	ds_read_b128 v[162:165], v214 offset:16384
	ds_read_b128 v[166:169], v214 offset:17408
	ds_read_b128 v[216:219], v214 offset:18432
	ds_read_b128 v[220:223], v214 offset:19456
	ds_read_b128 v[224:227], v214 offset:20480
	ds_read_b128 v[228:231], v214 offset:21504
	ds_read_b128 v[232:235], v214 offset:22528
	ds_read_b128 v[236:239], v214 offset:23552
	global_load_lds_dwordx4 v[202:203], off
	s_add_i32 m0, s63, 0x2000
	s_add_u32 s72, s94, 0x40000
	v_lshl_add_u64 v[240:241], s[94:95], 0, v[178:179]
	s_addc_u32 s73, s95, 0
	s_add_i32 s62, s62, s17
	global_load_lds_dwordx4 v[240:241], off
	v_lshl_add_u64 v[242:243], s[72:73], 0, v[174:175]
	s_mov_b32 m0, s62
	v_lshl_add_u64 v[244:245], s[96:97], 0, v[176:177]
	global_load_lds_dwordx4 v[242:243], off
	v_lshl_add_u64 v[242:243], s[72:73], 0, v[178:179]
	s_add_i32 m0, s62, 0x2000
	s_nop 0
	global_load_lds_dwordx4 v[242:243], off
	v_lshl_add_u64 v[242:243], s[96:97], 0, v[172:173]
	s_mov_b32 m0, s28
	s_nop 0
	global_load_lds_dwordx4 v[242:243], off
	s_mov_b32 m0, s29
	s_nop 0
	global_load_lds_dwordx4 v[244:245], off
	s_waitcnt vmcnt(8)
	s_waitcnt lgkmcnt(0)
	s_setprio 1
	s_barrier
	v_mfma_f32_16x16x32_bf16 v[62:65], v[114:117], v[162:165], v[62:65]
	v_mfma_f32_16x16x32_bf16 v[58:61], v[122:125], v[162:165], v[58:61]
	v_mfma_f32_16x16x32_bf16 v[50:53], v[114:117], v[216:219], v[50:53]
	v_mfma_f32_16x16x32_bf16 v[42:45], v[122:125], v[216:219], v[42:45]
	v_mfma_f32_16x16x32_bf16 v[34:37], v[114:117], v[224:227], v[34:37]
	v_mfma_f32_16x16x32_bf16 v[26:29], v[122:125], v[224:227], v[26:29]
	v_mfma_f32_16x16x32_bf16 v[18:21], v[114:117], v[232:235], v[18:21]
	v_mfma_f32_16x16x32_bf16 v[10:13], v[122:125], v[232:235], v[10:13]
	v_mfma_f32_16x16x32_bf16 v[62:65], v[118:121], v[166:169], v[62:65]
	v_mfma_f32_16x16x32_bf16 v[58:61], v[126:129], v[166:169], v[58:61]
	v_mfma_f32_16x16x32_bf16 v[50:53], v[118:121], v[220:223], v[50:53]
	v_mfma_f32_16x16x32_bf16 v[42:45], v[126:129], v[220:223], v[42:45]
	v_mfma_f32_16x16x32_bf16 v[34:37], v[118:121], v[228:231], v[34:37]
	v_mfma_f32_16x16x32_bf16 v[26:29], v[126:129], v[228:231], v[26:29]
	v_mfma_f32_16x16x32_bf16 v[18:21], v[118:121], v[236:239], v[18:21]
	v_mfma_f32_16x16x32_bf16 v[10:13], v[126:129], v[236:239], v[10:13]
	v_mfma_f32_16x16x32_bf16 v[54:57], v[146:149], v[162:165], v[54:57]
	v_mfma_f32_16x16x32_bf16 v[46:49], v[154:157], v[162:165], v[46:49]
	v_mfma_f32_16x16x32_bf16 v[38:41], v[146:149], v[216:219], v[38:41]
	v_mfma_f32_16x16x32_bf16 v[30:33], v[154:157], v[216:219], v[30:33]
	v_mfma_f32_16x16x32_bf16 v[22:25], v[146:149], v[224:227], v[22:25]
	v_mfma_f32_16x16x32_bf16 v[14:17], v[154:157], v[224:227], v[14:17]
	v_mfma_f32_16x16x32_bf16 v[6:9], v[146:149], v[232:235], v[6:9]
	v_mfma_f32_16x16x32_bf16 v[2:5], v[154:157], v[232:235], v[2:5]
	v_mfma_f32_16x16x32_bf16 v[54:57], v[150:153], v[166:169], v[54:57]
	v_mfma_f32_16x16x32_bf16 v[46:49], v[158:161], v[166:169], v[46:49]
	v_mfma_f32_16x16x32_bf16 v[38:41], v[150:153], v[220:223], v[38:41]
	v_mfma_f32_16x16x32_bf16 v[30:33], v[158:161], v[220:223], v[30:33]
	v_mfma_f32_16x16x32_bf16 v[22:25], v[150:153], v[228:231], v[22:25]
	v_mfma_f32_16x16x32_bf16 v[14:17], v[158:161], v[228:231], v[14:17]
	v_mfma_f32_16x16x32_bf16 v[6:9], v[150:153], v[236:239], v[6:9]
	v_mfma_f32_16x16x32_bf16 v[2:5], v[158:161], v[236:239], v[2:5]
	s_barrier
	s_setprio 0
	s_add_i32 s62, 0, 0x18000
	s_add_i32 s63, 0, 0x1c000
	v_add_u32_e32 v126, s62, v199
	v_add_u32_e32 v158, s63, v199
	ds_read_b128 v[114:117], v126
	ds_read_b128 v[118:121], v126 offset:1024
	ds_read_b128 v[122:125], v126 offset:2048
	ds_read_b128 v[126:129], v126 offset:3072
	ds_read_b128 v[146:149], v158
	ds_read_b128 v[150:153], v158 offset:1024
	ds_read_b128 v[154:157], v158 offset:2048
	ds_read_b128 v[158:161], v158 offset:3072
	s_add_u32 s72, s96, 0x40000
	s_addc_u32 s73, s97, 0
	s_mov_b32 m0, s30
	v_lshl_add_u64 v[246:247], s[72:73], 0, v[172:173]
	ds_read_b128 v[162:165], v214 offset:32768
	ds_read_b128 v[166:169], v214 offset:33792
	ds_read_b128 v[216:219], v214 offset:34816
	ds_read_b128 v[220:223], v214 offset:35840
	ds_read_b128 v[224:227], v214 offset:36864
	ds_read_b128 v[228:231], v214 offset:37888
	ds_read_b128 v[232:235], v214 offset:38912
	ds_read_b128 v[236:239], v214 offset:39936
	global_load_lds_dwordx4 v[246:247], off
	v_lshl_add_u64 v[246:247], s[72:73], 0, v[176:177]
	s_mov_b32 m0, s31
	s_nop 0
	global_load_lds_dwordx4 v[246:247], off
	s_waitcnt vmcnt(8)
	s_waitcnt lgkmcnt(0)
	s_setprio 1
	s_barrier
	v_mfma_f32_16x16x32_bf16 v[142:145], v[114:117], v[162:165], v[142:145]
	v_mfma_f32_16x16x32_bf16 v[138:141], v[122:125], v[162:165], v[138:141]
	v_mfma_f32_16x16x32_bf16 v[110:113], v[114:117], v[216:219], v[110:113]
	v_mfma_f32_16x16x32_bf16 v[106:109], v[122:125], v[216:219], v[106:109]
	v_mfma_f32_16x16x32_bf16 v[98:101], v[114:117], v[224:227], v[98:101]
	v_mfma_f32_16x16x32_bf16 v[90:93], v[122:125], v[224:227], v[90:93]
	v_mfma_f32_16x16x32_bf16 v[82:85], v[114:117], v[232:235], v[82:85]
	v_mfma_f32_16x16x32_bf16 v[74:77], v[122:125], v[232:235], v[74:77]
	v_mfma_f32_16x16x32_bf16 v[142:145], v[118:121], v[166:169], v[142:145]
	v_mfma_f32_16x16x32_bf16 v[138:141], v[126:129], v[166:169], v[138:141]
	v_mfma_f32_16x16x32_bf16 v[110:113], v[118:121], v[220:223], v[110:113]
	v_mfma_f32_16x16x32_bf16 v[106:109], v[126:129], v[220:223], v[106:109]
	v_mfma_f32_16x16x32_bf16 v[98:101], v[118:121], v[228:231], v[98:101]
	v_mfma_f32_16x16x32_bf16 v[90:93], v[126:129], v[228:231], v[90:93]
	v_mfma_f32_16x16x32_bf16 v[82:85], v[118:121], v[236:239], v[82:85]
	v_mfma_f32_16x16x32_bf16 v[74:77], v[126:129], v[236:239], v[74:77]
	v_mfma_f32_16x16x32_bf16 v[134:137], v[146:149], v[162:165], v[134:137]
	v_mfma_f32_16x16x32_bf16 v[130:133], v[154:157], v[162:165], v[130:133]
	v_mfma_f32_16x16x32_bf16 v[102:105], v[146:149], v[216:219], v[102:105]
	v_mfma_f32_16x16x32_bf16 v[94:97], v[154:157], v[216:219], v[94:97]
	v_mfma_f32_16x16x32_bf16 v[86:89], v[146:149], v[224:227], v[86:89]
	v_mfma_f32_16x16x32_bf16 v[78:81], v[154:157], v[224:227], v[78:81]
	v_mfma_f32_16x16x32_bf16 v[70:73], v[146:149], v[232:235], v[70:73]
	v_mfma_f32_16x16x32_bf16 v[66:69], v[154:157], v[232:235], v[66:69]
	v_mfma_f32_16x16x32_bf16 v[134:137], v[150:153], v[166:169], v[134:137]
	v_mfma_f32_16x16x32_bf16 v[130:133], v[158:161], v[166:169], v[130:133]
	v_mfma_f32_16x16x32_bf16 v[102:105], v[150:153], v[220:223], v[102:105]
	v_mfma_f32_16x16x32_bf16 v[94:97], v[158:161], v[220:223], v[94:97]
	v_mfma_f32_16x16x32_bf16 v[86:89], v[150:153], v[228:231], v[86:89]
	v_mfma_f32_16x16x32_bf16 v[78:81], v[158:161], v[228:231], v[78:81]
	v_mfma_f32_16x16x32_bf16 v[70:73], v[150:153], v[236:239], v[70:73]
	v_mfma_f32_16x16x32_bf16 v[66:69], v[158:161], v[236:239], v[66:69]
	s_barrier
	s_setprio 0
	s_add_i32 s62, s62, s17
	v_lshl_add_u64 v[202:203], v[202:203], 0, s[76:77]
	s_mov_b32 m0, s62
	ds_read_b128 v[162:165], v214 offset:49152
	ds_read_b128 v[166:169], v214 offset:50176
	ds_read_b128 v[216:219], v214 offset:51200
	ds_read_b128 v[220:223], v214 offset:52224
	ds_read_b128 v[224:227], v214 offset:53248
	ds_read_b128 v[228:231], v214 offset:54272
	ds_read_b128 v[232:235], v214 offset:55296
	ds_read_b128 v[236:239], v214 offset:56320
	global_load_lds_dwordx4 v[202:203], off
	s_add_i32 m0, s62, 0x2000
	s_add_u32 s72, s94, 0x40080
	v_lshl_add_u64 v[202:203], v[240:241], 0, s[76:77]
	s_addc_u32 s73, s95, 0
	s_add_i32 s62, s63, s17
	global_load_lds_dwordx4 v[202:203], off
	v_lshl_add_u64 v[202:203], s[72:73], 0, v[174:175]
	s_mov_b32 m0, s62
	s_nop 0
	global_load_lds_dwordx4 v[202:203], off
	v_lshl_add_u64 v[202:203], s[72:73], 0, v[178:179]
	s_add_i32 m0, s62, 0x2000
	s_nop 0
	global_load_lds_dwordx4 v[202:203], off
	v_lshl_add_u64 v[202:203], v[242:243], 0, s[76:77]
	s_mov_b32 m0, s44
	s_nop 0
	global_load_lds_dwordx4 v[202:203], off
	v_lshl_add_u64 v[202:203], v[244:245], 0, s[76:77]
	s_mov_b32 m0, s36
	s_nop 0
	global_load_lds_dwordx4 v[202:203], off
	s_waitcnt vmcnt(8)
	s_waitcnt lgkmcnt(0)
	s_setprio 1
	s_barrier
	v_mfma_f32_16x16x32_bf16 v[62:65], v[114:117], v[162:165], v[62:65]
	v_mfma_f32_16x16x32_bf16 v[58:61], v[122:125], v[162:165], v[58:61]
	v_mfma_f32_16x16x32_bf16 v[50:53], v[114:117], v[216:219], v[50:53]
	v_mfma_f32_16x16x32_bf16 v[42:45], v[122:125], v[216:219], v[42:45]
	v_mfma_f32_16x16x32_bf16 v[34:37], v[114:117], v[224:227], v[34:37]
	v_mfma_f32_16x16x32_bf16 v[26:29], v[122:125], v[224:227], v[26:29]
	v_mfma_f32_16x16x32_bf16 v[18:21], v[114:117], v[232:235], v[18:21]
	v_mfma_f32_16x16x32_bf16 v[10:13], v[122:125], v[232:235], v[10:13]
	v_mfma_f32_16x16x32_bf16 v[62:65], v[118:121], v[166:169], v[62:65]
	v_mfma_f32_16x16x32_bf16 v[58:61], v[126:129], v[166:169], v[58:61]
	v_mfma_f32_16x16x32_bf16 v[50:53], v[118:121], v[220:223], v[50:53]
	v_mfma_f32_16x16x32_bf16 v[42:45], v[126:129], v[220:223], v[42:45]
	v_mfma_f32_16x16x32_bf16 v[34:37], v[118:121], v[228:231], v[34:37]
	v_mfma_f32_16x16x32_bf16 v[26:29], v[126:129], v[228:231], v[26:29]
	v_mfma_f32_16x16x32_bf16 v[18:21], v[118:121], v[236:239], v[18:21]
	v_mfma_f32_16x16x32_bf16 v[10:13], v[126:129], v[236:239], v[10:13]
	v_mfma_f32_16x16x32_bf16 v[54:57], v[146:149], v[162:165], v[54:57]
	v_mfma_f32_16x16x32_bf16 v[46:49], v[154:157], v[162:165], v[46:49]
	v_mfma_f32_16x16x32_bf16 v[38:41], v[146:149], v[216:219], v[38:41]
	v_mfma_f32_16x16x32_bf16 v[30:33], v[154:157], v[216:219], v[30:33]
	v_mfma_f32_16x16x32_bf16 v[22:25], v[146:149], v[224:227], v[22:25]
	v_mfma_f32_16x16x32_bf16 v[14:17], v[154:157], v[224:227], v[14:17]
	v_mfma_f32_16x16x32_bf16 v[6:9], v[146:149], v[232:235], v[6:9]
	v_mfma_f32_16x16x32_bf16 v[2:5], v[154:157], v[232:235], v[2:5]
	v_mfma_f32_16x16x32_bf16 v[54:57], v[150:153], v[166:169], v[54:57]
	v_mfma_f32_16x16x32_bf16 v[46:49], v[158:161], v[166:169], v[46:49]
	v_mfma_f32_16x16x32_bf16 v[38:41], v[150:153], v[220:223], v[38:41]
	v_mfma_f32_16x16x32_bf16 v[30:33], v[158:161], v[220:223], v[30:33]
	v_mfma_f32_16x16x32_bf16 v[22:25], v[150:153], v[228:231], v[22:25]
	v_mfma_f32_16x16x32_bf16 v[14:17], v[158:161], v[228:231], v[14:17]
	v_mfma_f32_16x16x32_bf16 v[6:9], v[150:153], v[236:239], v[6:9]
	v_mfma_f32_16x16x32_bf16 v[2:5], v[158:161], v[236:239], v[2:5]
	s_barrier
	s_setprio 0
	s_add_u32 s10, s10, 0x100
	s_addc_u32 s11, s11, 0
	s_add_u32 vcc_lo, vcc_lo, 0x100
	s_addc_u32 vcc_hi, vcc_hi, 0
	s_cmp_ge_i32 s66, s18
	s_mov_b32 s94, s66
	s_cbranch_scc0 .LBB0_1428
	s_and_b64 vcc, exec, s[82:83]
	s_cbranch_vccz .LBB0_1431
	s_barrier

.LBB0_1618:
	s_add_u32 s24, s96, s20
	s_addc_u32 s25, s97, s21
	s_and_b64 s[14:15], s[4:5], exec
	s_cselect_b32 s14, s25, s29
	s_cselect_b32 s15, s24, s28
	s_add_u32 s26, s2, s22
	s_addc_u32 s27, s3, s23
	s_and_b64 s[36:37], s[4:5], exec
	s_cselect_b32 s17, s27, s31
	s_cselect_b32 s49, s26, s30
	s_add_u32 s28, s28, 0x40080
	s_addc_u32 s29, s29, 0
	s_add_u32 s50, s30, 0x100
	s_addc_u32 s51, s31, 0
	s_mov_b32 s62, -2
	ds_read_b128 v[154:157], v150
	ds_read_b128 v[158:161], v150 offset:1024
	ds_read_b128 v[162:165], v150 offset:2048
	ds_read_b128 v[166:169], v150 offset:3072
	ds_read_b128 v[170:173], v151
	ds_read_b128 v[174:177], v151 offset:1024
	ds_read_b128 v[178:181], v151 offset:2048
	ds_read_b128 v[182:185], v151 offset:3072
	s_add_u32 s30, s28, 0xfffc0080
	s_addc_u32 s31, s29, -1
	s_cmp_eq_u32 s62, 12
	s_cselect_b32 s37, s14, s31
	s_cselect_b32 s36, s15, s30
	s_cselect_b32 s31, s17, s51
	s_cselect_b32 s30, s49, s50
	v_lshl_add_u64 v[146:147], s[28:29], 0, v[138:139]
	s_add_i32 m0, s19, 0xc000
	ds_read_b128 v[186:189], v152
	ds_read_b128 v[190:193], v152 offset:1024
	ds_read_b128 v[194:197], v152 offset:2048
	ds_read_b128 v[198:201], v152 offset:3072
	ds_read_b128 v[206:209], v152 offset:4096
	ds_read_b128 v[210:213], v152 offset:5120
	ds_read_b128 v[214:217], v152 offset:6144
	ds_read_b128 v[218:221], v152 offset:7168
	global_load_lds_dwordx4 v[146:147], off
	v_lshl_add_u64 v[146:147], s[28:29], 0, v[140:141]
	s_add_i32 m0, s19, 0xe000
	s_nop 0
	global_load_lds_dwordx4 v[146:147], off
	s_waitcnt vmcnt(8)
	s_waitcnt lgkmcnt(0)
	s_setprio 1
	s_barrier
	v_mfma_f32_16x16x32_bf16 v[126:129], v[154:157], v[186:189], 0
	v_mfma_f32_16x16x32_bf16 v[122:125], v[162:165], v[186:189], 0
	v_mfma_f32_16x16x32_bf16 v[110:113], v[154:157], v[194:197], 0
	v_mfma_f32_16x16x32_bf16 v[106:109], v[162:165], v[194:197], 0
	v_mfma_f32_16x16x32_bf16 v[94:97], v[154:157], v[206:209], 0
	v_mfma_f32_16x16x32_bf16 v[90:93], v[162:165], v[206:209], 0
	v_mfma_f32_16x16x32_bf16 v[78:81], v[154:157], v[214:217], 0
	v_mfma_f32_16x16x32_bf16 v[74:77], v[162:165], v[214:217], 0
	v_mfma_f32_16x16x32_bf16 v[126:129], v[158:161], v[190:193], v[126:129]
	v_mfma_f32_16x16x32_bf16 v[122:125], v[166:169], v[190:193], v[122:125]
	v_mfma_f32_16x16x32_bf16 v[110:113], v[158:161], v[198:201], v[110:113]
	v_mfma_f32_16x16x32_bf16 v[106:109], v[166:169], v[198:201], v[106:109]
	v_mfma_f32_16x16x32_bf16 v[94:97], v[158:161], v[210:213], v[94:97]
	v_mfma_f32_16x16x32_bf16 v[90:93], v[166:169], v[210:213], v[90:93]
	v_mfma_f32_16x16x32_bf16 v[78:81], v[158:161], v[218:221], v[78:81]
	v_mfma_f32_16x16x32_bf16 v[74:77], v[166:169], v[218:221], v[74:77]
	v_mfma_f32_16x16x32_bf16 v[118:121], v[170:173], v[186:189], 0
	v_mfma_f32_16x16x32_bf16 v[114:117], v[178:181], v[186:189], 0
	v_mfma_f32_16x16x32_bf16 v[102:105], v[170:173], v[194:197], 0
	v_mfma_f32_16x16x32_bf16 v[98:101], v[178:181], v[194:197], 0
	v_mfma_f32_16x16x32_bf16 v[86:89], v[170:173], v[206:209], 0
	v_mfma_f32_16x16x32_bf16 v[82:85], v[178:181], v[206:209], 0
	v_mfma_f32_16x16x32_bf16 v[70:73], v[170:173], v[214:217], 0
	v_mfma_f32_16x16x32_bf16 v[66:69], v[178:181], v[214:217], 0
	v_mfma_f32_16x16x32_bf16 v[118:121], v[174:177], v[190:193], v[118:121]
	v_mfma_f32_16x16x32_bf16 v[114:117], v[182:185], v[190:193], v[114:117]
	v_mfma_f32_16x16x32_bf16 v[102:105], v[174:177], v[198:201], v[102:105]
	v_mfma_f32_16x16x32_bf16 v[98:101], v[182:185], v[198:201], v[98:101]
	v_mfma_f32_16x16x32_bf16 v[86:89], v[174:177], v[210:213], v[86:89]
	v_mfma_f32_16x16x32_bf16 v[82:85], v[182:185], v[210:213], v[82:85]
	v_mfma_f32_16x16x32_bf16 v[70:73], v[174:177], v[218:221], v[70:73]
	v_mfma_f32_16x16x32_bf16 v[66:69], v[182:185], v[218:221], v[66:69]
	s_barrier
	s_setprio 0
	s_add_i32 s63, s45, s12
	v_lshl_add_u64 v[146:147], s[30:31], 0, v[134:135]
	s_mov_b32 m0, s63
	ds_read_b128 v[186:189], v152 offset:16384
	ds_read_b128 v[190:193], v152 offset:17408
	ds_read_b128 v[194:197], v152 offset:18432
	ds_read_b128 v[198:201], v152 offset:19456
	ds_read_b128 v[206:209], v152 offset:20480
	ds_read_b128 v[210:213], v152 offset:21504
	ds_read_b128 v[214:217], v152 offset:22528
	ds_read_b128 v[218:221], v152 offset:23552
	global_load_lds_dwordx4 v[146:147], off
	s_add_i32 m0, s63, 0x2000
	s_add_u32 s64, s30, 0x40000
	v_lshl_add_u64 v[202:203], s[30:31], 0, v[130:131]
	s_addc_u32 s65, s31, 0
	s_add_i32 s63, s46, s12
	global_load_lds_dwordx4 v[202:203], off
	v_lshl_add_u64 v[222:223], s[64:65], 0, v[134:135]
	s_mov_b32 m0, s63
	v_lshl_add_u64 v[224:225], s[36:37], 0, v[132:133]
	global_load_lds_dwordx4 v[222:223], off
	v_lshl_add_u64 v[222:223], s[64:65], 0, v[130:131]
	s_add_i32 m0, s63, 0x2000
	s_nop 0
	global_load_lds_dwordx4 v[222:223], off
	v_lshl_add_u64 v[222:223], s[36:37], 0, v[136:137]
	s_mov_b32 m0, s19
	s_nop 0
	global_load_lds_dwordx4 v[222:223], off
	s_mov_b32 m0, s33
	s_nop 0
	global_load_lds_dwordx4 v[224:225], off
	s_waitcnt vmcnt(8)
	s_waitcnt lgkmcnt(0)
	s_setprio 1
	s_barrier
	v_mfma_f32_16x16x32_bf16 v[62:65], v[154:157], v[186:189], 0
	v_mfma_f32_16x16x32_bf16 v[58:61], v[162:165], v[186:189], 0
	v_mfma_f32_16x16x32_bf16 v[46:49], v[154:157], v[194:197], 0
	v_mfma_f32_16x16x32_bf16 v[42:45], v[162:165], v[194:197], 0
	v_mfma_f32_16x16x32_bf16 v[30:33], v[154:157], v[206:209], 0
	v_mfma_f32_16x16x32_bf16 v[26:29], v[162:165], v[206:209], 0
	v_mfma_f32_16x16x32_bf16 v[14:17], v[154:157], v[214:217], 0
	v_mfma_f32_16x16x32_bf16 v[10:13], v[162:165], v[214:217], 0
	v_mfma_f32_16x16x32_bf16 v[62:65], v[158:161], v[190:193], v[62:65]
	v_mfma_f32_16x16x32_bf16 v[58:61], v[166:169], v[190:193], v[58:61]
	v_mfma_f32_16x16x32_bf16 v[46:49], v[158:161], v[198:201], v[46:49]
	v_mfma_f32_16x16x32_bf16 v[42:45], v[166:169], v[198:201], v[42:45]
	v_mfma_f32_16x16x32_bf16 v[30:33], v[158:161], v[210:213], v[30:33]
	v_mfma_f32_16x16x32_bf16 v[26:29], v[166:169], v[210:213], v[26:29]
	v_mfma_f32_16x16x32_bf16 v[14:17], v[158:161], v[218:221], v[14:17]
	v_mfma_f32_16x16x32_bf16 v[10:13], v[166:169], v[218:221], v[10:13]
	v_mfma_f32_16x16x32_bf16 v[54:57], v[170:173], v[186:189], 0
	v_mfma_f32_16x16x32_bf16 v[50:53], v[178:181], v[186:189], 0
	v_mfma_f32_16x16x32_bf16 v[38:41], v[170:173], v[194:197], 0
	v_mfma_f32_16x16x32_bf16 v[34:37], v[178:181], v[194:197], 0
	v_mfma_f32_16x16x32_bf16 v[22:25], v[170:173], v[206:209], 0
	v_mfma_f32_16x16x32_bf16 v[18:21], v[178:181], v[206:209], 0
	v_mfma_f32_16x16x32_bf16 v[6:9], v[170:173], v[214:217], 0
	v_mfma_f32_16x16x32_bf16 v[2:5], v[178:181], v[214:217], 0
	v_mfma_f32_16x16x32_bf16 v[54:57], v[174:177], v[190:193], v[54:57]
	v_mfma_f32_16x16x32_bf16 v[50:53], v[182:185], v[190:193], v[50:53]
	v_mfma_f32_16x16x32_bf16 v[38:41], v[174:177], v[198:201], v[38:41]
	v_mfma_f32_16x16x32_bf16 v[34:37], v[182:185], v[198:201], v[34:37]
	v_mfma_f32_16x16x32_bf16 v[22:25], v[174:177], v[210:213], v[22:25]
	v_mfma_f32_16x16x32_bf16 v[18:21], v[182:185], v[210:213], v[18:21]
	v_mfma_f32_16x16x32_bf16 v[6:9], v[174:177], v[218:221], v[6:9]
	v_mfma_f32_16x16x32_bf16 v[2:5], v[182:185], v[218:221], v[2:5]
	s_barrier
	s_setprio 0
	s_add_i32 s63, 0, 0x18000
	v_add_u32_e32 v153, s63, v149
	s_add_i32 s64, 0, 0x1c000
	ds_read_b128 v[154:157], v153
	ds_read_b128 v[158:161], v153 offset:1024
	ds_read_b128 v[162:165], v153 offset:2048
	ds_read_b128 v[166:169], v153 offset:3072
	v_add_u32_e32 v153, s64, v149
	ds_read_b128 v[170:173], v153
	ds_read_b128 v[174:177], v153 offset:1024
	ds_read_b128 v[178:181], v153 offset:2048
	ds_read_b128 v[182:185], v153 offset:3072
	s_add_u32 s36, s36, 0x40000
	s_addc_u32 s37, s37, 0
	s_mov_b32 m0, s35
	v_lshl_add_u64 v[226:227], s[36:37], 0, v[136:137]
	ds_read_b128 v[186:189], v152 offset:32768
	ds_read_b128 v[190:193], v152 offset:33792
	ds_read_b128 v[194:197], v152 offset:34816
	ds_read_b128 v[198:201], v152 offset:35840
	ds_read_b128 v[206:209], v152 offset:36864
	ds_read_b128 v[210:213], v152 offset:37888
	ds_read_b128 v[214:217], v152 offset:38912
	ds_read_b128 v[218:221], v152 offset:39936
	global_load_lds_dwordx4 v[226:227], off
	v_lshl_add_u64 v[226:227], s[36:37], 0, v[132:133]
	s_mov_b32 m0, s38
	s_nop 0
	global_load_lds_dwordx4 v[226:227], off
	s_waitcnt vmcnt(8)
	s_waitcnt lgkmcnt(0)
	s_setprio 1
	s_barrier
	v_mfma_f32_16x16x32_bf16 v[126:129], v[154:157], v[186:189], v[126:129]
	v_mfma_f32_16x16x32_bf16 v[122:125], v[162:165], v[186:189], v[122:125]
	v_mfma_f32_16x16x32_bf16 v[110:113], v[154:157], v[194:197], v[110:113]
	v_mfma_f32_16x16x32_bf16 v[106:109], v[162:165], v[194:197], v[106:109]
	v_mfma_f32_16x16x32_bf16 v[94:97], v[154:157], v[206:209], v[94:97]
	v_mfma_f32_16x16x32_bf16 v[90:93], v[162:165], v[206:209], v[90:93]
	v_mfma_f32_16x16x32_bf16 v[78:81], v[154:157], v[214:217], v[78:81]
	v_mfma_f32_16x16x32_bf16 v[74:77], v[162:165], v[214:217], v[74:77]
	v_mfma_f32_16x16x32_bf16 v[126:129], v[158:161], v[190:193], v[126:129]
	v_mfma_f32_16x16x32_bf16 v[122:125], v[166:169], v[190:193], v[122:125]
	v_mfma_f32_16x16x32_bf16 v[110:113], v[158:161], v[198:201], v[110:113]
	v_mfma_f32_16x16x32_bf16 v[106:109], v[166:169], v[198:201], v[106:109]
	v_mfma_f32_16x16x32_bf16 v[94:97], v[158:161], v[210:213], v[94:97]
	v_mfma_f32_16x16x32_bf16 v[90:93], v[166:169], v[210:213], v[90:93]
	v_mfma_f32_16x16x32_bf16 v[78:81], v[158:161], v[218:221], v[78:81]
	v_mfma_f32_16x16x32_bf16 v[74:77], v[166:169], v[218:221], v[74:77]
	v_mfma_f32_16x16x32_bf16 v[118:121], v[170:173], v[186:189], v[118:121]
	v_mfma_f32_16x16x32_bf16 v[114:117], v[178:181], v[186:189], v[114:117]
	v_mfma_f32_16x16x32_bf16 v[102:105], v[170:173], v[194:197], v[102:105]
	v_mfma_f32_16x16x32_bf16 v[98:101], v[178:181], v[194:197], v[98:101]
	v_mfma_f32_16x16x32_bf16 v[86:89], v[170:173], v[206:209], v[86:89]
	v_mfma_f32_16x16x32_bf16 v[82:85], v[178:181], v[206:209], v[82:85]
	v_mfma_f32_16x16x32_bf16 v[70:73], v[170:173], v[214:217], v[70:73]
	v_mfma_f32_16x16x32_bf16 v[66:69], v[178:181], v[214:217], v[66:69]
	v_mfma_f32_16x16x32_bf16 v[118:121], v[174:177], v[190:193], v[118:121]
	v_mfma_f32_16x16x32_bf16 v[114:117], v[182:185], v[190:193], v[114:117]
	v_mfma_f32_16x16x32_bf16 v[102:105], v[174:177], v[198:201], v[102:105]
	v_mfma_f32_16x16x32_bf16 v[98:101], v[182:185], v[198:201], v[98:101]
	v_mfma_f32_16x16x32_bf16 v[86:89], v[174:177], v[210:213], v[86:89]
	v_mfma_f32_16x16x32_bf16 v[82:85], v[182:185], v[210:213], v[82:85]
	v_mfma_f32_16x16x32_bf16 v[70:73], v[174:177], v[218:221], v[70:73]
	v_mfma_f32_16x16x32_bf16 v[66:69], v[182:185], v[218:221], v[66:69]
	s_barrier
	s_setprio 0
	s_add_i32 s36, s63, s12
	v_lshl_add_u64 v[146:147], v[146:147], 0, s[8:9]
	s_mov_b32 m0, s36
	ds_read_b128 v[186:189], v152 offset:49152
	ds_read_b128 v[190:193], v152 offset:50176
	ds_read_b128 v[194:197], v152 offset:51200
	ds_read_b128 v[198:201], v152 offset:52224
	ds_read_b128 v[206:209], v152 offset:53248
	ds_read_b128 v[210:213], v152 offset:54272
	ds_read_b128 v[214:217], v152 offset:55296
	ds_read_b128 v[218:221], v152 offset:56320
	global_load_lds_dwordx4 v[146:147], off
	s_add_i32 m0, s36, 0x2000
	s_add_u32 s30, s30, 0x40080
	v_lshl_add_u64 v[146:147], v[202:203], 0, s[8:9]
	s_addc_u32 s31, s31, 0
	s_add_i32 s36, s64, s12
	global_load_lds_dwordx4 v[146:147], off
	v_lshl_add_u64 v[146:147], s[30:31], 0, v[134:135]
	s_mov_b32 m0, s36
	s_nop 0
	global_load_lds_dwordx4 v[146:147], off
	v_lshl_add_u64 v[146:147], s[30:31], 0, v[130:131]
	s_add_i32 m0, s36, 0x2000
	s_nop 0
	global_load_lds_dwordx4 v[146:147], off
	v_lshl_add_u64 v[146:147], v[222:223], 0, s[8:9]
	s_mov_b32 m0, s42
	s_nop 0
	global_load_lds_dwordx4 v[146:147], off
	v_lshl_add_u64 v[146:147], v[224:225], 0, s[8:9]
	s_mov_b32 m0, s43
	s_nop 0
	global_load_lds_dwordx4 v[146:147], off
	s_waitcnt vmcnt(8)
	s_waitcnt lgkmcnt(0)
	s_setprio 1
	s_barrier
	v_mfma_f32_16x16x32_bf16 v[62:65], v[154:157], v[186:189], v[62:65]
	v_mfma_f32_16x16x32_bf16 v[58:61], v[162:165], v[186:189], v[58:61]
	v_mfma_f32_16x16x32_bf16 v[46:49], v[154:157], v[194:197], v[46:49]
	v_mfma_f32_16x16x32_bf16 v[42:45], v[162:165], v[194:197], v[42:45]
	v_mfma_f32_16x16x32_bf16 v[30:33], v[154:157], v[206:209], v[30:33]
	v_mfma_f32_16x16x32_bf16 v[26:29], v[162:165], v[206:209], v[26:29]
	v_mfma_f32_16x16x32_bf16 v[14:17], v[154:157], v[214:217], v[14:17]
	v_mfma_f32_16x16x32_bf16 v[10:13], v[162:165], v[214:217], v[10:13]
	v_mfma_f32_16x16x32_bf16 v[62:65], v[158:161], v[190:193], v[62:65]
	v_mfma_f32_16x16x32_bf16 v[58:61], v[166:169], v[190:193], v[58:61]
	v_mfma_f32_16x16x32_bf16 v[46:49], v[158:161], v[198:201], v[46:49]
	v_mfma_f32_16x16x32_bf16 v[42:45], v[166:169], v[198:201], v[42:45]
	v_mfma_f32_16x16x32_bf16 v[30:33], v[158:161], v[210:213], v[30:33]
	v_mfma_f32_16x16x32_bf16 v[26:29], v[166:169], v[210:213], v[26:29]
	v_mfma_f32_16x16x32_bf16 v[14:17], v[158:161], v[218:221], v[14:17]
	v_mfma_f32_16x16x32_bf16 v[10:13], v[166:169], v[218:221], v[10:13]
	v_mfma_f32_16x16x32_bf16 v[54:57], v[170:173], v[186:189], v[54:57]
	v_mfma_f32_16x16x32_bf16 v[50:53], v[178:181], v[186:189], v[50:53]
	v_mfma_f32_16x16x32_bf16 v[38:41], v[170:173], v[194:197], v[38:41]
	v_mfma_f32_16x16x32_bf16 v[34:37], v[178:181], v[194:197], v[34:37]
	v_mfma_f32_16x16x32_bf16 v[22:25], v[170:173], v[206:209], v[22:25]
	v_mfma_f32_16x16x32_bf16 v[18:21], v[178:181], v[206:209], v[18:21]
	v_mfma_f32_16x16x32_bf16 v[6:9], v[170:173], v[214:217], v[6:9]
	v_mfma_f32_16x16x32_bf16 v[2:5], v[178:181], v[214:217], v[2:5]
	v_mfma_f32_16x16x32_bf16 v[54:57], v[174:177], v[190:193], v[54:57]
	v_mfma_f32_16x16x32_bf16 v[50:53], v[182:185], v[190:193], v[50:53]
	v_mfma_f32_16x16x32_bf16 v[38:41], v[174:177], v[198:201], v[38:41]
	v_mfma_f32_16x16x32_bf16 v[34:37], v[182:185], v[198:201], v[34:37]
	v_mfma_f32_16x16x32_bf16 v[22:25], v[174:177], v[210:213], v[22:25]
	v_mfma_f32_16x16x32_bf16 v[18:21], v[182:185], v[210:213], v[18:21]
	v_mfma_f32_16x16x32_bf16 v[6:9], v[174:177], v[218:221], v[6:9]
	v_mfma_f32_16x16x32_bf16 v[2:5], v[182:185], v[218:221], v[2:5]
	s_barrier
	s_setprio 0
	s_add_i32 s62, s62, 2
	s_add_u32 s28, s28, 0x100
	s_addc_u32 s29, s29, 0
	s_add_u32 s50, s50, 0x100
	s_addc_u32 s51, s51, 0
	s_cmp_gt_u32 s62, 13
.LBB0_1619:
	ds_read_b128 v[154:157], v150
	ds_read_b128 v[158:161], v150 offset:1024
	ds_read_b128 v[162:165], v150 offset:2048
	ds_read_b128 v[166:169], v150 offset:3072
	ds_read_b128 v[170:173], v151
	ds_read_b128 v[174:177], v151 offset:1024
	ds_read_b128 v[178:181], v151 offset:2048
	ds_read_b128 v[182:185], v151 offset:3072
	s_add_u32 s30, s28, 0xfffc0080
	s_addc_u32 s31, s29, -1
	s_cmp_eq_u32 s62, 12
	s_cselect_b32 s37, s14, s31
	s_cselect_b32 s36, s15, s30
	s_cselect_b32 s31, s17, s51
	s_cselect_b32 s30, s49, s50
	v_lshl_add_u64 v[146:147], s[28:29], 0, v[138:139]
	s_add_i32 m0, s19, 0xc000
	ds_read_b128 v[186:189], v152
	ds_read_b128 v[190:193], v152 offset:1024
	ds_read_b128 v[194:197], v152 offset:2048
	ds_read_b128 v[198:201], v152 offset:3072
	ds_read_b128 v[206:209], v152 offset:4096
	ds_read_b128 v[210:213], v152 offset:5120
	ds_read_b128 v[214:217], v152 offset:6144
	ds_read_b128 v[218:221], v152 offset:7168
	global_load_lds_dwordx4 v[146:147], off
	v_lshl_add_u64 v[146:147], s[28:29], 0, v[140:141]
	s_add_i32 m0, s19, 0xe000
	s_nop 0
	global_load_lds_dwordx4 v[146:147], off
	s_waitcnt vmcnt(8)
	s_waitcnt lgkmcnt(0)
	s_setprio 1
	s_barrier
	v_mfma_f32_16x16x32_bf16 v[126:129], v[154:157], v[186:189], v[126:129]
	v_mfma_f32_16x16x32_bf16 v[122:125], v[162:165], v[186:189], v[122:125]
	v_mfma_f32_16x16x32_bf16 v[110:113], v[154:157], v[194:197], v[110:113]
	v_mfma_f32_16x16x32_bf16 v[106:109], v[162:165], v[194:197], v[106:109]
	v_mfma_f32_16x16x32_bf16 v[94:97], v[154:157], v[206:209], v[94:97]
	v_mfma_f32_16x16x32_bf16 v[90:93], v[162:165], v[206:209], v[90:93]
	v_mfma_f32_16x16x32_bf16 v[78:81], v[154:157], v[214:217], v[78:81]
	v_mfma_f32_16x16x32_bf16 v[74:77], v[162:165], v[214:217], v[74:77]
	v_mfma_f32_16x16x32_bf16 v[126:129], v[158:161], v[190:193], v[126:129]
	v_mfma_f32_16x16x32_bf16 v[122:125], v[166:169], v[190:193], v[122:125]
	v_mfma_f32_16x16x32_bf16 v[110:113], v[158:161], v[198:201], v[110:113]
	v_mfma_f32_16x16x32_bf16 v[106:109], v[166:169], v[198:201], v[106:109]
	v_mfma_f32_16x16x32_bf16 v[94:97], v[158:161], v[210:213], v[94:97]
	v_mfma_f32_16x16x32_bf16 v[90:93], v[166:169], v[210:213], v[90:93]
	v_mfma_f32_16x16x32_bf16 v[78:81], v[158:161], v[218:221], v[78:81]
	v_mfma_f32_16x16x32_bf16 v[74:77], v[166:169], v[218:221], v[74:77]
	v_mfma_f32_16x16x32_bf16 v[118:121], v[170:173], v[186:189], v[118:121]
	v_mfma_f32_16x16x32_bf16 v[114:117], v[178:181], v[186:189], v[114:117]
	v_mfma_f32_16x16x32_bf16 v[102:105], v[170:173], v[194:197], v[102:105]
	v_mfma_f32_16x16x32_bf16 v[98:101], v[178:181], v[194:197], v[98:101]
	v_mfma_f32_16x16x32_bf16 v[86:89], v[170:173], v[206:209], v[86:89]
	v_mfma_f32_16x16x32_bf16 v[82:85], v[178:181], v[206:209], v[82:85]
	v_mfma_f32_16x16x32_bf16 v[70:73], v[170:173], v[214:217], v[70:73]
	v_mfma_f32_16x16x32_bf16 v[66:69], v[178:181], v[214:217], v[66:69]
	v_mfma_f32_16x16x32_bf16 v[118:121], v[174:177], v[190:193], v[118:121]
	v_mfma_f32_16x16x32_bf16 v[114:117], v[182:185], v[190:193], v[114:117]
	v_mfma_f32_16x16x32_bf16 v[102:105], v[174:177], v[198:201], v[102:105]
	v_mfma_f32_16x16x32_bf16 v[98:101], v[182:185], v[198:201], v[98:101]
	v_mfma_f32_16x16x32_bf16 v[86:89], v[174:177], v[210:213], v[86:89]
	v_mfma_f32_16x16x32_bf16 v[82:85], v[182:185], v[210:213], v[82:85]
	v_mfma_f32_16x16x32_bf16 v[70:73], v[174:177], v[218:221], v[70:73]
	v_mfma_f32_16x16x32_bf16 v[66:69], v[182:185], v[218:221], v[66:69]
	s_barrier
	s_setprio 0
	s_add_i32 s63, s45, s12
	v_lshl_add_u64 v[146:147], s[30:31], 0, v[134:135]
	s_mov_b32 m0, s63
	ds_read_b128 v[186:189], v152 offset:16384
	ds_read_b128 v[190:193], v152 offset:17408
	ds_read_b128 v[194:197], v152 offset:18432
	ds_read_b128 v[198:201], v152 offset:19456
	ds_read_b128 v[206:209], v152 offset:20480
	ds_read_b128 v[210:213], v152 offset:21504
	ds_read_b128 v[214:217], v152 offset:22528
	ds_read_b128 v[218:221], v152 offset:23552
	global_load_lds_dwordx4 v[146:147], off
	s_add_i32 m0, s63, 0x2000
	s_add_u32 s64, s30, 0x40000
	v_lshl_add_u64 v[202:203], s[30:31], 0, v[130:131]
	s_addc_u32 s65, s31, 0
	s_add_i32 s63, s46, s12
	global_load_lds_dwordx4 v[202:203], off
	v_lshl_add_u64 v[222:223], s[64:65], 0, v[134:135]
	s_mov_b32 m0, s63
	v_lshl_add_u64 v[224:225], s[36:37], 0, v[132:133]
	global_load_lds_dwordx4 v[222:223], off
	v_lshl_add_u64 v[222:223], s[64:65], 0, v[130:131]
	s_add_i32 m0, s63, 0x2000
	s_nop 0
	global_load_lds_dwordx4 v[222:223], off
	v_lshl_add_u64 v[222:223], s[36:37], 0, v[136:137]
	s_mov_b32 m0, s19
	s_nop 0
	global_load_lds_dwordx4 v[222:223], off
	s_mov_b32 m0, s33
	s_nop 0
	global_load_lds_dwordx4 v[224:225], off
	s_waitcnt vmcnt(8)
	s_waitcnt lgkmcnt(0)
	s_setprio 1
	s_barrier
	v_mfma_f32_16x16x32_bf16 v[62:65], v[154:157], v[186:189], v[62:65]
	v_mfma_f32_16x16x32_bf16 v[58:61], v[162:165], v[186:189], v[58:61]
	v_mfma_f32_16x16x32_bf16 v[46:49], v[154:157], v[194:197], v[46:49]
	v_mfma_f32_16x16x32_bf16 v[42:45], v[162:165], v[194:197], v[42:45]
	v_mfma_f32_16x16x32_bf16 v[30:33], v[154:157], v[206:209], v[30:33]
	v_mfma_f32_16x16x32_bf16 v[26:29], v[162:165], v[206:209], v[26:29]
	v_mfma_f32_16x16x32_bf16 v[14:17], v[154:157], v[214:217], v[14:17]
	v_mfma_f32_16x16x32_bf16 v[10:13], v[162:165], v[214:217], v[10:13]
	v_mfma_f32_16x16x32_bf16 v[62:65], v[158:161], v[190:193], v[62:65]
	v_mfma_f32_16x16x32_bf16 v[58:61], v[166:169], v[190:193], v[58:61]
	v_mfma_f32_16x16x32_bf16 v[46:49], v[158:161], v[198:201], v[46:49]
	v_mfma_f32_16x16x32_bf16 v[42:45], v[166:169], v[198:201], v[42:45]
	v_mfma_f32_16x16x32_bf16 v[30:33], v[158:161], v[210:213], v[30:33]
	v_mfma_f32_16x16x32_bf16 v[26:29], v[166:169], v[210:213], v[26:29]
	v_mfma_f32_16x16x32_bf16 v[14:17], v[158:161], v[218:221], v[14:17]
	v_mfma_f32_16x16x32_bf16 v[10:13], v[166:169], v[218:221], v[10:13]
	v_mfma_f32_16x16x32_bf16 v[54:57], v[170:173], v[186:189], v[54:57]
	v_mfma_f32_16x16x32_bf16 v[50:53], v[178:181], v[186:189], v[50:53]
	v_mfma_f32_16x16x32_bf16 v[38:41], v[170:173], v[194:197], v[38:41]
	v_mfma_f32_16x16x32_bf16 v[34:37], v[178:181], v[194:197], v[34:37]
	v_mfma_f32_16x16x32_bf16 v[22:25], v[170:173], v[206:209], v[22:25]
	v_mfma_f32_16x16x32_bf16 v[18:21], v[178:181], v[206:209], v[18:21]
	v_mfma_f32_16x16x32_bf16 v[6:9], v[170:173], v[214:217], v[6:9]
	v_mfma_f32_16x16x32_bf16 v[2:5], v[178:181], v[214:217], v[2:5]
	v_mfma_f32_16x16x32_bf16 v[54:57], v[174:177], v[190:193], v[54:57]
	v_mfma_f32_16x16x32_bf16 v[50:53], v[182:185], v[190:193], v[50:53]
	v_mfma_f32_16x16x32_bf16 v[38:41], v[174:177], v[198:201], v[38:41]
	v_mfma_f32_16x16x32_bf16 v[34:37], v[182:185], v[198:201], v[34:37]
	v_mfma_f32_16x16x32_bf16 v[22:25], v[174:177], v[210:213], v[22:25]
	v_mfma_f32_16x16x32_bf16 v[18:21], v[182:185], v[210:213], v[18:21]
	v_mfma_f32_16x16x32_bf16 v[6:9], v[174:177], v[218:221], v[6:9]
	v_mfma_f32_16x16x32_bf16 v[2:5], v[182:185], v[218:221], v[2:5]
	s_barrier
	s_setprio 0
	s_add_i32 s63, 0, 0x18000
	v_add_u32_e32 v153, s63, v149
	s_add_i32 s64, 0, 0x1c000
	ds_read_b128 v[154:157], v153
	ds_read_b128 v[158:161], v153 offset:1024
	ds_read_b128 v[162:165], v153 offset:2048
	ds_read_b128 v[166:169], v153 offset:3072
	v_add_u32_e32 v153, s64, v149
	ds_read_b128 v[170:173], v153
	ds_read_b128 v[174:177], v153 offset:1024
	ds_read_b128 v[178:181], v153 offset:2048
	ds_read_b128 v[182:185], v153 offset:3072
	s_add_u32 s36, s36, 0x40000
	s_addc_u32 s37, s37, 0
	s_mov_b32 m0, s35
	v_lshl_add_u64 v[226:227], s[36:37], 0, v[136:137]
	ds_read_b128 v[186:189], v152 offset:32768
	ds_read_b128 v[190:193], v152 offset:33792
	ds_read_b128 v[194:197], v152 offset:34816
	ds_read_b128 v[198:201], v152 offset:35840
	ds_read_b128 v[206:209], v152 offset:36864
	ds_read_b128 v[210:213], v152 offset:37888
	ds_read_b128 v[214:217], v152 offset:38912
	ds_read_b128 v[218:221], v152 offset:39936
	global_load_lds_dwordx4 v[226:227], off
	v_lshl_add_u64 v[226:227], s[36:37], 0, v[132:133]
	s_mov_b32 m0, s38
	s_nop 0
	global_load_lds_dwordx4 v[226:227], off
	s_waitcnt vmcnt(8)
	s_waitcnt lgkmcnt(0)
	s_setprio 1
	s_barrier
	v_mfma_f32_16x16x32_bf16 v[126:129], v[154:157], v[186:189], v[126:129]
	v_mfma_f32_16x16x32_bf16 v[122:125], v[162:165], v[186:189], v[122:125]
	v_mfma_f32_16x16x32_bf16 v[110:113], v[154:157], v[194:197], v[110:113]
	v_mfma_f32_16x16x32_bf16 v[106:109], v[162:165], v[194:197], v[106:109]
	v_mfma_f32_16x16x32_bf16 v[94:97], v[154:157], v[206:209], v[94:97]
	v_mfma_f32_16x16x32_bf16 v[90:93], v[162:165], v[206:209], v[90:93]
	v_mfma_f32_16x16x32_bf16 v[78:81], v[154:157], v[214:217], v[78:81]
	v_mfma_f32_16x16x32_bf16 v[74:77], v[162:165], v[214:217], v[74:77]
	v_mfma_f32_16x16x32_bf16 v[126:129], v[158:161], v[190:193], v[126:129]
	v_mfma_f32_16x16x32_bf16 v[122:125], v[166:169], v[190:193], v[122:125]
	v_mfma_f32_16x16x32_bf16 v[110:113], v[158:161], v[198:201], v[110:113]
	v_mfma_f32_16x16x32_bf16 v[106:109], v[166:169], v[198:201], v[106:109]
	v_mfma_f32_16x16x32_bf16 v[94:97], v[158:161], v[210:213], v[94:97]
	v_mfma_f32_16x16x32_bf16 v[90:93], v[166:169], v[210:213], v[90:93]
	v_mfma_f32_16x16x32_bf16 v[78:81], v[158:161], v[218:221], v[78:81]
	v_mfma_f32_16x16x32_bf16 v[74:77], v[166:169], v[218:221], v[74:77]
	v_mfma_f32_16x16x32_bf16 v[118:121], v[170:173], v[186:189], v[118:121]
	v_mfma_f32_16x16x32_bf16 v[114:117], v[178:181], v[186:189], v[114:117]
	v_mfma_f32_16x16x32_bf16 v[102:105], v[170:173], v[194:197], v[102:105]
	v_mfma_f32_16x16x32_bf16 v[98:101], v[178:181], v[194:197], v[98:101]
	v_mfma_f32_16x16x32_bf16 v[86:89], v[170:173], v[206:209], v[86:89]
	v_mfma_f32_16x16x32_bf16 v[82:85], v[178:181], v[206:209], v[82:85]
	v_mfma_f32_16x16x32_bf16 v[70:73], v[170:173], v[214:217], v[70:73]
	v_mfma_f32_16x16x32_bf16 v[66:69], v[178:181], v[214:217], v[66:69]
	v_mfma_f32_16x16x32_bf16 v[118:121], v[174:177], v[190:193], v[118:121]
	v_mfma_f32_16x16x32_bf16 v[114:117], v[182:185], v[190:193], v[114:117]
	v_mfma_f32_16x16x32_bf16 v[102:105], v[174:177], v[198:201], v[102:105]
	v_mfma_f32_16x16x32_bf16 v[98:101], v[182:185], v[198:201], v[98:101]
	v_mfma_f32_16x16x32_bf16 v[86:89], v[174:177], v[210:213], v[86:89]
	v_mfma_f32_16x16x32_bf16 v[82:85], v[182:185], v[210:213], v[82:85]
	v_mfma_f32_16x16x32_bf16 v[70:73], v[174:177], v[218:221], v[70:73]
	v_mfma_f32_16x16x32_bf16 v[66:69], v[182:185], v[218:221], v[66:69]
	s_barrier
	s_setprio 0
	s_add_i32 s36, s63, s12
	v_lshl_add_u64 v[146:147], v[146:147], 0, s[8:9]
	s_mov_b32 m0, s36
	ds_read_b128 v[186:189], v152 offset:49152
	ds_read_b128 v[190:193], v152 offset:50176
	ds_read_b128 v[194:197], v152 offset:51200
	ds_read_b128 v[198:201], v152 offset:52224
	ds_read_b128 v[206:209], v152 offset:53248
	ds_read_b128 v[210:213], v152 offset:54272
	ds_read_b128 v[214:217], v152 offset:55296
	ds_read_b128 v[218:221], v152 offset:56320
	global_load_lds_dwordx4 v[146:147], off
	s_add_i32 m0, s36, 0x2000
	s_add_u32 s30, s30, 0x40080
	v_lshl_add_u64 v[146:147], v[202:203], 0, s[8:9]
	s_addc_u32 s31, s31, 0
	s_add_i32 s36, s64, s12
	global_load_lds_dwordx4 v[146:147], off
	v_lshl_add_u64 v[146:147], s[30:31], 0, v[134:135]
	s_mov_b32 m0, s36
	s_nop 0
	global_load_lds_dwordx4 v[146:147], off
	v_lshl_add_u64 v[146:147], s[30:31], 0, v[130:131]
	s_add_i32 m0, s36, 0x2000
	s_nop 0
	global_load_lds_dwordx4 v[146:147], off
	v_lshl_add_u64 v[146:147], v[222:223], 0, s[8:9]
	s_mov_b32 m0, s42
	s_nop 0
	global_load_lds_dwordx4 v[146:147], off
	v_lshl_add_u64 v[146:147], v[224:225], 0, s[8:9]
	s_mov_b32 m0, s43
	s_nop 0
	global_load_lds_dwordx4 v[146:147], off
	s_waitcnt vmcnt(8)
	s_waitcnt lgkmcnt(0)
	s_setprio 1
	s_barrier
	v_mfma_f32_16x16x32_bf16 v[62:65], v[154:157], v[186:189], v[62:65]
	v_mfma_f32_16x16x32_bf16 v[58:61], v[162:165], v[186:189], v[58:61]
	v_mfma_f32_16x16x32_bf16 v[46:49], v[154:157], v[194:197], v[46:49]
	v_mfma_f32_16x16x32_bf16 v[42:45], v[162:165], v[194:197], v[42:45]
	v_mfma_f32_16x16x32_bf16 v[30:33], v[154:157], v[206:209], v[30:33]
	v_mfma_f32_16x16x32_bf16 v[26:29], v[162:165], v[206:209], v[26:29]
	v_mfma_f32_16x16x32_bf16 v[14:17], v[154:157], v[214:217], v[14:17]
	v_mfma_f32_16x16x32_bf16 v[10:13], v[162:165], v[214:217], v[10:13]
	v_mfma_f32_16x16x32_bf16 v[62:65], v[158:161], v[190:193], v[62:65]
	v_mfma_f32_16x16x32_bf16 v[58:61], v[166:169], v[190:193], v[58:61]
	v_mfma_f32_16x16x32_bf16 v[46:49], v[158:161], v[198:201], v[46:49]
	v_mfma_f32_16x16x32_bf16 v[42:45], v[166:169], v[198:201], v[42:45]
	v_mfma_f32_16x16x32_bf16 v[30:33], v[158:161], v[210:213], v[30:33]
	v_mfma_f32_16x16x32_bf16 v[26:29], v[166:169], v[210:213], v[26:29]
	v_mfma_f32_16x16x32_bf16 v[14:17], v[158:161], v[218:221], v[14:17]
	v_mfma_f32_16x16x32_bf16 v[10:13], v[166:169], v[218:221], v[10:13]
	v_mfma_f32_16x16x32_bf16 v[54:57], v[170:173], v[186:189], v[54:57]
	v_mfma_f32_16x16x32_bf16 v[50:53], v[178:181], v[186:189], v[50:53]
	v_mfma_f32_16x16x32_bf16 v[38:41], v[170:173], v[194:197], v[38:41]
	v_mfma_f32_16x16x32_bf16 v[34:37], v[178:181], v[194:197], v[34:37]
	v_mfma_f32_16x16x32_bf16 v[22:25], v[170:173], v[206:209], v[22:25]
	v_mfma_f32_16x16x32_bf16 v[18:21], v[178:181], v[206:209], v[18:21]
	v_mfma_f32_16x16x32_bf16 v[6:9], v[170:173], v[214:217], v[6:9]
	v_mfma_f32_16x16x32_bf16 v[2:5], v[178:181], v[214:217], v[2:5]
	v_mfma_f32_16x16x32_bf16 v[54:57], v[174:177], v[190:193], v[54:57]
	v_mfma_f32_16x16x32_bf16 v[50:53], v[182:185], v[190:193], v[50:53]
	v_mfma_f32_16x16x32_bf16 v[38:41], v[174:177], v[198:201], v[38:41]
	v_mfma_f32_16x16x32_bf16 v[34:37], v[182:185], v[198:201], v[34:37]
	v_mfma_f32_16x16x32_bf16 v[22:25], v[174:177], v[210:213], v[22:25]
	v_mfma_f32_16x16x32_bf16 v[18:21], v[182:185], v[210:213], v[18:21]
	v_mfma_f32_16x16x32_bf16 v[6:9], v[174:177], v[218:221], v[6:9]
	v_mfma_f32_16x16x32_bf16 v[2:5], v[182:185], v[218:221], v[2:5]
	s_barrier
	s_setprio 0
	s_add_i32 s62, s62, 2
	s_add_u32 s28, s28, 0x100
	s_addc_u32 s29, s29, 0
	s_add_u32 s50, s50, 0x100
	s_addc_u32 s51, s51, 0
	s_cmp_gt_u32 s62, 13
	s_cbranch_scc0 .LBB0_1619
	s_and_b64 vcc, exec, s[10:11]
	s_cbranch_vccz .LBB0_1622
	s_barrier

.LBB0_1707:
	v_readlane_b32 s46, v249, 32
	v_readlane_b32 s47, v249, 33
	s_add_u32 s46, s46, s42
	s_addc_u32 s47, s47, s43
	s_and_b64 s[48:49], s[44:45], exec
	s_cselect_b32 s34, s47, s51
	s_cselect_b32 s66, s46, s50
	s_add_u32 s48, s35, s40
	s_addc_u32 s49, s70, s41
	s_and_b64 s[64:65], s[44:45], exec
	s_cselect_b32 s67, s49, s63
	s_cselect_b32 s68, s48, s62
	s_add_i32 s69, s7, -2
	s_add_u32 s50, s50, 0x100080
	s_addc_u32 s51, s51, 0
	s_add_u32 s91, s62, 0x100
	s_addc_u32 s92, s63, 0
	s_mov_b32 s62, 0
	s_waitcnt vmcnt(0)
	ds_read_b128 v[130:133], v168
	ds_read_b128 v[134:137], v168 offset:1024
	ds_read_b128 v[138:141], v168 offset:2048
	ds_read_b128 v[142:145], v168 offset:3072
	ds_read_b128 v[162:165], v169
	ds_read_b128 v[172:175], v169 offset:1024
	ds_read_b128 v[176:179], v169 offset:2048
	ds_read_b128 v[180:183], v169 offset:3072
	s_add_i32 s93, s62, 2
	s_add_u32 s63, s50, 0xfff00080
	s_addc_u32 s64, s51, -1
	s_cmp_eq_u32 s69, s62
	s_cselect_b32 s62, s68, s91
	s_cselect_b32 s65, s34, s64
	s_cselect_b32 s64, s66, s63
	s_cselect_b32 s63, s67, s92
	v_lshl_add_u64 v[218:219], s[50:51], 0, v[156:157]
	s_add_i32 m0, s12, 0xc000
	ds_read_b128 v[184:187], v170
	ds_read_b128 v[188:191], v170 offset:1024
	ds_read_b128 v[192:195], v170 offset:2048
	ds_read_b128 v[196:199], v170 offset:3072
	ds_read_b128 v[200:203], v170 offset:4096
	ds_read_b128 v[206:209], v170 offset:5120
	ds_read_b128 v[210:213], v170 offset:6144
	ds_read_b128 v[214:217], v170 offset:7168
	global_load_lds_dwordx4 v[218:219], off
	v_lshl_add_u64 v[218:219], s[50:51], 0, v[158:159]
	s_add_i32 m0, s12, 0xe000
	s_nop 0
	global_load_lds_dwordx4 v[218:219], off
	s_waitcnt vmcnt(8)
	s_waitcnt lgkmcnt(0)
	s_setprio 1
	s_barrier
	v_mfma_f32_16x16x32_bf16 v[126:129], v[130:133], v[184:187], 0
	v_mfma_f32_16x16x32_bf16 v[122:125], v[138:141], v[184:187], 0
	v_mfma_f32_16x16x32_bf16 v[110:113], v[130:133], v[192:195], 0
	v_mfma_f32_16x16x32_bf16 v[106:109], v[138:141], v[192:195], 0
	v_mfma_f32_16x16x32_bf16 v[98:101], v[130:133], v[200:203], 0
	v_mfma_f32_16x16x32_bf16 v[90:93], v[138:141], v[200:203], 0
	v_mfma_f32_16x16x32_bf16 v[82:85], v[130:133], v[210:213], 0
	v_mfma_f32_16x16x32_bf16 v[74:77], v[138:141], v[210:213], 0
	v_mfma_f32_16x16x32_bf16 v[126:129], v[134:137], v[188:191], v[126:129]
	v_mfma_f32_16x16x32_bf16 v[122:125], v[142:145], v[188:191], v[122:125]
	v_mfma_f32_16x16x32_bf16 v[110:113], v[134:137], v[196:199], v[110:113]
	v_mfma_f32_16x16x32_bf16 v[106:109], v[142:145], v[196:199], v[106:109]
	v_mfma_f32_16x16x32_bf16 v[98:101], v[134:137], v[206:209], v[98:101]
	v_mfma_f32_16x16x32_bf16 v[90:93], v[142:145], v[206:209], v[90:93]
	v_mfma_f32_16x16x32_bf16 v[82:85], v[134:137], v[214:217], v[82:85]
	v_mfma_f32_16x16x32_bf16 v[74:77], v[142:145], v[214:217], v[74:77]
	v_mfma_f32_16x16x32_bf16 v[118:121], v[162:165], v[184:187], 0
	v_mfma_f32_16x16x32_bf16 v[114:117], v[176:179], v[184:187], 0
	v_mfma_f32_16x16x32_bf16 v[102:105], v[162:165], v[192:195], 0
	v_mfma_f32_16x16x32_bf16 v[94:97], v[176:179], v[192:195], 0
	v_mfma_f32_16x16x32_bf16 v[86:89], v[162:165], v[200:203], 0
	v_mfma_f32_16x16x32_bf16 v[78:81], v[176:179], v[200:203], 0
	v_mfma_f32_16x16x32_bf16 v[70:73], v[162:165], v[210:213], 0
	v_mfma_f32_16x16x32_bf16 v[66:69], v[176:179], v[210:213], 0
	v_mfma_f32_16x16x32_bf16 v[118:121], v[172:175], v[188:191], v[118:121]
	v_mfma_f32_16x16x32_bf16 v[114:117], v[180:183], v[188:191], v[114:117]
	v_mfma_f32_16x16x32_bf16 v[102:105], v[172:175], v[196:199], v[102:105]
	v_mfma_f32_16x16x32_bf16 v[94:97], v[180:183], v[196:199], v[94:97]
	v_mfma_f32_16x16x32_bf16 v[86:89], v[172:175], v[206:209], v[86:89]
	v_mfma_f32_16x16x32_bf16 v[78:81], v[180:183], v[206:209], v[78:81]
	v_mfma_f32_16x16x32_bf16 v[70:73], v[172:175], v[214:217], v[70:73]
	v_mfma_f32_16x16x32_bf16 v[66:69], v[180:183], v[214:217], v[66:69]
	s_barrier
	s_setprio 0
	s_add_i32 s94, s31, s2
	v_lshl_add_u64 v[218:219], s[62:63], 0, v[148:149]
	s_mov_b32 m0, s94
	ds_read_b128 v[184:187], v170 offset:16384
	ds_read_b128 v[188:191], v170 offset:17408
	ds_read_b128 v[192:195], v170 offset:18432
	ds_read_b128 v[196:199], v170 offset:19456
	ds_read_b128 v[200:203], v170 offset:20480
	ds_read_b128 v[206:209], v170 offset:21504
	ds_read_b128 v[210:213], v170 offset:22528
	ds_read_b128 v[214:217], v170 offset:23552
	global_load_lds_dwordx4 v[218:219], off
	s_add_i32 m0, s94, 0x2000
	s_add_u32 s94, s62, 0x100000
	v_lshl_add_u64 v[220:221], s[62:63], 0, v[152:153]
	s_addc_u32 s95, s63, 0
	s_add_i32 s96, s82, s2
	global_load_lds_dwordx4 v[220:221], off
	v_lshl_add_u64 v[222:223], s[94:95], 0, v[148:149]
	s_mov_b32 m0, s96
	v_lshl_add_u64 v[224:225], s[64:65], 0, v[150:151]
	global_load_lds_dwordx4 v[222:223], off
	v_lshl_add_u64 v[222:223], s[94:95], 0, v[152:153]
	s_add_i32 m0, s96, 0x2000
	s_nop 0
	global_load_lds_dwordx4 v[222:223], off
	v_lshl_add_u64 v[222:223], s[64:65], 0, v[146:147]
	s_mov_b32 m0, s12
	s_nop 0
	global_load_lds_dwordx4 v[222:223], off
	s_mov_b32 m0, s13
	s_nop 0
	global_load_lds_dwordx4 v[224:225], off
	s_waitcnt vmcnt(8)
	s_waitcnt lgkmcnt(0)
	s_setprio 1
	s_barrier
	v_mfma_f32_16x16x32_bf16 v[62:65], v[130:133], v[184:187], 0
	v_mfma_f32_16x16x32_bf16 v[58:61], v[138:141], v[184:187], 0
	v_mfma_f32_16x16x32_bf16 v[50:53], v[130:133], v[192:195], 0
	v_mfma_f32_16x16x32_bf16 v[42:45], v[138:141], v[192:195], 0
	v_mfma_f32_16x16x32_bf16 v[34:37], v[130:133], v[200:203], 0
	v_mfma_f32_16x16x32_bf16 v[26:29], v[138:141], v[200:203], 0
	v_mfma_f32_16x16x32_bf16 v[18:21], v[130:133], v[210:213], 0
	v_mfma_f32_16x16x32_bf16 v[10:13], v[138:141], v[210:213], 0
	v_mfma_f32_16x16x32_bf16 v[62:65], v[134:137], v[188:191], v[62:65]
	v_mfma_f32_16x16x32_bf16 v[58:61], v[142:145], v[188:191], v[58:61]
	v_mfma_f32_16x16x32_bf16 v[50:53], v[134:137], v[196:199], v[50:53]
	v_mfma_f32_16x16x32_bf16 v[42:45], v[142:145], v[196:199], v[42:45]
	v_mfma_f32_16x16x32_bf16 v[34:37], v[134:137], v[206:209], v[34:37]
	v_mfma_f32_16x16x32_bf16 v[26:29], v[142:145], v[206:209], v[26:29]
	v_mfma_f32_16x16x32_bf16 v[18:21], v[134:137], v[214:217], v[18:21]
	v_mfma_f32_16x16x32_bf16 v[10:13], v[142:145], v[214:217], v[10:13]
	v_mfma_f32_16x16x32_bf16 v[54:57], v[162:165], v[184:187], 0
	v_mfma_f32_16x16x32_bf16 v[46:49], v[176:179], v[184:187], 0
	v_mfma_f32_16x16x32_bf16 v[38:41], v[162:165], v[192:195], 0
	v_mfma_f32_16x16x32_bf16 v[30:33], v[176:179], v[192:195], 0
	v_mfma_f32_16x16x32_bf16 v[22:25], v[162:165], v[200:203], 0
	v_mfma_f32_16x16x32_bf16 v[14:17], v[176:179], v[200:203], 0
	v_mfma_f32_16x16x32_bf16 v[6:9], v[162:165], v[210:213], 0
	v_mfma_f32_16x16x32_bf16 v[2:5], v[176:179], v[210:213], 0
	v_mfma_f32_16x16x32_bf16 v[54:57], v[172:175], v[188:191], v[54:57]
	v_mfma_f32_16x16x32_bf16 v[46:49], v[180:183], v[188:191], v[46:49]
	v_mfma_f32_16x16x32_bf16 v[38:41], v[172:175], v[196:199], v[38:41]
	v_mfma_f32_16x16x32_bf16 v[30:33], v[180:183], v[196:199], v[30:33]
	v_mfma_f32_16x16x32_bf16 v[22:25], v[172:175], v[206:209], v[22:25]
	v_mfma_f32_16x16x32_bf16 v[14:17], v[180:183], v[206:209], v[14:17]
	v_mfma_f32_16x16x32_bf16 v[6:9], v[172:175], v[214:217], v[6:9]
	v_mfma_f32_16x16x32_bf16 v[2:5], v[180:183], v[214:217], v[2:5]
	s_barrier
	s_setprio 0
	s_add_i32 s94, 0, 0x18000
	s_add_i32 s95, 0, 0x1c000
	v_add_u32_e32 v142, s94, v167
	v_add_u32_e32 v154, s95, v167
	ds_read_b128 v[130:133], v142
	ds_read_b128 v[134:137], v142 offset:1024
	ds_read_b128 v[138:141], v142 offset:2048
	ds_read_b128 v[142:145], v142 offset:3072
	ds_read_b128 v[162:165], v154
	ds_read_b128 v[172:175], v154 offset:1024
	ds_read_b128 v[176:179], v154 offset:2048
	ds_read_b128 v[180:183], v154 offset:3072
	s_add_u32 s64, s64, 0x100000
	s_addc_u32 s65, s65, 0
	s_mov_b32 m0, s18
	v_lshl_add_u64 v[226:227], s[64:65], 0, v[146:147]
	ds_read_b128 v[184:187], v170 offset:32768
	ds_read_b128 v[188:191], v170 offset:33792
	ds_read_b128 v[192:195], v170 offset:34816
	ds_read_b128 v[196:199], v170 offset:35840
	ds_read_b128 v[200:203], v170 offset:36864
	ds_read_b128 v[206:209], v170 offset:37888
	ds_read_b128 v[210:213], v170 offset:38912
	ds_read_b128 v[214:217], v170 offset:39936
	global_load_lds_dwordx4 v[226:227], off
	v_lshl_add_u64 v[226:227], s[64:65], 0, v[150:151]
	s_mov_b32 m0, s19
	s_nop 0
	global_load_lds_dwordx4 v[226:227], off
	s_waitcnt vmcnt(8)
	s_waitcnt lgkmcnt(0)
	s_setprio 1
	s_barrier
	v_mfma_f32_16x16x32_bf16 v[126:129], v[130:133], v[184:187], v[126:129]
	v_mfma_f32_16x16x32_bf16 v[122:125], v[138:141], v[184:187], v[122:125]
	v_mfma_f32_16x16x32_bf16 v[110:113], v[130:133], v[192:195], v[110:113]
	v_mfma_f32_16x16x32_bf16 v[106:109], v[138:141], v[192:195], v[106:109]
	v_mfma_f32_16x16x32_bf16 v[98:101], v[130:133], v[200:203], v[98:101]
	v_mfma_f32_16x16x32_bf16 v[90:93], v[138:141], v[200:203], v[90:93]
	v_mfma_f32_16x16x32_bf16 v[82:85], v[130:133], v[210:213], v[82:85]
	v_mfma_f32_16x16x32_bf16 v[74:77], v[138:141], v[210:213], v[74:77]
	v_mfma_f32_16x16x32_bf16 v[126:129], v[134:137], v[188:191], v[126:129]
	v_mfma_f32_16x16x32_bf16 v[122:125], v[142:145], v[188:191], v[122:125]
	v_mfma_f32_16x16x32_bf16 v[110:113], v[134:137], v[196:199], v[110:113]
	v_mfma_f32_16x16x32_bf16 v[106:109], v[142:145], v[196:199], v[106:109]
	v_mfma_f32_16x16x32_bf16 v[98:101], v[134:137], v[206:209], v[98:101]
	v_mfma_f32_16x16x32_bf16 v[90:93], v[142:145], v[206:209], v[90:93]
	v_mfma_f32_16x16x32_bf16 v[82:85], v[134:137], v[214:217], v[82:85]
	v_mfma_f32_16x16x32_bf16 v[74:77], v[142:145], v[214:217], v[74:77]
	v_mfma_f32_16x16x32_bf16 v[118:121], v[162:165], v[184:187], v[118:121]
	v_mfma_f32_16x16x32_bf16 v[114:117], v[176:179], v[184:187], v[114:117]
	v_mfma_f32_16x16x32_bf16 v[102:105], v[162:165], v[192:195], v[102:105]
	v_mfma_f32_16x16x32_bf16 v[94:97], v[176:179], v[192:195], v[94:97]
	v_mfma_f32_16x16x32_bf16 v[86:89], v[162:165], v[200:203], v[86:89]
	v_mfma_f32_16x16x32_bf16 v[78:81], v[176:179], v[200:203], v[78:81]
	v_mfma_f32_16x16x32_bf16 v[70:73], v[162:165], v[210:213], v[70:73]
	v_mfma_f32_16x16x32_bf16 v[66:69], v[176:179], v[210:213], v[66:69]
	v_mfma_f32_16x16x32_bf16 v[118:121], v[172:175], v[188:191], v[118:121]
	v_mfma_f32_16x16x32_bf16 v[114:117], v[180:183], v[188:191], v[114:117]
	v_mfma_f32_16x16x32_bf16 v[102:105], v[172:175], v[196:199], v[102:105]
	v_mfma_f32_16x16x32_bf16 v[94:97], v[180:183], v[196:199], v[94:97]
	v_mfma_f32_16x16x32_bf16 v[86:89], v[172:175], v[206:209], v[86:89]
	v_mfma_f32_16x16x32_bf16 v[78:81], v[180:183], v[206:209], v[78:81]
	v_mfma_f32_16x16x32_bf16 v[70:73], v[172:175], v[214:217], v[70:73]
	v_mfma_f32_16x16x32_bf16 v[66:69], v[180:183], v[214:217], v[66:69]
	s_barrier
	s_setprio 0
	s_add_i32 s64, s94, s2
	v_lshl_add_u64 v[218:219], v[218:219], 0, s[16:17]
	s_mov_b32 m0, s64
	ds_read_b128 v[184:187], v170 offset:49152
	ds_read_b128 v[188:191], v170 offset:50176
	ds_read_b128 v[192:195], v170 offset:51200
	ds_read_b128 v[196:199], v170 offset:52224
	ds_read_b128 v[200:203], v170 offset:53248
	ds_read_b128 v[206:209], v170 offset:54272
	ds_read_b128 v[210:213], v170 offset:55296
	ds_read_b128 v[214:217], v170 offset:56320
	global_load_lds_dwordx4 v[218:219], off
	s_add_i32 m0, s64, 0x2000
	s_add_u32 s62, s62, 0x100080
	v_lshl_add_u64 v[218:219], v[220:221], 0, s[16:17]
	s_addc_u32 s63, s63, 0
	s_add_i32 s64, s95, s2
	global_load_lds_dwordx4 v[218:219], off
	v_lshl_add_u64 v[218:219], s[62:63], 0, v[148:149]
	s_mov_b32 m0, s64
	s_nop 0
	global_load_lds_dwordx4 v[218:219], off
	v_lshl_add_u64 v[218:219], s[62:63], 0, v[152:153]
	s_add_i32 m0, s64, 0x2000
	s_nop 0
	global_load_lds_dwordx4 v[218:219], off
	v_lshl_add_u64 v[218:219], v[222:223], 0, s[16:17]
	s_mov_b32 m0, s74
	s_nop 0
	global_load_lds_dwordx4 v[218:219], off
	v_lshl_add_u64 v[218:219], v[224:225], 0, s[16:17]
	s_mov_b32 m0, s75
	s_nop 0
	global_load_lds_dwordx4 v[218:219], off
	s_waitcnt vmcnt(8)
	s_waitcnt lgkmcnt(0)
	s_setprio 1
	s_barrier
	v_mfma_f32_16x16x32_bf16 v[62:65], v[130:133], v[184:187], v[62:65]
	v_mfma_f32_16x16x32_bf16 v[58:61], v[138:141], v[184:187], v[58:61]
	v_mfma_f32_16x16x32_bf16 v[50:53], v[130:133], v[192:195], v[50:53]
	v_mfma_f32_16x16x32_bf16 v[42:45], v[138:141], v[192:195], v[42:45]
	v_mfma_f32_16x16x32_bf16 v[34:37], v[130:133], v[200:203], v[34:37]
	v_mfma_f32_16x16x32_bf16 v[26:29], v[138:141], v[200:203], v[26:29]
	v_mfma_f32_16x16x32_bf16 v[18:21], v[130:133], v[210:213], v[18:21]
	v_mfma_f32_16x16x32_bf16 v[10:13], v[138:141], v[210:213], v[10:13]
	v_mfma_f32_16x16x32_bf16 v[62:65], v[134:137], v[188:191], v[62:65]
	v_mfma_f32_16x16x32_bf16 v[58:61], v[142:145], v[188:191], v[58:61]
	v_mfma_f32_16x16x32_bf16 v[50:53], v[134:137], v[196:199], v[50:53]
	v_mfma_f32_16x16x32_bf16 v[42:45], v[142:145], v[196:199], v[42:45]
	v_mfma_f32_16x16x32_bf16 v[34:37], v[134:137], v[206:209], v[34:37]
	v_mfma_f32_16x16x32_bf16 v[26:29], v[142:145], v[206:209], v[26:29]
	v_mfma_f32_16x16x32_bf16 v[18:21], v[134:137], v[214:217], v[18:21]
	v_mfma_f32_16x16x32_bf16 v[10:13], v[142:145], v[214:217], v[10:13]
	v_mfma_f32_16x16x32_bf16 v[54:57], v[162:165], v[184:187], v[54:57]
	v_mfma_f32_16x16x32_bf16 v[46:49], v[176:179], v[184:187], v[46:49]
	v_mfma_f32_16x16x32_bf16 v[38:41], v[162:165], v[192:195], v[38:41]
	v_mfma_f32_16x16x32_bf16 v[30:33], v[176:179], v[192:195], v[30:33]
	v_mfma_f32_16x16x32_bf16 v[22:25], v[162:165], v[200:203], v[22:25]
	v_mfma_f32_16x16x32_bf16 v[14:17], v[176:179], v[200:203], v[14:17]
	v_mfma_f32_16x16x32_bf16 v[6:9], v[162:165], v[210:213], v[6:9]
	v_mfma_f32_16x16x32_bf16 v[2:5], v[176:179], v[210:213], v[2:5]
	v_mfma_f32_16x16x32_bf16 v[54:57], v[172:175], v[188:191], v[54:57]
	v_mfma_f32_16x16x32_bf16 v[46:49], v[180:183], v[188:191], v[46:49]
	v_mfma_f32_16x16x32_bf16 v[38:41], v[172:175], v[196:199], v[38:41]
	v_mfma_f32_16x16x32_bf16 v[30:33], v[180:183], v[196:199], v[30:33]
	v_mfma_f32_16x16x32_bf16 v[22:25], v[172:175], v[206:209], v[22:25]
	v_mfma_f32_16x16x32_bf16 v[14:17], v[180:183], v[206:209], v[14:17]
	v_mfma_f32_16x16x32_bf16 v[6:9], v[172:175], v[214:217], v[6:9]
	v_mfma_f32_16x16x32_bf16 v[2:5], v[180:183], v[214:217], v[2:5]
	s_barrier
	s_setprio 0
	s_add_u32 s50, s50, 0x100
	s_addc_u32 s51, s51, 0
	s_add_u32 s91, s91, 0x100
	s_addc_u32 s92, s92, 0
	s_cmp_ge_i32 s93, s7
	s_mov_b32 s62, s93
.LBB0_1708:
	ds_read_b128 v[130:133], v168
	ds_read_b128 v[134:137], v168 offset:1024
	ds_read_b128 v[138:141], v168 offset:2048
	ds_read_b128 v[142:145], v168 offset:3072
	ds_read_b128 v[162:165], v169
	ds_read_b128 v[172:175], v169 offset:1024
	ds_read_b128 v[176:179], v169 offset:2048
	ds_read_b128 v[180:183], v169 offset:3072
	s_add_i32 s93, s62, 2
	s_add_u32 s63, s50, 0xfff00080
	s_addc_u32 s64, s51, -1
	s_cmp_eq_u32 s69, s62
	s_cselect_b32 s62, s68, s91
	s_cselect_b32 s65, s34, s64
	s_cselect_b32 s64, s66, s63
	s_cselect_b32 s63, s67, s92
	v_lshl_add_u64 v[218:219], s[50:51], 0, v[156:157]
	s_add_i32 m0, s12, 0xc000
	ds_read_b128 v[184:187], v170
	ds_read_b128 v[188:191], v170 offset:1024
	ds_read_b128 v[192:195], v170 offset:2048
	ds_read_b128 v[196:199], v170 offset:3072
	ds_read_b128 v[200:203], v170 offset:4096
	ds_read_b128 v[206:209], v170 offset:5120
	ds_read_b128 v[210:213], v170 offset:6144
	ds_read_b128 v[214:217], v170 offset:7168
	global_load_lds_dwordx4 v[218:219], off
	v_lshl_add_u64 v[218:219], s[50:51], 0, v[158:159]
	s_add_i32 m0, s12, 0xe000
	s_nop 0
	global_load_lds_dwordx4 v[218:219], off
	s_waitcnt vmcnt(8)
	s_waitcnt lgkmcnt(0)
	s_setprio 1
	s_barrier
	v_mfma_f32_16x16x32_bf16 v[126:129], v[130:133], v[184:187], v[126:129]
	v_mfma_f32_16x16x32_bf16 v[122:125], v[138:141], v[184:187], v[122:125]
	v_mfma_f32_16x16x32_bf16 v[110:113], v[130:133], v[192:195], v[110:113]
	v_mfma_f32_16x16x32_bf16 v[106:109], v[138:141], v[192:195], v[106:109]
	v_mfma_f32_16x16x32_bf16 v[98:101], v[130:133], v[200:203], v[98:101]
	v_mfma_f32_16x16x32_bf16 v[90:93], v[138:141], v[200:203], v[90:93]
	v_mfma_f32_16x16x32_bf16 v[82:85], v[130:133], v[210:213], v[82:85]
	v_mfma_f32_16x16x32_bf16 v[74:77], v[138:141], v[210:213], v[74:77]
	v_mfma_f32_16x16x32_bf16 v[126:129], v[134:137], v[188:191], v[126:129]
	v_mfma_f32_16x16x32_bf16 v[122:125], v[142:145], v[188:191], v[122:125]
	v_mfma_f32_16x16x32_bf16 v[110:113], v[134:137], v[196:199], v[110:113]
	v_mfma_f32_16x16x32_bf16 v[106:109], v[142:145], v[196:199], v[106:109]
	v_mfma_f32_16x16x32_bf16 v[98:101], v[134:137], v[206:209], v[98:101]
	v_mfma_f32_16x16x32_bf16 v[90:93], v[142:145], v[206:209], v[90:93]
	v_mfma_f32_16x16x32_bf16 v[82:85], v[134:137], v[214:217], v[82:85]
	v_mfma_f32_16x16x32_bf16 v[74:77], v[142:145], v[214:217], v[74:77]
	v_mfma_f32_16x16x32_bf16 v[118:121], v[162:165], v[184:187], v[118:121]
	v_mfma_f32_16x16x32_bf16 v[114:117], v[176:179], v[184:187], v[114:117]
	v_mfma_f32_16x16x32_bf16 v[102:105], v[162:165], v[192:195], v[102:105]
	v_mfma_f32_16x16x32_bf16 v[94:97], v[176:179], v[192:195], v[94:97]
	v_mfma_f32_16x16x32_bf16 v[86:89], v[162:165], v[200:203], v[86:89]
	v_mfma_f32_16x16x32_bf16 v[78:81], v[176:179], v[200:203], v[78:81]
	v_mfma_f32_16x16x32_bf16 v[70:73], v[162:165], v[210:213], v[70:73]
	v_mfma_f32_16x16x32_bf16 v[66:69], v[176:179], v[210:213], v[66:69]
	v_mfma_f32_16x16x32_bf16 v[118:121], v[172:175], v[188:191], v[118:121]
	v_mfma_f32_16x16x32_bf16 v[114:117], v[180:183], v[188:191], v[114:117]
	v_mfma_f32_16x16x32_bf16 v[102:105], v[172:175], v[196:199], v[102:105]
	v_mfma_f32_16x16x32_bf16 v[94:97], v[180:183], v[196:199], v[94:97]
	v_mfma_f32_16x16x32_bf16 v[86:89], v[172:175], v[206:209], v[86:89]
	v_mfma_f32_16x16x32_bf16 v[78:81], v[180:183], v[206:209], v[78:81]
	v_mfma_f32_16x16x32_bf16 v[70:73], v[172:175], v[214:217], v[70:73]
	v_mfma_f32_16x16x32_bf16 v[66:69], v[180:183], v[214:217], v[66:69]
	s_barrier
	s_setprio 0
	s_add_i32 s94, s31, s2
	v_lshl_add_u64 v[218:219], s[62:63], 0, v[148:149]
	s_mov_b32 m0, s94
	ds_read_b128 v[184:187], v170 offset:16384
	ds_read_b128 v[188:191], v170 offset:17408
	ds_read_b128 v[192:195], v170 offset:18432
	ds_read_b128 v[196:199], v170 offset:19456
	ds_read_b128 v[200:203], v170 offset:20480
	ds_read_b128 v[206:209], v170 offset:21504
	ds_read_b128 v[210:213], v170 offset:22528
	ds_read_b128 v[214:217], v170 offset:23552
	global_load_lds_dwordx4 v[218:219], off
	s_add_i32 m0, s94, 0x2000
	s_add_u32 s94, s62, 0x100000
	v_lshl_add_u64 v[220:221], s[62:63], 0, v[152:153]
	s_addc_u32 s95, s63, 0
	s_add_i32 s96, s82, s2
	global_load_lds_dwordx4 v[220:221], off
	v_lshl_add_u64 v[222:223], s[94:95], 0, v[148:149]
	s_mov_b32 m0, s96
	v_lshl_add_u64 v[224:225], s[64:65], 0, v[150:151]
	global_load_lds_dwordx4 v[222:223], off
	v_lshl_add_u64 v[222:223], s[94:95], 0, v[152:153]
	s_add_i32 m0, s96, 0x2000
	s_nop 0
	global_load_lds_dwordx4 v[222:223], off
	v_lshl_add_u64 v[222:223], s[64:65], 0, v[146:147]
	s_mov_b32 m0, s12
	s_nop 0
	global_load_lds_dwordx4 v[222:223], off
	s_mov_b32 m0, s13
	s_nop 0
	global_load_lds_dwordx4 v[224:225], off
	s_waitcnt vmcnt(8)
	s_waitcnt lgkmcnt(0)
	s_setprio 1
	s_barrier
	v_mfma_f32_16x16x32_bf16 v[62:65], v[130:133], v[184:187], v[62:65]
	v_mfma_f32_16x16x32_bf16 v[58:61], v[138:141], v[184:187], v[58:61]
	v_mfma_f32_16x16x32_bf16 v[50:53], v[130:133], v[192:195], v[50:53]
	v_mfma_f32_16x16x32_bf16 v[42:45], v[138:141], v[192:195], v[42:45]
	v_mfma_f32_16x16x32_bf16 v[34:37], v[130:133], v[200:203], v[34:37]
	v_mfma_f32_16x16x32_bf16 v[26:29], v[138:141], v[200:203], v[26:29]
	v_mfma_f32_16x16x32_bf16 v[18:21], v[130:133], v[210:213], v[18:21]
	v_mfma_f32_16x16x32_bf16 v[10:13], v[138:141], v[210:213], v[10:13]
	v_mfma_f32_16x16x32_bf16 v[62:65], v[134:137], v[188:191], v[62:65]
	v_mfma_f32_16x16x32_bf16 v[58:61], v[142:145], v[188:191], v[58:61]
	v_mfma_f32_16x16x32_bf16 v[50:53], v[134:137], v[196:199], v[50:53]
	v_mfma_f32_16x16x32_bf16 v[42:45], v[142:145], v[196:199], v[42:45]
	v_mfma_f32_16x16x32_bf16 v[34:37], v[134:137], v[206:209], v[34:37]
	v_mfma_f32_16x16x32_bf16 v[26:29], v[142:145], v[206:209], v[26:29]
	v_mfma_f32_16x16x32_bf16 v[18:21], v[134:137], v[214:217], v[18:21]
	v_mfma_f32_16x16x32_bf16 v[10:13], v[142:145], v[214:217], v[10:13]
	v_mfma_f32_16x16x32_bf16 v[54:57], v[162:165], v[184:187], v[54:57]
	v_mfma_f32_16x16x32_bf16 v[46:49], v[176:179], v[184:187], v[46:49]
	v_mfma_f32_16x16x32_bf16 v[38:41], v[162:165], v[192:195], v[38:41]
	v_mfma_f32_16x16x32_bf16 v[30:33], v[176:179], v[192:195], v[30:33]
	v_mfma_f32_16x16x32_bf16 v[22:25], v[162:165], v[200:203], v[22:25]
	v_mfma_f32_16x16x32_bf16 v[14:17], v[176:179], v[200:203], v[14:17]
	v_mfma_f32_16x16x32_bf16 v[6:9], v[162:165], v[210:213], v[6:9]
	v_mfma_f32_16x16x32_bf16 v[2:5], v[176:179], v[210:213], v[2:5]
	v_mfma_f32_16x16x32_bf16 v[54:57], v[172:175], v[188:191], v[54:57]
	v_mfma_f32_16x16x32_bf16 v[46:49], v[180:183], v[188:191], v[46:49]
	v_mfma_f32_16x16x32_bf16 v[38:41], v[172:175], v[196:199], v[38:41]
	v_mfma_f32_16x16x32_bf16 v[30:33], v[180:183], v[196:199], v[30:33]
	v_mfma_f32_16x16x32_bf16 v[22:25], v[172:175], v[206:209], v[22:25]
	v_mfma_f32_16x16x32_bf16 v[14:17], v[180:183], v[206:209], v[14:17]
	v_mfma_f32_16x16x32_bf16 v[6:9], v[172:175], v[214:217], v[6:9]
	v_mfma_f32_16x16x32_bf16 v[2:5], v[180:183], v[214:217], v[2:5]
	s_barrier
	s_setprio 0
	s_add_i32 s94, 0, 0x18000
	s_add_i32 s95, 0, 0x1c000
	v_add_u32_e32 v142, s94, v167
	v_add_u32_e32 v154, s95, v167
	ds_read_b128 v[130:133], v142
	ds_read_b128 v[134:137], v142 offset:1024
	ds_read_b128 v[138:141], v142 offset:2048
	ds_read_b128 v[142:145], v142 offset:3072
	ds_read_b128 v[162:165], v154
	ds_read_b128 v[172:175], v154 offset:1024
	ds_read_b128 v[176:179], v154 offset:2048
	ds_read_b128 v[180:183], v154 offset:3072
	s_add_u32 s64, s64, 0x100000
	s_addc_u32 s65, s65, 0
	s_mov_b32 m0, s18
	v_lshl_add_u64 v[226:227], s[64:65], 0, v[146:147]
	ds_read_b128 v[184:187], v170 offset:32768
	ds_read_b128 v[188:191], v170 offset:33792
	ds_read_b128 v[192:195], v170 offset:34816
	ds_read_b128 v[196:199], v170 offset:35840
	ds_read_b128 v[200:203], v170 offset:36864
	ds_read_b128 v[206:209], v170 offset:37888
	ds_read_b128 v[210:213], v170 offset:38912
	ds_read_b128 v[214:217], v170 offset:39936
	global_load_lds_dwordx4 v[226:227], off
	v_lshl_add_u64 v[226:227], s[64:65], 0, v[150:151]
	s_mov_b32 m0, s19
	s_nop 0
	global_load_lds_dwordx4 v[226:227], off
	s_waitcnt vmcnt(8)
	s_waitcnt lgkmcnt(0)
	s_setprio 1
	s_barrier
	v_mfma_f32_16x16x32_bf16 v[126:129], v[130:133], v[184:187], v[126:129]
	v_mfma_f32_16x16x32_bf16 v[122:125], v[138:141], v[184:187], v[122:125]
	v_mfma_f32_16x16x32_bf16 v[110:113], v[130:133], v[192:195], v[110:113]
	v_mfma_f32_16x16x32_bf16 v[106:109], v[138:141], v[192:195], v[106:109]
	v_mfma_f32_16x16x32_bf16 v[98:101], v[130:133], v[200:203], v[98:101]
	v_mfma_f32_16x16x32_bf16 v[90:93], v[138:141], v[200:203], v[90:93]
	v_mfma_f32_16x16x32_bf16 v[82:85], v[130:133], v[210:213], v[82:85]
	v_mfma_f32_16x16x32_bf16 v[74:77], v[138:141], v[210:213], v[74:77]
	v_mfma_f32_16x16x32_bf16 v[126:129], v[134:137], v[188:191], v[126:129]
	v_mfma_f32_16x16x32_bf16 v[122:125], v[142:145], v[188:191], v[122:125]
	v_mfma_f32_16x16x32_bf16 v[110:113], v[134:137], v[196:199], v[110:113]
	v_mfma_f32_16x16x32_bf16 v[106:109], v[142:145], v[196:199], v[106:109]
	v_mfma_f32_16x16x32_bf16 v[98:101], v[134:137], v[206:209], v[98:101]
	v_mfma_f32_16x16x32_bf16 v[90:93], v[142:145], v[206:209], v[90:93]
	v_mfma_f32_16x16x32_bf16 v[82:85], v[134:137], v[214:217], v[82:85]
	v_mfma_f32_16x16x32_bf16 v[74:77], v[142:145], v[214:217], v[74:77]
	v_mfma_f32_16x16x32_bf16 v[118:121], v[162:165], v[184:187], v[118:121]
	v_mfma_f32_16x16x32_bf16 v[114:117], v[176:179], v[184:187], v[114:117]
	v_mfma_f32_16x16x32_bf16 v[102:105], v[162:165], v[192:195], v[102:105]
	v_mfma_f32_16x16x32_bf16 v[94:97], v[176:179], v[192:195], v[94:97]
	v_mfma_f32_16x16x32_bf16 v[86:89], v[162:165], v[200:203], v[86:89]
	v_mfma_f32_16x16x32_bf16 v[78:81], v[176:179], v[200:203], v[78:81]
	v_mfma_f32_16x16x32_bf16 v[70:73], v[162:165], v[210:213], v[70:73]
	v_mfma_f32_16x16x32_bf16 v[66:69], v[176:179], v[210:213], v[66:69]
	v_mfma_f32_16x16x32_bf16 v[118:121], v[172:175], v[188:191], v[118:121]
	v_mfma_f32_16x16x32_bf16 v[114:117], v[180:183], v[188:191], v[114:117]
	v_mfma_f32_16x16x32_bf16 v[102:105], v[172:175], v[196:199], v[102:105]
	v_mfma_f32_16x16x32_bf16 v[94:97], v[180:183], v[196:199], v[94:97]
	v_mfma_f32_16x16x32_bf16 v[86:89], v[172:175], v[206:209], v[86:89]
	v_mfma_f32_16x16x32_bf16 v[78:81], v[180:183], v[206:209], v[78:81]
	v_mfma_f32_16x16x32_bf16 v[70:73], v[172:175], v[214:217], v[70:73]
	v_mfma_f32_16x16x32_bf16 v[66:69], v[180:183], v[214:217], v[66:69]
	s_barrier
	s_setprio 0
	s_add_i32 s64, s94, s2
	v_lshl_add_u64 v[218:219], v[218:219], 0, s[16:17]
	s_mov_b32 m0, s64
	ds_read_b128 v[184:187], v170 offset:49152
	ds_read_b128 v[188:191], v170 offset:50176
	ds_read_b128 v[192:195], v170 offset:51200
	ds_read_b128 v[196:199], v170 offset:52224
	ds_read_b128 v[200:203], v170 offset:53248
	ds_read_b128 v[206:209], v170 offset:54272
	ds_read_b128 v[210:213], v170 offset:55296
	ds_read_b128 v[214:217], v170 offset:56320
	global_load_lds_dwordx4 v[218:219], off
	s_add_i32 m0, s64, 0x2000
	s_add_u32 s62, s62, 0x100080
	v_lshl_add_u64 v[218:219], v[220:221], 0, s[16:17]
	s_addc_u32 s63, s63, 0
	s_add_i32 s64, s95, s2
	global_load_lds_dwordx4 v[218:219], off
	v_lshl_add_u64 v[218:219], s[62:63], 0, v[148:149]
	s_mov_b32 m0, s64
	s_nop 0
	global_load_lds_dwordx4 v[218:219], off
	v_lshl_add_u64 v[218:219], s[62:63], 0, v[152:153]
	s_add_i32 m0, s64, 0x2000
	s_nop 0
	global_load_lds_dwordx4 v[218:219], off
	v_lshl_add_u64 v[218:219], v[222:223], 0, s[16:17]
	s_mov_b32 m0, s74
	s_nop 0
	global_load_lds_dwordx4 v[218:219], off
	v_lshl_add_u64 v[218:219], v[224:225], 0, s[16:17]
	s_mov_b32 m0, s75
	s_nop 0
	global_load_lds_dwordx4 v[218:219], off
	s_waitcnt vmcnt(8)
	s_waitcnt lgkmcnt(0)
	s_setprio 1
	s_barrier
	v_mfma_f32_16x16x32_bf16 v[62:65], v[130:133], v[184:187], v[62:65]
	v_mfma_f32_16x16x32_bf16 v[58:61], v[138:141], v[184:187], v[58:61]
	v_mfma_f32_16x16x32_bf16 v[50:53], v[130:133], v[192:195], v[50:53]
	v_mfma_f32_16x16x32_bf16 v[42:45], v[138:141], v[192:195], v[42:45]
	v_mfma_f32_16x16x32_bf16 v[34:37], v[130:133], v[200:203], v[34:37]
	v_mfma_f32_16x16x32_bf16 v[26:29], v[138:141], v[200:203], v[26:29]
	v_mfma_f32_16x16x32_bf16 v[18:21], v[130:133], v[210:213], v[18:21]
	v_mfma_f32_16x16x32_bf16 v[10:13], v[138:141], v[210:213], v[10:13]
	v_mfma_f32_16x16x32_bf16 v[62:65], v[134:137], v[188:191], v[62:65]
	v_mfma_f32_16x16x32_bf16 v[58:61], v[142:145], v[188:191], v[58:61]
	v_mfma_f32_16x16x32_bf16 v[50:53], v[134:137], v[196:199], v[50:53]
	v_mfma_f32_16x16x32_bf16 v[42:45], v[142:145], v[196:199], v[42:45]
	v_mfma_f32_16x16x32_bf16 v[34:37], v[134:137], v[206:209], v[34:37]
	v_mfma_f32_16x16x32_bf16 v[26:29], v[142:145], v[206:209], v[26:29]
	v_mfma_f32_16x16x32_bf16 v[18:21], v[134:137], v[214:217], v[18:21]
	v_mfma_f32_16x16x32_bf16 v[10:13], v[142:145], v[214:217], v[10:13]
	v_mfma_f32_16x16x32_bf16 v[54:57], v[162:165], v[184:187], v[54:57]
	v_mfma_f32_16x16x32_bf16 v[46:49], v[176:179], v[184:187], v[46:49]
	v_mfma_f32_16x16x32_bf16 v[38:41], v[162:165], v[192:195], v[38:41]
	v_mfma_f32_16x16x32_bf16 v[30:33], v[176:179], v[192:195], v[30:33]
	v_mfma_f32_16x16x32_bf16 v[22:25], v[162:165], v[200:203], v[22:25]
	v_mfma_f32_16x16x32_bf16 v[14:17], v[176:179], v[200:203], v[14:17]
	v_mfma_f32_16x16x32_bf16 v[6:9], v[162:165], v[210:213], v[6:9]
	v_mfma_f32_16x16x32_bf16 v[2:5], v[176:179], v[210:213], v[2:5]
	v_mfma_f32_16x16x32_bf16 v[54:57], v[172:175], v[188:191], v[54:57]
	v_mfma_f32_16x16x32_bf16 v[46:49], v[180:183], v[188:191], v[46:49]
	v_mfma_f32_16x16x32_bf16 v[38:41], v[172:175], v[196:199], v[38:41]
	v_mfma_f32_16x16x32_bf16 v[30:33], v[180:183], v[196:199], v[30:33]
	v_mfma_f32_16x16x32_bf16 v[22:25], v[172:175], v[206:209], v[22:25]
	v_mfma_f32_16x16x32_bf16 v[14:17], v[180:183], v[206:209], v[14:17]
	v_mfma_f32_16x16x32_bf16 v[6:9], v[172:175], v[214:217], v[6:9]
	v_mfma_f32_16x16x32_bf16 v[2:5], v[180:183], v[214:217], v[2:5]
	s_barrier
	s_setprio 0
	s_add_u32 s50, s50, 0x100
	s_addc_u32 s51, s51, 0
	s_add_u32 s91, s91, 0x100
	s_addc_u32 s92, s92, 0
	s_cmp_ge_i32 s93, s7
	s_mov_b32 s62, s93
	s_cbranch_scc0 .LBB0_1708
	s_and_b64 vcc, exec, s[20:21]
	s_cbranch_vccz .LBB0_1711
	s_barrier
